# v86 + K-loop load segments reordered: fragment ds_reads issued first, scalar pointer math and DMA address adds after (M0 pads re-inserted)
# baseline (speedup 1.0000x reference)
; #define PG8_STAGE(bufoff, gbase, voff) do { _Pragma("unroll") for (int _i = 0; _i < 2; ++_i) \
;         __builtin_amdgcn_global_load_lds((const unsigned*)((const char*)(gbase) + (voff)[_i]), (PG8_LAS unsigned*)(lds + (bufoff) + ldsw + _i * 8192), 16, 0, 0); } while (0)
; #define PG8_LDA(dst, b, h) do { _Pragma("unroll") for (int m = 0; m < 4; ++m) _Pragma("unroll") for (int k = 0; k < 2; ++k) dst[m][k] = *(const PG8_LAS bf16x8*)(lds + PG8_SA(b, h) + aoff + m * 2048 + k * 1024); } while (0)
; #define PG8_LDB(dst, b, h) do { _Pragma("unroll") for (int n = 0; n < 2; ++n) _Pragma("unroll") for (int k = 0; k < 2; ++k) dst[n][k] = *(const PG8_LAS bf16x8*)(lds + PG8_SB(b, h) + boff + n * 2048 + k * 1024); } while (0)
; #define PG8_MMA(ai, bj, At, Bt) do { __builtin_amdgcn_s_setprio(1); _Pragma("unroll") for (int m = 0; m < 4; ++m) _Pragma("unroll") for (int n = 0; n < 2; ++n) _Pragma("unroll") for (int k = 0; k < 2; ++k) \
;         acc[ai][bj][m][n] = __builtin_amdgcn_mfma_f32_16x16x32_bf16(Bt[n][k], At[m][k], acc[ai][bj][m][n], 0, 0, 0); __builtin_amdgcn_s_setprio(0); } while (0)
; #define PG8_WAIT_V(n) asm volatile("s_waitcnt vmcnt(" #n ")" ::: "memory")
; #define PG8_WAIT_L(n) asm volatile("s_waitcnt lgkmcnt(" #n ")" ::: "memory")
; #define PG8_BAR __builtin_amdgcn_s_barrier()
; #define PG8_SCHED __builtin_amdgcn_sched_barrier(0)
;     ...
;             PG8_LDB(B0, 0, 0); PG8_LDB(B1, 0, 1); PG8_SCHED; PG8_LDA(At, 0, 0); PG8_STAGE(PG8_SA(1, 1), a1 + hstep, voffA);
;             PG8_WAIT_V(8); PG8_WAIT_L(0); PG8_BAR; PG8_MMA(0, 0, At, B0); PG8_MMA(0, 1, At, B1); PG8_BAR; PG8_SCHED;
;             PG8_LDA(At, 0, 1); PG8_STAGE(PG8_SB(0, 0), b2, voffB); PG8_STAGE(PG8_SB(0, 1), b2 + hstep, voffB); PG8_STAGE(PG8_SA(0, 0), a2, voffA);
;             PG8_WAIT_V(8); PG8_WAIT_L(0); PG8_BAR; PG8_MMA(1, 0, At, B0); PG8_MMA(1, 1, At, B1); PG8_BAR; PG8_SCHED;
.LBB0_198:
	ds_read_b128 v[142:145], v251
	ds_read_b128 v[146:149], v251 offset:1024
	ds_read_b128 v[150:153], v251 offset:2048
	ds_read_b128 v[158:161], v251 offset:3072
	ds_read_b128 v[162:165], v251 offset:16384
	ds_read_b128 v[166:169], v251 offset:17408
	ds_read_b128 v[170:173], v251 offset:18432
	ds_read_b128 v[174:177], v251 offset:19456
	ds_read_b128 v[178:181], v156
	ds_read_b128 v[182:185], v156 offset:1024
	ds_read_b128 v[186:189], v156 offset:2048
	ds_read_b128 v[190:193], v156 offset:3072
	ds_read_b128 v[194:197], v156 offset:4096
	ds_read_b128 v[210:213], v156 offset:5120
	ds_read_b128 v[214:217], v156 offset:6144
	ds_read_b128 v[218:221], v156 offset:7168
	s_add_u32 s48, s60, 0xfff80080
	s_addc_u32 s49, s61, -1
	s_add_i32 s87, 0, 0x10000
	s_cmp_eq_u32 s86, 28
	s_cselect_b32 s69, s25, s49
	s_cselect_b32 s68, s81, s48
	s_cselect_b32 s63, s15, s85
	s_cselect_b32 s62, s83, s84
	s_add_i32 s48, 0, 0x14000
	v_lshl_add_u64 v[198:199], s[60:61], 0, v[138:139]
	s_add_i32 m0, s20, 0xc000
	s_nop 0
	global_load_lds_dwordx4 v[198:199], off
	v_lshl_add_u64 v[198:199], s[60:61], 0, v[140:141]
	s_add_i32 m0, s20, 0xe000
	s_nop 0
	global_load_lds_dwordx4 v[198:199], off
	s_waitcnt vmcnt(8)
	s_waitcnt lgkmcnt(0)
	s_setprio 1
	s_barrier
	v_mfma_f32_16x16x32_bf16 v[128:131], v[142:145], v[178:181], v[128:131]
	v_mfma_f32_16x16x32_bf16 v[124:127], v[150:153], v[178:181], v[124:127]
	v_mfma_f32_16x16x32_bf16 v[112:115], v[142:145], v[186:189], v[112:115]
	v_mfma_f32_16x16x32_bf16 v[108:111], v[150:153], v[186:189], v[108:111]
	v_mfma_f32_16x16x32_bf16 v[96:99], v[142:145], v[194:197], v[96:99]
	v_mfma_f32_16x16x32_bf16 v[92:95], v[150:153], v[194:197], v[92:95]
	v_mfma_f32_16x16x32_bf16 v[80:83], v[142:145], v[214:217], v[80:83]
	v_mfma_f32_16x16x32_bf16 v[76:79], v[150:153], v[214:217], v[76:79]
	v_mfma_f32_16x16x32_bf16 v[128:131], v[146:149], v[182:185], v[128:131]
	v_mfma_f32_16x16x32_bf16 v[124:127], v[158:161], v[182:185], v[124:127]
	v_mfma_f32_16x16x32_bf16 v[112:115], v[146:149], v[190:193], v[112:115]
	v_mfma_f32_16x16x32_bf16 v[108:111], v[158:161], v[190:193], v[108:111]
	v_mfma_f32_16x16x32_bf16 v[96:99], v[146:149], v[210:213], v[96:99]
	v_mfma_f32_16x16x32_bf16 v[92:95], v[158:161], v[210:213], v[92:95]
	v_mfma_f32_16x16x32_bf16 v[80:83], v[146:149], v[218:221], v[80:83]
	v_mfma_f32_16x16x32_bf16 v[76:79], v[158:161], v[218:221], v[76:79]
	s_setprio 0
	s_setprio 1
	v_mfma_f32_16x16x32_bf16 v[120:123], v[162:165], v[178:181], v[120:123]
	v_mfma_f32_16x16x32_bf16 v[116:119], v[170:173], v[178:181], v[116:119]
	v_mfma_f32_16x16x32_bf16 v[104:107], v[162:165], v[186:189], v[104:107]
	v_mfma_f32_16x16x32_bf16 v[100:103], v[170:173], v[186:189], v[100:103]
	v_mfma_f32_16x16x32_bf16 v[88:91], v[162:165], v[194:197], v[88:91]
	v_mfma_f32_16x16x32_bf16 v[84:87], v[170:173], v[194:197], v[84:87]
	v_mfma_f32_16x16x32_bf16 v[72:75], v[162:165], v[214:217], v[72:75]
	v_mfma_f32_16x16x32_bf16 v[68:71], v[170:173], v[214:217], v[68:71]
	v_mfma_f32_16x16x32_bf16 v[120:123], v[166:169], v[182:185], v[120:123]
	v_mfma_f32_16x16x32_bf16 v[116:119], v[174:177], v[182:185], v[116:119]
	v_mfma_f32_16x16x32_bf16 v[104:107], v[166:169], v[190:193], v[104:107]
	v_mfma_f32_16x16x32_bf16 v[100:103], v[174:177], v[190:193], v[100:103]
	v_mfma_f32_16x16x32_bf16 v[88:91], v[166:169], v[210:213], v[88:91]
	v_mfma_f32_16x16x32_bf16 v[84:87], v[174:177], v[210:213], v[84:87]
	v_mfma_f32_16x16x32_bf16 v[72:75], v[166:169], v[218:221], v[72:75]
	v_mfma_f32_16x16x32_bf16 v[68:71], v[174:177], v[218:221], v[68:71]
	s_barrier
	s_setprio 0
	ds_read_b128 v[178:181], v156 offset:16384
	ds_read_b128 v[182:185], v156 offset:17408
	ds_read_b128 v[186:189], v156 offset:18432
	ds_read_b128 v[190:193], v156 offset:19456
	ds_read_b128 v[194:197], v156 offset:20480
	ds_read_b128 v[210:213], v156 offset:21504
	ds_read_b128 v[214:217], v156 offset:22528
	ds_read_b128 v[218:221], v156 offset:23552
	s_add_i32 s49, s87, s1
	v_lshl_add_u64 v[198:199], s[62:63], 0, v[200:201]
	s_mov_b32 m0, s49
	s_nop 0
	global_load_lds_dwordx4 v[198:199], off
	s_add_i32 m0, s49, 0x2000
	s_add_u32 s88, s62, 0x80000
	v_lshl_add_u64 v[206:207], s[62:63], 0, v[132:133]
	s_addc_u32 s89, s63, 0
	s_add_i32 s48, s48, s1
	global_load_lds_dwordx4 v[206:207], off
	v_lshl_add_u64 v[208:209], s[88:89], 0, v[200:201]
	s_mov_b32 m0, s48
	v_lshl_add_u64 v[222:223], s[68:69], 0, v[134:135]
	global_load_lds_dwordx4 v[208:209], off
	v_lshl_add_u64 v[208:209], s[88:89], 0, v[132:133]
	s_add_i32 m0, s48, 0x2000
	s_nop 0
	global_load_lds_dwordx4 v[208:209], off
	v_lshl_add_u64 v[208:209], s[68:69], 0, v[136:137]
	s_mov_b32 m0, s20
	s_nop 0
	global_load_lds_dwordx4 v[208:209], off
	s_mov_b32 m0, s21
	s_nop 0
	global_load_lds_dwordx4 v[222:223], off
	s_waitcnt vmcnt(8)
	s_waitcnt lgkmcnt(0)
	s_setprio 1
	s_barrier
; #define PG8_STAGE(bufoff, gbase, voff) do { _Pragma("unroll") for (int _i = 0; _i < 2; ++_i) \
;         __builtin_amdgcn_global_load_lds((const unsigned*)((const char*)(gbase) + (voff)[_i]), (PG8_LAS unsigned*)(lds + (bufoff) + ldsw + _i * 8192), 16, 0, 0); } while (0)
; #define PG8_LDA(dst, b, h) do { _Pragma("unroll") for (int m = 0; m < 4; ++m) _Pragma("unroll") for (int k = 0; k < 2; ++k) dst[m][k] = *(const PG8_LAS bf16x8*)(lds + PG8_SA(b, h) + aoff + m * 2048 + k * 1024); } while (0)
; #define PG8_LDB(dst, b, h) do { _Pragma("unroll") for (int n = 0; n < 2; ++n) _Pragma("unroll") for (int k = 0; k < 2; ++k) dst[n][k] = *(const PG8_LAS bf16x8*)(lds + PG8_SB(b, h) + boff + n * 2048 + k * 1024); } while (0)
; #define PG8_MMA(ai, bj, At, Bt) do { __builtin_amdgcn_s_setprio(1); _Pragma("unroll") for (int m = 0; m < 4; ++m) _Pragma("unroll") for (int n = 0; n < 2; ++n) _Pragma("unroll") for (int k = 0; k < 2; ++k) \
;         acc[ai][bj][m][n] = __builtin_amdgcn_mfma_f32_16x16x32_bf16(Bt[n][k], At[m][k], acc[ai][bj][m][n], 0, 0, 0); __builtin_amdgcn_s_setprio(0); } while (0)
; #define PG8_WAIT_V(n) asm volatile("s_waitcnt vmcnt(" #n ")" ::: "memory")
; #define PG8_WAIT_L(n) asm volatile("s_waitcnt lgkmcnt(" #n ")" ::: "memory")
; #define PG8_BAR __builtin_amdgcn_s_barrier()
; #define PG8_SCHED __builtin_amdgcn_sched_barrier(0)
;     ...
;             PG8_WAIT_V(8); PG8_WAIT_L(0); PG8_BAR; PG8_MMA(1, 0, At, B0); PG8_MMA(1, 1, At, B1); PG8_BAR; PG8_SCHED;
;             PG8_LDB(B0, 1, 0); PG8_LDB(B1, 1, 1); PG8_SCHED; PG8_LDA(At, 1, 0); PG8_STAGE(PG8_SA(0, 1), a2 + hstep, voffA);
;             PG8_WAIT_V(8); PG8_WAIT_L(0); PG8_BAR; PG8_MMA(0, 0, At, B0); PG8_MMA(0, 1, At, B1); PG8_BAR; PG8_SCHED;
	v_mfma_f32_16x16x32_bf16 v[64:67], v[142:145], v[178:181], v[64:67]
	v_mfma_f32_16x16x32_bf16 v[60:63], v[150:153], v[178:181], v[60:63]
	v_mfma_f32_16x16x32_bf16 v[48:51], v[142:145], v[186:189], v[48:51]
	v_mfma_f32_16x16x32_bf16 v[44:47], v[150:153], v[186:189], v[44:47]
	v_mfma_f32_16x16x32_bf16 v[32:35], v[142:145], v[194:197], v[32:35]
	v_mfma_f32_16x16x32_bf16 v[28:31], v[150:153], v[194:197], v[28:31]
	v_mfma_f32_16x16x32_bf16 v[16:19], v[142:145], v[214:217], v[16:19]
	v_mfma_f32_16x16x32_bf16 v[12:15], v[150:153], v[214:217], v[12:15]
	v_mfma_f32_16x16x32_bf16 v[64:67], v[146:149], v[182:185], v[64:67]
	v_mfma_f32_16x16x32_bf16 v[60:63], v[158:161], v[182:185], v[60:63]
	v_mfma_f32_16x16x32_bf16 v[48:51], v[146:149], v[190:193], v[48:51]
	v_mfma_f32_16x16x32_bf16 v[44:47], v[158:161], v[190:193], v[44:47]
	v_mfma_f32_16x16x32_bf16 v[32:35], v[146:149], v[210:213], v[32:35]
	v_mfma_f32_16x16x32_bf16 v[28:31], v[158:161], v[210:213], v[28:31]
	v_mfma_f32_16x16x32_bf16 v[16:19], v[146:149], v[218:221], v[16:19]
	v_mfma_f32_16x16x32_bf16 v[12:15], v[158:161], v[218:221], v[12:15]
	s_setprio 0
	s_setprio 1
	v_mfma_f32_16x16x32_bf16 v[56:59], v[162:165], v[178:181], v[56:59]
	v_mfma_f32_16x16x32_bf16 v[52:55], v[170:173], v[178:181], v[52:55]
	v_mfma_f32_16x16x32_bf16 v[40:43], v[162:165], v[186:189], v[40:43]
	v_mfma_f32_16x16x32_bf16 v[36:39], v[170:173], v[186:189], v[36:39]
	v_mfma_f32_16x16x32_bf16 v[24:27], v[162:165], v[194:197], v[24:27]
	v_mfma_f32_16x16x32_bf16 v[20:23], v[170:173], v[194:197], v[20:23]
	v_mfma_f32_16x16x32_bf16 v[8:11], v[162:165], v[214:217], v[8:11]
	v_mfma_f32_16x16x32_bf16 v[4:7], v[170:173], v[214:217], v[4:7]
	v_mfma_f32_16x16x32_bf16 v[56:59], v[166:169], v[182:185], v[56:59]
	v_mfma_f32_16x16x32_bf16 v[52:55], v[174:177], v[182:185], v[52:55]
	v_mfma_f32_16x16x32_bf16 v[40:43], v[166:169], v[190:193], v[40:43]
	v_mfma_f32_16x16x32_bf16 v[36:39], v[174:177], v[190:193], v[36:39]
	v_mfma_f32_16x16x32_bf16 v[24:27], v[166:169], v[210:213], v[24:27]
	v_mfma_f32_16x16x32_bf16 v[20:23], v[174:177], v[210:213], v[20:23]
	v_mfma_f32_16x16x32_bf16 v[8:11], v[166:169], v[218:221], v[8:11]
	v_mfma_f32_16x16x32_bf16 v[4:7], v[174:177], v[218:221], v[4:7]
	s_barrier
	s_setprio 0
	ds_read_b128 v[142:145], v251 offset:32768
	ds_read_b128 v[146:149], v251 offset:33792
	ds_read_b128 v[150:153], v251 offset:34816
	ds_read_b128 v[158:161], v251 offset:35840
	ds_read_b128 v[162:165], v251 offset:49152
	ds_read_b128 v[166:169], v251 offset:50176
	ds_read_b128 v[170:173], v251 offset:51200
	ds_read_b128 v[174:177], v251 offset:52224
	ds_read_b128 v[178:181], v156 offset:32768
	ds_read_b128 v[182:185], v156 offset:33792
	ds_read_b128 v[186:189], v156 offset:34816
	ds_read_b128 v[190:193], v156 offset:35840
	ds_read_b128 v[194:197], v156 offset:36864
	ds_read_b128 v[210:213], v156 offset:37888
	ds_read_b128 v[214:217], v156 offset:38912
	ds_read_b128 v[218:221], v156 offset:39936
	s_add_i32 s48, 0, 0x18000
	s_add_i32 s49, 0, 0x1c000
	s_add_u32 s68, s68, 0x80000
	s_addc_u32 s69, s69, 0
	s_mov_b32 m0, s23
	v_lshl_add_u64 v[224:225], s[68:69], 0, v[136:137]
	global_load_lds_dwordx4 v[224:225], off
	v_lshl_add_u64 v[224:225], s[68:69], 0, v[134:135]
	s_mov_b32 m0, s42
	s_nop 0
	global_load_lds_dwordx4 v[224:225], off
	s_waitcnt vmcnt(8)
	s_waitcnt lgkmcnt(0)
	s_setprio 1
	s_barrier
	v_mfma_f32_16x16x32_bf16 v[128:131], v[142:145], v[178:181], v[128:131]
	v_mfma_f32_16x16x32_bf16 v[124:127], v[150:153], v[178:181], v[124:127]
	v_mfma_f32_16x16x32_bf16 v[112:115], v[142:145], v[186:189], v[112:115]
	v_mfma_f32_16x16x32_bf16 v[108:111], v[150:153], v[186:189], v[108:111]
	v_mfma_f32_16x16x32_bf16 v[96:99], v[142:145], v[194:197], v[96:99]
	v_mfma_f32_16x16x32_bf16 v[92:95], v[150:153], v[194:197], v[92:95]
	v_mfma_f32_16x16x32_bf16 v[80:83], v[142:145], v[214:217], v[80:83]
	v_mfma_f32_16x16x32_bf16 v[76:79], v[150:153], v[214:217], v[76:79]
	v_mfma_f32_16x16x32_bf16 v[128:131], v[146:149], v[182:185], v[128:131]
	v_mfma_f32_16x16x32_bf16 v[124:127], v[158:161], v[182:185], v[124:127]
	v_mfma_f32_16x16x32_bf16 v[112:115], v[146:149], v[190:193], v[112:115]
	v_mfma_f32_16x16x32_bf16 v[108:111], v[158:161], v[190:193], v[108:111]
	v_mfma_f32_16x16x32_bf16 v[96:99], v[146:149], v[210:213], v[96:99]
	v_mfma_f32_16x16x32_bf16 v[92:95], v[158:161], v[210:213], v[92:95]
	v_mfma_f32_16x16x32_bf16 v[80:83], v[146:149], v[218:221], v[80:83]
	v_mfma_f32_16x16x32_bf16 v[76:79], v[158:161], v[218:221], v[76:79]
	s_setprio 0
	s_setprio 1
	v_mfma_f32_16x16x32_bf16 v[120:123], v[162:165], v[178:181], v[120:123]
	v_mfma_f32_16x16x32_bf16 v[116:119], v[170:173], v[178:181], v[116:119]
	v_mfma_f32_16x16x32_bf16 v[104:107], v[162:165], v[186:189], v[104:107]
	v_mfma_f32_16x16x32_bf16 v[100:103], v[170:173], v[186:189], v[100:103]
	v_mfma_f32_16x16x32_bf16 v[88:91], v[162:165], v[194:197], v[88:91]
	v_mfma_f32_16x16x32_bf16 v[84:87], v[170:173], v[194:197], v[84:87]
	v_mfma_f32_16x16x32_bf16 v[72:75], v[162:165], v[214:217], v[72:75]
	v_mfma_f32_16x16x32_bf16 v[68:71], v[170:173], v[214:217], v[68:71]
	v_mfma_f32_16x16x32_bf16 v[120:123], v[166:169], v[182:185], v[120:123]
	v_mfma_f32_16x16x32_bf16 v[116:119], v[174:177], v[182:185], v[116:119]
	v_mfma_f32_16x16x32_bf16 v[104:107], v[166:169], v[190:193], v[104:107]
	v_mfma_f32_16x16x32_bf16 v[100:103], v[174:177], v[190:193], v[100:103]
	v_mfma_f32_16x16x32_bf16 v[88:91], v[166:169], v[210:213], v[88:91]
	v_mfma_f32_16x16x32_bf16 v[84:87], v[174:177], v[210:213], v[84:87]
	v_mfma_f32_16x16x32_bf16 v[72:75], v[166:169], v[218:221], v[72:75]
	v_mfma_f32_16x16x32_bf16 v[68:71], v[174:177], v[218:221], v[68:71]
	s_barrier
; #define PG8_STAGE(bufoff, gbase, voff) do { _Pragma("unroll") for (int _i = 0; _i < 2; ++_i) \
;         __builtin_amdgcn_global_load_lds((const unsigned*)((const char*)(gbase) + (voff)[_i]), (PG8_LAS unsigned*)(lds + (bufoff) + ldsw + _i * 8192), 16, 0, 0); } while (0)
; #define PG8_LDA(dst, b, h) do { _Pragma("unroll") for (int m = 0; m < 4; ++m) _Pragma("unroll") for (int k = 0; k < 2; ++k) dst[m][k] = *(const PG8_LAS bf16x8*)(lds + PG8_SA(b, h) + aoff + m * 2048 + k * 1024); } while (0)
; #define PG8_MMA(ai, bj, At, Bt) do { __builtin_amdgcn_s_setprio(1); _Pragma("unroll") for (int m = 0; m < 4; ++m) _Pragma("unroll") for (int n = 0; n < 2; ++n) _Pragma("unroll") for (int k = 0; k < 2; ++k) \
;         acc[ai][bj][m][n] = __builtin_amdgcn_mfma_f32_16x16x32_bf16(Bt[n][k], At[m][k], acc[ai][bj][m][n], 0, 0, 0); __builtin_amdgcn_s_setprio(0); } while (0)
; #define PG8_WAIT_V(n) asm volatile("s_waitcnt vmcnt(" #n ")" ::: "memory")
; #define PG8_WAIT_L(n) asm volatile("s_waitcnt lgkmcnt(" #n ")" ::: "memory")
; #define PG8_BAR __builtin_amdgcn_s_barrier()
; #define PG8_SCHED __builtin_amdgcn_sched_barrier(0)
;     ...
;             PG8_LDA(At, 1, 1); PG8_STAGE(PG8_SB(1, 0), b3, voffB); PG8_STAGE(PG8_SB(1, 1), b3 + hstep, voffB); PG8_STAGE(PG8_SA(1, 0), a3, voffA);
;             PG8_WAIT_V(8); PG8_WAIT_L(0); PG8_BAR; PG8_MMA(1, 0, At, B0); PG8_MMA(1, 1, At, B1); PG8_BAR; PG8_SCHED;
	s_setprio 0
	ds_read_b128 v[178:181], v156 offset:49152
	ds_read_b128 v[182:185], v156 offset:50176
	ds_read_b128 v[186:189], v156 offset:51200
	ds_read_b128 v[190:193], v156 offset:52224
	ds_read_b128 v[194:197], v156 offset:53248
	ds_read_b128 v[210:213], v156 offset:54272
	ds_read_b128 v[214:217], v156 offset:55296
	ds_read_b128 v[218:221], v156 offset:56320
	s_add_i32 s48, s48, s1
	v_lshl_add_u64 v[198:199], v[198:199], 0, s[66:67]
	s_mov_b32 m0, s48
	s_nop 0
	global_load_lds_dwordx4 v[198:199], off
	s_add_i32 m0, s48, 0x2000
	s_add_u32 s62, s62, 0x80080
	v_lshl_add_u64 v[198:199], v[206:207], 0, s[66:67]
	s_addc_u32 s63, s63, 0
	s_add_i32 s48, s49, s1
	global_load_lds_dwordx4 v[198:199], off
	v_lshl_add_u64 v[198:199], s[62:63], 0, v[200:201]
	s_mov_b32 m0, s48
	s_nop 0
	global_load_lds_dwordx4 v[198:199], off
	v_lshl_add_u64 v[198:199], s[62:63], 0, v[132:133]
	s_add_i32 m0, s48, 0x2000
	s_nop 0
	global_load_lds_dwordx4 v[198:199], off
	v_lshl_add_u64 v[198:199], v[208:209], 0, s[66:67]
	s_mov_b32 m0, s55
	s_nop 0
	global_load_lds_dwordx4 v[198:199], off
	v_lshl_add_u64 v[198:199], v[222:223], 0, s[66:67]
	s_mov_b32 m0, s56
	s_nop 0
	global_load_lds_dwordx4 v[198:199], off
	s_waitcnt vmcnt(8)
	s_waitcnt lgkmcnt(0)
	s_setprio 1
	s_barrier
	v_mfma_f32_16x16x32_bf16 v[64:67], v[142:145], v[178:181], v[64:67]
	v_mfma_f32_16x16x32_bf16 v[60:63], v[150:153], v[178:181], v[60:63]
	v_mfma_f32_16x16x32_bf16 v[48:51], v[142:145], v[186:189], v[48:51]
	v_mfma_f32_16x16x32_bf16 v[44:47], v[150:153], v[186:189], v[44:47]
	v_mfma_f32_16x16x32_bf16 v[32:35], v[142:145], v[194:197], v[32:35]
	v_mfma_f32_16x16x32_bf16 v[28:31], v[150:153], v[194:197], v[28:31]
	v_mfma_f32_16x16x32_bf16 v[16:19], v[142:145], v[214:217], v[16:19]
	v_mfma_f32_16x16x32_bf16 v[12:15], v[150:153], v[214:217], v[12:15]
	v_mfma_f32_16x16x32_bf16 v[64:67], v[146:149], v[182:185], v[64:67]
	v_mfma_f32_16x16x32_bf16 v[60:63], v[158:161], v[182:185], v[60:63]
	v_mfma_f32_16x16x32_bf16 v[48:51], v[146:149], v[190:193], v[48:51]
	v_mfma_f32_16x16x32_bf16 v[44:47], v[158:161], v[190:193], v[44:47]
	v_mfma_f32_16x16x32_bf16 v[32:35], v[146:149], v[210:213], v[32:35]
	v_mfma_f32_16x16x32_bf16 v[28:31], v[158:161], v[210:213], v[28:31]
	v_mfma_f32_16x16x32_bf16 v[16:19], v[146:149], v[218:221], v[16:19]
	v_mfma_f32_16x16x32_bf16 v[12:15], v[158:161], v[218:221], v[12:15]
	s_setprio 0
	s_setprio 1
	v_mfma_f32_16x16x32_bf16 v[56:59], v[162:165], v[178:181], v[56:59]
	v_mfma_f32_16x16x32_bf16 v[52:55], v[170:173], v[178:181], v[52:55]
	v_mfma_f32_16x16x32_bf16 v[40:43], v[162:165], v[186:189], v[40:43]
	v_mfma_f32_16x16x32_bf16 v[36:39], v[170:173], v[186:189], v[36:39]
	v_mfma_f32_16x16x32_bf16 v[24:27], v[162:165], v[194:197], v[24:27]
	v_mfma_f32_16x16x32_bf16 v[20:23], v[170:173], v[194:197], v[20:23]
	v_mfma_f32_16x16x32_bf16 v[8:11], v[162:165], v[214:217], v[8:11]
	v_mfma_f32_16x16x32_bf16 v[4:7], v[170:173], v[214:217], v[4:7]
	v_mfma_f32_16x16x32_bf16 v[56:59], v[166:169], v[182:185], v[56:59]
	v_mfma_f32_16x16x32_bf16 v[52:55], v[174:177], v[182:185], v[52:55]
	v_mfma_f32_16x16x32_bf16 v[40:43], v[166:169], v[190:193], v[40:43]
	v_mfma_f32_16x16x32_bf16 v[36:39], v[174:177], v[190:193], v[36:39]
	v_mfma_f32_16x16x32_bf16 v[24:27], v[166:169], v[210:213], v[24:27]
	v_mfma_f32_16x16x32_bf16 v[20:23], v[174:177], v[210:213], v[20:23]
	v_mfma_f32_16x16x32_bf16 v[8:11], v[166:169], v[218:221], v[8:11]
	v_mfma_f32_16x16x32_bf16 v[4:7], v[174:177], v[218:221], v[4:7]
	s_barrier
	s_setprio 0
	s_add_i32 s86, s86, 2
	s_add_u32 s60, s60, 0x100
	s_addc_u32 s61, s61, 0
	s_add_u32 s84, s84, 0x100
	s_addc_u32 s85, s85, 0
	s_cmp_gt_u32 s86, 29
	s_cbranch_scc0 .LBB0_198
	s_and_b64 vcc, exec, s[12:13]
	s_cbranch_vccz .LBB0_201
	s_barrier

; #define PG8_STAGE(bufoff, gbase, voff) do { _Pragma("unroll") for (int _i = 0; _i < 2; ++_i) \
;         __builtin_amdgcn_global_load_lds((const unsigned*)((const char*)(gbase) + (voff)[_i]), (PG8_LAS unsigned*)(lds + (bufoff) + ldsw + _i * 8192), 16, 0, 0); } while (0)
; #define PG8_LDA(dst, b, h) do { _Pragma("unroll") for (int m = 0; m < 4; ++m) _Pragma("unroll") for (int k = 0; k < 2; ++k) dst[m][k] = *(const PG8_LAS bf16x8*)(lds + PG8_SA(b, h) + aoff + m * 2048 + k * 1024); } while (0)
; #define PG8_LDB(dst, b, h) do { _Pragma("unroll") for (int n = 0; n < 2; ++n) _Pragma("unroll") for (int k = 0; k < 2; ++k) dst[n][k] = *(const PG8_LAS bf16x8*)(lds + PG8_SB(b, h) + boff + n * 2048 + k * 1024); } while (0)
; #define PG8_MMA(ai, bj, At, Bt) do { __builtin_amdgcn_s_setprio(1); _Pragma("unroll") for (int m = 0; m < 4; ++m) _Pragma("unroll") for (int n = 0; n < 2; ++n) _Pragma("unroll") for (int k = 0; k < 2; ++k) \
;         acc[ai][bj][m][n] = __builtin_amdgcn_mfma_f32_16x16x32_bf16(Bt[n][k], At[m][k], acc[ai][bj][m][n], 0, 0, 0); __builtin_amdgcn_s_setprio(0); } while (0)
; #define PG8_WAIT_V(n) asm volatile("s_waitcnt vmcnt(" #n ")" ::: "memory")
; #define PG8_WAIT_L(n) asm volatile("s_waitcnt lgkmcnt(" #n ")" ::: "memory")
; #define PG8_BAR __builtin_amdgcn_s_barrier()
; #define PG8_SCHED __builtin_amdgcn_sched_barrier(0)
;     ...
;             PG8_LDB(B0, 0, 0); PG8_LDB(B1, 0, 1); PG8_SCHED; PG8_LDA(At, 0, 0); PG8_STAGE(PG8_SA(1, 1), a1 + hstep, voffA);
;             PG8_WAIT_V(8); PG8_WAIT_L(0); PG8_BAR; PG8_MMA(0, 0, At, B0); PG8_MMA(0, 1, At, B1); PG8_BAR; PG8_SCHED;
;             PG8_LDA(At, 0, 1); PG8_STAGE(PG8_SB(0, 0), b2, voffB); PG8_STAGE(PG8_SB(0, 1), b2 + hstep, voffB); PG8_STAGE(PG8_SA(0, 0), a2, voffA);
;             PG8_WAIT_V(8); PG8_WAIT_L(0); PG8_BAR; PG8_MMA(1, 0, At, B0); PG8_MMA(1, 1, At, B1); PG8_BAR; PG8_SCHED;
.LBB0_279:
	ds_read_b128 v[146:149], v251
	ds_read_b128 v[150:153], v251 offset:1024
	ds_read_b128 v[154:157], v251 offset:2048
	ds_read_b128 v[158:161], v251 offset:3072
	ds_read_b128 v[162:165], v251 offset:16384
	ds_read_b128 v[166:169], v251 offset:17408
	ds_read_b128 v[170:173], v251 offset:18432
	ds_read_b128 v[174:177], v251 offset:19456
	ds_read_b128 v[178:181], v144
	ds_read_b128 v[182:185], v144 offset:1024
	ds_read_b128 v[186:189], v144 offset:2048
	ds_read_b128 v[190:193], v144 offset:3072
	ds_read_b128 v[194:197], v144 offset:4096
	ds_read_b128 v[210:213], v144 offset:5120
	ds_read_b128 v[214:217], v144 offset:6144
	ds_read_b128 v[218:221], v144 offset:7168
	s_add_u32 s10, s56, s6
	s_addc_u32 s11, s73, s7
	s_add_u32 s10, s10, 0x1d800100
	s_addc_u32 s11, s11, 0
	s_add_u32 s48, s0, s6
	s_addc_u32 s49, s50, s7
	s_add_i32 s52, 0, 0x10000
	s_cmpk_eq_i32 s6, 0xf00
	s_cselect_b32 s13, s55, s11
	s_cselect_b32 s12, s54, s10
	s_cselect_b32 s11, s5, s49
	s_cselect_b32 s10, s4, s48
	s_add_i32 s48, 0, 0x14000
	v_lshl_add_u64 v[198:199], v[138:139], 0, s[6:7]
	s_add_i32 m0, s15, 0xc000
	s_nop 0
	global_load_lds_dwordx4 v[198:199], off
	v_lshl_add_u64 v[198:199], v[140:141], 0, s[6:7]
	s_add_i32 m0, s15, 0xe000
	s_nop 0
	global_load_lds_dwordx4 v[198:199], off
	s_waitcnt vmcnt(8)
	s_waitcnt lgkmcnt(0)
	s_setprio 1
	s_barrier
	v_mfma_f32_16x16x32_bf16 v[128:131], v[146:149], v[178:181], v[128:131]
	v_mfma_f32_16x16x32_bf16 v[124:127], v[154:157], v[178:181], v[124:127]
	v_mfma_f32_16x16x32_bf16 v[112:115], v[146:149], v[186:189], v[112:115]
	v_mfma_f32_16x16x32_bf16 v[108:111], v[154:157], v[186:189], v[108:111]
	v_mfma_f32_16x16x32_bf16 v[96:99], v[146:149], v[194:197], v[96:99]
	v_mfma_f32_16x16x32_bf16 v[92:95], v[154:157], v[194:197], v[92:95]
	v_mfma_f32_16x16x32_bf16 v[80:83], v[146:149], v[214:217], v[80:83]
	v_mfma_f32_16x16x32_bf16 v[76:79], v[154:157], v[214:217], v[76:79]
	v_mfma_f32_16x16x32_bf16 v[128:131], v[150:153], v[182:185], v[128:131]
	v_mfma_f32_16x16x32_bf16 v[124:127], v[158:161], v[182:185], v[124:127]
	v_mfma_f32_16x16x32_bf16 v[112:115], v[150:153], v[190:193], v[112:115]
	v_mfma_f32_16x16x32_bf16 v[108:111], v[158:161], v[190:193], v[108:111]
	v_mfma_f32_16x16x32_bf16 v[96:99], v[150:153], v[210:213], v[96:99]
	v_mfma_f32_16x16x32_bf16 v[92:95], v[158:161], v[210:213], v[92:95]
	v_mfma_f32_16x16x32_bf16 v[80:83], v[150:153], v[218:221], v[80:83]
	v_mfma_f32_16x16x32_bf16 v[76:79], v[158:161], v[218:221], v[76:79]
	s_setprio 0
	s_setprio 1
	v_mfma_f32_16x16x32_bf16 v[120:123], v[162:165], v[178:181], v[120:123]
	v_mfma_f32_16x16x32_bf16 v[116:119], v[170:173], v[178:181], v[116:119]
	v_mfma_f32_16x16x32_bf16 v[104:107], v[162:165], v[186:189], v[104:107]
	v_mfma_f32_16x16x32_bf16 v[100:103], v[170:173], v[186:189], v[100:103]
	v_mfma_f32_16x16x32_bf16 v[88:91], v[162:165], v[194:197], v[88:91]
	v_mfma_f32_16x16x32_bf16 v[84:87], v[170:173], v[194:197], v[84:87]
	v_mfma_f32_16x16x32_bf16 v[72:75], v[162:165], v[214:217], v[72:75]
	v_mfma_f32_16x16x32_bf16 v[68:71], v[170:173], v[214:217], v[68:71]
	v_mfma_f32_16x16x32_bf16 v[120:123], v[166:169], v[182:185], v[120:123]
	v_mfma_f32_16x16x32_bf16 v[116:119], v[174:177], v[182:185], v[116:119]
	v_mfma_f32_16x16x32_bf16 v[104:107], v[166:169], v[190:193], v[104:107]
	v_mfma_f32_16x16x32_bf16 v[100:103], v[174:177], v[190:193], v[100:103]
	v_mfma_f32_16x16x32_bf16 v[88:91], v[166:169], v[210:213], v[88:91]
	v_mfma_f32_16x16x32_bf16 v[84:87], v[174:177], v[210:213], v[84:87]
	v_mfma_f32_16x16x32_bf16 v[72:75], v[166:169], v[218:221], v[72:75]
	v_mfma_f32_16x16x32_bf16 v[68:71], v[174:177], v[218:221], v[68:71]
	s_barrier
	s_setprio 0
	ds_read_b128 v[178:181], v144 offset:16384
	ds_read_b128 v[182:185], v144 offset:17408
	ds_read_b128 v[186:189], v144 offset:18432
	ds_read_b128 v[190:193], v144 offset:19456
	ds_read_b128 v[194:197], v144 offset:20480
	ds_read_b128 v[210:213], v144 offset:21504
	ds_read_b128 v[214:217], v144 offset:22528
	ds_read_b128 v[218:221], v144 offset:23552
	s_add_i32 s49, s52, s14
	v_lshl_add_u64 v[198:199], s[10:11], 0, v[200:201]
	s_mov_b32 m0, s49
	s_nop 0
	global_load_lds_dwordx4 v[198:199], off
	s_add_i32 m0, s49, 0x2000
	s_add_u32 s52, s10, 0x80000
	v_lshl_add_u64 v[206:207], s[10:11], 0, v[136:137]
	s_addc_u32 s53, s11, 0
	s_add_i32 s48, s48, s14
	global_load_lds_dwordx4 v[206:207], off
	v_lshl_add_u64 v[208:209], s[52:53], 0, v[200:201]
	s_mov_b32 m0, s48
	v_lshl_add_u64 v[222:223], s[12:13], 0, v[134:135]
	global_load_lds_dwordx4 v[208:209], off
	v_lshl_add_u64 v[208:209], s[52:53], 0, v[136:137]
	s_add_i32 m0, s48, 0x2000
	s_nop 0
	global_load_lds_dwordx4 v[208:209], off
	v_lshl_add_u64 v[208:209], s[12:13], 0, v[132:133]
	s_mov_b32 m0, s15
	s_nop 0
	global_load_lds_dwordx4 v[208:209], off
	s_mov_b32 m0, s20
	s_nop 0
	global_load_lds_dwordx4 v[222:223], off
	s_waitcnt vmcnt(8)
	s_waitcnt lgkmcnt(0)
	s_setprio 1
	s_barrier
; #define PG8_STAGE(bufoff, gbase, voff) do { _Pragma("unroll") for (int _i = 0; _i < 2; ++_i) \
;         __builtin_amdgcn_global_load_lds((const unsigned*)((const char*)(gbase) + (voff)[_i]), (PG8_LAS unsigned*)(lds + (bufoff) + ldsw + _i * 8192), 16, 0, 0); } while (0)
; #define PG8_LDA(dst, b, h) do { _Pragma("unroll") for (int m = 0; m < 4; ++m) _Pragma("unroll") for (int k = 0; k < 2; ++k) dst[m][k] = *(const PG8_LAS bf16x8*)(lds + PG8_SA(b, h) + aoff + m * 2048 + k * 1024); } while (0)
; #define PG8_LDB(dst, b, h) do { _Pragma("unroll") for (int n = 0; n < 2; ++n) _Pragma("unroll") for (int k = 0; k < 2; ++k) dst[n][k] = *(const PG8_LAS bf16x8*)(lds + PG8_SB(b, h) + boff + n * 2048 + k * 1024); } while (0)
; #define PG8_MMA(ai, bj, At, Bt) do { __builtin_amdgcn_s_setprio(1); _Pragma("unroll") for (int m = 0; m < 4; ++m) _Pragma("unroll") for (int n = 0; n < 2; ++n) _Pragma("unroll") for (int k = 0; k < 2; ++k) \
;         acc[ai][bj][m][n] = __builtin_amdgcn_mfma_f32_16x16x32_bf16(Bt[n][k], At[m][k], acc[ai][bj][m][n], 0, 0, 0); __builtin_amdgcn_s_setprio(0); } while (0)
; #define PG8_WAIT_V(n) asm volatile("s_waitcnt vmcnt(" #n ")" ::: "memory")
; #define PG8_WAIT_L(n) asm volatile("s_waitcnt lgkmcnt(" #n ")" ::: "memory")
; #define PG8_BAR __builtin_amdgcn_s_barrier()
; #define PG8_SCHED __builtin_amdgcn_sched_barrier(0)
;     ...
;             PG8_WAIT_V(8); PG8_WAIT_L(0); PG8_BAR; PG8_MMA(1, 0, At, B0); PG8_MMA(1, 1, At, B1); PG8_BAR; PG8_SCHED;
;             PG8_LDB(B0, 1, 0); PG8_LDB(B1, 1, 1); PG8_SCHED; PG8_LDA(At, 1, 0); PG8_STAGE(PG8_SA(0, 1), a2 + hstep, voffA);
;             PG8_WAIT_V(8); PG8_WAIT_L(0); PG8_BAR; PG8_MMA(0, 0, At, B0); PG8_MMA(0, 1, At, B1); PG8_BAR; PG8_SCHED;
	v_mfma_f32_16x16x32_bf16 v[64:67], v[146:149], v[178:181], v[64:67]
	v_mfma_f32_16x16x32_bf16 v[60:63], v[154:157], v[178:181], v[60:63]
	v_mfma_f32_16x16x32_bf16 v[48:51], v[146:149], v[186:189], v[48:51]
	v_mfma_f32_16x16x32_bf16 v[44:47], v[154:157], v[186:189], v[44:47]
	v_mfma_f32_16x16x32_bf16 v[32:35], v[146:149], v[194:197], v[32:35]
	v_mfma_f32_16x16x32_bf16 v[28:31], v[154:157], v[194:197], v[28:31]
	v_mfma_f32_16x16x32_bf16 v[16:19], v[146:149], v[214:217], v[16:19]
	v_mfma_f32_16x16x32_bf16 v[12:15], v[154:157], v[214:217], v[12:15]
	v_mfma_f32_16x16x32_bf16 v[64:67], v[150:153], v[182:185], v[64:67]
	v_mfma_f32_16x16x32_bf16 v[60:63], v[158:161], v[182:185], v[60:63]
	v_mfma_f32_16x16x32_bf16 v[48:51], v[150:153], v[190:193], v[48:51]
	v_mfma_f32_16x16x32_bf16 v[44:47], v[158:161], v[190:193], v[44:47]
	v_mfma_f32_16x16x32_bf16 v[32:35], v[150:153], v[210:213], v[32:35]
	v_mfma_f32_16x16x32_bf16 v[28:31], v[158:161], v[210:213], v[28:31]
	v_mfma_f32_16x16x32_bf16 v[16:19], v[150:153], v[218:221], v[16:19]
	v_mfma_f32_16x16x32_bf16 v[12:15], v[158:161], v[218:221], v[12:15]
	s_setprio 0
	s_setprio 1
	v_mfma_f32_16x16x32_bf16 v[56:59], v[162:165], v[178:181], v[56:59]
	v_mfma_f32_16x16x32_bf16 v[52:55], v[170:173], v[178:181], v[52:55]
	v_mfma_f32_16x16x32_bf16 v[40:43], v[162:165], v[186:189], v[40:43]
	v_mfma_f32_16x16x32_bf16 v[36:39], v[170:173], v[186:189], v[36:39]
	v_mfma_f32_16x16x32_bf16 v[24:27], v[162:165], v[194:197], v[24:27]
	v_mfma_f32_16x16x32_bf16 v[20:23], v[170:173], v[194:197], v[20:23]
	v_mfma_f32_16x16x32_bf16 v[8:11], v[162:165], v[214:217], v[8:11]
	v_mfma_f32_16x16x32_bf16 v[4:7], v[170:173], v[214:217], v[4:7]
	v_mfma_f32_16x16x32_bf16 v[56:59], v[166:169], v[182:185], v[56:59]
	v_mfma_f32_16x16x32_bf16 v[52:55], v[174:177], v[182:185], v[52:55]
	v_mfma_f32_16x16x32_bf16 v[40:43], v[166:169], v[190:193], v[40:43]
	v_mfma_f32_16x16x32_bf16 v[36:39], v[174:177], v[190:193], v[36:39]
	v_mfma_f32_16x16x32_bf16 v[24:27], v[166:169], v[210:213], v[24:27]
	v_mfma_f32_16x16x32_bf16 v[20:23], v[174:177], v[210:213], v[20:23]
	v_mfma_f32_16x16x32_bf16 v[8:11], v[166:169], v[218:221], v[8:11]
	v_mfma_f32_16x16x32_bf16 v[4:7], v[174:177], v[218:221], v[4:7]
	s_barrier
	s_setprio 0
	ds_read_b128 v[146:149], v251 offset:32768
	ds_read_b128 v[150:153], v251 offset:33792
	ds_read_b128 v[154:157], v251 offset:34816
	ds_read_b128 v[158:161], v251 offset:35840
	ds_read_b128 v[162:165], v251 offset:49152
	ds_read_b128 v[166:169], v251 offset:50176
	ds_read_b128 v[170:173], v251 offset:51200
	ds_read_b128 v[174:177], v251 offset:52224
	ds_read_b128 v[178:181], v144 offset:32768
	ds_read_b128 v[182:185], v144 offset:33792
	ds_read_b128 v[186:189], v144 offset:34816
	ds_read_b128 v[190:193], v144 offset:35840
	ds_read_b128 v[194:197], v144 offset:36864
	ds_read_b128 v[210:213], v144 offset:37888
	ds_read_b128 v[214:217], v144 offset:38912
	ds_read_b128 v[218:221], v144 offset:39936
	s_add_i32 s48, 0, 0x18000
	s_add_i32 s49, 0, 0x1c000
	s_add_u32 s12, s12, 0x80000
	s_addc_u32 s13, s13, 0
	s_mov_b32 m0, s21
	v_lshl_add_u64 v[224:225], s[12:13], 0, v[132:133]
	global_load_lds_dwordx4 v[224:225], off
	v_lshl_add_u64 v[224:225], s[12:13], 0, v[134:135]
	s_mov_b32 m0, s23
	s_nop 0
	global_load_lds_dwordx4 v[224:225], off
	s_waitcnt vmcnt(8)
	s_waitcnt lgkmcnt(0)
	s_setprio 1
	s_barrier
	v_mfma_f32_16x16x32_bf16 v[128:131], v[146:149], v[178:181], v[128:131]
	v_mfma_f32_16x16x32_bf16 v[124:127], v[154:157], v[178:181], v[124:127]
	v_mfma_f32_16x16x32_bf16 v[112:115], v[146:149], v[186:189], v[112:115]
	v_mfma_f32_16x16x32_bf16 v[108:111], v[154:157], v[186:189], v[108:111]
	v_mfma_f32_16x16x32_bf16 v[96:99], v[146:149], v[194:197], v[96:99]
	v_mfma_f32_16x16x32_bf16 v[92:95], v[154:157], v[194:197], v[92:95]
	v_mfma_f32_16x16x32_bf16 v[80:83], v[146:149], v[214:217], v[80:83]
	v_mfma_f32_16x16x32_bf16 v[76:79], v[154:157], v[214:217], v[76:79]
	v_mfma_f32_16x16x32_bf16 v[128:131], v[150:153], v[182:185], v[128:131]
	v_mfma_f32_16x16x32_bf16 v[124:127], v[158:161], v[182:185], v[124:127]
	v_mfma_f32_16x16x32_bf16 v[112:115], v[150:153], v[190:193], v[112:115]
	v_mfma_f32_16x16x32_bf16 v[108:111], v[158:161], v[190:193], v[108:111]
	v_mfma_f32_16x16x32_bf16 v[96:99], v[150:153], v[210:213], v[96:99]
	v_mfma_f32_16x16x32_bf16 v[92:95], v[158:161], v[210:213], v[92:95]
	v_mfma_f32_16x16x32_bf16 v[80:83], v[150:153], v[218:221], v[80:83]
	v_mfma_f32_16x16x32_bf16 v[76:79], v[158:161], v[218:221], v[76:79]
	s_setprio 0
	s_setprio 1
	v_mfma_f32_16x16x32_bf16 v[120:123], v[162:165], v[178:181], v[120:123]
	v_mfma_f32_16x16x32_bf16 v[116:119], v[170:173], v[178:181], v[116:119]
	v_mfma_f32_16x16x32_bf16 v[104:107], v[162:165], v[186:189], v[104:107]
	v_mfma_f32_16x16x32_bf16 v[100:103], v[170:173], v[186:189], v[100:103]
	v_mfma_f32_16x16x32_bf16 v[88:91], v[162:165], v[194:197], v[88:91]
	v_mfma_f32_16x16x32_bf16 v[84:87], v[170:173], v[194:197], v[84:87]
	v_mfma_f32_16x16x32_bf16 v[72:75], v[162:165], v[214:217], v[72:75]
	v_mfma_f32_16x16x32_bf16 v[68:71], v[170:173], v[214:217], v[68:71]
	v_mfma_f32_16x16x32_bf16 v[120:123], v[166:169], v[182:185], v[120:123]
	v_mfma_f32_16x16x32_bf16 v[116:119], v[174:177], v[182:185], v[116:119]
	v_mfma_f32_16x16x32_bf16 v[104:107], v[166:169], v[190:193], v[104:107]
	v_mfma_f32_16x16x32_bf16 v[100:103], v[174:177], v[190:193], v[100:103]
	v_mfma_f32_16x16x32_bf16 v[88:91], v[166:169], v[210:213], v[88:91]
	v_mfma_f32_16x16x32_bf16 v[84:87], v[174:177], v[210:213], v[84:87]
	v_mfma_f32_16x16x32_bf16 v[72:75], v[166:169], v[218:221], v[72:75]
	v_mfma_f32_16x16x32_bf16 v[68:71], v[174:177], v[218:221], v[68:71]
	s_barrier
; #define PG8_STAGE(bufoff, gbase, voff) do { _Pragma("unroll") for (int _i = 0; _i < 2; ++_i) \
;         __builtin_amdgcn_global_load_lds((const unsigned*)((const char*)(gbase) + (voff)[_i]), (PG8_LAS unsigned*)(lds + (bufoff) + ldsw + _i * 8192), 16, 0, 0); } while (0)
; #define PG8_LDA(dst, b, h) do { _Pragma("unroll") for (int m = 0; m < 4; ++m) _Pragma("unroll") for (int k = 0; k < 2; ++k) dst[m][k] = *(const PG8_LAS bf16x8*)(lds + PG8_SA(b, h) + aoff + m * 2048 + k * 1024); } while (0)
; #define PG8_MMA(ai, bj, At, Bt) do { __builtin_amdgcn_s_setprio(1); _Pragma("unroll") for (int m = 0; m < 4; ++m) _Pragma("unroll") for (int n = 0; n < 2; ++n) _Pragma("unroll") for (int k = 0; k < 2; ++k) \
;         acc[ai][bj][m][n] = __builtin_amdgcn_mfma_f32_16x16x32_bf16(Bt[n][k], At[m][k], acc[ai][bj][m][n], 0, 0, 0); __builtin_amdgcn_s_setprio(0); } while (0)
; #define PG8_WAIT_V(n) asm volatile("s_waitcnt vmcnt(" #n ")" ::: "memory")
; #define PG8_WAIT_L(n) asm volatile("s_waitcnt lgkmcnt(" #n ")" ::: "memory")
; #define PG8_BAR __builtin_amdgcn_s_barrier()
; #define PG8_SCHED __builtin_amdgcn_sched_barrier(0)
;     ...
;         for (int t = 0; t < nt; t += 2) {
;     ...
;             PG8_LDA(At, 1, 1); PG8_STAGE(PG8_SB(1, 0), b3, voffB); PG8_STAGE(PG8_SB(1, 1), b3 + hstep, voffB); PG8_STAGE(PG8_SA(1, 0), a3, voffA);
;             PG8_WAIT_V(8); PG8_WAIT_L(0); PG8_BAR; PG8_MMA(1, 0, At, B0); PG8_MMA(1, 1, At, B1); PG8_BAR; PG8_SCHED;
	s_setprio 0
	ds_read_b128 v[178:181], v144 offset:49152
	ds_read_b128 v[182:185], v144 offset:50176
	ds_read_b128 v[186:189], v144 offset:51200
	ds_read_b128 v[190:193], v144 offset:52224
	ds_read_b128 v[194:197], v144 offset:53248
	ds_read_b128 v[210:213], v144 offset:54272
	ds_read_b128 v[214:217], v144 offset:55296
	ds_read_b128 v[218:221], v144 offset:56320
	s_add_i32 s12, s48, s14
	v_lshl_add_u64 v[198:199], v[198:199], 0, s[66:67]
	s_mov_b32 m0, s12
	s_nop 0
	global_load_lds_dwordx4 v[198:199], off
	s_add_i32 m0, s12, 0x2000
	s_add_u32 s10, s10, 0x80080
	v_lshl_add_u64 v[198:199], v[206:207], 0, s[66:67]
	s_addc_u32 s11, s11, 0
	s_add_i32 s12, s49, s14
	global_load_lds_dwordx4 v[198:199], off
	v_lshl_add_u64 v[198:199], s[10:11], 0, v[200:201]
	s_mov_b32 m0, s12
	s_nop 0
	global_load_lds_dwordx4 v[198:199], off
	v_lshl_add_u64 v[198:199], s[10:11], 0, v[136:137]
	s_add_i32 m0, s12, 0x2000
	s_nop 0
	global_load_lds_dwordx4 v[198:199], off
	v_lshl_add_u64 v[198:199], v[208:209], 0, s[66:67]
	s_mov_b32 m0, s42
	s_nop 0
	global_load_lds_dwordx4 v[198:199], off
	v_lshl_add_u64 v[198:199], v[222:223], 0, s[66:67]
	s_mov_b32 m0, s44
	s_nop 0
	global_load_lds_dwordx4 v[198:199], off
	s_waitcnt vmcnt(8)
	s_waitcnt lgkmcnt(0)
	s_setprio 1
	s_barrier
	v_mfma_f32_16x16x32_bf16 v[64:67], v[146:149], v[178:181], v[64:67]
	v_mfma_f32_16x16x32_bf16 v[60:63], v[154:157], v[178:181], v[60:63]
	v_mfma_f32_16x16x32_bf16 v[48:51], v[146:149], v[186:189], v[48:51]
	v_mfma_f32_16x16x32_bf16 v[44:47], v[154:157], v[186:189], v[44:47]
	v_mfma_f32_16x16x32_bf16 v[32:35], v[146:149], v[194:197], v[32:35]
	v_mfma_f32_16x16x32_bf16 v[28:31], v[154:157], v[194:197], v[28:31]
	v_mfma_f32_16x16x32_bf16 v[16:19], v[146:149], v[214:217], v[16:19]
	v_mfma_f32_16x16x32_bf16 v[12:15], v[154:157], v[214:217], v[12:15]
	v_mfma_f32_16x16x32_bf16 v[64:67], v[150:153], v[182:185], v[64:67]
	v_mfma_f32_16x16x32_bf16 v[60:63], v[158:161], v[182:185], v[60:63]
	v_mfma_f32_16x16x32_bf16 v[48:51], v[150:153], v[190:193], v[48:51]
	v_mfma_f32_16x16x32_bf16 v[44:47], v[158:161], v[190:193], v[44:47]
	v_mfma_f32_16x16x32_bf16 v[32:35], v[150:153], v[210:213], v[32:35]
	v_mfma_f32_16x16x32_bf16 v[28:31], v[158:161], v[210:213], v[28:31]
	v_mfma_f32_16x16x32_bf16 v[16:19], v[150:153], v[218:221], v[16:19]
	v_mfma_f32_16x16x32_bf16 v[12:15], v[158:161], v[218:221], v[12:15]
	s_setprio 0
	s_setprio 1
	v_mfma_f32_16x16x32_bf16 v[56:59], v[162:165], v[178:181], v[56:59]
	v_mfma_f32_16x16x32_bf16 v[52:55], v[170:173], v[178:181], v[52:55]
	v_mfma_f32_16x16x32_bf16 v[40:43], v[162:165], v[186:189], v[40:43]
	v_mfma_f32_16x16x32_bf16 v[36:39], v[170:173], v[186:189], v[36:39]
	v_mfma_f32_16x16x32_bf16 v[24:27], v[162:165], v[194:197], v[24:27]
	v_mfma_f32_16x16x32_bf16 v[20:23], v[170:173], v[194:197], v[20:23]
	v_mfma_f32_16x16x32_bf16 v[8:11], v[162:165], v[214:217], v[8:11]
	v_mfma_f32_16x16x32_bf16 v[4:7], v[170:173], v[214:217], v[4:7]
	v_mfma_f32_16x16x32_bf16 v[56:59], v[166:169], v[182:185], v[56:59]
	v_mfma_f32_16x16x32_bf16 v[52:55], v[174:177], v[182:185], v[52:55]
	v_mfma_f32_16x16x32_bf16 v[40:43], v[166:169], v[190:193], v[40:43]
	v_mfma_f32_16x16x32_bf16 v[36:39], v[174:177], v[190:193], v[36:39]
	v_mfma_f32_16x16x32_bf16 v[24:27], v[166:169], v[210:213], v[24:27]
	v_mfma_f32_16x16x32_bf16 v[20:23], v[174:177], v[210:213], v[20:23]
	v_mfma_f32_16x16x32_bf16 v[8:11], v[166:169], v[218:221], v[8:11]
	v_mfma_f32_16x16x32_bf16 v[4:7], v[174:177], v[218:221], v[4:7]
	s_barrier
	s_setprio 0
	s_add_i32 s51, s51, 2
	s_add_u32 s6, s6, 0x100
	s_addc_u32 s7, s7, 0
	s_cmp_gt_u32 s51, 29
	s_cbranch_scc0 .LBB0_279
	s_cmpk_lt_u32 s1, 0x100
	s_cbranch_scc0 .LBB0_282
	s_barrier

; #define PG8_STAGE(bufoff, gbase, voff) do { _Pragma("unroll") for (int _i = 0; _i < 2; ++_i) \
;         __builtin_amdgcn_global_load_lds((const unsigned*)((const char*)(gbase) + (voff)[_i]), (PG8_LAS unsigned*)(lds + (bufoff) + ldsw + _i * 8192), 16, 0, 0); } while (0)
; #define PG8_LDA(dst, b, h) do { _Pragma("unroll") for (int m = 0; m < 4; ++m) _Pragma("unroll") for (int k = 0; k < 2; ++k) dst[m][k] = *(const PG8_LAS bf16x8*)(lds + PG8_SA(b, h) + aoff + m * 2048 + k * 1024); } while (0)
; #define PG8_LDB(dst, b, h) do { _Pragma("unroll") for (int n = 0; n < 2; ++n) _Pragma("unroll") for (int k = 0; k < 2; ++k) dst[n][k] = *(const PG8_LAS bf16x8*)(lds + PG8_SB(b, h) + boff + n * 2048 + k * 1024); } while (0)
; #define PG8_MMA(ai, bj, At, Bt) do { __builtin_amdgcn_s_setprio(1); _Pragma("unroll") for (int m = 0; m < 4; ++m) _Pragma("unroll") for (int n = 0; n < 2; ++n) _Pragma("unroll") for (int k = 0; k < 2; ++k) \
;         acc[ai][bj][m][n] = __builtin_amdgcn_mfma_f32_16x16x32_bf16(Bt[n][k], At[m][k], acc[ai][bj][m][n], 0, 0, 0); __builtin_amdgcn_s_setprio(0); } while (0)
; #define PG8_WAIT_V(n) asm volatile("s_waitcnt vmcnt(" #n ")" ::: "memory")
; #define PG8_WAIT_L(n) asm volatile("s_waitcnt lgkmcnt(" #n ")" ::: "memory")
; #define PG8_BAR __builtin_amdgcn_s_barrier()
; #define PG8_SCHED __builtin_amdgcn_sched_barrier(0)
;     ...
;             PG8_LDB(B0, 0, 0); PG8_LDB(B1, 0, 1); PG8_SCHED; PG8_LDA(At, 0, 0); PG8_STAGE(PG8_SA(1, 1), a1 + hstep, voffA);
;             PG8_WAIT_V(8); PG8_WAIT_L(0); PG8_BAR; PG8_MMA(0, 0, At, B0); PG8_MMA(0, 1, At, B1); PG8_BAR; PG8_SCHED;
;             PG8_LDA(At, 0, 1); PG8_STAGE(PG8_SB(0, 0), b2, voffB); PG8_STAGE(PG8_SB(0, 1), b2 + hstep, voffB); PG8_STAGE(PG8_SA(0, 0), a2, voffA);
;             PG8_WAIT_V(8); PG8_WAIT_L(0); PG8_BAR; PG8_MMA(1, 0, At, B0); PG8_MMA(1, 1, At, B1); PG8_BAR; PG8_SCHED;
.LBB0_290:
	ds_read_b128 v[142:145], v251
	ds_read_b128 v[152:155], v251 offset:1024
	ds_read_b128 v[156:159], v251 offset:2048
	ds_read_b128 v[160:163], v251 offset:3072
	ds_read_b128 v[164:167], v251 offset:16384
	ds_read_b128 v[168:171], v251 offset:17408
	ds_read_b128 v[172:175], v251 offset:18432
	ds_read_b128 v[176:179], v251 offset:19456
	ds_read_b128 v[180:183], v150
	ds_read_b128 v[184:187], v150 offset:1024
	ds_read_b128 v[188:191], v150 offset:2048
	ds_read_b128 v[192:195], v150 offset:3072
	ds_read_b128 v[196:199], v150 offset:4096
	ds_read_b128 v[210:213], v150 offset:5120
	ds_read_b128 v[214:217], v150 offset:6144
	ds_read_b128 v[218:221], v150 offset:7168
	s_add_u32 s48, s24, 0xfffe0080
	s_addc_u32 s49, s25, -1
	s_add_i32 s84, 0, 0x10000
	s_cmp_eq_u32 s83, 4
	s_cselect_b32 s61, s68, s49
	s_cselect_b32 s60, s69, s48
	s_cselect_b32 s51, s70, s81
	s_cselect_b32 s50, s71, s73
	s_add_i32 s48, 0, 0x14000
	v_lshl_add_u64 v[146:147], s[24:25], 0, v[140:141]
	s_add_i32 m0, s23, 0xc000
	s_nop 0
	global_load_lds_dwordx4 v[146:147], off
	v_lshl_add_u64 v[146:147], s[24:25], 0, v[138:139]
	s_add_i32 m0, s23, 0xe000
	s_nop 0
	global_load_lds_dwordx4 v[146:147], off
	s_waitcnt vmcnt(8)
	s_waitcnt lgkmcnt(0)
	s_setprio 1
	s_barrier
	v_mfma_f32_16x16x32_bf16 v[128:131], v[142:145], v[180:183], v[128:131]
	v_mfma_f32_16x16x32_bf16 v[124:127], v[156:159], v[180:183], v[124:127]
	v_mfma_f32_16x16x32_bf16 v[112:115], v[142:145], v[188:191], v[112:115]
	v_mfma_f32_16x16x32_bf16 v[108:111], v[156:159], v[188:191], v[108:111]
	v_mfma_f32_16x16x32_bf16 v[96:99], v[142:145], v[196:199], v[96:99]
	v_mfma_f32_16x16x32_bf16 v[92:95], v[156:159], v[196:199], v[92:95]
	v_mfma_f32_16x16x32_bf16 v[80:83], v[142:145], v[214:217], v[80:83]
	v_mfma_f32_16x16x32_bf16 v[76:79], v[156:159], v[214:217], v[76:79]
	v_mfma_f32_16x16x32_bf16 v[128:131], v[152:155], v[184:187], v[128:131]
	v_mfma_f32_16x16x32_bf16 v[124:127], v[160:163], v[184:187], v[124:127]
	v_mfma_f32_16x16x32_bf16 v[112:115], v[152:155], v[192:195], v[112:115]
	v_mfma_f32_16x16x32_bf16 v[108:111], v[160:163], v[192:195], v[108:111]
	v_mfma_f32_16x16x32_bf16 v[96:99], v[152:155], v[210:213], v[96:99]
	v_mfma_f32_16x16x32_bf16 v[92:95], v[160:163], v[210:213], v[92:95]
	v_mfma_f32_16x16x32_bf16 v[80:83], v[152:155], v[218:221], v[80:83]
	v_mfma_f32_16x16x32_bf16 v[76:79], v[160:163], v[218:221], v[76:79]
	s_setprio 0
	s_setprio 1
	v_mfma_f32_16x16x32_bf16 v[120:123], v[164:167], v[180:183], v[120:123]
	v_mfma_f32_16x16x32_bf16 v[116:119], v[172:175], v[180:183], v[116:119]
	v_mfma_f32_16x16x32_bf16 v[104:107], v[164:167], v[188:191], v[104:107]
	v_mfma_f32_16x16x32_bf16 v[100:103], v[172:175], v[188:191], v[100:103]
	v_mfma_f32_16x16x32_bf16 v[88:91], v[164:167], v[196:199], v[88:91]
	v_mfma_f32_16x16x32_bf16 v[84:87], v[172:175], v[196:199], v[84:87]
	v_mfma_f32_16x16x32_bf16 v[72:75], v[164:167], v[214:217], v[72:75]
	v_mfma_f32_16x16x32_bf16 v[68:71], v[172:175], v[214:217], v[68:71]
	v_mfma_f32_16x16x32_bf16 v[120:123], v[168:171], v[184:187], v[120:123]
	v_mfma_f32_16x16x32_bf16 v[116:119], v[176:179], v[184:187], v[116:119]
	v_mfma_f32_16x16x32_bf16 v[104:107], v[168:171], v[192:195], v[104:107]
	v_mfma_f32_16x16x32_bf16 v[100:103], v[176:179], v[192:195], v[100:103]
	v_mfma_f32_16x16x32_bf16 v[88:91], v[168:171], v[210:213], v[88:91]
	v_mfma_f32_16x16x32_bf16 v[84:87], v[176:179], v[210:213], v[84:87]
	v_mfma_f32_16x16x32_bf16 v[72:75], v[168:171], v[218:221], v[72:75]
	v_mfma_f32_16x16x32_bf16 v[68:71], v[176:179], v[218:221], v[68:71]
	s_barrier
	s_setprio 0
	ds_read_b128 v[180:183], v150 offset:16384
	ds_read_b128 v[184:187], v150 offset:17408
	ds_read_b128 v[188:191], v150 offset:18432
	ds_read_b128 v[192:195], v150 offset:19456
	ds_read_b128 v[196:199], v150 offset:20480
	ds_read_b128 v[210:213], v150 offset:21504
	ds_read_b128 v[214:217], v150 offset:22528
	ds_read_b128 v[218:221], v150 offset:23552
	s_add_i32 s49, s84, s21
	v_lshl_add_u64 v[146:147], s[50:51], 0, v[200:201]
	s_mov_b32 m0, s49
	s_nop 0
	global_load_lds_dwordx4 v[146:147], off
	s_add_i32 m0, s49, 0x2000
	s_add_u32 s84, s50, 0x20000
	v_lshl_add_u64 v[206:207], s[50:51], 0, v[132:133]
	s_addc_u32 s85, s51, 0
	s_add_i32 s48, s48, s21
	global_load_lds_dwordx4 v[206:207], off
	v_lshl_add_u64 v[208:209], s[84:85], 0, v[200:201]
	s_mov_b32 m0, s48
	v_lshl_add_u64 v[222:223], s[60:61], 0, v[134:135]
	global_load_lds_dwordx4 v[208:209], off
	v_lshl_add_u64 v[208:209], s[84:85], 0, v[132:133]
	s_add_i32 m0, s48, 0x2000
	s_nop 0
	global_load_lds_dwordx4 v[208:209], off
	v_lshl_add_u64 v[208:209], s[60:61], 0, v[136:137]
	s_mov_b32 m0, s23
	s_nop 0
	global_load_lds_dwordx4 v[208:209], off
	s_mov_b32 m0, s42
	s_nop 0
	global_load_lds_dwordx4 v[222:223], off
	s_waitcnt vmcnt(8)
	s_waitcnt lgkmcnt(0)
	s_setprio 1
	s_barrier
; #define PG8_STAGE(bufoff, gbase, voff) do { _Pragma("unroll") for (int _i = 0; _i < 2; ++_i) \
;         __builtin_amdgcn_global_load_lds((const unsigned*)((const char*)(gbase) + (voff)[_i]), (PG8_LAS unsigned*)(lds + (bufoff) + ldsw + _i * 8192), 16, 0, 0); } while (0)
; #define PG8_LDA(dst, b, h) do { _Pragma("unroll") for (int m = 0; m < 4; ++m) _Pragma("unroll") for (int k = 0; k < 2; ++k) dst[m][k] = *(const PG8_LAS bf16x8*)(lds + PG8_SA(b, h) + aoff + m * 2048 + k * 1024); } while (0)
; #define PG8_LDB(dst, b, h) do { _Pragma("unroll") for (int n = 0; n < 2; ++n) _Pragma("unroll") for (int k = 0; k < 2; ++k) dst[n][k] = *(const PG8_LAS bf16x8*)(lds + PG8_SB(b, h) + boff + n * 2048 + k * 1024); } while (0)
; #define PG8_MMA(ai, bj, At, Bt) do { __builtin_amdgcn_s_setprio(1); _Pragma("unroll") for (int m = 0; m < 4; ++m) _Pragma("unroll") for (int n = 0; n < 2; ++n) _Pragma("unroll") for (int k = 0; k < 2; ++k) \
;         acc[ai][bj][m][n] = __builtin_amdgcn_mfma_f32_16x16x32_bf16(Bt[n][k], At[m][k], acc[ai][bj][m][n], 0, 0, 0); __builtin_amdgcn_s_setprio(0); } while (0)
; #define PG8_WAIT_V(n) asm volatile("s_waitcnt vmcnt(" #n ")" ::: "memory")
; #define PG8_WAIT_L(n) asm volatile("s_waitcnt lgkmcnt(" #n ")" ::: "memory")
; #define PG8_BAR __builtin_amdgcn_s_barrier()
; #define PG8_SCHED __builtin_amdgcn_sched_barrier(0)
;     ...
;             PG8_WAIT_V(8); PG8_WAIT_L(0); PG8_BAR; PG8_MMA(1, 0, At, B0); PG8_MMA(1, 1, At, B1); PG8_BAR; PG8_SCHED;
;             PG8_LDB(B0, 1, 0); PG8_LDB(B1, 1, 1); PG8_SCHED; PG8_LDA(At, 1, 0); PG8_STAGE(PG8_SA(0, 1), a2 + hstep, voffA);
;             PG8_WAIT_V(8); PG8_WAIT_L(0); PG8_BAR; PG8_MMA(0, 0, At, B0); PG8_MMA(0, 1, At, B1); PG8_BAR; PG8_SCHED;
	v_mfma_f32_16x16x32_bf16 v[64:67], v[142:145], v[180:183], v[64:67]
	v_mfma_f32_16x16x32_bf16 v[60:63], v[156:159], v[180:183], v[60:63]
	v_mfma_f32_16x16x32_bf16 v[48:51], v[142:145], v[188:191], v[48:51]
	v_mfma_f32_16x16x32_bf16 v[44:47], v[156:159], v[188:191], v[44:47]
	v_mfma_f32_16x16x32_bf16 v[32:35], v[142:145], v[196:199], v[32:35]
	v_mfma_f32_16x16x32_bf16 v[28:31], v[156:159], v[196:199], v[28:31]
	v_mfma_f32_16x16x32_bf16 v[16:19], v[142:145], v[214:217], v[16:19]
	v_mfma_f32_16x16x32_bf16 v[12:15], v[156:159], v[214:217], v[12:15]
	v_mfma_f32_16x16x32_bf16 v[64:67], v[152:155], v[184:187], v[64:67]
	v_mfma_f32_16x16x32_bf16 v[60:63], v[160:163], v[184:187], v[60:63]
	v_mfma_f32_16x16x32_bf16 v[48:51], v[152:155], v[192:195], v[48:51]
	v_mfma_f32_16x16x32_bf16 v[44:47], v[160:163], v[192:195], v[44:47]
	v_mfma_f32_16x16x32_bf16 v[32:35], v[152:155], v[210:213], v[32:35]
	v_mfma_f32_16x16x32_bf16 v[28:31], v[160:163], v[210:213], v[28:31]
	v_mfma_f32_16x16x32_bf16 v[16:19], v[152:155], v[218:221], v[16:19]
	v_mfma_f32_16x16x32_bf16 v[12:15], v[160:163], v[218:221], v[12:15]
	s_setprio 0
	s_setprio 1
	v_mfma_f32_16x16x32_bf16 v[56:59], v[164:167], v[180:183], v[56:59]
	v_mfma_f32_16x16x32_bf16 v[52:55], v[172:175], v[180:183], v[52:55]
	v_mfma_f32_16x16x32_bf16 v[40:43], v[164:167], v[188:191], v[40:43]
	v_mfma_f32_16x16x32_bf16 v[36:39], v[172:175], v[188:191], v[36:39]
	v_mfma_f32_16x16x32_bf16 v[24:27], v[164:167], v[196:199], v[24:27]
	v_mfma_f32_16x16x32_bf16 v[20:23], v[172:175], v[196:199], v[20:23]
	v_mfma_f32_16x16x32_bf16 v[8:11], v[164:167], v[214:217], v[8:11]
	v_mfma_f32_16x16x32_bf16 v[4:7], v[172:175], v[214:217], v[4:7]
	v_mfma_f32_16x16x32_bf16 v[56:59], v[168:171], v[184:187], v[56:59]
	v_mfma_f32_16x16x32_bf16 v[52:55], v[176:179], v[184:187], v[52:55]
	v_mfma_f32_16x16x32_bf16 v[40:43], v[168:171], v[192:195], v[40:43]
	v_mfma_f32_16x16x32_bf16 v[36:39], v[176:179], v[192:195], v[36:39]
	v_mfma_f32_16x16x32_bf16 v[24:27], v[168:171], v[210:213], v[24:27]
	v_mfma_f32_16x16x32_bf16 v[20:23], v[176:179], v[210:213], v[20:23]
	v_mfma_f32_16x16x32_bf16 v[8:11], v[168:171], v[218:221], v[8:11]
	v_mfma_f32_16x16x32_bf16 v[4:7], v[176:179], v[218:221], v[4:7]
	s_barrier
	s_setprio 0
	ds_read_b128 v[142:145], v251 offset:32768
	ds_read_b128 v[152:155], v251 offset:33792
	ds_read_b128 v[156:159], v251 offset:34816
	ds_read_b128 v[160:163], v251 offset:35840
	ds_read_b128 v[164:167], v251 offset:49152
	ds_read_b128 v[168:171], v251 offset:50176
	ds_read_b128 v[172:175], v251 offset:51200
	ds_read_b128 v[176:179], v251 offset:52224
	ds_read_b128 v[180:183], v150 offset:32768
	ds_read_b128 v[184:187], v150 offset:33792
	ds_read_b128 v[188:191], v150 offset:34816
	ds_read_b128 v[192:195], v150 offset:35840
	ds_read_b128 v[196:199], v150 offset:36864
	ds_read_b128 v[210:213], v150 offset:37888
	ds_read_b128 v[214:217], v150 offset:38912
	ds_read_b128 v[218:221], v150 offset:39936
	s_add_i32 s48, 0, 0x18000
	s_add_i32 s49, 0, 0x1c000
	s_add_u32 s60, s60, 0x20000
	s_addc_u32 s61, s61, 0
	s_mov_b32 m0, s44
	v_lshl_add_u64 v[224:225], s[60:61], 0, v[136:137]
	global_load_lds_dwordx4 v[224:225], off
	v_lshl_add_u64 v[224:225], s[60:61], 0, v[134:135]
	s_mov_b32 m0, s52
	s_nop 0
	global_load_lds_dwordx4 v[224:225], off
	s_waitcnt vmcnt(8)
	s_waitcnt lgkmcnt(0)
	s_setprio 1
	s_barrier
	v_mfma_f32_16x16x32_bf16 v[128:131], v[142:145], v[180:183], v[128:131]
	v_mfma_f32_16x16x32_bf16 v[124:127], v[156:159], v[180:183], v[124:127]
	v_mfma_f32_16x16x32_bf16 v[112:115], v[142:145], v[188:191], v[112:115]
	v_mfma_f32_16x16x32_bf16 v[108:111], v[156:159], v[188:191], v[108:111]
	v_mfma_f32_16x16x32_bf16 v[96:99], v[142:145], v[196:199], v[96:99]
	v_mfma_f32_16x16x32_bf16 v[92:95], v[156:159], v[196:199], v[92:95]
	v_mfma_f32_16x16x32_bf16 v[80:83], v[142:145], v[214:217], v[80:83]
	v_mfma_f32_16x16x32_bf16 v[76:79], v[156:159], v[214:217], v[76:79]
	v_mfma_f32_16x16x32_bf16 v[128:131], v[152:155], v[184:187], v[128:131]
	v_mfma_f32_16x16x32_bf16 v[124:127], v[160:163], v[184:187], v[124:127]
	v_mfma_f32_16x16x32_bf16 v[112:115], v[152:155], v[192:195], v[112:115]
	v_mfma_f32_16x16x32_bf16 v[108:111], v[160:163], v[192:195], v[108:111]
	v_mfma_f32_16x16x32_bf16 v[96:99], v[152:155], v[210:213], v[96:99]
	v_mfma_f32_16x16x32_bf16 v[92:95], v[160:163], v[210:213], v[92:95]
	v_mfma_f32_16x16x32_bf16 v[80:83], v[152:155], v[218:221], v[80:83]
	v_mfma_f32_16x16x32_bf16 v[76:79], v[160:163], v[218:221], v[76:79]
	s_setprio 0
	s_setprio 1
	v_mfma_f32_16x16x32_bf16 v[120:123], v[164:167], v[180:183], v[120:123]
	v_mfma_f32_16x16x32_bf16 v[116:119], v[172:175], v[180:183], v[116:119]
	v_mfma_f32_16x16x32_bf16 v[104:107], v[164:167], v[188:191], v[104:107]
	v_mfma_f32_16x16x32_bf16 v[100:103], v[172:175], v[188:191], v[100:103]
	v_mfma_f32_16x16x32_bf16 v[88:91], v[164:167], v[196:199], v[88:91]
	v_mfma_f32_16x16x32_bf16 v[84:87], v[172:175], v[196:199], v[84:87]
	v_mfma_f32_16x16x32_bf16 v[72:75], v[164:167], v[214:217], v[72:75]
	v_mfma_f32_16x16x32_bf16 v[68:71], v[172:175], v[214:217], v[68:71]
	v_mfma_f32_16x16x32_bf16 v[120:123], v[168:171], v[184:187], v[120:123]
	v_mfma_f32_16x16x32_bf16 v[116:119], v[176:179], v[184:187], v[116:119]
	v_mfma_f32_16x16x32_bf16 v[104:107], v[168:171], v[192:195], v[104:107]
	v_mfma_f32_16x16x32_bf16 v[100:103], v[176:179], v[192:195], v[100:103]
	v_mfma_f32_16x16x32_bf16 v[88:91], v[168:171], v[210:213], v[88:91]
	v_mfma_f32_16x16x32_bf16 v[84:87], v[176:179], v[210:213], v[84:87]
	v_mfma_f32_16x16x32_bf16 v[72:75], v[168:171], v[218:221], v[72:75]
	v_mfma_f32_16x16x32_bf16 v[68:71], v[176:179], v[218:221], v[68:71]
	s_barrier
; #define PG8_STAGE(bufoff, gbase, voff) do { _Pragma("unroll") for (int _i = 0; _i < 2; ++_i) \
;         __builtin_amdgcn_global_load_lds((const unsigned*)((const char*)(gbase) + (voff)[_i]), (PG8_LAS unsigned*)(lds + (bufoff) + ldsw + _i * 8192), 16, 0, 0); } while (0)
; #define PG8_LDA(dst, b, h) do { _Pragma("unroll") for (int m = 0; m < 4; ++m) _Pragma("unroll") for (int k = 0; k < 2; ++k) dst[m][k] = *(const PG8_LAS bf16x8*)(lds + PG8_SA(b, h) + aoff + m * 2048 + k * 1024); } while (0)
; #define PG8_MMA(ai, bj, At, Bt) do { __builtin_amdgcn_s_setprio(1); _Pragma("unroll") for (int m = 0; m < 4; ++m) _Pragma("unroll") for (int n = 0; n < 2; ++n) _Pragma("unroll") for (int k = 0; k < 2; ++k) \
;         acc[ai][bj][m][n] = __builtin_amdgcn_mfma_f32_16x16x32_bf16(Bt[n][k], At[m][k], acc[ai][bj][m][n], 0, 0, 0); __builtin_amdgcn_s_setprio(0); } while (0)
; #define PG8_WAIT_V(n) asm volatile("s_waitcnt vmcnt(" #n ")" ::: "memory")
; #define PG8_WAIT_L(n) asm volatile("s_waitcnt lgkmcnt(" #n ")" ::: "memory")
; #define PG8_BAR __builtin_amdgcn_s_barrier()
; #define PG8_SCHED __builtin_amdgcn_sched_barrier(0)
;     __device__ __forceinline__ void operator()(const f32x4 (&acc)[2][2][4][2], const Unit& u, int wr, int wc, int fr_, int fq_, int ui) const {
;     ...
;         const int row0 = u.pm * BM + wr * 64 + fr, dim0 = wc * 32 + 8 * fq;
;         float r[2][4]; load_rs(r, rsl, wr, fr);
; #pragma unroll
;         for (int ai = 0; ai < 2; ++ai)
; #pragma unroll
;             for (int m = 0; m < 4; ++m) { const int row = row0 + ai * HALF + m * 16, b = row >> 12, s = row & 4095;
;                 const size_t o = (((size_t)b * 16 + u.pn) * 4096 + s) * 128 + dim0;
;     ...
;             PG8_LDA(At, 1, 1); PG8_STAGE(PG8_SB(1, 0), b3, voffB); PG8_STAGE(PG8_SB(1, 1), b3 + hstep, voffB); PG8_STAGE(PG8_SA(1, 0), a3, voffA);
;             PG8_WAIT_V(8); PG8_WAIT_L(0); PG8_BAR; PG8_MMA(1, 0, At, B0); PG8_MMA(1, 1, At, B1); PG8_BAR; PG8_SCHED;
	s_setprio 0
	ds_read_b128 v[180:183], v150 offset:49152
	ds_read_b128 v[184:187], v150 offset:50176
	ds_read_b128 v[188:191], v150 offset:51200
	ds_read_b128 v[192:195], v150 offset:52224
	ds_read_b128 v[196:199], v150 offset:53248
	ds_read_b128 v[210:213], v150 offset:54272
	ds_read_b128 v[214:217], v150 offset:55296
	ds_read_b128 v[218:221], v150 offset:56320
	s_add_i32 s48, s48, s21
	v_lshl_add_u64 v[146:147], v[146:147], 0, s[66:67]
	s_mov_b32 m0, s48
	s_nop 0
	global_load_lds_dwordx4 v[146:147], off
	s_add_i32 m0, s48, 0x2000
	s_add_u32 s50, s50, 0x20080
	v_lshl_add_u64 v[146:147], v[206:207], 0, s[66:67]
	s_addc_u32 s51, s51, 0
	s_add_i32 s48, s49, s21
	global_load_lds_dwordx4 v[146:147], off
	v_lshl_add_u64 v[146:147], s[50:51], 0, v[200:201]
	s_mov_b32 m0, s48
	s_nop 0
	global_load_lds_dwordx4 v[146:147], off
	v_lshl_add_u64 v[146:147], s[50:51], 0, v[132:133]
	s_add_i32 m0, s48, 0x2000
	s_nop 0
	global_load_lds_dwordx4 v[146:147], off
	v_lshl_add_u64 v[146:147], v[208:209], 0, s[66:67]
	s_mov_b32 m0, s54
	s_nop 0
	global_load_lds_dwordx4 v[146:147], off
	v_lshl_add_u64 v[146:147], v[222:223], 0, s[66:67]
	s_mov_b32 m0, s55
	s_nop 0
	global_load_lds_dwordx4 v[146:147], off
	s_waitcnt vmcnt(8)
	s_waitcnt lgkmcnt(0)
	s_setprio 1
	s_barrier
	v_mfma_f32_16x16x32_bf16 v[64:67], v[142:145], v[180:183], v[64:67]
	v_mfma_f32_16x16x32_bf16 v[60:63], v[156:159], v[180:183], v[60:63]
	v_mfma_f32_16x16x32_bf16 v[48:51], v[142:145], v[188:191], v[48:51]
	v_mfma_f32_16x16x32_bf16 v[44:47], v[156:159], v[188:191], v[44:47]
	v_mfma_f32_16x16x32_bf16 v[32:35], v[142:145], v[196:199], v[32:35]
	v_mfma_f32_16x16x32_bf16 v[28:31], v[156:159], v[196:199], v[28:31]
	v_mfma_f32_16x16x32_bf16 v[16:19], v[142:145], v[214:217], v[16:19]
	v_mfma_f32_16x16x32_bf16 v[12:15], v[156:159], v[214:217], v[12:15]
	v_mfma_f32_16x16x32_bf16 v[64:67], v[152:155], v[184:187], v[64:67]
	v_mfma_f32_16x16x32_bf16 v[60:63], v[160:163], v[184:187], v[60:63]
	v_mfma_f32_16x16x32_bf16 v[48:51], v[152:155], v[192:195], v[48:51]
	v_mfma_f32_16x16x32_bf16 v[44:47], v[160:163], v[192:195], v[44:47]
	v_mfma_f32_16x16x32_bf16 v[32:35], v[152:155], v[210:213], v[32:35]
	v_mfma_f32_16x16x32_bf16 v[28:31], v[160:163], v[210:213], v[28:31]
	v_mfma_f32_16x16x32_bf16 v[16:19], v[152:155], v[218:221], v[16:19]
	v_mfma_f32_16x16x32_bf16 v[12:15], v[160:163], v[218:221], v[12:15]
	s_setprio 0
	s_setprio 1
	v_mfma_f32_16x16x32_bf16 v[56:59], v[164:167], v[180:183], v[56:59]
	v_mfma_f32_16x16x32_bf16 v[52:55], v[172:175], v[180:183], v[52:55]
	v_mfma_f32_16x16x32_bf16 v[40:43], v[164:167], v[188:191], v[40:43]
	v_mfma_f32_16x16x32_bf16 v[36:39], v[172:175], v[188:191], v[36:39]
	v_mfma_f32_16x16x32_bf16 v[24:27], v[164:167], v[196:199], v[24:27]
	v_mfma_f32_16x16x32_bf16 v[20:23], v[172:175], v[196:199], v[20:23]
	v_mfma_f32_16x16x32_bf16 v[8:11], v[164:167], v[214:217], v[8:11]
	v_mfma_f32_16x16x32_bf16 v[4:7], v[172:175], v[214:217], v[4:7]
	v_mfma_f32_16x16x32_bf16 v[56:59], v[168:171], v[184:187], v[56:59]
	v_mfma_f32_16x16x32_bf16 v[52:55], v[176:179], v[184:187], v[52:55]
	v_mfma_f32_16x16x32_bf16 v[40:43], v[168:171], v[192:195], v[40:43]
	v_mfma_f32_16x16x32_bf16 v[36:39], v[176:179], v[192:195], v[36:39]
	v_mfma_f32_16x16x32_bf16 v[24:27], v[168:171], v[210:213], v[24:27]
	v_mfma_f32_16x16x32_bf16 v[20:23], v[176:179], v[210:213], v[20:23]
	v_mfma_f32_16x16x32_bf16 v[8:11], v[168:171], v[218:221], v[8:11]
	v_mfma_f32_16x16x32_bf16 v[4:7], v[176:179], v[218:221], v[4:7]
	s_barrier
	s_setprio 0
	s_add_i32 s83, s83, 2
	s_add_u32 s73, s73, 0x100
	s_addc_u32 s81, s81, 0
	s_add_u32 s24, s24, 0x100
	s_addc_u32 s25, s25, 0
	s_cmp_gt_u32 s83, 5
	s_cbranch_scc0 .LBB0_290
	v_mov_b32_e32 v142, v148
	v_mov_b32_e32 v143, v3
	v_readlane_b32 s84, v255, 29
	s_add_i32 s24, s63, s84
	v_add_u32_e32 v151, s56, v143
	v_ashrrev_i32_e32 v156, 12, v151
	s_ashr_i32 s25, s24, 31
	v_ashrrev_i32_e32 v157, 31, v156
	s_lshl_b64 s[24:25], s[24:25], 12
	v_lshlrev_b64 v[156:157], 16, v[156:157]
	v_lshl_add_u32 v143, v143, 2, s58
	v_lshl_add_u64 v[156:157], v[156:157], 0, s[24:25]
	v_lshl_add_u32 v142, v142, 3, s53
	ds_read2_b32 v[152:153], v143 offset1:16
	ds_read2_b32 v[154:155], v143 offset0:32 offset1:48
	ds_read2_b32 v[146:147], v143 offset0:128 offset1:144
	ds_read2_b32 v[144:145], v143 offset0:160 offset1:176
	v_and_or_b32 v156, v151, s17, v156
	v_ashrrev_i32_e32 v143, 31, v142
	v_lshlrev_b64 v[156:157], 7, v[156:157]
	v_lshl_add_u64 v[156:157], v[156:157], 0, v[142:143]
	s_waitcnt lgkmcnt(0)
; #define PG8_G __attribute__((address_space(1)))
; __device__ __forceinline__ u32x4 pack8bf(const f32x4 a, const f32x4 b) { u32x4 w; w.x = cvt_pk_bf16(a[0], a[1]); w.y = cvt_pk_bf16(a[2], a[3]); w.z = cvt_pk_bf16(b[0], b[1]); w.w = cvt_pk_bf16(b[2], b[3]); return w; }
;     __device__ __forceinline__ void operator()(const f32x4 (&acc)[2][2][4][2], const Unit& u, int wr, int wc, int fr_, int fq_, int ui) const {
;     ...
;         float r[2][4]; load_rs(r, rsl, wr, fr);
; #pragma unroll
;         for (int ai = 0; ai < 2; ++ai)
; #pragma unroll
;             for (int m = 0; m < 4; ++m) { const int row = row0 + ai * HALF + m * 16, b = row >> 12, s = row & 4095;
;                 const size_t o = (((size_t)b * 16 + u.pn) * 4096 + s) * 128 + dim0;
;                 *(PG8_G u32x4*)(KH + o) = pack8bf(acc[ai][0][m][0] * r[ai][m], acc[ai][0][m][1] * r[ai][m]); *(PG8_G u32x4*)(VH + o) = pack8bf(acc[ai][1][m][0] * r[ai][m], acc[ai][1][m][1] * r[ai][m]); }
	v_pk_mul_f32 v[128:129], v[128:129], v[152:153] op_sel_hi:[1,0]
	v_pk_mul_f32 v[130:131], v[130:131], v[152:153] op_sel_hi:[1,0]
	v_pk_mul_f32 v[158:159], v[126:127], v[152:153] op_sel_hi:[1,0]
	v_pk_mul_f32 v[126:127], v[124:125], v[152:153] op_sel_hi:[1,0]
	v_cvt_pk_bf16_f32 v124, v128, v129
	v_lshlrev_b64 v[128:129], 1, v[156:157]
	v_cvt_pk_bf16_f32 v125, v130, v131
	v_lshl_add_u64 v[130:131], s[12:13], 0, v[128:129]
	v_cvt_pk_bf16_f32 v126, v126, v127
	v_cvt_pk_bf16_f32 v127, v158, v159
	global_store_dwordx4 v[130:131], v[124:127], off
	v_pk_mul_f32 v[120:121], v[120:121], v[152:153] op_sel_hi:[1,0]
	v_pk_mul_f32 v[122:123], v[122:123], v[152:153] op_sel_hi:[1,0]
	v_pk_mul_f32 v[124:125], v[118:119], v[152:153] op_sel_hi:[1,0]
	v_pk_mul_f32 v[118:119], v[116:117], v[152:153] op_sel_hi:[1,0]
	v_cvt_pk_bf16_f32 v116, v120, v121
	v_cvt_pk_bf16_f32 v117, v122, v123
	v_lshl_add_u64 v[120:121], s[14:15], 0, v[128:129]
	v_cvt_pk_bf16_f32 v118, v118, v119
	v_cvt_pk_bf16_f32 v119, v124, v125
	global_store_dwordx4 v[120:121], v[116:119], off
	v_pk_mul_f32 v[96:97], v[96:97], v[154:155] op_sel_hi:[1,0]
	v_pk_mul_f32 v[98:99], v[98:99], v[154:155] op_sel_hi:[1,0]
	v_add_u32_e32 v118, 16, v151
	v_ashrrev_i32_e32 v116, 12, v118
	v_ashrrev_i32_e32 v117, 31, v116
	v_lshlrev_b64 v[116:117], 16, v[116:117]
	v_lshl_add_u64 v[116:117], v[116:117], 0, s[24:25]
	v_and_or_b32 v116, v118, s17, v116
	v_lshlrev_b64 v[116:117], 7, v[116:117]
	v_mov_b32_e32 v118, v153
	v_lshl_add_u64 v[116:117], v[116:117], 0, v[142:143]
	v_pk_mul_f32 v[112:113], v[112:113], v[118:119] op_sel_hi:[1,0]
	v_pk_mul_f32 v[114:115], v[114:115], v[118:119] op_sel_hi:[1,0]
	v_pk_mul_f32 v[120:121], v[110:111], v[118:119] op_sel_hi:[1,0]
	v_pk_mul_f32 v[110:111], v[108:109], v[118:119] op_sel_hi:[1,0]
	v_cvt_pk_bf16_f32 v108, v112, v113
	v_lshlrev_b64 v[112:113], 1, v[116:117]
	v_cvt_pk_bf16_f32 v109, v114, v115
	v_lshl_add_u64 v[114:115], s[12:13], 0, v[112:113]
	v_cvt_pk_bf16_f32 v110, v110, v111
	v_cvt_pk_bf16_f32 v111, v120, v121
	global_store_dwordx4 v[114:115], v[108:111], off
	v_pk_mul_f32 v[104:105], v[104:105], v[118:119] op_sel_hi:[1,0]
	v_pk_mul_f32 v[106:107], v[106:107], v[118:119] op_sel_hi:[1,0]
	v_pk_mul_f32 v[108:109], v[102:103], v[118:119] op_sel_hi:[1,0]
	v_pk_mul_f32 v[102:103], v[100:101], v[118:119] op_sel_hi:[1,0]
	v_cvt_pk_bf16_f32 v100, v104, v105
	v_cvt_pk_bf16_f32 v101, v106, v107
	v_lshl_add_u64 v[104:105], s[14:15], 0, v[112:113]
	v_cvt_pk_bf16_f32 v102, v102, v103
	v_cvt_pk_bf16_f32 v103, v108, v109
	global_store_dwordx4 v[104:105], v[100:103], off
	v_pk_mul_f32 v[88:89], v[88:89], v[154:155] op_sel_hi:[1,0]
	v_pk_mul_f32 v[90:91], v[90:91], v[154:155] op_sel_hi:[1,0]
	v_add_u32_e32 v102, 32, v151
	v_ashrrev_i32_e32 v100, 12, v102
	v_ashrrev_i32_e32 v101, 31, v100
	v_lshlrev_b64 v[100:101], 16, v[100:101]
	v_lshl_add_u64 v[100:101], v[100:101], 0, s[24:25]
	v_and_or_b32 v100, v102, s17, v100
	v_lshlrev_b64 v[100:101], 7, v[100:101]
	v_lshl_add_u64 v[100:101], v[100:101], 0, v[142:143]
	v_pk_mul_f32 v[102:103], v[94:95], v[154:155] op_sel_hi:[1,0]
	v_pk_mul_f32 v[94:95], v[92:93], v[154:155] op_sel_hi:[1,0]
	v_cvt_pk_bf16_f32 v92, v96, v97
	v_lshlrev_b64 v[96:97], 1, v[100:101]
	v_cvt_pk_bf16_f32 v93, v98, v99
	v_lshl_add_u64 v[98:99], s[12:13], 0, v[96:97]
	v_cvt_pk_bf16_f32 v94, v94, v95
	v_cvt_pk_bf16_f32 v95, v102, v103
	global_store_dwordx4 v[98:99], v[92:95], off
	v_pk_mul_f32 v[64:65], v[64:65], v[146:147] op_sel_hi:[1,0]
	v_pk_mul_f32 v[66:67], v[66:67], v[146:147] op_sel_hi:[1,0]
	v_pk_mul_f32 v[92:93], v[86:87], v[154:155] op_sel_hi:[1,0]
	v_pk_mul_f32 v[86:87], v[84:85], v[154:155] op_sel_hi:[1,0]
	v_cvt_pk_bf16_f32 v84, v88, v89
	v_cvt_pk_bf16_f32 v85, v90, v91
	v_lshl_add_u64 v[88:89], s[14:15], 0, v[96:97]
	v_cvt_pk_bf16_f32 v86, v86, v87
	v_cvt_pk_bf16_f32 v87, v92, v93
	global_store_dwordx4 v[88:89], v[84:87], off
	v_pk_mul_f32 v[56:57], v[56:57], v[146:147] op_sel_hi:[1,0]
	v_pk_mul_f32 v[58:59], v[58:59], v[146:147] op_sel_hi:[1,0]
	v_add_u32_e32 v86, 48, v151
	v_ashrrev_i32_e32 v84, 12, v86
	v_ashrrev_i32_e32 v85, 31, v84
	v_lshlrev_b64 v[84:85], 16, v[84:85]
	v_lshl_add_u64 v[84:85], v[84:85], 0, s[24:25]
	v_and_or_b32 v84, v86, s17, v84
	v_lshlrev_b64 v[84:85], 7, v[84:85]
	v_mov_b32_e32 v86, v155
	v_lshl_add_u64 v[84:85], v[84:85], 0, v[142:143]
	v_pk_mul_f32 v[80:81], v[80:81], v[86:87] op_sel_hi:[1,0]
	v_pk_mul_f32 v[82:83], v[82:83], v[86:87] op_sel_hi:[1,0]
	v_pk_mul_f32 v[88:89], v[78:79], v[86:87] op_sel_hi:[1,0]
	v_pk_mul_f32 v[78:79], v[76:77], v[86:87] op_sel_hi:[1,0]
	v_cvt_pk_bf16_f32 v76, v80, v81
	v_lshlrev_b64 v[80:81], 1, v[84:85]
	v_cvt_pk_bf16_f32 v77, v82, v83
	v_lshl_add_u64 v[82:83], s[12:13], 0, v[80:81]
	v_cvt_pk_bf16_f32 v78, v78, v79
	v_cvt_pk_bf16_f32 v79, v88, v89
	global_store_dwordx4 v[82:83], v[76:79], off
	v_pk_mul_f32 v[72:73], v[72:73], v[86:87] op_sel_hi:[1,0]
	v_pk_mul_f32 v[74:75], v[74:75], v[86:87] op_sel_hi:[1,0]
	v_pk_mul_f32 v[76:77], v[70:71], v[86:87] op_sel_hi:[1,0]
	v_pk_mul_f32 v[70:71], v[68:69], v[86:87] op_sel_hi:[1,0]
	v_cvt_pk_bf16_f32 v68, v72, v73
	v_cvt_pk_bf16_f32 v69, v74, v75
	v_lshl_add_u64 v[72:73], s[14:15], 0, v[80:81]
; #define PG8_G __attribute__((address_space(1)))
; __device__ __forceinline__ u32x4 pack8bf(const f32x4 a, const f32x4 b) { u32x4 w; w.x = cvt_pk_bf16(a[0], a[1]); w.y = cvt_pk_bf16(a[2], a[3]); w.z = cvt_pk_bf16(b[0], b[1]); w.w = cvt_pk_bf16(b[2], b[3]); return w; }
;     __device__ __forceinline__ void operator()(const f32x4 (&acc)[2][2][4][2], const Unit& u, int wr, int wc, int fr_, int fq_, int ui) const {
;     ...
;         float r[2][4]; load_rs(r, rsl, wr, fr);
; #pragma unroll
;         for (int ai = 0; ai < 2; ++ai)
; #pragma unroll
;             for (int m = 0; m < 4; ++m) { const int row = row0 + ai * HALF + m * 16, b = row >> 12, s = row & 4095;
;                 const size_t o = (((size_t)b * 16 + u.pn) * 4096 + s) * 128 + dim0;
;                 *(PG8_G u32x4*)(KH + o) = pack8bf(acc[ai][0][m][0] * r[ai][m], acc[ai][0][m][1] * r[ai][m]); *(PG8_G u32x4*)(VH + o) = pack8bf(acc[ai][1][m][0] * r[ai][m], acc[ai][1][m][1] * r[ai][m]); }
;     ...
;         if (!has_next) break;
	v_cvt_pk_bf16_f32 v70, v70, v71
	v_cvt_pk_bf16_f32 v71, v76, v77
	global_store_dwordx4 v[72:73], v[68:71], off
	v_pk_mul_f32 v[32:33], v[32:33], v[144:145] op_sel_hi:[1,0]
	v_pk_mul_f32 v[34:35], v[34:35], v[144:145] op_sel_hi:[1,0]
	v_add_u32_e32 v70, 0x80, v151
	v_ashrrev_i32_e32 v68, 12, v70
	v_ashrrev_i32_e32 v69, 31, v68
	v_lshlrev_b64 v[68:69], 16, v[68:69]
	v_lshl_add_u64 v[68:69], v[68:69], 0, s[24:25]
	v_and_or_b32 v68, v70, s17, v68
	v_lshlrev_b64 v[68:69], 7, v[68:69]
	v_lshl_add_u64 v[68:69], v[68:69], 0, v[142:143]
	v_pk_mul_f32 v[70:71], v[62:63], v[146:147] op_sel_hi:[1,0]
	v_pk_mul_f32 v[62:63], v[60:61], v[146:147] op_sel_hi:[1,0]
	v_cvt_pk_bf16_f32 v60, v64, v65
	v_lshlrev_b64 v[64:65], 1, v[68:69]
	v_cvt_pk_bf16_f32 v61, v66, v67
	v_lshl_add_u64 v[66:67], s[12:13], 0, v[64:65]
	v_cvt_pk_bf16_f32 v62, v62, v63
	v_cvt_pk_bf16_f32 v63, v70, v71
	global_store_dwordx4 v[66:67], v[60:63], off
	v_pk_mul_f32 v[24:25], v[24:25], v[144:145] op_sel_hi:[1,0]
	v_pk_mul_f32 v[26:27], v[26:27], v[144:145] op_sel_hi:[1,0]
	v_pk_mul_f32 v[60:61], v[54:55], v[146:147] op_sel_hi:[1,0]
	v_pk_mul_f32 v[54:55], v[52:53], v[146:147] op_sel_hi:[1,0]
	v_cvt_pk_bf16_f32 v52, v56, v57
	v_cvt_pk_bf16_f32 v53, v58, v59
	v_lshl_add_u64 v[56:57], s[14:15], 0, v[64:65]
	v_cvt_pk_bf16_f32 v54, v54, v55
	v_cvt_pk_bf16_f32 v55, v60, v61
	global_store_dwordx4 v[56:57], v[52:55], off
	s_cmp_eq_u32 s62, 8
	s_mov_b32 s63, s62
	v_add_u32_e32 v54, 0x90, v151
	v_ashrrev_i32_e32 v52, 12, v54
	v_ashrrev_i32_e32 v53, 31, v52
	v_lshlrev_b64 v[52:53], 16, v[52:53]
	v_lshl_add_u64 v[52:53], v[52:53], 0, s[24:25]
	v_and_or_b32 v52, v54, s17, v52
	v_lshlrev_b64 v[52:53], 7, v[52:53]
	v_mov_b32_e32 v54, v147
	v_lshl_add_u64 v[52:53], v[52:53], 0, v[142:143]
	v_pk_mul_f32 v[48:49], v[48:49], v[54:55] op_sel_hi:[1,0]
	v_pk_mul_f32 v[50:51], v[50:51], v[54:55] op_sel_hi:[1,0]
	v_pk_mul_f32 v[56:57], v[46:47], v[54:55] op_sel_hi:[1,0]
	v_pk_mul_f32 v[46:47], v[44:45], v[54:55] op_sel_hi:[1,0]
	v_cvt_pk_bf16_f32 v44, v48, v49
	v_lshlrev_b64 v[48:49], 1, v[52:53]
	v_cvt_pk_bf16_f32 v45, v50, v51
	v_lshl_add_u64 v[50:51], s[12:13], 0, v[48:49]
	v_cvt_pk_bf16_f32 v46, v46, v47
	v_cvt_pk_bf16_f32 v47, v56, v57
	global_store_dwordx4 v[50:51], v[44:47], off
	v_pk_mul_f32 v[40:41], v[40:41], v[54:55] op_sel_hi:[1,0]
	v_pk_mul_f32 v[42:43], v[42:43], v[54:55] op_sel_hi:[1,0]
	v_pk_mul_f32 v[44:45], v[38:39], v[54:55] op_sel_hi:[1,0]
	v_pk_mul_f32 v[38:39], v[36:37], v[54:55] op_sel_hi:[1,0]
	v_cvt_pk_bf16_f32 v36, v40, v41
	v_cvt_pk_bf16_f32 v37, v42, v43
	v_lshl_add_u64 v[40:41], s[14:15], 0, v[48:49]
	v_cvt_pk_bf16_f32 v38, v38, v39
	v_cvt_pk_bf16_f32 v39, v44, v45
	global_store_dwordx4 v[40:41], v[36:39], off
	v_readlane_b32 s85, v255, 30
	s_nop 0
	v_add_u32_e32 v38, 0xa0, v151
	v_ashrrev_i32_e32 v36, 12, v38
	v_ashrrev_i32_e32 v37, 31, v36
	v_lshlrev_b64 v[36:37], 16, v[36:37]
	v_lshl_add_u64 v[36:37], v[36:37], 0, s[24:25]
	v_and_or_b32 v36, v38, s17, v36
	v_lshlrev_b64 v[36:37], 7, v[36:37]
	v_lshl_add_u64 v[36:37], v[36:37], 0, v[142:143]
	v_pk_mul_f32 v[38:39], v[30:31], v[144:145] op_sel_hi:[1,0]
	v_pk_mul_f32 v[30:31], v[28:29], v[144:145] op_sel_hi:[1,0]
	v_cvt_pk_bf16_f32 v28, v32, v33
	v_lshlrev_b64 v[32:33], 1, v[36:37]
	v_cvt_pk_bf16_f32 v29, v34, v35
	v_lshl_add_u64 v[34:35], s[12:13], 0, v[32:33]
	v_cvt_pk_bf16_f32 v30, v30, v31
	v_cvt_pk_bf16_f32 v31, v38, v39
	global_store_dwordx4 v[34:35], v[28:31], off
	s_nop 1
	v_pk_mul_f32 v[28:29], v[22:23], v[144:145] op_sel_hi:[1,0]
	v_pk_mul_f32 v[22:23], v[20:21], v[144:145] op_sel_hi:[1,0]
	v_cvt_pk_bf16_f32 v20, v24, v25
	v_cvt_pk_bf16_f32 v21, v26, v27
	v_lshl_add_u64 v[24:25], s[14:15], 0, v[32:33]
	v_cvt_pk_bf16_f32 v22, v22, v23
	v_cvt_pk_bf16_f32 v23, v28, v29
	global_store_dwordx4 v[24:25], v[20:23], off
	s_nop 1
	v_add_u32_e32 v22, 0xb0, v151
	v_ashrrev_i32_e32 v20, 12, v22
	v_ashrrev_i32_e32 v21, 31, v20
	v_lshlrev_b64 v[20:21], 16, v[20:21]
	v_lshl_add_u64 v[20:21], v[20:21], 0, s[24:25]
	v_and_or_b32 v20, v22, s17, v20
	v_lshlrev_b64 v[20:21], 7, v[20:21]
	v_mov_b32_e32 v22, v145
	v_lshl_add_u64 v[20:21], v[20:21], 0, v[142:143]
	v_pk_mul_f32 v[16:17], v[16:17], v[22:23] op_sel_hi:[1,0]
	v_pk_mul_f32 v[18:19], v[18:19], v[22:23] op_sel_hi:[1,0]
	v_pk_mul_f32 v[24:25], v[14:15], v[22:23] op_sel_hi:[1,0]
	v_pk_mul_f32 v[14:15], v[12:13], v[22:23] op_sel_hi:[1,0]
	v_cvt_pk_bf16_f32 v12, v16, v17
	v_lshlrev_b64 v[16:17], 1, v[20:21]
	v_cvt_pk_bf16_f32 v13, v18, v19
	v_lshl_add_u64 v[18:19], s[12:13], 0, v[16:17]
	v_pk_mul_f32 v[8:9], v[8:9], v[22:23] op_sel_hi:[1,0]
	v_cvt_pk_bf16_f32 v14, v14, v15
	v_cvt_pk_bf16_f32 v15, v24, v25
	global_store_dwordx4 v[18:19], v[12:15], off
	v_pk_mul_f32 v[10:11], v[10:11], v[22:23] op_sel_hi:[1,0]
	s_nop 0
	v_pk_mul_f32 v[12:13], v[6:7], v[22:23] op_sel_hi:[1,0]
	v_pk_mul_f32 v[6:7], v[4:5], v[22:23] op_sel_hi:[1,0]
	v_cvt_pk_bf16_f32 v4, v8, v9
	v_lshl_add_u64 v[8:9], s[14:15], 0, v[16:17]
	v_cvt_pk_bf16_f32 v5, v10, v11
	v_cvt_pk_bf16_f32 v6, v6, v7
	v_cvt_pk_bf16_f32 v7, v12, v13
	global_store_dwordx4 v[8:9], v[4:7], off
	s_cbranch_scc0 .LBB0_289
	s_waitcnt vmcnt(0)
	s_cmpk_gt_u32 s20, 0xff
	s_cbranch_scc1 .LBB0_294
	s_barrier

; #define PG8_STAGE(bufoff, gbase, voff) do { _Pragma("unroll") for (int _i = 0; _i < 2; ++_i) \
;         __builtin_amdgcn_global_load_lds((const unsigned*)((const char*)(gbase) + (voff)[_i]), (PG8_LAS unsigned*)(lds + (bufoff) + ldsw + _i * 8192), 16, 0, 0); } while (0)
; #define PG8_LDA(dst, b, h) do { _Pragma("unroll") for (int m = 0; m < 4; ++m) _Pragma("unroll") for (int k = 0; k < 2; ++k) dst[m][k] = *(const PG8_LAS bf16x8*)(lds + PG8_SA(b, h) + aoff + m * 2048 + k * 1024); } while (0)
; #define PG8_LDB(dst, b, h) do { _Pragma("unroll") for (int n = 0; n < 2; ++n) _Pragma("unroll") for (int k = 0; k < 2; ++k) dst[n][k] = *(const PG8_LAS bf16x8*)(lds + PG8_SB(b, h) + boff + n * 2048 + k * 1024); } while (0)
; #define PG8_MMA(ai, bj, At, Bt) do { __builtin_amdgcn_s_setprio(1); _Pragma("unroll") for (int m = 0; m < 4; ++m) _Pragma("unroll") for (int n = 0; n < 2; ++n) _Pragma("unroll") for (int k = 0; k < 2; ++k) \
;         acc[ai][bj][m][n] = __builtin_amdgcn_mfma_f32_16x16x32_bf16(Bt[n][k], At[m][k], acc[ai][bj][m][n], 0, 0, 0); __builtin_amdgcn_s_setprio(0); } while (0)
; #define PG8_WAIT_V(n) asm volatile("s_waitcnt vmcnt(" #n ")" ::: "memory")
; #define PG8_WAIT_L(n) asm volatile("s_waitcnt lgkmcnt(" #n ")" ::: "memory")
; #define PG8_BAR __builtin_amdgcn_s_barrier()
; #define PG8_SCHED __builtin_amdgcn_sched_barrier(0)
;     ...
;             PG8_LDB(B0, 0, 0); PG8_LDB(B1, 0, 1); PG8_SCHED; PG8_LDA(At, 0, 0); PG8_STAGE(PG8_SA(1, 1), a1 + hstep, voffA);
;             PG8_WAIT_V(8); PG8_WAIT_L(0); PG8_BAR; PG8_MMA(0, 0, At, B0); PG8_MMA(0, 1, At, B1); PG8_BAR; PG8_SCHED;
;             PG8_LDA(At, 0, 1); PG8_STAGE(PG8_SB(0, 0), b2, voffB); PG8_STAGE(PG8_SB(0, 1), b2 + hstep, voffB); PG8_STAGE(PG8_SA(0, 0), a2, voffA);
;             PG8_WAIT_V(8); PG8_WAIT_L(0); PG8_BAR; PG8_MMA(1, 0, At, B0); PG8_MMA(1, 1, At, B1); PG8_BAR; PG8_SCHED;
.LBB0_301:
	ds_read_b128 v[132:135], v251
	ds_read_b128 v[146:149], v251 offset:1024
	ds_read_b128 v[150:153], v251 offset:2048
	ds_read_b128 v[154:157], v251 offset:3072
	ds_read_b128 v[158:161], v251 offset:16384
	ds_read_b128 v[162:165], v251 offset:17408
	ds_read_b128 v[166:169], v251 offset:18432
	ds_read_b128 v[176:179], v251 offset:19456
	ds_read_b128 v[180:183], v174
	ds_read_b128 v[184:187], v174 offset:1024
	ds_read_b128 v[188:191], v174 offset:2048
	ds_read_b128 v[192:195], v174 offset:3072
	ds_read_b128 v[196:199], v174 offset:4096
	ds_read_b128 v[210:213], v174 offset:5120
	ds_read_b128 v[214:217], v174 offset:6144
	ds_read_b128 v[218:221], v174 offset:7168
	s_add_u32 s24, s14, 0xfffe0080
	s_addc_u32 s25, s15, -1
	s_add_i32 s48, 0, 0x10000
	s_cmp_eq_u32 s54, 4
	s_cselect_b32 s51, s21, s25
	s_cselect_b32 s50, s23, s24
	s_cselect_b32 s25, s42, s53
	s_cselect_b32 s24, s44, s52
	s_add_i32 s49, 0, 0x14000
	v_lshl_add_u64 v[170:171], s[14:15], 0, v[144:145]
	s_add_i32 m0, s62, 0xc000
	s_nop 0
	global_load_lds_dwordx4 v[170:171], off
	v_lshl_add_u64 v[170:171], s[14:15], 0, v[142:143]
	s_add_i32 m0, s62, 0xe000
	s_nop 0
	global_load_lds_dwordx4 v[170:171], off
	s_waitcnt vmcnt(8)
	s_waitcnt lgkmcnt(0)
	s_setprio 1
	s_barrier
	v_mfma_f32_16x16x32_bf16 v[128:131], v[132:135], v[180:183], v[128:131]
	v_mfma_f32_16x16x32_bf16 v[124:127], v[150:153], v[180:183], v[124:127]
	v_mfma_f32_16x16x32_bf16 v[116:119], v[132:135], v[188:191], v[116:119]
	v_mfma_f32_16x16x32_bf16 v[108:111], v[150:153], v[188:191], v[108:111]
	v_mfma_f32_16x16x32_bf16 v[100:103], v[132:135], v[196:199], v[100:103]
	v_mfma_f32_16x16x32_bf16 v[92:95], v[150:153], v[196:199], v[92:95]
	v_mfma_f32_16x16x32_bf16 v[84:87], v[132:135], v[214:217], v[84:87]
	v_mfma_f32_16x16x32_bf16 v[76:79], v[150:153], v[214:217], v[76:79]
	v_mfma_f32_16x16x32_bf16 v[128:131], v[146:149], v[184:187], v[128:131]
	v_mfma_f32_16x16x32_bf16 v[124:127], v[154:157], v[184:187], v[124:127]
	v_mfma_f32_16x16x32_bf16 v[116:119], v[146:149], v[192:195], v[116:119]
	v_mfma_f32_16x16x32_bf16 v[108:111], v[154:157], v[192:195], v[108:111]
	v_mfma_f32_16x16x32_bf16 v[100:103], v[146:149], v[210:213], v[100:103]
	v_mfma_f32_16x16x32_bf16 v[92:95], v[154:157], v[210:213], v[92:95]
	v_mfma_f32_16x16x32_bf16 v[84:87], v[146:149], v[218:221], v[84:87]
	v_mfma_f32_16x16x32_bf16 v[76:79], v[154:157], v[218:221], v[76:79]
	s_setprio 0
	s_setprio 1
	v_mfma_f32_16x16x32_bf16 v[120:123], v[158:161], v[180:183], v[120:123]
	v_mfma_f32_16x16x32_bf16 v[112:115], v[166:169], v[180:183], v[112:115]
	v_mfma_f32_16x16x32_bf16 v[104:107], v[158:161], v[188:191], v[104:107]
	v_mfma_f32_16x16x32_bf16 v[96:99], v[166:169], v[188:191], v[96:99]
	v_mfma_f32_16x16x32_bf16 v[88:91], v[158:161], v[196:199], v[88:91]
	v_mfma_f32_16x16x32_bf16 v[80:83], v[166:169], v[196:199], v[80:83]
	v_mfma_f32_16x16x32_bf16 v[72:75], v[158:161], v[214:217], v[72:75]
	v_mfma_f32_16x16x32_bf16 v[68:71], v[166:169], v[214:217], v[68:71]
	v_mfma_f32_16x16x32_bf16 v[120:123], v[162:165], v[184:187], v[120:123]
	v_mfma_f32_16x16x32_bf16 v[112:115], v[176:179], v[184:187], v[112:115]
	v_mfma_f32_16x16x32_bf16 v[104:107], v[162:165], v[192:195], v[104:107]
	v_mfma_f32_16x16x32_bf16 v[96:99], v[176:179], v[192:195], v[96:99]
	v_mfma_f32_16x16x32_bf16 v[88:91], v[162:165], v[210:213], v[88:91]
	v_mfma_f32_16x16x32_bf16 v[80:83], v[176:179], v[210:213], v[80:83]
	v_mfma_f32_16x16x32_bf16 v[72:75], v[162:165], v[218:221], v[72:75]
	v_mfma_f32_16x16x32_bf16 v[68:71], v[176:179], v[218:221], v[68:71]
	s_barrier
	s_setprio 0
	ds_read_b128 v[180:183], v174 offset:16384
	ds_read_b128 v[184:187], v174 offset:17408
	ds_read_b128 v[188:191], v174 offset:18432
	ds_read_b128 v[192:195], v174 offset:19456
	ds_read_b128 v[196:199], v174 offset:20480
	ds_read_b128 v[210:213], v174 offset:21504
	ds_read_b128 v[214:217], v174 offset:22528
	ds_read_b128 v[218:221], v174 offset:23552
	s_add_i32 s48, s48, s61
	v_lshl_add_u64 v[170:171], s[24:25], 0, v[200:201]
	s_mov_b32 m0, s48
	s_nop 0
	global_load_lds_dwordx4 v[170:171], off
	s_add_i32 m0, s48, 0x2000
	s_add_u32 s84, s24, 0x20000
	v_lshl_add_u64 v[206:207], s[24:25], 0, v[136:137]
	s_addc_u32 s85, s25, 0
	s_add_i32 s48, s49, s61
	global_load_lds_dwordx4 v[206:207], off
	v_lshl_add_u64 v[208:209], s[84:85], 0, v[200:201]
	s_mov_b32 m0, s48
	v_lshl_add_u64 v[222:223], s[50:51], 0, v[138:139]
	global_load_lds_dwordx4 v[208:209], off
	v_lshl_add_u64 v[208:209], s[84:85], 0, v[136:137]
	s_add_i32 m0, s48, 0x2000
	s_nop 0
	global_load_lds_dwordx4 v[208:209], off
	v_lshl_add_u64 v[208:209], s[50:51], 0, v[140:141]
	s_mov_b32 m0, s62
	s_nop 0
	global_load_lds_dwordx4 v[208:209], off
	s_mov_b32 m0, s63
	s_nop 0
	global_load_lds_dwordx4 v[222:223], off
	s_waitcnt vmcnt(8)
	s_waitcnt lgkmcnt(0)
	s_setprio 1
	s_barrier
; #define PG8_STAGE(bufoff, gbase, voff) do { _Pragma("unroll") for (int _i = 0; _i < 2; ++_i) \
;         __builtin_amdgcn_global_load_lds((const unsigned*)((const char*)(gbase) + (voff)[_i]), (PG8_LAS unsigned*)(lds + (bufoff) + ldsw + _i * 8192), 16, 0, 0); } while (0)
; #define PG8_LDA(dst, b, h) do { _Pragma("unroll") for (int m = 0; m < 4; ++m) _Pragma("unroll") for (int k = 0; k < 2; ++k) dst[m][k] = *(const PG8_LAS bf16x8*)(lds + PG8_SA(b, h) + aoff + m * 2048 + k * 1024); } while (0)
; #define PG8_LDB(dst, b, h) do { _Pragma("unroll") for (int n = 0; n < 2; ++n) _Pragma("unroll") for (int k = 0; k < 2; ++k) dst[n][k] = *(const PG8_LAS bf16x8*)(lds + PG8_SB(b, h) + boff + n * 2048 + k * 1024); } while (0)
; #define PG8_MMA(ai, bj, At, Bt) do { __builtin_amdgcn_s_setprio(1); _Pragma("unroll") for (int m = 0; m < 4; ++m) _Pragma("unroll") for (int n = 0; n < 2; ++n) _Pragma("unroll") for (int k = 0; k < 2; ++k) \
;         acc[ai][bj][m][n] = __builtin_amdgcn_mfma_f32_16x16x32_bf16(Bt[n][k], At[m][k], acc[ai][bj][m][n], 0, 0, 0); __builtin_amdgcn_s_setprio(0); } while (0)
; #define PG8_WAIT_V(n) asm volatile("s_waitcnt vmcnt(" #n ")" ::: "memory")
; #define PG8_WAIT_L(n) asm volatile("s_waitcnt lgkmcnt(" #n ")" ::: "memory")
; #define PG8_BAR __builtin_amdgcn_s_barrier()
; #define PG8_SCHED __builtin_amdgcn_sched_barrier(0)
;     ...
;             PG8_WAIT_V(8); PG8_WAIT_L(0); PG8_BAR; PG8_MMA(1, 0, At, B0); PG8_MMA(1, 1, At, B1); PG8_BAR; PG8_SCHED;
;             PG8_LDB(B0, 1, 0); PG8_LDB(B1, 1, 1); PG8_SCHED; PG8_LDA(At, 1, 0); PG8_STAGE(PG8_SA(0, 1), a2 + hstep, voffA);
;             PG8_WAIT_V(8); PG8_WAIT_L(0); PG8_BAR; PG8_MMA(0, 0, At, B0); PG8_MMA(0, 1, At, B1); PG8_BAR; PG8_SCHED;
	v_mfma_f32_16x16x32_bf16 v[64:67], v[132:135], v[180:183], v[64:67]
	v_mfma_f32_16x16x32_bf16 v[60:63], v[150:153], v[180:183], v[60:63]
	v_mfma_f32_16x16x32_bf16 v[52:55], v[132:135], v[188:191], v[52:55]
	v_mfma_f32_16x16x32_bf16 v[44:47], v[150:153], v[188:191], v[44:47]
	v_mfma_f32_16x16x32_bf16 v[36:39], v[132:135], v[196:199], v[36:39]
	v_mfma_f32_16x16x32_bf16 v[28:31], v[150:153], v[196:199], v[28:31]
	v_mfma_f32_16x16x32_bf16 v[20:23], v[132:135], v[214:217], v[20:23]
	v_mfma_f32_16x16x32_bf16 v[12:15], v[150:153], v[214:217], v[12:15]
	v_mfma_f32_16x16x32_bf16 v[64:67], v[146:149], v[184:187], v[64:67]
	v_mfma_f32_16x16x32_bf16 v[60:63], v[154:157], v[184:187], v[60:63]
	v_mfma_f32_16x16x32_bf16 v[52:55], v[146:149], v[192:195], v[52:55]
	v_mfma_f32_16x16x32_bf16 v[44:47], v[154:157], v[192:195], v[44:47]
	v_mfma_f32_16x16x32_bf16 v[36:39], v[146:149], v[210:213], v[36:39]
	v_mfma_f32_16x16x32_bf16 v[28:31], v[154:157], v[210:213], v[28:31]
	v_mfma_f32_16x16x32_bf16 v[20:23], v[146:149], v[218:221], v[20:23]
	v_mfma_f32_16x16x32_bf16 v[12:15], v[154:157], v[218:221], v[12:15]
	s_setprio 0
	s_setprio 1
	v_mfma_f32_16x16x32_bf16 v[56:59], v[158:161], v[180:183], v[56:59]
	v_mfma_f32_16x16x32_bf16 v[48:51], v[166:169], v[180:183], v[48:51]
	v_mfma_f32_16x16x32_bf16 v[40:43], v[158:161], v[188:191], v[40:43]
	v_mfma_f32_16x16x32_bf16 v[32:35], v[166:169], v[188:191], v[32:35]
	v_mfma_f32_16x16x32_bf16 v[24:27], v[158:161], v[196:199], v[24:27]
	v_mfma_f32_16x16x32_bf16 v[16:19], v[166:169], v[196:199], v[16:19]
	v_mfma_f32_16x16x32_bf16 v[8:11], v[158:161], v[214:217], v[8:11]
	v_mfma_f32_16x16x32_bf16 v[4:7], v[166:169], v[214:217], v[4:7]
	v_mfma_f32_16x16x32_bf16 v[56:59], v[162:165], v[184:187], v[56:59]
	v_mfma_f32_16x16x32_bf16 v[48:51], v[176:179], v[184:187], v[48:51]
	v_mfma_f32_16x16x32_bf16 v[40:43], v[162:165], v[192:195], v[40:43]
	v_mfma_f32_16x16x32_bf16 v[32:35], v[176:179], v[192:195], v[32:35]
	v_mfma_f32_16x16x32_bf16 v[24:27], v[162:165], v[210:213], v[24:27]
	v_mfma_f32_16x16x32_bf16 v[16:19], v[176:179], v[210:213], v[16:19]
	v_mfma_f32_16x16x32_bf16 v[8:11], v[162:165], v[218:221], v[8:11]
	v_mfma_f32_16x16x32_bf16 v[4:7], v[176:179], v[218:221], v[4:7]
	s_barrier
	s_setprio 0
	ds_read_b128 v[132:135], v251 offset:32768
	ds_read_b128 v[146:149], v251 offset:33792
	ds_read_b128 v[150:153], v251 offset:34816
	ds_read_b128 v[154:157], v251 offset:35840
	ds_read_b128 v[158:161], v251 offset:49152
	ds_read_b128 v[162:165], v251 offset:50176
	ds_read_b128 v[166:169], v251 offset:51200
	ds_read_b128 v[176:179], v251 offset:52224
	ds_read_b128 v[180:183], v174 offset:32768
	ds_read_b128 v[184:187], v174 offset:33792
	ds_read_b128 v[188:191], v174 offset:34816
	ds_read_b128 v[192:195], v174 offset:35840
	ds_read_b128 v[196:199], v174 offset:36864
	ds_read_b128 v[210:213], v174 offset:37888
	ds_read_b128 v[214:217], v174 offset:38912
	ds_read_b128 v[218:221], v174 offset:39936
	s_add_i32 s48, 0, 0x18000
	s_add_i32 s49, 0, 0x1c000
	s_add_u32 s50, s50, 0x20000
	s_addc_u32 s51, s51, 0
	s_mov_b32 m0, s68
	v_lshl_add_u64 v[224:225], s[50:51], 0, v[140:141]
	global_load_lds_dwordx4 v[224:225], off
	v_lshl_add_u64 v[224:225], s[50:51], 0, v[138:139]
	s_mov_b32 m0, s69
	s_nop 0
	global_load_lds_dwordx4 v[224:225], off
	s_waitcnt vmcnt(8)
	s_waitcnt lgkmcnt(0)
	s_setprio 1
	s_barrier
	v_mfma_f32_16x16x32_bf16 v[128:131], v[132:135], v[180:183], v[128:131]
	v_mfma_f32_16x16x32_bf16 v[124:127], v[150:153], v[180:183], v[124:127]
	v_mfma_f32_16x16x32_bf16 v[116:119], v[132:135], v[188:191], v[116:119]
	v_mfma_f32_16x16x32_bf16 v[108:111], v[150:153], v[188:191], v[108:111]
	v_mfma_f32_16x16x32_bf16 v[100:103], v[132:135], v[196:199], v[100:103]
	v_mfma_f32_16x16x32_bf16 v[92:95], v[150:153], v[196:199], v[92:95]
	v_mfma_f32_16x16x32_bf16 v[84:87], v[132:135], v[214:217], v[84:87]
	v_mfma_f32_16x16x32_bf16 v[76:79], v[150:153], v[214:217], v[76:79]
	v_mfma_f32_16x16x32_bf16 v[128:131], v[146:149], v[184:187], v[128:131]
	v_mfma_f32_16x16x32_bf16 v[124:127], v[154:157], v[184:187], v[124:127]
	v_mfma_f32_16x16x32_bf16 v[116:119], v[146:149], v[192:195], v[116:119]
	v_mfma_f32_16x16x32_bf16 v[108:111], v[154:157], v[192:195], v[108:111]
	v_mfma_f32_16x16x32_bf16 v[100:103], v[146:149], v[210:213], v[100:103]
	v_mfma_f32_16x16x32_bf16 v[92:95], v[154:157], v[210:213], v[92:95]
	v_mfma_f32_16x16x32_bf16 v[84:87], v[146:149], v[218:221], v[84:87]
	v_mfma_f32_16x16x32_bf16 v[76:79], v[154:157], v[218:221], v[76:79]
	s_setprio 0
	s_setprio 1
	v_mfma_f32_16x16x32_bf16 v[120:123], v[158:161], v[180:183], v[120:123]
	v_mfma_f32_16x16x32_bf16 v[112:115], v[166:169], v[180:183], v[112:115]
	v_mfma_f32_16x16x32_bf16 v[104:107], v[158:161], v[188:191], v[104:107]
	v_mfma_f32_16x16x32_bf16 v[96:99], v[166:169], v[188:191], v[96:99]
	v_mfma_f32_16x16x32_bf16 v[88:91], v[158:161], v[196:199], v[88:91]
	v_mfma_f32_16x16x32_bf16 v[80:83], v[166:169], v[196:199], v[80:83]
	v_mfma_f32_16x16x32_bf16 v[72:75], v[158:161], v[214:217], v[72:75]
	v_mfma_f32_16x16x32_bf16 v[68:71], v[166:169], v[214:217], v[68:71]
	v_mfma_f32_16x16x32_bf16 v[120:123], v[162:165], v[184:187], v[120:123]
	v_mfma_f32_16x16x32_bf16 v[112:115], v[176:179], v[184:187], v[112:115]
	v_mfma_f32_16x16x32_bf16 v[104:107], v[162:165], v[192:195], v[104:107]
	v_mfma_f32_16x16x32_bf16 v[96:99], v[176:179], v[192:195], v[96:99]
	v_mfma_f32_16x16x32_bf16 v[88:91], v[162:165], v[210:213], v[88:91]
	v_mfma_f32_16x16x32_bf16 v[80:83], v[176:179], v[210:213], v[80:83]
	v_mfma_f32_16x16x32_bf16 v[72:75], v[162:165], v[218:221], v[72:75]
	v_mfma_f32_16x16x32_bf16 v[68:71], v[176:179], v[218:221], v[68:71]
	s_barrier
; #define PG8_STAGE(bufoff, gbase, voff) do { _Pragma("unroll") for (int _i = 0; _i < 2; ++_i) \
;         __builtin_amdgcn_global_load_lds((const unsigned*)((const char*)(gbase) + (voff)[_i]), (PG8_LAS unsigned*)(lds + (bufoff) + ldsw + _i * 8192), 16, 0, 0); } while (0)
; #define PG8_LDA(dst, b, h) do { _Pragma("unroll") for (int m = 0; m < 4; ++m) _Pragma("unroll") for (int k = 0; k < 2; ++k) dst[m][k] = *(const PG8_LAS bf16x8*)(lds + PG8_SA(b, h) + aoff + m * 2048 + k * 1024); } while (0)
; #define PG8_MMA(ai, bj, At, Bt) do { __builtin_amdgcn_s_setprio(1); _Pragma("unroll") for (int m = 0; m < 4; ++m) _Pragma("unroll") for (int n = 0; n < 2; ++n) _Pragma("unroll") for (int k = 0; k < 2; ++k) \
;         acc[ai][bj][m][n] = __builtin_amdgcn_mfma_f32_16x16x32_bf16(Bt[n][k], At[m][k], acc[ai][bj][m][n], 0, 0, 0); __builtin_amdgcn_s_setprio(0); } while (0)
; #define PG8_WAIT_V(n) asm volatile("s_waitcnt vmcnt(" #n ")" ::: "memory")
; #define PG8_WAIT_L(n) asm volatile("s_waitcnt lgkmcnt(" #n ")" ::: "memory")
; #define PG8_BAR __builtin_amdgcn_s_barrier()
; #define PG8_SCHED __builtin_amdgcn_sched_barrier(0)
;     __device__ __forceinline__ void operator()(const f32x4 (&acc)[2][2][4][2], const Unit& u, int wr, int wc, int fr_, int fq_, int ui) const {
;     ...
;         const int row0 = u.pm * BM + wr * 64 + fr;
;         float r[2][4]; load_rs(r, rsl, wr, fr);
;         if (u.pn < 8) {
;     ...
;             PG8_LDA(At, 1, 1); PG8_STAGE(PG8_SB(1, 0), b3, voffB); PG8_STAGE(PG8_SB(1, 1), b3 + hstep, voffB); PG8_STAGE(PG8_SA(1, 0), a3, voffA);
;             PG8_WAIT_V(8); PG8_WAIT_L(0); PG8_BAR; PG8_MMA(1, 0, At, B0); PG8_MMA(1, 1, At, B1); PG8_BAR; PG8_SCHED;
	s_setprio 0
	ds_read_b128 v[180:183], v174 offset:49152
	ds_read_b128 v[184:187], v174 offset:50176
	ds_read_b128 v[188:191], v174 offset:51200
	ds_read_b128 v[192:195], v174 offset:52224
	ds_read_b128 v[196:199], v174 offset:53248
	ds_read_b128 v[210:213], v174 offset:54272
	ds_read_b128 v[214:217], v174 offset:55296
	ds_read_b128 v[218:221], v174 offset:56320
	s_add_i32 s48, s48, s61
	v_lshl_add_u64 v[170:171], v[170:171], 0, s[66:67]
	s_mov_b32 m0, s48
	s_nop 0
	global_load_lds_dwordx4 v[170:171], off
	s_add_i32 m0, s48, 0x2000
	s_add_u32 s24, s24, 0x20080
	v_lshl_add_u64 v[170:171], v[206:207], 0, s[66:67]
	s_addc_u32 s25, s25, 0
	s_add_i32 s48, s49, s61
	global_load_lds_dwordx4 v[170:171], off
	v_lshl_add_u64 v[170:171], s[24:25], 0, v[200:201]
	s_mov_b32 m0, s48
	s_nop 0
	global_load_lds_dwordx4 v[170:171], off
	v_lshl_add_u64 v[170:171], s[24:25], 0, v[136:137]
	s_add_i32 m0, s48, 0x2000
	s_nop 0
	global_load_lds_dwordx4 v[170:171], off
	v_lshl_add_u64 v[170:171], v[208:209], 0, s[66:67]
	s_mov_b32 m0, s71
	s_nop 0
	global_load_lds_dwordx4 v[170:171], off
	v_lshl_add_u64 v[170:171], v[222:223], 0, s[66:67]
	s_mov_b32 m0, s73
	s_nop 0
	global_load_lds_dwordx4 v[170:171], off
	s_waitcnt vmcnt(8)
	s_waitcnt lgkmcnt(0)
	s_setprio 1
	s_barrier
	v_mfma_f32_16x16x32_bf16 v[64:67], v[132:135], v[180:183], v[64:67]
	v_mfma_f32_16x16x32_bf16 v[60:63], v[150:153], v[180:183], v[60:63]
	v_mfma_f32_16x16x32_bf16 v[52:55], v[132:135], v[188:191], v[52:55]
	v_mfma_f32_16x16x32_bf16 v[44:47], v[150:153], v[188:191], v[44:47]
	v_mfma_f32_16x16x32_bf16 v[36:39], v[132:135], v[196:199], v[36:39]
	v_mfma_f32_16x16x32_bf16 v[28:31], v[150:153], v[196:199], v[28:31]
	v_mfma_f32_16x16x32_bf16 v[20:23], v[132:135], v[214:217], v[20:23]
	v_mfma_f32_16x16x32_bf16 v[12:15], v[150:153], v[214:217], v[12:15]
	v_mfma_f32_16x16x32_bf16 v[64:67], v[146:149], v[184:187], v[64:67]
	v_mfma_f32_16x16x32_bf16 v[60:63], v[154:157], v[184:187], v[60:63]
	v_mfma_f32_16x16x32_bf16 v[52:55], v[146:149], v[192:195], v[52:55]
	v_mfma_f32_16x16x32_bf16 v[44:47], v[154:157], v[192:195], v[44:47]
	v_mfma_f32_16x16x32_bf16 v[36:39], v[146:149], v[210:213], v[36:39]
	v_mfma_f32_16x16x32_bf16 v[28:31], v[154:157], v[210:213], v[28:31]
	v_mfma_f32_16x16x32_bf16 v[20:23], v[146:149], v[218:221], v[20:23]
	v_mfma_f32_16x16x32_bf16 v[12:15], v[154:157], v[218:221], v[12:15]
	s_setprio 0
	s_setprio 1
	v_mfma_f32_16x16x32_bf16 v[56:59], v[158:161], v[180:183], v[56:59]
	v_mfma_f32_16x16x32_bf16 v[48:51], v[166:169], v[180:183], v[48:51]
	v_mfma_f32_16x16x32_bf16 v[40:43], v[158:161], v[188:191], v[40:43]
	v_mfma_f32_16x16x32_bf16 v[32:35], v[166:169], v[188:191], v[32:35]
	v_mfma_f32_16x16x32_bf16 v[24:27], v[158:161], v[196:199], v[24:27]
	v_mfma_f32_16x16x32_bf16 v[16:19], v[166:169], v[196:199], v[16:19]
	v_mfma_f32_16x16x32_bf16 v[8:11], v[158:161], v[214:217], v[8:11]
	v_mfma_f32_16x16x32_bf16 v[4:7], v[166:169], v[214:217], v[4:7]
	v_mfma_f32_16x16x32_bf16 v[56:59], v[162:165], v[184:187], v[56:59]
	v_mfma_f32_16x16x32_bf16 v[48:51], v[176:179], v[184:187], v[48:51]
	v_mfma_f32_16x16x32_bf16 v[40:43], v[162:165], v[192:195], v[40:43]
	v_mfma_f32_16x16x32_bf16 v[32:35], v[176:179], v[192:195], v[32:35]
	v_mfma_f32_16x16x32_bf16 v[24:27], v[162:165], v[210:213], v[24:27]
	v_mfma_f32_16x16x32_bf16 v[16:19], v[176:179], v[210:213], v[16:19]
	v_mfma_f32_16x16x32_bf16 v[8:11], v[162:165], v[218:221], v[8:11]
	v_mfma_f32_16x16x32_bf16 v[4:7], v[176:179], v[218:221], v[4:7]
	s_barrier
	s_setprio 0
	s_add_i32 s54, s54, 2
	s_add_u32 s52, s52, 0x100
	s_addc_u32 s53, s53, 0
	s_add_u32 s14, s14, 0x100
	s_addc_u32 s15, s15, 0
	s_cmp_gt_u32 s54, 5
	s_cbranch_scc0 .LBB0_301
	v_mov_b32_e32 v132, v3
	v_mov_b32_e32 v133, v172
	v_readlane_b32 s14, v254, 30
	v_add_u32_e32 v146, s1, v132
	v_lshl_add_u32 v132, v132, 2, s78
	ds_read2_b32 v[164:165], v132 offset1:16
	ds_read2_b32 v[158:159], v132 offset0:32 offset1:48
	ds_read2_b32 v[152:153], v132 offset0:128 offset1:144
	ds_read2_b32 v[148:149], v132 offset0:160 offset1:176
	s_add_i32 s14, s20, s14
	s_lshl_b32 s20, s14, 8
	s_cmp_gt_u32 s14, 7
	v_lshlrev_b32_e32 v168, 3, v133
	v_ashrrev_i32_e32 v147, 31, v146
	s_mov_b64 s[14:15], -1
	v_add_u32_e32 v166, 16, v146
	v_add_u32_e32 v162, 32, v146
	v_add_u32_e32 v160, 48, v146
	v_add_u32_e32 v156, 0x80, v146
	v_add_u32_e32 v154, 0x90, v146
	v_add_u32_e32 v150, 0xa0, v146
	s_cbranch_scc0 .LBB0_304
; #define PG8_G __attribute__((address_space(1)))
; __device__ __forceinline__ u32x4 pack8bf(const f32x4 a, const f32x4 b) { u32x4 w; w.x = cvt_pk_bf16(a[0], a[1]); w.y = cvt_pk_bf16(a[2], a[3]); w.z = cvt_pk_bf16(b[0], b[1]); w.w = cvt_pk_bf16(b[2], b[3]); return w; }
;     __device__ __forceinline__ void operator()(const f32x4 (&acc)[2][2][4][2], const Unit& u, int wr, int wc, int fr_, int fq_, int ui) const {
;     ...
;                 for (int m = 0; m < 4; ++m) { const int row = row0 + ai * HALF + m * 16;
;                     const f32x4 c0 = *(const PG8_G f32x4*)(cosT + (size_t)row * 32 + i0), c1 = *(const PG8_G f32x4*)(cosT + (size_t)row * 32 + i0 + 4);
;                     const f32x4 s0 = *(const PG8_G f32x4*)(sinT + (size_t)row * 32 + i0), s1 = *(const PG8_G f32x4*)(sinT + (size_t)row * 32 + i0 + 4);
;                     const f32x4 x1a = acc[ai][0][m][0] * r[ai][m], x1b = acc[ai][0][m][1] * r[ai][m], x2a = acc[ai][1][m][0] * r[ai][m], x2b = acc[ai][1][m][1] * r[ai][m];
;                     const f32x4 y1a = x1a * c0 - x2a * s0, y1b = x1b * c1 - x2b * s1, y2a = x2a * c0 + x1a * s0, y2b = x2b * c1 + x1b * s1;
;                     bf16_t* dst = Q + (size_t)row * 3072 + 2048 + head * 64 + i0;
;                     *(PG8_G u32x4*)dst = pack8bf(y1a, y1b); *(PG8_G u32x4*)(dst + 32) = pack8bf(y2a, y2b); }
	v_ashrrev_i32_e32 v169, 31, v168
	v_lshlrev_b64 v[180:181], 7, v[146:147]
	v_lshl_add_u64 v[132:133], s[38:39], 0, v[180:181]
	v_lshlrev_b64 v[170:171], 2, v[168:169]
	v_lshl_add_u64 v[180:181], s[40:41], 0, v[180:181]
	v_lshl_add_u64 v[176:177], v[132:133], 0, v[170:171]
	v_lshl_add_u64 v[184:185], v[180:181], 0, v[170:171]
	global_load_dwordx4 v[132:135], v[176:177], off offset:16
	s_nop 0
	global_load_dwordx4 v[176:179], v[176:177], off
	s_nop 0
	global_load_dwordx4 v[180:183], v[184:185], off offset:16
	s_nop 0
	global_load_dwordx4 v[184:187], v[184:185], off
	s_waitcnt lgkmcnt(0)
	v_pk_mul_f32 v[188:189], v[130:131], v[164:165] op_sel_hi:[1,0]
	v_pk_mul_f32 v[196:197], v[122:123], v[164:165] op_sel_hi:[1,0]
	v_pk_mul_f32 v[190:191], v[128:129], v[164:165] op_sel_hi:[1,0]
	v_pk_mul_f32 v[194:195], v[124:125], v[164:165] op_sel_hi:[1,0]
	v_pk_mul_f32 v[198:199], v[120:121], v[164:165] op_sel_hi:[1,0]
	v_pk_mul_f32 v[208:209], v[112:113], v[164:165] op_sel_hi:[1,0]
	v_pk_mul_f32 v[192:193], v[126:127], v[164:165] op_sel_hi:[1,0]
	v_pk_mul_f32 v[206:207], v[114:115], v[164:165] op_sel_hi:[1,0]
	s_add_i32 s44, s0, s20
	s_mov_b64 s[48:49], 0x1000
	v_ashrrev_i32_e32 v167, 31, v166
	v_ashrrev_i32_e32 v163, 31, v162
	v_ashrrev_i32_e32 v161, 31, v160
	v_ashrrev_i32_e32 v157, 31, v156
	v_ashrrev_i32_e32 v155, 31, v154
	v_ashrrev_i32_e32 v151, 31, v150
	s_waitcnt vmcnt(0)
	v_pk_mul_f32 v[216:217], v[208:209], v[180:181]
	v_pk_mul_f32 v[210:211], v[196:197], v[186:187]
	v_pk_mul_f32 v[186:187], v[188:189], v[186:187]
	v_pk_mul_f32 v[212:213], v[198:199], v[184:185]
	v_pk_fma_f32 v[210:211], v[188:189], v[178:179], v[210:211] neg_lo:[0,0,1] neg_hi:[0,0,1]
	v_pk_mul_f32 v[184:185], v[190:191], v[184:185]
	v_pk_fma_f32 v[186:187], v[196:197], v[178:179], v[186:187]
	v_pk_mul_f32 v[178:179], v[194:195], v[180:181]
	v_pk_fma_f32 v[212:213], v[190:191], v[176:177], v[212:213] neg_lo:[0,0,1] neg_hi:[0,0,1]
	v_pk_mul_f32 v[214:215], v[206:207], v[182:183]
	v_pk_fma_f32 v[216:217], v[194:195], v[132:133], v[216:217] neg_lo:[0,0,1] neg_hi:[0,0,1]
	v_pk_fma_f32 v[184:185], v[198:199], v[176:177], v[184:185]
	v_pk_mul_f32 v[176:177], v[192:193], v[182:183]
	v_pk_fma_f32 v[182:183], v[208:209], v[132:133], v[178:179]
	v_mov_b64_e32 v[132:133], s[10:11]
	v_pk_fma_f32 v[214:215], v[192:193], v[134:135], v[214:215] neg_lo:[0,0,1] neg_hi:[0,0,1]
	v_pk_fma_f32 v[180:181], v[206:207], v[134:135], v[176:177]
	v_mad_i64_i32 v[134:135], s[14:15], v146, s26, v[132:133]
	s_lshl_b64 s[14:15], s[44:45], 1
	s_nop 0
	v_lshl_add_u64 v[176:177], v[134:135], 0, s[14:15]
	v_lshlrev_b64 v[134:135], 1, v[168:169]
	v_lshl_add_u64 v[188:189], v[176:177], 0, v[134:135]
	v_lshl_add_u64 v[190:191], v[188:189], 0, s[48:49]
	v_add_co_u32_e32 v188, vcc, s27, v188
	v_cvt_pk_bf16_f32 v176, v212, v213
	v_cvt_pk_bf16_f32 v177, v210, v211
	v_cvt_pk_bf16_f32 v178, v216, v217
	v_cvt_pk_bf16_f32 v179, v214, v215
	s_nop 1
	v_addc_co_u32_e32 v189, vcc, 0, v189, vcc
	global_store_dwordx4 v[188:189], v[176:179], off
	v_mov_b32_e32 v192, v165
	v_pk_mul_f32 v[194:195], v[118:119], v[192:193] op_sel_hi:[1,0]
	v_cvt_pk_bf16_f32 v176, v184, v185
	v_cvt_pk_bf16_f32 v177, v186, v187
	v_lshlrev_b64 v[184:185], 7, v[166:167]
	v_cvt_pk_bf16_f32 v178, v182, v183
	v_cvt_pk_bf16_f32 v179, v180, v181
	global_store_dwordx4 v[190:191], v[176:179], off offset:64
	v_pk_mul_f32 v[196:197], v[116:117], v[192:193] op_sel_hi:[1,0]
	v_pk_mul_f32 v[198:199], v[110:111], v[192:193] op_sel_hi:[1,0]
	v_lshl_add_u64 v[176:177], s[38:39], 0, v[184:185]
	v_lshl_add_u64 v[184:185], s[40:41], 0, v[184:185]
	v_lshl_add_u64 v[180:181], v[176:177], 0, v[170:171]
	v_lshl_add_u64 v[188:189], v[184:185], 0, v[170:171]
	global_load_dwordx4 v[176:179], v[180:181], off offset:16
	s_nop 0
	global_load_dwordx4 v[180:183], v[180:181], off
	s_nop 0
	global_load_dwordx4 v[184:187], v[188:189], off offset:16
	s_nop 0
	global_load_dwordx4 v[188:191], v[188:189], off
	v_pk_mul_f32 v[206:207], v[108:109], v[192:193] op_sel_hi:[1,0]
	v_pk_mul_f32 v[208:209], v[106:107], v[192:193] op_sel_hi:[1,0]
	v_pk_mul_f32 v[210:211], v[104:105], v[192:193] op_sel_hi:[1,0]
	v_pk_mul_f32 v[212:213], v[98:99], v[192:193] op_sel_hi:[1,0]
	v_pk_mul_f32 v[192:193], v[96:97], v[192:193] op_sel_hi:[1,0]
	s_waitcnt vmcnt(1)
	v_pk_mul_f32 v[218:219], v[212:213], v[186:187]
	v_pk_mul_f32 v[220:221], v[192:193], v[184:185]
	v_pk_mul_f32 v[184:185], v[206:207], v[184:185]
	v_pk_fma_f32 v[220:221], v[206:207], v[176:177], v[220:221] neg_lo:[0,0,1] neg_hi:[0,0,1]
	v_pk_fma_f32 v[184:185], v[192:193], v[176:177], v[184:185]
	v_mad_i64_i32 v[176:177], s[24:25], v166, s26, v[132:133]
	s_waitcnt vmcnt(0)
; #define PG8_G __attribute__((address_space(1)))
; __device__ __forceinline__ u32x4 pack8bf(const f32x4 a, const f32x4 b) { u32x4 w; w.x = cvt_pk_bf16(a[0], a[1]); w.y = cvt_pk_bf16(a[2], a[3]); w.z = cvt_pk_bf16(b[0], b[1]); w.w = cvt_pk_bf16(b[2], b[3]); return w; }
;     __device__ __forceinline__ void operator()(const f32x4 (&acc)[2][2][4][2], const Unit& u, int wr, int wc, int fr_, int fq_, int ui) const {
;     ...
;                 for (int m = 0; m < 4; ++m) { const int row = row0 + ai * HALF + m * 16;
;                     const f32x4 c0 = *(const PG8_G f32x4*)(cosT + (size_t)row * 32 + i0), c1 = *(const PG8_G f32x4*)(cosT + (size_t)row * 32 + i0 + 4);
;                     const f32x4 s0 = *(const PG8_G f32x4*)(sinT + (size_t)row * 32 + i0), s1 = *(const PG8_G f32x4*)(sinT + (size_t)row * 32 + i0 + 4);
;                     const f32x4 x1a = acc[ai][0][m][0] * r[ai][m], x1b = acc[ai][0][m][1] * r[ai][m], x2a = acc[ai][1][m][0] * r[ai][m], x2b = acc[ai][1][m][1] * r[ai][m];
;                     const f32x4 y1a = x1a * c0 - x2a * s0, y1b = x1b * c1 - x2b * s1, y2a = x2a * c0 + x1a * s0, y2b = x2b * c1 + x1b * s1;
;                     bf16_t* dst = Q + (size_t)row * 3072 + 2048 + head * 64 + i0;
;                     *(PG8_G u32x4*)dst = pack8bf(y1a, y1b); *(PG8_G u32x4*)(dst + 32) = pack8bf(y2a, y2b); }
	v_pk_mul_f32 v[216:217], v[210:211], v[188:189]
	v_pk_mul_f32 v[188:189], v[196:197], v[188:189]
	v_lshl_add_u64 v[176:177], v[176:177], 0, s[14:15]
	v_pk_mul_f32 v[214:215], v[208:209], v[190:191]
	v_pk_fma_f32 v[216:217], v[196:197], v[180:181], v[216:217] neg_lo:[0,0,1] neg_hi:[0,0,1]
	v_pk_mul_f32 v[190:191], v[194:195], v[190:191]
	v_pk_fma_f32 v[180:181], v[210:211], v[180:181], v[188:189]
	v_lshl_add_u64 v[188:189], v[176:177], 0, v[134:135]
	v_pk_fma_f32 v[214:215], v[194:195], v[182:183], v[214:215] neg_lo:[0,0,1] neg_hi:[0,0,1]
	v_pk_fma_f32 v[182:183], v[208:209], v[182:183], v[190:191]
	v_pk_mul_f32 v[186:187], v[198:199], v[186:187]
	v_lshl_add_u64 v[190:191], v[188:189], 0, s[48:49]
	v_add_co_u32_e32 v188, vcc, s27, v188
	v_pk_fma_f32 v[218:219], v[198:199], v[178:179], v[218:219] neg_lo:[0,0,1] neg_hi:[0,0,1]
	v_pk_fma_f32 v[186:187], v[212:213], v[178:179], v[186:187]
	v_cvt_pk_bf16_f32 v176, v216, v217
	v_cvt_pk_bf16_f32 v177, v214, v215
	v_cvt_pk_bf16_f32 v178, v220, v221
	v_addc_co_u32_e32 v189, vcc, 0, v189, vcc
	v_cvt_pk_bf16_f32 v179, v218, v219
	global_store_dwordx4 v[188:189], v[176:179], off
	v_pk_mul_f32 v[198:199], v[92:93], v[158:159] op_sel_hi:[1,0]
	v_pk_mul_f32 v[212:213], v[80:81], v[158:159] op_sel_hi:[1,0]
	v_cvt_pk_bf16_f32 v176, v180, v181
	v_cvt_pk_bf16_f32 v177, v182, v183
	v_cvt_pk_bf16_f32 v178, v184, v185
	v_lshlrev_b64 v[184:185], 7, v[162:163]
	v_cvt_pk_bf16_f32 v179, v186, v187
	global_store_dwordx4 v[190:191], v[176:179], off offset:64
	v_pk_mul_f32 v[194:195], v[100:101], v[158:159] op_sel_hi:[1,0]
	v_pk_mul_f32 v[208:209], v[88:89], v[158:159] op_sel_hi:[1,0]
	v_lshl_add_u64 v[176:177], s[38:39], 0, v[184:185]
	v_lshl_add_u64 v[184:185], s[40:41], 0, v[184:185]
	v_lshl_add_u64 v[180:181], v[176:177], 0, v[170:171]
	v_lshl_add_u64 v[188:189], v[184:185], 0, v[170:171]
	global_load_dwordx4 v[176:179], v[180:181], off offset:16
	s_nop 0
	global_load_dwordx4 v[180:183], v[180:181], off
	s_nop 0
	global_load_dwordx4 v[184:187], v[188:189], off offset:16
	s_nop 0
	global_load_dwordx4 v[188:191], v[188:189], off
	v_pk_mul_f32 v[192:193], v[102:103], v[158:159] op_sel_hi:[1,0]
	v_pk_mul_f32 v[206:207], v[90:91], v[158:159] op_sel_hi:[1,0]
	v_pk_mul_f32 v[196:197], v[94:95], v[158:159] op_sel_hi:[1,0]
	v_pk_mul_f32 v[210:211], v[82:83], v[158:159] op_sel_hi:[1,0]
	s_waitcnt vmcnt(1)
	v_pk_mul_f32 v[220:221], v[212:213], v[184:185]
	v_pk_mul_f32 v[184:185], v[198:199], v[184:185]
	v_pk_fma_f32 v[220:221], v[198:199], v[176:177], v[220:221] neg_lo:[0,0,1] neg_hi:[0,0,1]
	v_pk_fma_f32 v[184:185], v[212:213], v[176:177], v[184:185]
	v_mad_i64_i32 v[176:177], s[24:25], v162, s26, v[132:133]
	s_waitcnt vmcnt(0)
	v_pk_mul_f32 v[216:217], v[208:209], v[188:189]
	v_pk_mul_f32 v[188:189], v[194:195], v[188:189]
	v_lshl_add_u64 v[176:177], v[176:177], 0, s[14:15]
	v_pk_mul_f32 v[214:215], v[206:207], v[190:191]
	v_pk_fma_f32 v[216:217], v[194:195], v[180:181], v[216:217] neg_lo:[0,0,1] neg_hi:[0,0,1]
	v_pk_mul_f32 v[190:191], v[192:193], v[190:191]
	v_pk_fma_f32 v[180:181], v[208:209], v[180:181], v[188:189]
	v_lshl_add_u64 v[188:189], v[176:177], 0, v[134:135]
	v_pk_fma_f32 v[214:215], v[192:193], v[182:183], v[214:215] neg_lo:[0,0,1] neg_hi:[0,0,1]
	v_pk_mul_f32 v[218:219], v[210:211], v[186:187]
	v_pk_fma_f32 v[182:183], v[206:207], v[182:183], v[190:191]
	v_pk_mul_f32 v[186:187], v[196:197], v[186:187]
	v_lshl_add_u64 v[190:191], v[188:189], 0, s[48:49]
	v_add_co_u32_e32 v188, vcc, s27, v188
	v_pk_fma_f32 v[218:219], v[196:197], v[178:179], v[218:219] neg_lo:[0,0,1] neg_hi:[0,0,1]
	v_pk_fma_f32 v[186:187], v[210:211], v[178:179], v[186:187]
	v_cvt_pk_bf16_f32 v176, v216, v217
	v_cvt_pk_bf16_f32 v177, v214, v215
	v_cvt_pk_bf16_f32 v178, v220, v221
	v_addc_co_u32_e32 v189, vcc, 0, v189, vcc
	v_cvt_pk_bf16_f32 v179, v218, v219
	global_store_dwordx4 v[188:189], v[176:179], off
	v_mov_b32_e32 v192, v159
	v_pk_mul_f32 v[194:195], v[86:87], v[192:193] op_sel_hi:[1,0]
	v_cvt_pk_bf16_f32 v176, v180, v181
	v_cvt_pk_bf16_f32 v177, v182, v183
	v_cvt_pk_bf16_f32 v178, v184, v185
	v_lshlrev_b64 v[184:185], 7, v[160:161]
	v_cvt_pk_bf16_f32 v179, v186, v187
	global_store_dwordx4 v[190:191], v[176:179], off offset:64
	v_pk_mul_f32 v[196:197], v[84:85], v[192:193] op_sel_hi:[1,0]
	v_pk_mul_f32 v[198:199], v[78:79], v[192:193] op_sel_hi:[1,0]
	v_lshl_add_u64 v[176:177], s[38:39], 0, v[184:185]
	v_lshl_add_u64 v[184:185], s[40:41], 0, v[184:185]
	v_lshl_add_u64 v[180:181], v[176:177], 0, v[170:171]
	v_lshl_add_u64 v[188:189], v[184:185], 0, v[170:171]
	global_load_dwordx4 v[176:179], v[180:181], off offset:16
	s_nop 0
	global_load_dwordx4 v[180:183], v[180:181], off
	s_nop 0
	global_load_dwordx4 v[184:187], v[188:189], off offset:16
	s_nop 0
	global_load_dwordx4 v[188:191], v[188:189], off
	v_pk_mul_f32 v[206:207], v[76:77], v[192:193] op_sel_hi:[1,0]
	v_pk_mul_f32 v[208:209], v[74:75], v[192:193] op_sel_hi:[1,0]
	v_pk_mul_f32 v[210:211], v[72:73], v[192:193] op_sel_hi:[1,0]
	v_pk_mul_f32 v[212:213], v[70:71], v[192:193] op_sel_hi:[1,0]
	v_pk_mul_f32 v[192:193], v[68:69], v[192:193] op_sel_hi:[1,0]
	s_waitcnt vmcnt(1)
	v_pk_mul_f32 v[218:219], v[212:213], v[186:187]
	v_pk_mul_f32 v[220:221], v[192:193], v[184:185]
	v_pk_mul_f32 v[184:185], v[206:207], v[184:185]
	v_pk_fma_f32 v[220:221], v[206:207], v[176:177], v[220:221] neg_lo:[0,0,1] neg_hi:[0,0,1]
	v_pk_fma_f32 v[184:185], v[192:193], v[176:177], v[184:185]
	v_mad_i64_i32 v[176:177], s[24:25], v160, s26, v[132:133]
	s_waitcnt vmcnt(0)
; #define PG8_G __attribute__((address_space(1)))
; __device__ __forceinline__ u32x4 pack8bf(const f32x4 a, const f32x4 b) { u32x4 w; w.x = cvt_pk_bf16(a[0], a[1]); w.y = cvt_pk_bf16(a[2], a[3]); w.z = cvt_pk_bf16(b[0], b[1]); w.w = cvt_pk_bf16(b[2], b[3]); return w; }
;     __device__ __forceinline__ void operator()(const f32x4 (&acc)[2][2][4][2], const Unit& u, int wr, int wc, int fr_, int fq_, int ui) const {
;     ...
;                 for (int m = 0; m < 4; ++m) { const int row = row0 + ai * HALF + m * 16;
;                     const f32x4 c0 = *(const PG8_G f32x4*)(cosT + (size_t)row * 32 + i0), c1 = *(const PG8_G f32x4*)(cosT + (size_t)row * 32 + i0 + 4);
;                     const f32x4 s0 = *(const PG8_G f32x4*)(sinT + (size_t)row * 32 + i0), s1 = *(const PG8_G f32x4*)(sinT + (size_t)row * 32 + i0 + 4);
;                     const f32x4 x1a = acc[ai][0][m][0] * r[ai][m], x1b = acc[ai][0][m][1] * r[ai][m], x2a = acc[ai][1][m][0] * r[ai][m], x2b = acc[ai][1][m][1] * r[ai][m];
;                     const f32x4 y1a = x1a * c0 - x2a * s0, y1b = x1b * c1 - x2b * s1, y2a = x2a * c0 + x1a * s0, y2b = x2b * c1 + x1b * s1;
;                     bf16_t* dst = Q + (size_t)row * 3072 + 2048 + head * 64 + i0;
;                     *(PG8_G u32x4*)dst = pack8bf(y1a, y1b); *(PG8_G u32x4*)(dst + 32) = pack8bf(y2a, y2b); }
	v_pk_mul_f32 v[216:217], v[210:211], v[188:189]
	v_pk_mul_f32 v[188:189], v[196:197], v[188:189]
	v_lshl_add_u64 v[176:177], v[176:177], 0, s[14:15]
	v_pk_mul_f32 v[214:215], v[208:209], v[190:191]
	v_pk_fma_f32 v[216:217], v[196:197], v[180:181], v[216:217] neg_lo:[0,0,1] neg_hi:[0,0,1]
	v_pk_mul_f32 v[190:191], v[194:195], v[190:191]
	v_pk_fma_f32 v[180:181], v[210:211], v[180:181], v[188:189]
	v_lshl_add_u64 v[188:189], v[176:177], 0, v[134:135]
	v_pk_fma_f32 v[214:215], v[194:195], v[182:183], v[214:215] neg_lo:[0,0,1] neg_hi:[0,0,1]
	v_pk_fma_f32 v[182:183], v[208:209], v[182:183], v[190:191]
	v_pk_mul_f32 v[186:187], v[198:199], v[186:187]
	v_lshl_add_u64 v[190:191], v[188:189], 0, s[48:49]
	v_add_co_u32_e32 v188, vcc, s27, v188
	v_pk_fma_f32 v[218:219], v[198:199], v[178:179], v[218:219] neg_lo:[0,0,1] neg_hi:[0,0,1]
	v_pk_fma_f32 v[186:187], v[212:213], v[178:179], v[186:187]
	v_cvt_pk_bf16_f32 v176, v216, v217
	v_cvt_pk_bf16_f32 v177, v214, v215
	v_cvt_pk_bf16_f32 v178, v220, v221
	v_addc_co_u32_e32 v189, vcc, 0, v189, vcc
	v_cvt_pk_bf16_f32 v179, v218, v219
	global_store_dwordx4 v[188:189], v[176:179], off
	v_pk_mul_f32 v[198:199], v[60:61], v[152:153] op_sel_hi:[1,0]
	v_pk_mul_f32 v[212:213], v[48:49], v[152:153] op_sel_hi:[1,0]
	v_cvt_pk_bf16_f32 v176, v180, v181
	v_cvt_pk_bf16_f32 v177, v182, v183
	v_cvt_pk_bf16_f32 v178, v184, v185
	v_lshlrev_b64 v[184:185], 7, v[156:157]
	v_cvt_pk_bf16_f32 v179, v186, v187
	global_store_dwordx4 v[190:191], v[176:179], off offset:64
	v_pk_mul_f32 v[194:195], v[64:65], v[152:153] op_sel_hi:[1,0]
	v_pk_mul_f32 v[208:209], v[56:57], v[152:153] op_sel_hi:[1,0]
	v_lshl_add_u64 v[176:177], s[38:39], 0, v[184:185]
	v_lshl_add_u64 v[184:185], s[40:41], 0, v[184:185]
	v_lshl_add_u64 v[180:181], v[176:177], 0, v[170:171]
	v_lshl_add_u64 v[188:189], v[184:185], 0, v[170:171]
	global_load_dwordx4 v[176:179], v[180:181], off offset:16
	s_nop 0
	global_load_dwordx4 v[180:183], v[180:181], off
	s_nop 0
	global_load_dwordx4 v[184:187], v[188:189], off offset:16
	s_nop 0
	global_load_dwordx4 v[188:191], v[188:189], off
	v_pk_mul_f32 v[192:193], v[66:67], v[152:153] op_sel_hi:[1,0]
	v_pk_mul_f32 v[206:207], v[58:59], v[152:153] op_sel_hi:[1,0]
	v_pk_mul_f32 v[196:197], v[62:63], v[152:153] op_sel_hi:[1,0]
	v_pk_mul_f32 v[210:211], v[50:51], v[152:153] op_sel_hi:[1,0]
	s_waitcnt vmcnt(1)
	v_pk_mul_f32 v[220:221], v[212:213], v[184:185]
	v_pk_mul_f32 v[184:185], v[198:199], v[184:185]
	v_pk_fma_f32 v[220:221], v[198:199], v[176:177], v[220:221] neg_lo:[0,0,1] neg_hi:[0,0,1]
	v_pk_fma_f32 v[184:185], v[212:213], v[176:177], v[184:185]
	v_mad_i64_i32 v[176:177], s[24:25], v156, s26, v[132:133]
	s_waitcnt vmcnt(0)
	v_pk_mul_f32 v[216:217], v[208:209], v[188:189]
	v_pk_mul_f32 v[188:189], v[194:195], v[188:189]
	v_lshl_add_u64 v[176:177], v[176:177], 0, s[14:15]
	v_pk_mul_f32 v[214:215], v[206:207], v[190:191]
	v_pk_fma_f32 v[216:217], v[194:195], v[180:181], v[216:217] neg_lo:[0,0,1] neg_hi:[0,0,1]
	v_pk_mul_f32 v[190:191], v[192:193], v[190:191]
	v_pk_fma_f32 v[180:181], v[208:209], v[180:181], v[188:189]
	v_lshl_add_u64 v[188:189], v[176:177], 0, v[134:135]
	v_pk_fma_f32 v[214:215], v[192:193], v[182:183], v[214:215] neg_lo:[0,0,1] neg_hi:[0,0,1]
	v_pk_mul_f32 v[218:219], v[210:211], v[186:187]
	v_pk_fma_f32 v[182:183], v[206:207], v[182:183], v[190:191]
	v_pk_mul_f32 v[186:187], v[196:197], v[186:187]
	v_lshl_add_u64 v[190:191], v[188:189], 0, s[48:49]
	v_add_co_u32_e32 v188, vcc, s27, v188
	v_pk_fma_f32 v[218:219], v[196:197], v[178:179], v[218:219] neg_lo:[0,0,1] neg_hi:[0,0,1]
	v_pk_fma_f32 v[186:187], v[210:211], v[178:179], v[186:187]
	v_cvt_pk_bf16_f32 v176, v216, v217
	v_cvt_pk_bf16_f32 v177, v214, v215
	v_cvt_pk_bf16_f32 v178, v220, v221
	v_addc_co_u32_e32 v189, vcc, 0, v189, vcc
	v_cvt_pk_bf16_f32 v179, v218, v219
	global_store_dwordx4 v[188:189], v[176:179], off
	v_mov_b32_e32 v192, v153
	v_pk_mul_f32 v[194:195], v[54:55], v[192:193] op_sel_hi:[1,0]
	v_cvt_pk_bf16_f32 v176, v180, v181
	v_cvt_pk_bf16_f32 v177, v182, v183
	v_cvt_pk_bf16_f32 v178, v184, v185
	v_lshlrev_b64 v[184:185], 7, v[154:155]
	v_cvt_pk_bf16_f32 v179, v186, v187
	global_store_dwordx4 v[190:191], v[176:179], off offset:64
	v_pk_mul_f32 v[196:197], v[52:53], v[192:193] op_sel_hi:[1,0]
	v_pk_mul_f32 v[198:199], v[46:47], v[192:193] op_sel_hi:[1,0]
	v_lshl_add_u64 v[176:177], s[38:39], 0, v[184:185]
	v_lshl_add_u64 v[184:185], s[40:41], 0, v[184:185]
	v_lshl_add_u64 v[180:181], v[176:177], 0, v[170:171]
	v_lshl_add_u64 v[188:189], v[184:185], 0, v[170:171]
	global_load_dwordx4 v[176:179], v[180:181], off offset:16
	s_nop 0
	global_load_dwordx4 v[180:183], v[180:181], off
	s_nop 0
	global_load_dwordx4 v[184:187], v[188:189], off offset:16
	s_nop 0
	global_load_dwordx4 v[188:191], v[188:189], off
	v_pk_mul_f32 v[206:207], v[44:45], v[192:193] op_sel_hi:[1,0]
	v_pk_mul_f32 v[208:209], v[42:43], v[192:193] op_sel_hi:[1,0]
	v_pk_mul_f32 v[210:211], v[40:41], v[192:193] op_sel_hi:[1,0]
	v_pk_mul_f32 v[212:213], v[34:35], v[192:193] op_sel_hi:[1,0]
	v_pk_mul_f32 v[192:193], v[32:33], v[192:193] op_sel_hi:[1,0]
	s_waitcnt vmcnt(1)
	v_pk_mul_f32 v[218:219], v[212:213], v[186:187]
	v_pk_mul_f32 v[220:221], v[192:193], v[184:185]
	v_pk_mul_f32 v[184:185], v[206:207], v[184:185]
	v_pk_fma_f32 v[220:221], v[206:207], v[176:177], v[220:221] neg_lo:[0,0,1] neg_hi:[0,0,1]
	v_pk_fma_f32 v[184:185], v[192:193], v[176:177], v[184:185]
	v_mad_i64_i32 v[176:177], s[24:25], v154, s26, v[132:133]
	s_waitcnt vmcnt(0)
; #define PG8_G __attribute__((address_space(1)))
; __device__ __forceinline__ u32x4 pack8bf(const f32x4 a, const f32x4 b) { u32x4 w; w.x = cvt_pk_bf16(a[0], a[1]); w.y = cvt_pk_bf16(a[2], a[3]); w.z = cvt_pk_bf16(b[0], b[1]); w.w = cvt_pk_bf16(b[2], b[3]); return w; }
;     __device__ __forceinline__ void operator()(const f32x4 (&acc)[2][2][4][2], const Unit& u, int wr, int wc, int fr_, int fq_, int ui) const {
;     ...
;                 for (int m = 0; m < 4; ++m) { const int row = row0 + ai * HALF + m * 16;
;                     const f32x4 c0 = *(const PG8_G f32x4*)(cosT + (size_t)row * 32 + i0), c1 = *(const PG8_G f32x4*)(cosT + (size_t)row * 32 + i0 + 4);
;                     const f32x4 s0 = *(const PG8_G f32x4*)(sinT + (size_t)row * 32 + i0), s1 = *(const PG8_G f32x4*)(sinT + (size_t)row * 32 + i0 + 4);
;                     const f32x4 x1a = acc[ai][0][m][0] * r[ai][m], x1b = acc[ai][0][m][1] * r[ai][m], x2a = acc[ai][1][m][0] * r[ai][m], x2b = acc[ai][1][m][1] * r[ai][m];
;                     const f32x4 y1a = x1a * c0 - x2a * s0, y1b = x1b * c1 - x2b * s1, y2a = x2a * c0 + x1a * s0, y2b = x2b * c1 + x1b * s1;
;                     bf16_t* dst = Q + (size_t)row * 3072 + 2048 + head * 64 + i0;
;                     *(PG8_G u32x4*)dst = pack8bf(y1a, y1b); *(PG8_G u32x4*)(dst + 32) = pack8bf(y2a, y2b); }
	v_pk_mul_f32 v[216:217], v[210:211], v[188:189]
	v_pk_mul_f32 v[188:189], v[196:197], v[188:189]
	v_lshl_add_u64 v[176:177], v[176:177], 0, s[14:15]
	v_pk_mul_f32 v[214:215], v[208:209], v[190:191]
	v_pk_fma_f32 v[216:217], v[196:197], v[180:181], v[216:217] neg_lo:[0,0,1] neg_hi:[0,0,1]
	v_pk_mul_f32 v[190:191], v[194:195], v[190:191]
	v_pk_fma_f32 v[180:181], v[210:211], v[180:181], v[188:189]
	v_lshl_add_u64 v[188:189], v[176:177], 0, v[134:135]
	v_pk_fma_f32 v[214:215], v[194:195], v[182:183], v[214:215] neg_lo:[0,0,1] neg_hi:[0,0,1]
	v_pk_fma_f32 v[182:183], v[208:209], v[182:183], v[190:191]
	v_pk_mul_f32 v[186:187], v[198:199], v[186:187]
	v_lshl_add_u64 v[190:191], v[188:189], 0, s[48:49]
	v_add_co_u32_e32 v188, vcc, s27, v188
	v_pk_fma_f32 v[218:219], v[198:199], v[178:179], v[218:219] neg_lo:[0,0,1] neg_hi:[0,0,1]
	v_pk_fma_f32 v[186:187], v[212:213], v[178:179], v[186:187]
	v_cvt_pk_bf16_f32 v176, v216, v217
	v_cvt_pk_bf16_f32 v177, v214, v215
	v_cvt_pk_bf16_f32 v178, v220, v221
	v_addc_co_u32_e32 v189, vcc, 0, v189, vcc
	v_cvt_pk_bf16_f32 v179, v218, v219
	global_store_dwordx4 v[188:189], v[176:179], off
	v_pk_mul_f32 v[198:199], v[28:29], v[148:149] op_sel_hi:[1,0]
	v_pk_mul_f32 v[212:213], v[16:17], v[148:149] op_sel_hi:[1,0]
	v_cvt_pk_bf16_f32 v176, v180, v181
	v_cvt_pk_bf16_f32 v177, v182, v183
	v_cvt_pk_bf16_f32 v178, v184, v185
	v_lshlrev_b64 v[184:185], 7, v[150:151]
	v_cvt_pk_bf16_f32 v179, v186, v187
	global_store_dwordx4 v[190:191], v[176:179], off offset:64
	v_pk_mul_f32 v[194:195], v[36:37], v[148:149] op_sel_hi:[1,0]
	v_pk_mul_f32 v[208:209], v[24:25], v[148:149] op_sel_hi:[1,0]
	v_lshl_add_u64 v[176:177], s[38:39], 0, v[184:185]
	v_lshl_add_u64 v[184:185], s[40:41], 0, v[184:185]
	v_lshl_add_u64 v[180:181], v[176:177], 0, v[170:171]
	v_lshl_add_u64 v[188:189], v[184:185], 0, v[170:171]
	global_load_dwordx4 v[176:179], v[180:181], off offset:16
	s_nop 0
	global_load_dwordx4 v[180:183], v[180:181], off
	s_nop 0
	global_load_dwordx4 v[184:187], v[188:189], off offset:16
	s_nop 0
	global_load_dwordx4 v[188:191], v[188:189], off
	v_pk_mul_f32 v[192:193], v[38:39], v[148:149] op_sel_hi:[1,0]
	v_pk_mul_f32 v[206:207], v[26:27], v[148:149] op_sel_hi:[1,0]
	v_pk_mul_f32 v[196:197], v[30:31], v[148:149] op_sel_hi:[1,0]
	v_pk_mul_f32 v[210:211], v[18:19], v[148:149] op_sel_hi:[1,0]
	s_waitcnt vmcnt(1)
	v_pk_mul_f32 v[220:221], v[212:213], v[184:185]
	v_pk_mul_f32 v[184:185], v[198:199], v[184:185]
	v_pk_fma_f32 v[220:221], v[198:199], v[176:177], v[220:221] neg_lo:[0,0,1] neg_hi:[0,0,1]
	v_pk_fma_f32 v[184:185], v[212:213], v[176:177], v[184:185]
	v_mad_i64_i32 v[176:177], s[24:25], v150, s26, v[132:133]
	s_waitcnt vmcnt(0)
	v_pk_mul_f32 v[216:217], v[208:209], v[188:189]
	v_pk_mul_f32 v[188:189], v[194:195], v[188:189]
	v_lshl_add_u64 v[176:177], v[176:177], 0, s[14:15]
	v_pk_mul_f32 v[214:215], v[206:207], v[190:191]
	v_pk_fma_f32 v[216:217], v[194:195], v[180:181], v[216:217] neg_lo:[0,0,1] neg_hi:[0,0,1]
	v_pk_mul_f32 v[190:191], v[192:193], v[190:191]
	v_pk_fma_f32 v[180:181], v[208:209], v[180:181], v[188:189]
	v_lshl_add_u64 v[188:189], v[176:177], 0, v[134:135]
	v_pk_fma_f32 v[214:215], v[192:193], v[182:183], v[214:215] neg_lo:[0,0,1] neg_hi:[0,0,1]
	v_pk_mul_f32 v[218:219], v[210:211], v[186:187]
	v_pk_fma_f32 v[182:183], v[206:207], v[182:183], v[190:191]
	v_pk_mul_f32 v[186:187], v[196:197], v[186:187]
	v_lshl_add_u64 v[190:191], v[188:189], 0, s[48:49]
	v_add_co_u32_e32 v188, vcc, s27, v188
	v_add_u32_e32 v192, 0xb0, v146
	v_pk_fma_f32 v[218:219], v[196:197], v[178:179], v[218:219] neg_lo:[0,0,1] neg_hi:[0,0,1]
	v_pk_fma_f32 v[186:187], v[210:211], v[178:179], v[186:187]
	v_cvt_pk_bf16_f32 v176, v216, v217
	v_cvt_pk_bf16_f32 v177, v214, v215
	v_cvt_pk_bf16_f32 v178, v220, v221
	v_addc_co_u32_e32 v189, vcc, 0, v189, vcc
	v_ashrrev_i32_e32 v193, 31, v192
	v_cvt_pk_bf16_f32 v179, v218, v219
	global_store_dwordx4 v[188:189], v[176:179], off
	v_mad_i64_i32 v[132:133], s[24:25], v192, s26, v[132:133]
	s_nop 0
	v_cvt_pk_bf16_f32 v176, v180, v181
	v_cvt_pk_bf16_f32 v177, v182, v183
	v_cvt_pk_bf16_f32 v178, v184, v185
	v_lshlrev_b64 v[184:185], 7, v[192:193]
	v_cvt_pk_bf16_f32 v179, v186, v187
	global_store_dwordx4 v[190:191], v[176:179], off offset:64
	v_lshl_add_u64 v[132:133], v[132:133], 0, s[14:15]
	s_mov_b64 s[14:15], 0x1040
	v_lshl_add_u64 v[176:177], s[38:39], 0, v[184:185]
	v_lshl_add_u64 v[184:185], s[40:41], 0, v[184:185]
	v_lshl_add_u64 v[180:181], v[176:177], 0, v[170:171]
	v_lshl_add_u64 v[170:171], v[184:185], 0, v[170:171]
	global_load_dwordx4 v[176:179], v[180:181], off offset:16
	s_nop 0
	global_load_dwordx4 v[180:183], v[180:181], off
	s_nop 0
	global_load_dwordx4 v[184:187], v[170:171], off offset:16
	global_load_dwordx4 v[188:191], v[170:171], off
	v_mov_b32_e32 v170, v149
	v_pk_mul_f32 v[194:195], v[22:23], v[170:171] op_sel_hi:[1,0]
	v_pk_mul_f32 v[196:197], v[20:21], v[170:171] op_sel_hi:[1,0]
	v_pk_mul_f32 v[198:199], v[14:15], v[170:171] op_sel_hi:[1,0]
	v_pk_mul_f32 v[206:207], v[12:13], v[170:171] op_sel_hi:[1,0]
	v_pk_mul_f32 v[208:209], v[10:11], v[170:171] op_sel_hi:[1,0]
	v_pk_mul_f32 v[210:211], v[8:9], v[170:171] op_sel_hi:[1,0]
	v_pk_mul_f32 v[212:213], v[6:7], v[170:171] op_sel_hi:[1,0]
	v_pk_mul_f32 v[170:171], v[4:5], v[170:171] op_sel_hi:[1,0]
	s_waitcnt vmcnt(1)
	v_pk_mul_f32 v[218:219], v[212:213], v[186:187]
	v_pk_mul_f32 v[220:221], v[170:171], v[184:185]
	v_pk_mul_f32 v[184:185], v[206:207], v[184:185]
	v_pk_fma_f32 v[220:221], v[206:207], v[176:177], v[220:221] neg_lo:[0,0,1] neg_hi:[0,0,1]
	v_pk_fma_f32 v[170:171], v[170:171], v[176:177], v[184:185]
	v_lshl_add_u64 v[176:177], v[132:133], 0, v[134:135]
	s_waitcnt vmcnt(0)
	v_pk_mul_f32 v[214:215], v[208:209], v[190:191]
	v_pk_mul_f32 v[216:217], v[210:211], v[188:189]
	v_add_co_u32_e32 v184, vcc, s27, v176
	v_pk_fma_f32 v[214:215], v[194:195], v[182:183], v[214:215] neg_lo:[0,0,1] neg_hi:[0,0,1]
	v_pk_fma_f32 v[216:217], v[196:197], v[180:181], v[216:217] neg_lo:[0,0,1] neg_hi:[0,0,1]
	v_pk_fma_f32 v[218:219], v[198:199], v[178:179], v[218:219] neg_lo:[0,0,1] neg_hi:[0,0,1]
	v_pk_mul_f32 v[190:191], v[194:195], v[190:191]
	v_pk_mul_f32 v[188:189], v[196:197], v[188:189]
	v_pk_mul_f32 v[186:187], v[198:199], v[186:187]
	v_cvt_pk_bf16_f32 v132, v216, v217
	v_cvt_pk_bf16_f32 v133, v214, v215
	v_cvt_pk_bf16_f32 v134, v220, v221
	v_cvt_pk_bf16_f32 v135, v218, v219
	v_addc_co_u32_e32 v185, vcc, 0, v177, vcc
	v_pk_fma_f32 v[182:183], v[208:209], v[182:183], v[190:191]
	v_pk_fma_f32 v[180:181], v[210:211], v[180:181], v[188:189]
	v_pk_fma_f32 v[178:179], v[212:213], v[178:179], v[186:187]
	global_store_dwordx4 v[184:185], v[132:135], off
	s_nop 1
	v_cvt_pk_bf16_f32 v132, v180, v181
	v_cvt_pk_bf16_f32 v133, v182, v183
	v_cvt_pk_bf16_f32 v134, v170, v171
	v_cvt_pk_bf16_f32 v135, v178, v179
	v_lshl_add_u64 v[170:171], v[176:177], 0, s[14:15]
	s_mov_b64 s[14:15], 0

; #define PG8_STAGE(bufoff, gbase, voff) do { _Pragma("unroll") for (int _i = 0; _i < 2; ++_i) \
;         __builtin_amdgcn_global_load_lds((const unsigned*)((const char*)(gbase) + (voff)[_i]), (PG8_LAS unsigned*)(lds + (bufoff) + ldsw + _i * 8192), 16, 0, 0); } while (0)
; #define PG8_LDA(dst, b, h) do { _Pragma("unroll") for (int m = 0; m < 4; ++m) _Pragma("unroll") for (int k = 0; k < 2; ++k) dst[m][k] = *(const PG8_LAS bf16x8*)(lds + PG8_SA(b, h) + aoff + m * 2048 + k * 1024); } while (0)
; #define PG8_LDB(dst, b, h) do { _Pragma("unroll") for (int n = 0; n < 2; ++n) _Pragma("unroll") for (int k = 0; k < 2; ++k) dst[n][k] = *(const PG8_LAS bf16x8*)(lds + PG8_SB(b, h) + boff + n * 2048 + k * 1024); } while (0)
; #define PG8_MMA(ai, bj, At, Bt) do { __builtin_amdgcn_s_setprio(1); _Pragma("unroll") for (int m = 0; m < 4; ++m) _Pragma("unroll") for (int n = 0; n < 2; ++n) _Pragma("unroll") for (int k = 0; k < 2; ++k) \
;         acc[ai][bj][m][n] = __builtin_amdgcn_mfma_f32_16x16x32_bf16(Bt[n][k], At[m][k], acc[ai][bj][m][n], 0, 0, 0); __builtin_amdgcn_s_setprio(0); } while (0)
; #define PG8_WAIT_V(n) asm volatile("s_waitcnt vmcnt(" #n ")" ::: "memory")
; #define PG8_WAIT_L(n) asm volatile("s_waitcnt lgkmcnt(" #n ")" ::: "memory")
; #define PG8_BAR __builtin_amdgcn_s_barrier()
; #define PG8_SCHED __builtin_amdgcn_sched_barrier(0)
;     ...
;             PG8_LDB(B0, 0, 0); PG8_LDB(B1, 0, 1); PG8_SCHED; PG8_LDA(At, 0, 0); PG8_STAGE(PG8_SA(1, 1), a1 + hstep, voffA);
;             PG8_WAIT_V(8); PG8_WAIT_L(0); PG8_BAR; PG8_MMA(0, 0, At, B0); PG8_MMA(0, 1, At, B1); PG8_BAR; PG8_SCHED;
;             PG8_LDA(At, 0, 1); PG8_STAGE(PG8_SB(0, 0), b2, voffB); PG8_STAGE(PG8_SB(0, 1), b2 + hstep, voffB); PG8_STAGE(PG8_SA(0, 0), a2, voffA);
;             PG8_WAIT_V(8); PG8_WAIT_L(0); PG8_BAR; PG8_MMA(1, 0, At, B0); PG8_MMA(1, 1, At, B1); PG8_BAR; PG8_SCHED;
.LBB0_454:
	ds_read_b128 v[108:111], v251
	ds_read_b128 v[112:115], v251 offset:1024
	ds_read_b128 v[128:131], v251 offset:2048
	ds_read_b128 v[136:139], v251 offset:3072
	ds_read_b128 v[148:151], v251 offset:16384
	ds_read_b128 v[152:155], v251 offset:17408
	ds_read_b128 v[156:159], v251 offset:18432
	ds_read_b128 v[160:163], v251 offset:19456
	ds_read_b128 v[164:167], v234
	ds_read_b128 v[168:171], v234 offset:1024
	ds_read_b128 v[172:175], v234 offset:2048
	ds_read_b128 v[176:179], v234 offset:3072
	ds_read_b128 v[180:183], v234 offset:4096
	ds_read_b128 v[184:187], v234 offset:5120
	ds_read_b128 v[206:209], v234 offset:6144
	ds_read_b128 v[210:213], v234 offset:7168
	s_add_u32 s48, s62, 0xfff80080
	s_addc_u32 s49, s63, -1
	s_add_i32 s82, 0, 0x10000
	s_cmp_eq_u32 s81, 28
	s_cselect_b32 s71, s25, s49
	s_cselect_b32 s70, s76, s48
	s_cselect_b32 s69, s15, s79
	s_cselect_b32 s68, s77, s78
	s_add_i32 s48, 0, 0x14000
	v_lshl_add_u64 v[198:199], s[62:63], 0, v[196:197]
	s_add_i32 m0, s20, 0xc000
	s_nop 0
	global_load_lds_dwordx4 v[198:199], off
	v_lshl_add_u64 v[198:199], s[62:63], 0, v[194:195]
	s_add_i32 m0, s20, 0xe000
	s_nop 0
	global_load_lds_dwordx4 v[198:199], off
	s_waitcnt vmcnt(8)
	s_waitcnt lgkmcnt(0)
	s_setprio 1
	s_barrier
	v_mfma_f32_16x16x32_bf16 v[144:147], v[108:111], v[164:167], v[144:147]
	v_mfma_f32_16x16x32_bf16 v[140:143], v[128:131], v[164:167], v[140:143]
	v_mfma_f32_16x16x32_bf16 v[120:123], v[108:111], v[172:175], v[120:123]
	v_mfma_f32_16x16x32_bf16 v[116:119], v[128:131], v[172:175], v[116:119]
	v_mfma_f32_16x16x32_bf16 v[96:99], v[108:111], v[180:183], v[96:99]
	v_mfma_f32_16x16x32_bf16 v[92:95], v[128:131], v[180:183], v[92:95]
	v_mfma_f32_16x16x32_bf16 v[80:83], v[108:111], v[206:209], v[80:83]
	v_mfma_f32_16x16x32_bf16 v[76:79], v[128:131], v[206:209], v[76:79]
	v_mfma_f32_16x16x32_bf16 v[144:147], v[112:115], v[168:171], v[144:147]
	v_mfma_f32_16x16x32_bf16 v[140:143], v[136:139], v[168:171], v[140:143]
	v_mfma_f32_16x16x32_bf16 v[120:123], v[112:115], v[176:179], v[120:123]
	v_mfma_f32_16x16x32_bf16 v[116:119], v[136:139], v[176:179], v[116:119]
	v_mfma_f32_16x16x32_bf16 v[96:99], v[112:115], v[184:187], v[96:99]
	v_mfma_f32_16x16x32_bf16 v[92:95], v[136:139], v[184:187], v[92:95]
	v_mfma_f32_16x16x32_bf16 v[80:83], v[112:115], v[210:213], v[80:83]
	v_mfma_f32_16x16x32_bf16 v[76:79], v[136:139], v[210:213], v[76:79]
	s_setprio 0
	s_setprio 1
	v_mfma_f32_16x16x32_bf16 v[132:135], v[148:151], v[164:167], v[132:135]
	v_mfma_f32_16x16x32_bf16 v[124:127], v[156:159], v[164:167], v[124:127]
	v_mfma_f32_16x16x32_bf16 v[104:107], v[148:151], v[172:175], v[104:107]
	v_mfma_f32_16x16x32_bf16 v[100:103], v[156:159], v[172:175], v[100:103]
	v_mfma_f32_16x16x32_bf16 v[88:91], v[148:151], v[180:183], v[88:91]
	v_mfma_f32_16x16x32_bf16 v[84:87], v[156:159], v[180:183], v[84:87]
	v_mfma_f32_16x16x32_bf16 v[72:75], v[148:151], v[206:209], v[72:75]
	v_mfma_f32_16x16x32_bf16 v[68:71], v[156:159], v[206:209], v[68:71]
	v_mfma_f32_16x16x32_bf16 v[132:135], v[152:155], v[168:171], v[132:135]
	v_mfma_f32_16x16x32_bf16 v[124:127], v[160:163], v[168:171], v[124:127]
	v_mfma_f32_16x16x32_bf16 v[104:107], v[152:155], v[176:179], v[104:107]
	v_mfma_f32_16x16x32_bf16 v[100:103], v[160:163], v[176:179], v[100:103]
	v_mfma_f32_16x16x32_bf16 v[88:91], v[152:155], v[184:187], v[88:91]
	v_mfma_f32_16x16x32_bf16 v[84:87], v[160:163], v[184:187], v[84:87]
	v_mfma_f32_16x16x32_bf16 v[72:75], v[152:155], v[210:213], v[72:75]
	v_mfma_f32_16x16x32_bf16 v[68:71], v[160:163], v[210:213], v[68:71]
	s_barrier
	s_setprio 0
	ds_read_b128 v[164:167], v234 offset:16384
	ds_read_b128 v[168:171], v234 offset:17408
	ds_read_b128 v[172:175], v234 offset:18432
	ds_read_b128 v[176:179], v234 offset:19456
	ds_read_b128 v[180:183], v234 offset:20480
	ds_read_b128 v[184:187], v234 offset:21504
	ds_read_b128 v[206:209], v234 offset:22528
	ds_read_b128 v[210:213], v234 offset:23552
	s_add_i32 s49, s82, s5
	v_lshl_add_u64 v[198:199], s[68:69], 0, v[200:201]
	s_mov_b32 m0, s49
	s_nop 0
	global_load_lds_dwordx4 v[198:199], off
	s_add_i32 m0, s49, 0x2000
	s_add_u32 s82, s68, 0x80000
	v_lshl_add_u64 v[214:215], s[68:69], 0, v[188:189]
	s_addc_u32 s83, s69, 0
	s_add_i32 s48, s48, s5
	global_load_lds_dwordx4 v[214:215], off
	v_lshl_add_u64 v[216:217], s[82:83], 0, v[200:201]
	s_mov_b32 m0, s48
	v_lshl_add_u64 v[218:219], s[70:71], 0, v[190:191]
	global_load_lds_dwordx4 v[216:217], off
	v_lshl_add_u64 v[216:217], s[82:83], 0, v[188:189]
	s_add_i32 m0, s48, 0x2000
	s_nop 0
	global_load_lds_dwordx4 v[216:217], off
	v_lshl_add_u64 v[216:217], s[70:71], 0, v[192:193]
	s_mov_b32 m0, s20
	s_nop 0
	global_load_lds_dwordx4 v[216:217], off
	s_mov_b32 m0, s21
	s_nop 0
	global_load_lds_dwordx4 v[218:219], off
	s_waitcnt vmcnt(8)
	s_waitcnt lgkmcnt(0)
	s_setprio 1
	s_barrier
; #define PG8_STAGE(bufoff, gbase, voff) do { _Pragma("unroll") for (int _i = 0; _i < 2; ++_i) \
;         __builtin_amdgcn_global_load_lds((const unsigned*)((const char*)(gbase) + (voff)[_i]), (PG8_LAS unsigned*)(lds + (bufoff) + ldsw + _i * 8192), 16, 0, 0); } while (0)
; #define PG8_LDA(dst, b, h) do { _Pragma("unroll") for (int m = 0; m < 4; ++m) _Pragma("unroll") for (int k = 0; k < 2; ++k) dst[m][k] = *(const PG8_LAS bf16x8*)(lds + PG8_SA(b, h) + aoff + m * 2048 + k * 1024); } while (0)
; #define PG8_LDB(dst, b, h) do { _Pragma("unroll") for (int n = 0; n < 2; ++n) _Pragma("unroll") for (int k = 0; k < 2; ++k) dst[n][k] = *(const PG8_LAS bf16x8*)(lds + PG8_SB(b, h) + boff + n * 2048 + k * 1024); } while (0)
; #define PG8_MMA(ai, bj, At, Bt) do { __builtin_amdgcn_s_setprio(1); _Pragma("unroll") for (int m = 0; m < 4; ++m) _Pragma("unroll") for (int n = 0; n < 2; ++n) _Pragma("unroll") for (int k = 0; k < 2; ++k) \
;         acc[ai][bj][m][n] = __builtin_amdgcn_mfma_f32_16x16x32_bf16(Bt[n][k], At[m][k], acc[ai][bj][m][n], 0, 0, 0); __builtin_amdgcn_s_setprio(0); } while (0)
; #define PG8_WAIT_V(n) asm volatile("s_waitcnt vmcnt(" #n ")" ::: "memory")
; #define PG8_WAIT_L(n) asm volatile("s_waitcnt lgkmcnt(" #n ")" ::: "memory")
; #define PG8_BAR __builtin_amdgcn_s_barrier()
; #define PG8_SCHED __builtin_amdgcn_sched_barrier(0)
;     ...
;             PG8_WAIT_V(8); PG8_WAIT_L(0); PG8_BAR; PG8_MMA(1, 0, At, B0); PG8_MMA(1, 1, At, B1); PG8_BAR; PG8_SCHED;
;             PG8_LDB(B0, 1, 0); PG8_LDB(B1, 1, 1); PG8_SCHED; PG8_LDA(At, 1, 0); PG8_STAGE(PG8_SA(0, 1), a2 + hstep, voffA);
;             PG8_WAIT_V(8); PG8_WAIT_L(0); PG8_BAR; PG8_MMA(0, 0, At, B0); PG8_MMA(0, 1, At, B1); PG8_BAR; PG8_SCHED;
	v_mfma_f32_16x16x32_bf16 v[64:67], v[108:111], v[164:167], v[64:67]
	v_mfma_f32_16x16x32_bf16 v[60:63], v[128:131], v[164:167], v[60:63]
	v_mfma_f32_16x16x32_bf16 v[48:51], v[108:111], v[172:175], v[48:51]
	v_mfma_f32_16x16x32_bf16 v[44:47], v[128:131], v[172:175], v[44:47]
	v_mfma_f32_16x16x32_bf16 v[32:35], v[108:111], v[180:183], v[32:35]
	v_mfma_f32_16x16x32_bf16 v[28:31], v[128:131], v[180:183], v[28:31]
	v_mfma_f32_16x16x32_bf16 v[16:19], v[108:111], v[206:209], v[16:19]
	v_mfma_f32_16x16x32_bf16 v[12:15], v[128:131], v[206:209], v[12:15]
	v_mfma_f32_16x16x32_bf16 v[64:67], v[112:115], v[168:171], v[64:67]
	v_mfma_f32_16x16x32_bf16 v[60:63], v[136:139], v[168:171], v[60:63]
	v_mfma_f32_16x16x32_bf16 v[48:51], v[112:115], v[176:179], v[48:51]
	v_mfma_f32_16x16x32_bf16 v[44:47], v[136:139], v[176:179], v[44:47]
	v_mfma_f32_16x16x32_bf16 v[32:35], v[112:115], v[184:187], v[32:35]
	v_mfma_f32_16x16x32_bf16 v[28:31], v[136:139], v[184:187], v[28:31]
	v_mfma_f32_16x16x32_bf16 v[16:19], v[112:115], v[210:213], v[16:19]
	v_mfma_f32_16x16x32_bf16 v[12:15], v[136:139], v[210:213], v[12:15]
	s_setprio 0
	s_setprio 1
	v_mfma_f32_16x16x32_bf16 v[56:59], v[148:151], v[164:167], v[56:59]
	v_mfma_f32_16x16x32_bf16 v[52:55], v[156:159], v[164:167], v[52:55]
	v_mfma_f32_16x16x32_bf16 v[40:43], v[148:151], v[172:175], v[40:43]
	v_mfma_f32_16x16x32_bf16 v[36:39], v[156:159], v[172:175], v[36:39]
	v_mfma_f32_16x16x32_bf16 v[24:27], v[148:151], v[180:183], v[24:27]
	v_mfma_f32_16x16x32_bf16 v[20:23], v[156:159], v[180:183], v[20:23]
	v_mfma_f32_16x16x32_bf16 v[8:11], v[148:151], v[206:209], v[8:11]
	v_mfma_f32_16x16x32_bf16 v[4:7], v[156:159], v[206:209], v[4:7]
	v_mfma_f32_16x16x32_bf16 v[56:59], v[152:155], v[168:171], v[56:59]
	v_mfma_f32_16x16x32_bf16 v[52:55], v[160:163], v[168:171], v[52:55]
	v_mfma_f32_16x16x32_bf16 v[40:43], v[152:155], v[176:179], v[40:43]
	v_mfma_f32_16x16x32_bf16 v[36:39], v[160:163], v[176:179], v[36:39]
	v_mfma_f32_16x16x32_bf16 v[24:27], v[152:155], v[184:187], v[24:27]
	v_mfma_f32_16x16x32_bf16 v[20:23], v[160:163], v[184:187], v[20:23]
	v_mfma_f32_16x16x32_bf16 v[8:11], v[152:155], v[210:213], v[8:11]
	v_mfma_f32_16x16x32_bf16 v[4:7], v[160:163], v[210:213], v[4:7]
	s_barrier
	s_setprio 0
	ds_read_b128 v[108:111], v251 offset:32768
	ds_read_b128 v[112:115], v251 offset:33792
	ds_read_b128 v[128:131], v251 offset:34816
	ds_read_b128 v[136:139], v251 offset:35840
	ds_read_b128 v[148:151], v251 offset:49152
	ds_read_b128 v[152:155], v251 offset:50176
	ds_read_b128 v[156:159], v251 offset:51200
	ds_read_b128 v[160:163], v251 offset:52224
	ds_read_b128 v[164:167], v234 offset:32768
	ds_read_b128 v[168:171], v234 offset:33792
	ds_read_b128 v[172:175], v234 offset:34816
	ds_read_b128 v[176:179], v234 offset:35840
	ds_read_b128 v[180:183], v234 offset:36864
	ds_read_b128 v[184:187], v234 offset:37888
	ds_read_b128 v[206:209], v234 offset:38912
	ds_read_b128 v[210:213], v234 offset:39936
	s_add_i32 s48, 0, 0x18000
	s_add_i32 s49, 0, 0x1c000
	s_add_u32 s70, s70, 0x80000
	s_addc_u32 s71, s71, 0
	s_mov_b32 m0, s23
	v_lshl_add_u64 v[220:221], s[70:71], 0, v[192:193]
	global_load_lds_dwordx4 v[220:221], off
	v_lshl_add_u64 v[220:221], s[70:71], 0, v[190:191]
	s_mov_b32 m0, s42
	s_nop 0
	global_load_lds_dwordx4 v[220:221], off
	s_waitcnt vmcnt(8)
	s_waitcnt lgkmcnt(0)
	s_setprio 1
	s_barrier
	v_mfma_f32_16x16x32_bf16 v[144:147], v[108:111], v[164:167], v[144:147]
	v_mfma_f32_16x16x32_bf16 v[140:143], v[128:131], v[164:167], v[140:143]
	v_mfma_f32_16x16x32_bf16 v[120:123], v[108:111], v[172:175], v[120:123]
	v_mfma_f32_16x16x32_bf16 v[116:119], v[128:131], v[172:175], v[116:119]
	v_mfma_f32_16x16x32_bf16 v[96:99], v[108:111], v[180:183], v[96:99]
	v_mfma_f32_16x16x32_bf16 v[92:95], v[128:131], v[180:183], v[92:95]
	v_mfma_f32_16x16x32_bf16 v[80:83], v[108:111], v[206:209], v[80:83]
	v_mfma_f32_16x16x32_bf16 v[76:79], v[128:131], v[206:209], v[76:79]
	v_mfma_f32_16x16x32_bf16 v[144:147], v[112:115], v[168:171], v[144:147]
	v_mfma_f32_16x16x32_bf16 v[140:143], v[136:139], v[168:171], v[140:143]
	v_mfma_f32_16x16x32_bf16 v[120:123], v[112:115], v[176:179], v[120:123]
	v_mfma_f32_16x16x32_bf16 v[116:119], v[136:139], v[176:179], v[116:119]
	v_mfma_f32_16x16x32_bf16 v[96:99], v[112:115], v[184:187], v[96:99]
	v_mfma_f32_16x16x32_bf16 v[92:95], v[136:139], v[184:187], v[92:95]
	v_mfma_f32_16x16x32_bf16 v[80:83], v[112:115], v[210:213], v[80:83]
	v_mfma_f32_16x16x32_bf16 v[76:79], v[136:139], v[210:213], v[76:79]
	s_setprio 0
	s_setprio 1
	v_mfma_f32_16x16x32_bf16 v[132:135], v[148:151], v[164:167], v[132:135]
	v_mfma_f32_16x16x32_bf16 v[124:127], v[156:159], v[164:167], v[124:127]
	v_mfma_f32_16x16x32_bf16 v[104:107], v[148:151], v[172:175], v[104:107]
	v_mfma_f32_16x16x32_bf16 v[100:103], v[156:159], v[172:175], v[100:103]
	v_mfma_f32_16x16x32_bf16 v[88:91], v[148:151], v[180:183], v[88:91]
	v_mfma_f32_16x16x32_bf16 v[84:87], v[156:159], v[180:183], v[84:87]
	v_mfma_f32_16x16x32_bf16 v[72:75], v[148:151], v[206:209], v[72:75]
	v_mfma_f32_16x16x32_bf16 v[68:71], v[156:159], v[206:209], v[68:71]
	v_mfma_f32_16x16x32_bf16 v[132:135], v[152:155], v[168:171], v[132:135]
	v_mfma_f32_16x16x32_bf16 v[124:127], v[160:163], v[168:171], v[124:127]
	v_mfma_f32_16x16x32_bf16 v[104:107], v[152:155], v[176:179], v[104:107]
	v_mfma_f32_16x16x32_bf16 v[100:103], v[160:163], v[176:179], v[100:103]
	v_mfma_f32_16x16x32_bf16 v[88:91], v[152:155], v[184:187], v[88:91]
	v_mfma_f32_16x16x32_bf16 v[84:87], v[160:163], v[184:187], v[84:87]
	v_mfma_f32_16x16x32_bf16 v[72:75], v[152:155], v[210:213], v[72:75]
	v_mfma_f32_16x16x32_bf16 v[68:71], v[160:163], v[210:213], v[68:71]
	s_barrier
; #define PG8_STAGE(bufoff, gbase, voff) do { _Pragma("unroll") for (int _i = 0; _i < 2; ++_i) \
;         __builtin_amdgcn_global_load_lds((const unsigned*)((const char*)(gbase) + (voff)[_i]), (PG8_LAS unsigned*)(lds + (bufoff) + ldsw + _i * 8192), 16, 0, 0); } while (0)
; #define PG8_LDA(dst, b, h) do { _Pragma("unroll") for (int m = 0; m < 4; ++m) _Pragma("unroll") for (int k = 0; k < 2; ++k) dst[m][k] = *(const PG8_LAS bf16x8*)(lds + PG8_SA(b, h) + aoff + m * 2048 + k * 1024); } while (0)
; #define PG8_MMA(ai, bj, At, Bt) do { __builtin_amdgcn_s_setprio(1); _Pragma("unroll") for (int m = 0; m < 4; ++m) _Pragma("unroll") for (int n = 0; n < 2; ++n) _Pragma("unroll") for (int k = 0; k < 2; ++k) \
;         acc[ai][bj][m][n] = __builtin_amdgcn_mfma_f32_16x16x32_bf16(Bt[n][k], At[m][k], acc[ai][bj][m][n], 0, 0, 0); __builtin_amdgcn_s_setprio(0); } while (0)
; #define PG8_WAIT_V(n) asm volatile("s_waitcnt vmcnt(" #n ")" ::: "memory")
; #define PG8_WAIT_L(n) asm volatile("s_waitcnt lgkmcnt(" #n ")" ::: "memory")
; #define PG8_BAR __builtin_amdgcn_s_barrier()
; #define PG8_SCHED __builtin_amdgcn_sched_barrier(0)
;     ...
;         for (int t = 0; t < nt; t += 2) {
;     ...
;             PG8_LDA(At, 1, 1); PG8_STAGE(PG8_SB(1, 0), b3, voffB); PG8_STAGE(PG8_SB(1, 1), b3 + hstep, voffB); PG8_STAGE(PG8_SA(1, 0), a3, voffA);
;             PG8_WAIT_V(8); PG8_WAIT_L(0); PG8_BAR; PG8_MMA(1, 0, At, B0); PG8_MMA(1, 1, At, B1); PG8_BAR; PG8_SCHED;
	s_setprio 0
	ds_read_b128 v[164:167], v234 offset:49152
	ds_read_b128 v[168:171], v234 offset:50176
	ds_read_b128 v[172:175], v234 offset:51200
	ds_read_b128 v[176:179], v234 offset:52224
	ds_read_b128 v[180:183], v234 offset:53248
	ds_read_b128 v[184:187], v234 offset:54272
	ds_read_b128 v[206:209], v234 offset:55296
	ds_read_b128 v[210:213], v234 offset:56320
	s_add_i32 s48, s48, s5
	v_lshl_add_u64 v[198:199], v[198:199], 0, s[66:67]
	s_mov_b32 m0, s48
	s_nop 0
	global_load_lds_dwordx4 v[198:199], off
	s_add_i32 m0, s48, 0x2000
	s_add_u32 s68, s68, 0x80080
	v_lshl_add_u64 v[198:199], v[214:215], 0, s[66:67]
	s_addc_u32 s69, s69, 0
	s_add_i32 s48, s49, s5
	global_load_lds_dwordx4 v[198:199], off
	v_lshl_add_u64 v[198:199], s[68:69], 0, v[200:201]
	s_mov_b32 m0, s48
	s_nop 0
	global_load_lds_dwordx4 v[198:199], off
	v_lshl_add_u64 v[198:199], s[68:69], 0, v[188:189]
	s_add_i32 m0, s48, 0x2000
	s_nop 0
	global_load_lds_dwordx4 v[198:199], off
	v_lshl_add_u64 v[198:199], v[216:217], 0, s[66:67]
	s_mov_b32 m0, s55
	s_nop 0
	global_load_lds_dwordx4 v[198:199], off
	v_lshl_add_u64 v[198:199], v[218:219], 0, s[66:67]
	s_mov_b32 m0, s56
	s_nop 0
	global_load_lds_dwordx4 v[198:199], off
	s_waitcnt vmcnt(8)
	s_waitcnt lgkmcnt(0)
	s_setprio 1
	s_barrier
	v_mfma_f32_16x16x32_bf16 v[64:67], v[108:111], v[164:167], v[64:67]
	v_mfma_f32_16x16x32_bf16 v[60:63], v[128:131], v[164:167], v[60:63]
	v_mfma_f32_16x16x32_bf16 v[48:51], v[108:111], v[172:175], v[48:51]
	v_mfma_f32_16x16x32_bf16 v[44:47], v[128:131], v[172:175], v[44:47]
	v_mfma_f32_16x16x32_bf16 v[32:35], v[108:111], v[180:183], v[32:35]
	v_mfma_f32_16x16x32_bf16 v[28:31], v[128:131], v[180:183], v[28:31]
	v_mfma_f32_16x16x32_bf16 v[16:19], v[108:111], v[206:209], v[16:19]
	v_mfma_f32_16x16x32_bf16 v[12:15], v[128:131], v[206:209], v[12:15]
	v_mfma_f32_16x16x32_bf16 v[64:67], v[112:115], v[168:171], v[64:67]
	v_mfma_f32_16x16x32_bf16 v[60:63], v[136:139], v[168:171], v[60:63]
	v_mfma_f32_16x16x32_bf16 v[48:51], v[112:115], v[176:179], v[48:51]
	v_mfma_f32_16x16x32_bf16 v[44:47], v[136:139], v[176:179], v[44:47]
	v_mfma_f32_16x16x32_bf16 v[32:35], v[112:115], v[184:187], v[32:35]
	v_mfma_f32_16x16x32_bf16 v[28:31], v[136:139], v[184:187], v[28:31]
	v_mfma_f32_16x16x32_bf16 v[16:19], v[112:115], v[210:213], v[16:19]
	v_mfma_f32_16x16x32_bf16 v[12:15], v[136:139], v[210:213], v[12:15]
	s_setprio 0
	s_setprio 1
	v_mfma_f32_16x16x32_bf16 v[56:59], v[148:151], v[164:167], v[56:59]
	v_mfma_f32_16x16x32_bf16 v[52:55], v[156:159], v[164:167], v[52:55]
	v_mfma_f32_16x16x32_bf16 v[40:43], v[148:151], v[172:175], v[40:43]
	v_mfma_f32_16x16x32_bf16 v[36:39], v[156:159], v[172:175], v[36:39]
	v_mfma_f32_16x16x32_bf16 v[24:27], v[148:151], v[180:183], v[24:27]
	v_mfma_f32_16x16x32_bf16 v[20:23], v[156:159], v[180:183], v[20:23]
	v_mfma_f32_16x16x32_bf16 v[8:11], v[148:151], v[206:209], v[8:11]
	v_mfma_f32_16x16x32_bf16 v[4:7], v[156:159], v[206:209], v[4:7]
	v_mfma_f32_16x16x32_bf16 v[56:59], v[152:155], v[168:171], v[56:59]
	v_mfma_f32_16x16x32_bf16 v[52:55], v[160:163], v[168:171], v[52:55]
	v_mfma_f32_16x16x32_bf16 v[40:43], v[152:155], v[176:179], v[40:43]
	v_mfma_f32_16x16x32_bf16 v[36:39], v[160:163], v[176:179], v[36:39]
	v_mfma_f32_16x16x32_bf16 v[24:27], v[152:155], v[184:187], v[24:27]
	v_mfma_f32_16x16x32_bf16 v[20:23], v[160:163], v[184:187], v[20:23]
	v_mfma_f32_16x16x32_bf16 v[8:11], v[152:155], v[210:213], v[8:11]
	v_mfma_f32_16x16x32_bf16 v[4:7], v[160:163], v[210:213], v[4:7]
	s_barrier
	s_setprio 0
	s_add_i32 s81, s81, 2
	s_add_u32 s78, s78, 0x100
	s_addc_u32 s79, s79, 0
	s_add_u32 s62, s62, 0x100
	s_addc_u32 s63, s63, 0
	s_cmp_gt_u32 s81, 29
	s_cbranch_scc0 .LBB0_454
	s_and_b64 vcc, exec, s[12:13]
	s_cbranch_vccz .LBB0_457
	s_barrier

; #define PG8_STAGE(bufoff, gbase, voff) do { _Pragma("unroll") for (int _i = 0; _i < 2; ++_i) \
;         __builtin_amdgcn_global_load_lds((const unsigned*)((const char*)(gbase) + (voff)[_i]), (PG8_LAS unsigned*)(lds + (bufoff) + ldsw + _i * 8192), 16, 0, 0); } while (0)
; #define PG8_LDA(dst, b, h) do { _Pragma("unroll") for (int m = 0; m < 4; ++m) _Pragma("unroll") for (int k = 0; k < 2; ++k) dst[m][k] = *(const PG8_LAS bf16x8*)(lds + PG8_SA(b, h) + aoff + m * 2048 + k * 1024); } while (0)
; #define PG8_LDB(dst, b, h) do { _Pragma("unroll") for (int n = 0; n < 2; ++n) _Pragma("unroll") for (int k = 0; k < 2; ++k) dst[n][k] = *(const PG8_LAS bf16x8*)(lds + PG8_SB(b, h) + boff + n * 2048 + k * 1024); } while (0)
; #define PG8_MMA(ai, bj, At, Bt) do { __builtin_amdgcn_s_setprio(1); _Pragma("unroll") for (int m = 0; m < 4; ++m) _Pragma("unroll") for (int n = 0; n < 2; ++n) _Pragma("unroll") for (int k = 0; k < 2; ++k) \
;         acc[ai][bj][m][n] = __builtin_amdgcn_mfma_f32_16x16x32_bf16(Bt[n][k], At[m][k], acc[ai][bj][m][n], 0, 0, 0); __builtin_amdgcn_s_setprio(0); } while (0)
; #define PG8_WAIT_V(n) asm volatile("s_waitcnt vmcnt(" #n ")" ::: "memory")
; #define PG8_WAIT_L(n) asm volatile("s_waitcnt lgkmcnt(" #n ")" ::: "memory")
; #define PG8_BAR __builtin_amdgcn_s_barrier()
; #define PG8_SCHED __builtin_amdgcn_sched_barrier(0)
;     ...
;             PG8_LDB(B0, 0, 0); PG8_LDB(B1, 0, 1); PG8_SCHED; PG8_LDA(At, 0, 0); PG8_STAGE(PG8_SA(1, 1), a1 + hstep, voffA);
;             PG8_WAIT_V(8); PG8_WAIT_L(0); PG8_BAR; PG8_MMA(0, 0, At, B0); PG8_MMA(0, 1, At, B1); PG8_BAR; PG8_SCHED;
;             PG8_LDA(At, 0, 1); PG8_STAGE(PG8_SB(0, 0), b2, voffB); PG8_STAGE(PG8_SB(0, 1), b2 + hstep, voffB); PG8_STAGE(PG8_SA(0, 0), a2, voffA);
;             PG8_WAIT_V(8); PG8_WAIT_L(0); PG8_BAR; PG8_MMA(1, 0, At, B0); PG8_MMA(1, 1, At, B1); PG8_BAR; PG8_SCHED;
.LBB0_542:
	ds_read_b128 v[106:109], v251
	ds_read_b128 v[110:113], v251 offset:1024
	ds_read_b128 v[114:117], v251 offset:2048
	ds_read_b128 v[118:121], v251 offset:3072
	ds_read_b128 v[122:125], v251 offset:16384
	ds_read_b128 v[126:129], v251 offset:17408
	ds_read_b128 v[130:133], v251 offset:18432
	ds_read_b128 v[134:137], v251 offset:19456
	ds_read_b128 v[166:169], v222
	ds_read_b128 v[170:173], v222 offset:1024
	ds_read_b128 v[174:177], v222 offset:2048
	ds_read_b128 v[178:181], v222 offset:3072
	ds_read_b128 v[194:197], v222 offset:4096
	ds_read_b128 v[206:209], v222 offset:5120
	ds_read_b128 v[210:213], v222 offset:6144
	ds_read_b128 v[214:217], v222 offset:7168
	s_add_u32 s12, s10, 0xfff80080
	s_addc_u32 s13, s11, -1
	s_add_i32 s48, 0, 0x10000
	s_cmp_eq_u32 s89, 28
	s_cselect_b32 s15, s25, s13
	s_cselect_b32 s14, s69, s12
	s_cselect_b32 s13, s76, s83
	s_cselect_b32 s12, s77, s82
	s_add_i32 s49, 0, 0x14000
	v_lshl_add_u64 v[100:101], s[10:11], 0, v[190:191]
	s_add_i32 m0, s1, 0xc000
	s_nop 0
	global_load_lds_dwordx4 v[100:101], off
	v_lshl_add_u64 v[100:101], s[10:11], 0, v[192:193]
	s_add_i32 m0, s1, 0xe000
	s_nop 0
	global_load_lds_dwordx4 v[100:101], off
	s_waitcnt vmcnt(8)
	s_waitcnt lgkmcnt(0)
	s_setprio 1
	s_barrier
	v_mfma_f32_16x16x32_bf16 v[4:7], v[106:109], v[166:169], v[4:7]
	v_mfma_f32_16x16x32_bf16 v[72:75], v[114:117], v[166:169], v[72:75]
	v_mfma_f32_16x16x32_bf16 v[162:165], v[106:109], v[174:177], v[162:165]
	v_mfma_f32_16x16x32_bf16 v[60:63], v[114:117], v[174:177], v[60:63]
	v_mfma_f32_16x16x32_bf16 v[158:161], v[106:109], v[194:197], v[158:161]
	v_mfma_f32_16x16x32_bf16 v[56:59], v[114:117], v[194:197], v[56:59]
	v_mfma_f32_16x16x32_bf16 v[96:99], v[106:109], v[210:213], v[96:99]
	v_mfma_f32_16x16x32_bf16 v[76:79], v[114:117], v[210:213], v[76:79]
	v_mfma_f32_16x16x32_bf16 v[4:7], v[110:113], v[170:173], v[4:7]
	v_mfma_f32_16x16x32_bf16 v[72:75], v[118:121], v[170:173], v[72:75]
	v_mfma_f32_16x16x32_bf16 v[162:165], v[110:113], v[178:181], v[162:165]
	v_mfma_f32_16x16x32_bf16 v[60:63], v[118:121], v[178:181], v[60:63]
	v_mfma_f32_16x16x32_bf16 v[158:161], v[110:113], v[206:209], v[158:161]
	v_mfma_f32_16x16x32_bf16 v[56:59], v[118:121], v[206:209], v[56:59]
	v_mfma_f32_16x16x32_bf16 v[96:99], v[110:113], v[214:217], v[96:99]
	v_mfma_f32_16x16x32_bf16 v[76:79], v[118:121], v[214:217], v[76:79]
	s_setprio 0
	s_setprio 1
	v_mfma_f32_16x16x32_bf16 v[8:11], v[122:125], v[166:169], v[8:11]
	v_mfma_f32_16x16x32_bf16 v[64:67], v[130:133], v[166:169], v[64:67]
	v_mfma_f32_16x16x32_bf16 v[154:157], v[122:125], v[174:177], v[154:157]
	v_mfma_f32_16x16x32_bf16 v[52:55], v[130:133], v[174:177], v[52:55]
	v_mfma_f32_16x16x32_bf16 v[150:153], v[122:125], v[194:197], v[150:153]
	v_mfma_f32_16x16x32_bf16 v[48:51], v[130:133], v[194:197], v[48:51]
	v_mfma_f32_16x16x32_bf16 v[92:95], v[122:125], v[210:213], v[92:95]
	v_mfma_f32_16x16x32_bf16 v[68:71], v[130:133], v[210:213], v[68:71]
	v_mfma_f32_16x16x32_bf16 v[8:11], v[126:129], v[170:173], v[8:11]
	v_mfma_f32_16x16x32_bf16 v[64:67], v[134:137], v[170:173], v[64:67]
	v_mfma_f32_16x16x32_bf16 v[154:157], v[126:129], v[178:181], v[154:157]
	v_mfma_f32_16x16x32_bf16 v[52:55], v[134:137], v[178:181], v[52:55]
	v_mfma_f32_16x16x32_bf16 v[150:153], v[126:129], v[206:209], v[150:153]
	v_mfma_f32_16x16x32_bf16 v[48:51], v[134:137], v[206:209], v[48:51]
	v_mfma_f32_16x16x32_bf16 v[92:95], v[126:129], v[214:217], v[92:95]
	v_mfma_f32_16x16x32_bf16 v[68:71], v[134:137], v[214:217], v[68:71]
	s_barrier
	s_setprio 0
	ds_read_b128 v[166:169], v222 offset:16384
	ds_read_b128 v[170:173], v222 offset:17408
	ds_read_b128 v[174:177], v222 offset:18432
	ds_read_b128 v[178:181], v222 offset:19456
	ds_read_b128 v[194:197], v222 offset:20480
	ds_read_b128 v[206:209], v222 offset:21504
	ds_read_b128 v[210:213], v222 offset:22528
	ds_read_b128 v[214:217], v222 offset:23552
	s_add_i32 s48, s48, s0
	v_lshl_add_u64 v[198:199], s[12:13], 0, v[186:187]
	s_mov_b32 m0, s48
	s_nop 0
	global_load_lds_dwordx4 v[198:199], off
	s_add_i32 m0, s48, 0x2000
	s_add_u32 vcc_lo, s12, 0x80000
	v_lshl_add_u64 v[218:219], s[12:13], 0, v[182:183]
	s_addc_u32 vcc_hi, s13, 0
	s_add_i32 s48, s49, s0
	global_load_lds_dwordx4 v[218:219], off
	v_lshl_add_u64 v[100:101], vcc, 0, v[186:187]
	s_mov_b32 m0, s48
	v_lshl_add_u64 v[224:225], s[14:15], 0, v[188:189]
	global_load_lds_dwordx4 v[100:101], off
	v_lshl_add_u64 v[100:101], vcc, 0, v[182:183]
	s_add_i32 m0, s48, 0x2000
	v_lshl_add_u64 v[232:233], s[14:15], 0, v[184:185]
	global_load_lds_dwordx4 v[100:101], off
	s_mov_b32 m0, s1
	s_nop 0
	global_load_lds_dwordx4 v[224:225], off
	s_mov_b32 m0, s4
	s_nop 0
	global_load_lds_dwordx4 v[232:233], off
	s_waitcnt vmcnt(8)
	s_waitcnt lgkmcnt(0)
	s_setprio 1
	s_barrier
; #define PG8_STAGE(bufoff, gbase, voff) do { _Pragma("unroll") for (int _i = 0; _i < 2; ++_i) \
;         __builtin_amdgcn_global_load_lds((const unsigned*)((const char*)(gbase) + (voff)[_i]), (PG8_LAS unsigned*)(lds + (bufoff) + ldsw + _i * 8192), 16, 0, 0); } while (0)
; #define PG8_LDA(dst, b, h) do { _Pragma("unroll") for (int m = 0; m < 4; ++m) _Pragma("unroll") for (int k = 0; k < 2; ++k) dst[m][k] = *(const PG8_LAS bf16x8*)(lds + PG8_SA(b, h) + aoff + m * 2048 + k * 1024); } while (0)
; #define PG8_LDB(dst, b, h) do { _Pragma("unroll") for (int n = 0; n < 2; ++n) _Pragma("unroll") for (int k = 0; k < 2; ++k) dst[n][k] = *(const PG8_LAS bf16x8*)(lds + PG8_SB(b, h) + boff + n * 2048 + k * 1024); } while (0)
; #define PG8_MMA(ai, bj, At, Bt) do { __builtin_amdgcn_s_setprio(1); _Pragma("unroll") for (int m = 0; m < 4; ++m) _Pragma("unroll") for (int n = 0; n < 2; ++n) _Pragma("unroll") for (int k = 0; k < 2; ++k) \
;         acc[ai][bj][m][n] = __builtin_amdgcn_mfma_f32_16x16x32_bf16(Bt[n][k], At[m][k], acc[ai][bj][m][n], 0, 0, 0); __builtin_amdgcn_s_setprio(0); } while (0)
; #define PG8_WAIT_V(n) asm volatile("s_waitcnt vmcnt(" #n ")" ::: "memory")
; #define PG8_WAIT_L(n) asm volatile("s_waitcnt lgkmcnt(" #n ")" ::: "memory")
; #define PG8_BAR __builtin_amdgcn_s_barrier()
; #define PG8_SCHED __builtin_amdgcn_sched_barrier(0)
;     ...
;             PG8_WAIT_V(8); PG8_WAIT_L(0); PG8_BAR; PG8_MMA(1, 0, At, B0); PG8_MMA(1, 1, At, B1); PG8_BAR; PG8_SCHED;
;             PG8_LDB(B0, 1, 0); PG8_LDB(B1, 1, 1); PG8_SCHED; PG8_LDA(At, 1, 0); PG8_STAGE(PG8_SA(0, 1), a2 + hstep, voffA);
;             PG8_WAIT_V(8); PG8_WAIT_L(0); PG8_BAR; PG8_MMA(0, 0, At, B0); PG8_MMA(0, 1, At, B1); PG8_BAR; PG8_SCHED;
	v_mfma_f32_16x16x32_bf16 v[146:149], v[106:109], v[166:169], v[146:149]
	v_mfma_f32_16x16x32_bf16 v[44:47], v[114:117], v[166:169], v[44:47]
	v_mfma_f32_16x16x32_bf16 v[142:145], v[106:109], v[174:177], v[142:145]
	v_mfma_f32_16x16x32_bf16 v[40:43], v[114:117], v[174:177], v[40:43]
	v_mfma_f32_16x16x32_bf16 v[138:141], v[106:109], v[194:197], v[138:141]
	v_mfma_f32_16x16x32_bf16 v[36:39], v[114:117], v[194:197], v[36:39]
	v_mfma_f32_16x16x32_bf16 v[80:83], v[106:109], v[210:213], v[80:83]
	v_mfma_f32_16x16x32_bf16 v[20:23], v[114:117], v[210:213], v[20:23]
	v_mfma_f32_16x16x32_bf16 v[146:149], v[110:113], v[170:173], v[146:149]
	v_mfma_f32_16x16x32_bf16 v[44:47], v[118:121], v[170:173], v[44:47]
	v_mfma_f32_16x16x32_bf16 v[142:145], v[110:113], v[178:181], v[142:145]
	v_mfma_f32_16x16x32_bf16 v[40:43], v[118:121], v[178:181], v[40:43]
	v_mfma_f32_16x16x32_bf16 v[138:141], v[110:113], v[206:209], v[138:141]
	v_mfma_f32_16x16x32_bf16 v[36:39], v[118:121], v[206:209], v[36:39]
	v_mfma_f32_16x16x32_bf16 v[80:83], v[110:113], v[214:217], v[80:83]
	v_mfma_f32_16x16x32_bf16 v[20:23], v[118:121], v[214:217], v[20:23]
	s_setprio 0
	s_setprio 1
	v_mfma_f32_16x16x32_bf16 v[100:103], v[122:125], v[166:169], v[102:105]
	v_mfma_f32_16x16x32_bf16 v[32:35], v[130:133], v[166:169], v[32:35]
	v_mfma_f32_16x16x32_bf16 v[88:91], v[122:125], v[174:177], v[88:91]
	v_mfma_f32_16x16x32_bf16 v[28:31], v[130:133], v[174:177], v[28:31]
	v_mfma_f32_16x16x32_bf16 v[84:87], v[122:125], v[194:197], v[84:87]
	v_mfma_f32_16x16x32_bf16 v[24:27], v[130:133], v[194:197], v[24:27]
	v_mfma_f32_16x16x32_bf16 v[16:19], v[122:125], v[210:213], v[16:19]
	v_mfma_f32_16x16x32_bf16 v[12:15], v[130:133], v[210:213], v[12:15]
	v_mfma_f32_16x16x32_bf16 v[100:103], v[126:129], v[170:173], v[100:103]
	v_mfma_f32_16x16x32_bf16 v[32:35], v[134:137], v[170:173], v[32:35]
	v_mfma_f32_16x16x32_bf16 v[88:91], v[126:129], v[178:181], v[88:91]
	v_mfma_f32_16x16x32_bf16 v[28:31], v[134:137], v[178:181], v[28:31]
	v_mfma_f32_16x16x32_bf16 v[84:87], v[126:129], v[206:209], v[84:87]
	v_mfma_f32_16x16x32_bf16 v[24:27], v[134:137], v[206:209], v[24:27]
	v_mfma_f32_16x16x32_bf16 v[16:19], v[126:129], v[214:217], v[16:19]
	v_mfma_f32_16x16x32_bf16 v[12:15], v[134:137], v[214:217], v[12:15]
	s_barrier
	s_setprio 0
	ds_read_b128 v[104:107], v251 offset:32768
	ds_read_b128 v[108:111], v251 offset:33792
	ds_read_b128 v[112:115], v251 offset:34816
	ds_read_b128 v[116:119], v251 offset:35840
	ds_read_b128 v[120:123], v251 offset:49152
	ds_read_b128 v[124:127], v251 offset:50176
	ds_read_b128 v[128:131], v251 offset:51200
	ds_read_b128 v[132:135], v251 offset:52224
	ds_read_b128 v[166:169], v222 offset:32768
	ds_read_b128 v[170:173], v222 offset:33792
	ds_read_b128 v[174:177], v222 offset:34816
	ds_read_b128 v[178:181], v222 offset:35840
	ds_read_b128 v[194:197], v222 offset:36864
	ds_read_b128 v[206:209], v222 offset:37888
	ds_read_b128 v[210:213], v222 offset:38912
	ds_read_b128 v[214:217], v222 offset:39936
	s_add_i32 s48, 0, 0x18000
	s_add_i32 s49, 0, 0x1c000
	s_add_u32 s14, s14, 0x80000
	s_addc_u32 s15, s15, 0
	s_mov_b32 m0, s5
	v_lshl_add_u64 v[136:137], s[14:15], 0, v[188:189]
	global_load_lds_dwordx4 v[136:137], off
	v_lshl_add_u64 v[136:137], s[14:15], 0, v[184:185]
	s_mov_b32 m0, s44
	s_nop 0
	global_load_lds_dwordx4 v[136:137], off
	s_waitcnt vmcnt(8)
	s_waitcnt lgkmcnt(0)
	s_setprio 1
	s_barrier
	v_mfma_f32_16x16x32_bf16 v[4:7], v[104:107], v[166:169], v[4:7]
	v_mfma_f32_16x16x32_bf16 v[72:75], v[112:115], v[166:169], v[72:75]
	v_mfma_f32_16x16x32_bf16 v[162:165], v[104:107], v[174:177], v[162:165]
	v_mfma_f32_16x16x32_bf16 v[60:63], v[112:115], v[174:177], v[60:63]
	v_mfma_f32_16x16x32_bf16 v[158:161], v[104:107], v[194:197], v[158:161]
	v_mfma_f32_16x16x32_bf16 v[56:59], v[112:115], v[194:197], v[56:59]
	v_mfma_f32_16x16x32_bf16 v[96:99], v[104:107], v[210:213], v[96:99]
	v_mfma_f32_16x16x32_bf16 v[76:79], v[112:115], v[210:213], v[76:79]
	v_mfma_f32_16x16x32_bf16 v[4:7], v[108:111], v[170:173], v[4:7]
	v_mfma_f32_16x16x32_bf16 v[72:75], v[116:119], v[170:173], v[72:75]
	v_mfma_f32_16x16x32_bf16 v[162:165], v[108:111], v[178:181], v[162:165]
	v_mfma_f32_16x16x32_bf16 v[60:63], v[116:119], v[178:181], v[60:63]
	v_mfma_f32_16x16x32_bf16 v[158:161], v[108:111], v[206:209], v[158:161]
	v_mfma_f32_16x16x32_bf16 v[56:59], v[116:119], v[206:209], v[56:59]
	v_mfma_f32_16x16x32_bf16 v[96:99], v[108:111], v[214:217], v[96:99]
	v_mfma_f32_16x16x32_bf16 v[76:79], v[116:119], v[214:217], v[76:79]
	s_setprio 0
	s_setprio 1
	v_mfma_f32_16x16x32_bf16 v[8:11], v[120:123], v[166:169], v[8:11]
	v_mfma_f32_16x16x32_bf16 v[64:67], v[128:131], v[166:169], v[64:67]
	v_mfma_f32_16x16x32_bf16 v[154:157], v[120:123], v[174:177], v[154:157]
	v_mfma_f32_16x16x32_bf16 v[52:55], v[128:131], v[174:177], v[52:55]
	v_mfma_f32_16x16x32_bf16 v[150:153], v[120:123], v[194:197], v[150:153]
	v_mfma_f32_16x16x32_bf16 v[48:51], v[128:131], v[194:197], v[48:51]
	v_mfma_f32_16x16x32_bf16 v[92:95], v[120:123], v[210:213], v[92:95]
	v_mfma_f32_16x16x32_bf16 v[68:71], v[128:131], v[210:213], v[68:71]
	v_mfma_f32_16x16x32_bf16 v[8:11], v[124:127], v[170:173], v[8:11]
	v_mfma_f32_16x16x32_bf16 v[64:67], v[132:135], v[170:173], v[64:67]
	v_mfma_f32_16x16x32_bf16 v[154:157], v[124:127], v[178:181], v[154:157]
	v_mfma_f32_16x16x32_bf16 v[52:55], v[132:135], v[178:181], v[52:55]
	v_mfma_f32_16x16x32_bf16 v[150:153], v[124:127], v[206:209], v[150:153]
	v_mfma_f32_16x16x32_bf16 v[48:51], v[132:135], v[206:209], v[48:51]
	v_mfma_f32_16x16x32_bf16 v[92:95], v[124:127], v[214:217], v[92:95]
	v_mfma_f32_16x16x32_bf16 v[68:71], v[132:135], v[214:217], v[68:71]
	s_barrier
; #define PG8_STAGE(bufoff, gbase, voff) do { _Pragma("unroll") for (int _i = 0; _i < 2; ++_i) \
;         __builtin_amdgcn_global_load_lds((const unsigned*)((const char*)(gbase) + (voff)[_i]), (PG8_LAS unsigned*)(lds + (bufoff) + ldsw + _i * 8192), 16, 0, 0); } while (0)
; #define PG8_LDA(dst, b, h) do { _Pragma("unroll") for (int m = 0; m < 4; ++m) _Pragma("unroll") for (int k = 0; k < 2; ++k) dst[m][k] = *(const PG8_LAS bf16x8*)(lds + PG8_SA(b, h) + aoff + m * 2048 + k * 1024); } while (0)
; #define PG8_MMA(ai, bj, At, Bt) do { __builtin_amdgcn_s_setprio(1); _Pragma("unroll") for (int m = 0; m < 4; ++m) _Pragma("unroll") for (int n = 0; n < 2; ++n) _Pragma("unroll") for (int k = 0; k < 2; ++k) \
;         acc[ai][bj][m][n] = __builtin_amdgcn_mfma_f32_16x16x32_bf16(Bt[n][k], At[m][k], acc[ai][bj][m][n], 0, 0, 0); __builtin_amdgcn_s_setprio(0); } while (0)
; #define PG8_WAIT_V(n) asm volatile("s_waitcnt vmcnt(" #n ")" ::: "memory")
; #define PG8_WAIT_L(n) asm volatile("s_waitcnt lgkmcnt(" #n ")" ::: "memory")
; #define PG8_BAR __builtin_amdgcn_s_barrier()
; #define PG8_SCHED __builtin_amdgcn_sched_barrier(0)
;     ...
;         for (int t = 0; t < nt; t += 2) {
;     ...
;             PG8_LDA(At, 1, 1); PG8_STAGE(PG8_SB(1, 0), b3, voffB); PG8_STAGE(PG8_SB(1, 1), b3 + hstep, voffB); PG8_STAGE(PG8_SA(1, 0), a3, voffA);
;             PG8_WAIT_V(8); PG8_WAIT_L(0); PG8_BAR; PG8_MMA(1, 0, At, B0); PG8_MMA(1, 1, At, B1); PG8_BAR; PG8_SCHED;
	s_setprio 0
	ds_read_b128 v[166:169], v222 offset:49152
	ds_read_b128 v[170:173], v222 offset:50176
	ds_read_b128 v[174:177], v222 offset:51200
	ds_read_b128 v[178:181], v222 offset:52224
	ds_read_b128 v[194:197], v222 offset:53248
	ds_read_b128 v[206:209], v222 offset:54272
	ds_read_b128 v[210:213], v222 offset:55296
	ds_read_b128 v[214:217], v222 offset:56320
	s_add_i32 s14, s48, s0
	v_lshl_add_u64 v[136:137], v[198:199], 0, s[66:67]
	s_mov_b32 m0, s14
	s_nop 0
	global_load_lds_dwordx4 v[136:137], off
	s_add_i32 m0, s14, 0x2000
	s_add_u32 s12, s12, 0x80080
	v_lshl_add_u64 v[136:137], v[218:219], 0, s[66:67]
	s_addc_u32 s13, s13, 0
	s_add_i32 s14, s49, s0
	global_load_lds_dwordx4 v[136:137], off
	v_lshl_add_u64 v[136:137], s[12:13], 0, v[186:187]
	s_mov_b32 m0, s14
	s_nop 0
	global_load_lds_dwordx4 v[136:137], off
	v_lshl_add_u64 v[136:137], s[12:13], 0, v[182:183]
	s_add_i32 m0, s14, 0x2000
	s_nop 0
	global_load_lds_dwordx4 v[136:137], off
	v_lshl_add_u64 v[136:137], v[224:225], 0, s[66:67]
	s_mov_b32 m0, s81
	s_nop 0
	global_load_lds_dwordx4 v[136:137], off
	v_lshl_add_u64 v[136:137], v[232:233], 0, s[66:67]
	s_mov_b32 m0, s42
	s_nop 0
	global_load_lds_dwordx4 v[136:137], off
	s_waitcnt vmcnt(8)
	s_waitcnt lgkmcnt(0)
	s_setprio 1
	s_barrier
	v_mfma_f32_16x16x32_bf16 v[146:149], v[104:107], v[166:169], v[146:149]
	v_mfma_f32_16x16x32_bf16 v[44:47], v[112:115], v[166:169], v[44:47]
	v_mfma_f32_16x16x32_bf16 v[142:145], v[104:107], v[174:177], v[142:145]
	v_mfma_f32_16x16x32_bf16 v[40:43], v[112:115], v[174:177], v[40:43]
	v_mfma_f32_16x16x32_bf16 v[136:139], v[104:107], v[194:197], v[138:141]
	v_mfma_f32_16x16x32_bf16 v[36:39], v[112:115], v[194:197], v[36:39]
	v_mfma_f32_16x16x32_bf16 v[80:83], v[104:107], v[210:213], v[80:83]
	v_mfma_f32_16x16x32_bf16 v[20:23], v[112:115], v[210:213], v[20:23]
	v_mfma_f32_16x16x32_bf16 v[146:149], v[108:111], v[170:173], v[146:149]
	v_mfma_f32_16x16x32_bf16 v[44:47], v[116:119], v[170:173], v[44:47]
	v_mfma_f32_16x16x32_bf16 v[142:145], v[108:111], v[178:181], v[142:145]
	v_mfma_f32_16x16x32_bf16 v[40:43], v[116:119], v[178:181], v[40:43]
	v_mfma_f32_16x16x32_bf16 v[138:141], v[108:111], v[206:209], v[136:139]
	v_mfma_f32_16x16x32_bf16 v[36:39], v[116:119], v[206:209], v[36:39]
	v_mfma_f32_16x16x32_bf16 v[80:83], v[108:111], v[214:217], v[80:83]
	v_mfma_f32_16x16x32_bf16 v[20:23], v[116:119], v[214:217], v[20:23]
	s_setprio 0
	s_setprio 1
	v_mfma_f32_16x16x32_bf16 v[100:103], v[120:123], v[166:169], v[100:103]
	v_mfma_f32_16x16x32_bf16 v[32:35], v[128:131], v[166:169], v[32:35]
	v_mfma_f32_16x16x32_bf16 v[88:91], v[120:123], v[174:177], v[88:91]
	v_mfma_f32_16x16x32_bf16 v[28:31], v[128:131], v[174:177], v[28:31]
	v_mfma_f32_16x16x32_bf16 v[84:87], v[120:123], v[194:197], v[84:87]
	v_mfma_f32_16x16x32_bf16 v[24:27], v[128:131], v[194:197], v[24:27]
	v_mfma_f32_16x16x32_bf16 v[16:19], v[120:123], v[210:213], v[16:19]
	v_mfma_f32_16x16x32_bf16 v[12:15], v[128:131], v[210:213], v[12:15]
	v_mfma_f32_16x16x32_bf16 v[102:105], v[124:127], v[170:173], v[100:103]
	v_mfma_f32_16x16x32_bf16 v[32:35], v[132:135], v[170:173], v[32:35]
	v_mfma_f32_16x16x32_bf16 v[88:91], v[124:127], v[178:181], v[88:91]
	v_mfma_f32_16x16x32_bf16 v[28:31], v[132:135], v[178:181], v[28:31]
	v_mfma_f32_16x16x32_bf16 v[84:87], v[124:127], v[206:209], v[84:87]
	v_mfma_f32_16x16x32_bf16 v[24:27], v[132:135], v[206:209], v[24:27]
	v_mfma_f32_16x16x32_bf16 v[16:19], v[124:127], v[214:217], v[16:19]
	v_mfma_f32_16x16x32_bf16 v[12:15], v[132:135], v[214:217], v[12:15]
	s_barrier
	s_setprio 0
	s_add_i32 s89, s89, 2
	s_add_u32 s10, s10, 0x100
	s_addc_u32 s11, s11, 0
	s_add_u32 s82, s82, 0x100
	s_addc_u32 s83, s83, 0
	s_cmp_gt_u32 s89, 29
	s_cbranch_scc0 .LBB0_542
	s_and_b64 vcc, exec, s[70:71]
	s_cbranch_vccz .LBB0_545
	s_barrier

; #define PG8_STAGE(bufoff, gbase, voff) do { _Pragma("unroll") for (int _i = 0; _i < 2; ++_i) \
;         __builtin_amdgcn_global_load_lds((const unsigned*)((const char*)(gbase) + (voff)[_i]), (PG8_LAS unsigned*)(lds + (bufoff) + ldsw + _i * 8192), 16, 0, 0); } while (0)
; #define PG8_LDA(dst, b, h) do { _Pragma("unroll") for (int m = 0; m < 4; ++m) _Pragma("unroll") for (int k = 0; k < 2; ++k) dst[m][k] = *(const PG8_LAS bf16x8*)(lds + PG8_SA(b, h) + aoff + m * 2048 + k * 1024); } while (0)
; #define PG8_LDB(dst, b, h) do { _Pragma("unroll") for (int n = 0; n < 2; ++n) _Pragma("unroll") for (int k = 0; k < 2; ++k) dst[n][k] = *(const PG8_LAS bf16x8*)(lds + PG8_SB(b, h) + boff + n * 2048 + k * 1024); } while (0)
; #define PG8_MMA(ai, bj, At, Bt) do { __builtin_amdgcn_s_setprio(1); _Pragma("unroll") for (int m = 0; m < 4; ++m) _Pragma("unroll") for (int n = 0; n < 2; ++n) _Pragma("unroll") for (int k = 0; k < 2; ++k) \
;         acc[ai][bj][m][n] = __builtin_amdgcn_mfma_f32_16x16x32_bf16(Bt[n][k], At[m][k], acc[ai][bj][m][n], 0, 0, 0); __builtin_amdgcn_s_setprio(0); } while (0)
; #define PG8_WAIT_V(n) asm volatile("s_waitcnt vmcnt(" #n ")" ::: "memory")
; #define PG8_WAIT_L(n) asm volatile("s_waitcnt lgkmcnt(" #n ")" ::: "memory")
; #define PG8_BAR __builtin_amdgcn_s_barrier()
; #define PG8_SCHED __builtin_amdgcn_sched_barrier(0)
;     ...
;             PG8_LDB(B0, 0, 0); PG8_LDB(B1, 0, 1); PG8_SCHED; PG8_LDA(At, 0, 0); PG8_STAGE(PG8_SA(1, 1), a1 + hstep, voffA);
;             PG8_WAIT_V(8); PG8_WAIT_L(0); PG8_BAR; PG8_MMA(0, 0, At, B0); PG8_MMA(0, 1, At, B1); PG8_BAR; PG8_SCHED;
;             PG8_LDA(At, 0, 1); PG8_STAGE(PG8_SB(0, 0), b2, voffB); PG8_STAGE(PG8_SB(0, 1), b2 + hstep, voffB); PG8_STAGE(PG8_SA(0, 0), a2, voffA);
;             PG8_WAIT_V(8); PG8_WAIT_L(0); PG8_BAR; PG8_MMA(1, 0, At, B0); PG8_MMA(1, 1, At, B1); PG8_BAR; PG8_SCHED;
.LBB0_667:
	ds_read_b128 v[108:111], v251
	ds_read_b128 v[112:115], v251 offset:1024
	ds_read_b128 v[128:131], v251 offset:2048
	ds_read_b128 v[136:139], v251 offset:3072
	ds_read_b128 v[148:151], v251 offset:16384
	ds_read_b128 v[152:155], v251 offset:17408
	ds_read_b128 v[156:159], v251 offset:18432
	ds_read_b128 v[160:163], v251 offset:19456
	ds_read_b128 v[164:167], v234
	ds_read_b128 v[168:171], v234 offset:1024
	ds_read_b128 v[172:175], v234 offset:2048
	ds_read_b128 v[176:179], v234 offset:3072
	ds_read_b128 v[180:183], v234 offset:4096
	ds_read_b128 v[184:187], v234 offset:5120
	ds_read_b128 v[206:209], v234 offset:6144
	ds_read_b128 v[210:213], v234 offset:7168
	s_add_u32 s68, s62, 0x100
	s_addc_u32 s69, s63, 0
	s_add_i32 s48, 0, 0x10000
	s_cmpk_eq_i32 s78, 0x54
	s_cselect_b32 s77, s11, s69
	s_cselect_b32 s76, s10, s68
	s_cselect_b32 s71, s61, s75
	s_cselect_b32 s70, s60, s73
	s_add_i32 s49, 0, 0x14000
	v_lshl_add_u64 v[198:199], s[62:63], 0, v[196:197]
	s_add_i32 m0, s6, 0xc000
	s_nop 0
	global_load_lds_dwordx4 v[198:199], off
	v_lshl_add_u64 v[198:199], s[62:63], 0, v[194:195]
	s_add_i32 m0, s6, 0xe000
	s_nop 0
	global_load_lds_dwordx4 v[198:199], off
	s_waitcnt vmcnt(8)
	s_waitcnt lgkmcnt(0)
	s_setprio 1
	s_barrier
	v_mfma_f32_16x16x32_bf16 v[144:147], v[108:111], v[164:167], v[144:147]
	v_mfma_f32_16x16x32_bf16 v[140:143], v[128:131], v[164:167], v[140:143]
	v_mfma_f32_16x16x32_bf16 v[120:123], v[108:111], v[172:175], v[120:123]
	v_mfma_f32_16x16x32_bf16 v[116:119], v[128:131], v[172:175], v[116:119]
	v_mfma_f32_16x16x32_bf16 v[96:99], v[108:111], v[180:183], v[96:99]
	v_mfma_f32_16x16x32_bf16 v[92:95], v[128:131], v[180:183], v[92:95]
	v_mfma_f32_16x16x32_bf16 v[80:83], v[108:111], v[206:209], v[80:83]
	v_mfma_f32_16x16x32_bf16 v[76:79], v[128:131], v[206:209], v[76:79]
	v_mfma_f32_16x16x32_bf16 v[144:147], v[112:115], v[168:171], v[144:147]
	v_mfma_f32_16x16x32_bf16 v[140:143], v[136:139], v[168:171], v[140:143]
	v_mfma_f32_16x16x32_bf16 v[120:123], v[112:115], v[176:179], v[120:123]
	v_mfma_f32_16x16x32_bf16 v[116:119], v[136:139], v[176:179], v[116:119]
	v_mfma_f32_16x16x32_bf16 v[96:99], v[112:115], v[184:187], v[96:99]
	v_mfma_f32_16x16x32_bf16 v[92:95], v[136:139], v[184:187], v[92:95]
	v_mfma_f32_16x16x32_bf16 v[80:83], v[112:115], v[210:213], v[80:83]
	v_mfma_f32_16x16x32_bf16 v[76:79], v[136:139], v[210:213], v[76:79]
	s_setprio 0
	s_setprio 1
	v_mfma_f32_16x16x32_bf16 v[132:135], v[148:151], v[164:167], v[132:135]
	v_mfma_f32_16x16x32_bf16 v[124:127], v[156:159], v[164:167], v[124:127]
	v_mfma_f32_16x16x32_bf16 v[104:107], v[148:151], v[172:175], v[104:107]
	v_mfma_f32_16x16x32_bf16 v[100:103], v[156:159], v[172:175], v[100:103]
	v_mfma_f32_16x16x32_bf16 v[88:91], v[148:151], v[180:183], v[88:91]
	v_mfma_f32_16x16x32_bf16 v[84:87], v[156:159], v[180:183], v[84:87]
	v_mfma_f32_16x16x32_bf16 v[72:75], v[148:151], v[206:209], v[72:75]
	v_mfma_f32_16x16x32_bf16 v[68:71], v[156:159], v[206:209], v[68:71]
	v_mfma_f32_16x16x32_bf16 v[132:135], v[152:155], v[168:171], v[132:135]
	v_mfma_f32_16x16x32_bf16 v[124:127], v[160:163], v[168:171], v[124:127]
	v_mfma_f32_16x16x32_bf16 v[104:107], v[152:155], v[176:179], v[104:107]
	v_mfma_f32_16x16x32_bf16 v[100:103], v[160:163], v[176:179], v[100:103]
	v_mfma_f32_16x16x32_bf16 v[88:91], v[152:155], v[184:187], v[88:91]
	v_mfma_f32_16x16x32_bf16 v[84:87], v[160:163], v[184:187], v[84:87]
	v_mfma_f32_16x16x32_bf16 v[72:75], v[152:155], v[210:213], v[72:75]
	v_mfma_f32_16x16x32_bf16 v[68:71], v[160:163], v[210:213], v[68:71]
	s_barrier
	s_setprio 0
	ds_read_b128 v[164:167], v234 offset:16384
	ds_read_b128 v[168:171], v234 offset:17408
	ds_read_b128 v[172:175], v234 offset:18432
	ds_read_b128 v[176:179], v234 offset:19456
	ds_read_b128 v[180:183], v234 offset:20480
	ds_read_b128 v[184:187], v234 offset:21504
	ds_read_b128 v[206:209], v234 offset:22528
	ds_read_b128 v[210:213], v234 offset:23552
	s_add_i32 s48, s48, s5
	v_lshl_add_u64 v[198:199], s[70:71], 0, v[200:201]
	s_mov_b32 m0, s48
	s_nop 0
	global_load_lds_dwordx4 v[198:199], off
	s_add_i32 m0, s48, 0x2000
	s_add_u32 s62, s70, 0x160000
	v_lshl_add_u64 v[214:215], s[70:71], 0, v[188:189]
	s_addc_u32 s63, s71, 0
	s_add_i32 s48, s49, s5
	global_load_lds_dwordx4 v[214:215], off
	v_lshl_add_u64 v[216:217], s[62:63], 0, v[200:201]
	s_mov_b32 m0, s48
	v_lshl_add_u64 v[218:219], s[76:77], 0, v[190:191]
	global_load_lds_dwordx4 v[216:217], off
	v_lshl_add_u64 v[216:217], s[62:63], 0, v[188:189]
	s_add_i32 m0, s48, 0x2000
	s_nop 0
	global_load_lds_dwordx4 v[216:217], off
	v_lshl_add_u64 v[216:217], s[76:77], 0, v[192:193]
	s_mov_b32 m0, s6
	s_nop 0
	global_load_lds_dwordx4 v[216:217], off
	s_mov_b32 m0, s7
	s_nop 0
	global_load_lds_dwordx4 v[218:219], off
	s_waitcnt vmcnt(8)
	s_waitcnt lgkmcnt(0)
	s_setprio 1
	s_barrier
; #define PG8_STAGE(bufoff, gbase, voff) do { _Pragma("unroll") for (int _i = 0; _i < 2; ++_i) \
;         __builtin_amdgcn_global_load_lds((const unsigned*)((const char*)(gbase) + (voff)[_i]), (PG8_LAS unsigned*)(lds + (bufoff) + ldsw + _i * 8192), 16, 0, 0); } while (0)
; #define PG8_LDA(dst, b, h) do { _Pragma("unroll") for (int m = 0; m < 4; ++m) _Pragma("unroll") for (int k = 0; k < 2; ++k) dst[m][k] = *(const PG8_LAS bf16x8*)(lds + PG8_SA(b, h) + aoff + m * 2048 + k * 1024); } while (0)
; #define PG8_LDB(dst, b, h) do { _Pragma("unroll") for (int n = 0; n < 2; ++n) _Pragma("unroll") for (int k = 0; k < 2; ++k) dst[n][k] = *(const PG8_LAS bf16x8*)(lds + PG8_SB(b, h) + boff + n * 2048 + k * 1024); } while (0)
; #define PG8_MMA(ai, bj, At, Bt) do { __builtin_amdgcn_s_setprio(1); _Pragma("unroll") for (int m = 0; m < 4; ++m) _Pragma("unroll") for (int n = 0; n < 2; ++n) _Pragma("unroll") for (int k = 0; k < 2; ++k) \
;         acc[ai][bj][m][n] = __builtin_amdgcn_mfma_f32_16x16x32_bf16(Bt[n][k], At[m][k], acc[ai][bj][m][n], 0, 0, 0); __builtin_amdgcn_s_setprio(0); } while (0)
; #define PG8_WAIT_V(n) asm volatile("s_waitcnt vmcnt(" #n ")" ::: "memory")
; #define PG8_WAIT_L(n) asm volatile("s_waitcnt lgkmcnt(" #n ")" ::: "memory")
; #define PG8_BAR __builtin_amdgcn_s_barrier()
; #define PG8_SCHED __builtin_amdgcn_sched_barrier(0)
;     ...
;             PG8_WAIT_V(8); PG8_WAIT_L(0); PG8_BAR; PG8_MMA(1, 0, At, B0); PG8_MMA(1, 1, At, B1); PG8_BAR; PG8_SCHED;
;             PG8_LDB(B0, 1, 0); PG8_LDB(B1, 1, 1); PG8_SCHED; PG8_LDA(At, 1, 0); PG8_STAGE(PG8_SA(0, 1), a2 + hstep, voffA);
;             PG8_WAIT_V(8); PG8_WAIT_L(0); PG8_BAR; PG8_MMA(0, 0, At, B0); PG8_MMA(0, 1, At, B1); PG8_BAR; PG8_SCHED;
	v_mfma_f32_16x16x32_bf16 v[64:67], v[108:111], v[164:167], v[64:67]
	v_mfma_f32_16x16x32_bf16 v[60:63], v[128:131], v[164:167], v[60:63]
	v_mfma_f32_16x16x32_bf16 v[48:51], v[108:111], v[172:175], v[48:51]
	v_mfma_f32_16x16x32_bf16 v[44:47], v[128:131], v[172:175], v[44:47]
	v_mfma_f32_16x16x32_bf16 v[32:35], v[108:111], v[180:183], v[32:35]
	v_mfma_f32_16x16x32_bf16 v[28:31], v[128:131], v[180:183], v[28:31]
	v_mfma_f32_16x16x32_bf16 v[16:19], v[108:111], v[206:209], v[16:19]
	v_mfma_f32_16x16x32_bf16 v[12:15], v[128:131], v[206:209], v[12:15]
	v_mfma_f32_16x16x32_bf16 v[64:67], v[112:115], v[168:171], v[64:67]
	v_mfma_f32_16x16x32_bf16 v[60:63], v[136:139], v[168:171], v[60:63]
	v_mfma_f32_16x16x32_bf16 v[48:51], v[112:115], v[176:179], v[48:51]
	v_mfma_f32_16x16x32_bf16 v[44:47], v[136:139], v[176:179], v[44:47]
	v_mfma_f32_16x16x32_bf16 v[32:35], v[112:115], v[184:187], v[32:35]
	v_mfma_f32_16x16x32_bf16 v[28:31], v[136:139], v[184:187], v[28:31]
	v_mfma_f32_16x16x32_bf16 v[16:19], v[112:115], v[210:213], v[16:19]
	v_mfma_f32_16x16x32_bf16 v[12:15], v[136:139], v[210:213], v[12:15]
	s_setprio 0
	s_setprio 1
	v_mfma_f32_16x16x32_bf16 v[56:59], v[148:151], v[164:167], v[56:59]
	v_mfma_f32_16x16x32_bf16 v[52:55], v[156:159], v[164:167], v[52:55]
	v_mfma_f32_16x16x32_bf16 v[40:43], v[148:151], v[172:175], v[40:43]
	v_mfma_f32_16x16x32_bf16 v[36:39], v[156:159], v[172:175], v[36:39]
	v_mfma_f32_16x16x32_bf16 v[24:27], v[148:151], v[180:183], v[24:27]
	v_mfma_f32_16x16x32_bf16 v[20:23], v[156:159], v[180:183], v[20:23]
	v_mfma_f32_16x16x32_bf16 v[8:11], v[148:151], v[206:209], v[8:11]
	v_mfma_f32_16x16x32_bf16 v[4:7], v[156:159], v[206:209], v[4:7]
	v_mfma_f32_16x16x32_bf16 v[56:59], v[152:155], v[168:171], v[56:59]
	v_mfma_f32_16x16x32_bf16 v[52:55], v[160:163], v[168:171], v[52:55]
	v_mfma_f32_16x16x32_bf16 v[40:43], v[152:155], v[176:179], v[40:43]
	v_mfma_f32_16x16x32_bf16 v[36:39], v[160:163], v[176:179], v[36:39]
	v_mfma_f32_16x16x32_bf16 v[24:27], v[152:155], v[184:187], v[24:27]
	v_mfma_f32_16x16x32_bf16 v[20:23], v[160:163], v[184:187], v[20:23]
	v_mfma_f32_16x16x32_bf16 v[8:11], v[152:155], v[210:213], v[8:11]
	v_mfma_f32_16x16x32_bf16 v[4:7], v[160:163], v[210:213], v[4:7]
	s_barrier
	s_setprio 0
	ds_read_b128 v[108:111], v251 offset:32768
	ds_read_b128 v[112:115], v251 offset:33792
	ds_read_b128 v[128:131], v251 offset:34816
	ds_read_b128 v[136:139], v251 offset:35840
	ds_read_b128 v[148:151], v251 offset:49152
	ds_read_b128 v[152:155], v251 offset:50176
	ds_read_b128 v[156:159], v251 offset:51200
	ds_read_b128 v[160:163], v251 offset:52224
	ds_read_b128 v[164:167], v234 offset:32768
	ds_read_b128 v[168:171], v234 offset:33792
	ds_read_b128 v[172:175], v234 offset:34816
	ds_read_b128 v[176:179], v234 offset:35840
	ds_read_b128 v[180:183], v234 offset:36864
	ds_read_b128 v[184:187], v234 offset:37888
	ds_read_b128 v[206:209], v234 offset:38912
	ds_read_b128 v[210:213], v234 offset:39936
	s_add_i32 s48, 0, 0x18000
	s_add_i32 s49, 0, 0x1c000
	s_add_u32 s62, s76, 0x160000
	s_addc_u32 s63, s77, 0
	s_mov_b32 m0, s20
	v_lshl_add_u64 v[220:221], s[62:63], 0, v[192:193]
	global_load_lds_dwordx4 v[220:221], off
	v_lshl_add_u64 v[220:221], s[62:63], 0, v[190:191]
	s_mov_b32 m0, s21
	s_nop 0
	global_load_lds_dwordx4 v[220:221], off
	s_waitcnt vmcnt(8)
	s_waitcnt lgkmcnt(0)
	s_setprio 1
	s_barrier
	v_mfma_f32_16x16x32_bf16 v[144:147], v[108:111], v[164:167], v[144:147]
	v_mfma_f32_16x16x32_bf16 v[140:143], v[128:131], v[164:167], v[140:143]
	v_mfma_f32_16x16x32_bf16 v[120:123], v[108:111], v[172:175], v[120:123]
	v_mfma_f32_16x16x32_bf16 v[116:119], v[128:131], v[172:175], v[116:119]
	v_mfma_f32_16x16x32_bf16 v[96:99], v[108:111], v[180:183], v[96:99]
	v_mfma_f32_16x16x32_bf16 v[92:95], v[128:131], v[180:183], v[92:95]
	v_mfma_f32_16x16x32_bf16 v[80:83], v[108:111], v[206:209], v[80:83]
	v_mfma_f32_16x16x32_bf16 v[76:79], v[128:131], v[206:209], v[76:79]
	v_mfma_f32_16x16x32_bf16 v[144:147], v[112:115], v[168:171], v[144:147]
	v_mfma_f32_16x16x32_bf16 v[140:143], v[136:139], v[168:171], v[140:143]
	v_mfma_f32_16x16x32_bf16 v[120:123], v[112:115], v[176:179], v[120:123]
	v_mfma_f32_16x16x32_bf16 v[116:119], v[136:139], v[176:179], v[116:119]
	v_mfma_f32_16x16x32_bf16 v[96:99], v[112:115], v[184:187], v[96:99]
	v_mfma_f32_16x16x32_bf16 v[92:95], v[136:139], v[184:187], v[92:95]
	v_mfma_f32_16x16x32_bf16 v[80:83], v[112:115], v[210:213], v[80:83]
	v_mfma_f32_16x16x32_bf16 v[76:79], v[136:139], v[210:213], v[76:79]
	s_setprio 0
	s_setprio 1
	v_mfma_f32_16x16x32_bf16 v[132:135], v[148:151], v[164:167], v[132:135]
	v_mfma_f32_16x16x32_bf16 v[124:127], v[156:159], v[164:167], v[124:127]
	v_mfma_f32_16x16x32_bf16 v[104:107], v[148:151], v[172:175], v[104:107]
	v_mfma_f32_16x16x32_bf16 v[100:103], v[156:159], v[172:175], v[100:103]
	v_mfma_f32_16x16x32_bf16 v[88:91], v[148:151], v[180:183], v[88:91]
	v_mfma_f32_16x16x32_bf16 v[84:87], v[156:159], v[180:183], v[84:87]
	v_mfma_f32_16x16x32_bf16 v[72:75], v[148:151], v[206:209], v[72:75]
	v_mfma_f32_16x16x32_bf16 v[68:71], v[156:159], v[206:209], v[68:71]
	v_mfma_f32_16x16x32_bf16 v[132:135], v[152:155], v[168:171], v[132:135]
	v_mfma_f32_16x16x32_bf16 v[124:127], v[160:163], v[168:171], v[124:127]
	v_mfma_f32_16x16x32_bf16 v[104:107], v[152:155], v[176:179], v[104:107]
	v_mfma_f32_16x16x32_bf16 v[100:103], v[160:163], v[176:179], v[100:103]
	v_mfma_f32_16x16x32_bf16 v[88:91], v[152:155], v[184:187], v[88:91]
	v_mfma_f32_16x16x32_bf16 v[84:87], v[160:163], v[184:187], v[84:87]
	v_mfma_f32_16x16x32_bf16 v[72:75], v[152:155], v[210:213], v[72:75]
	v_mfma_f32_16x16x32_bf16 v[68:71], v[160:163], v[210:213], v[68:71]
	s_barrier
; #define PG8_STAGE(bufoff, gbase, voff) do { _Pragma("unroll") for (int _i = 0; _i < 2; ++_i) \
;         __builtin_amdgcn_global_load_lds((const unsigned*)((const char*)(gbase) + (voff)[_i]), (PG8_LAS unsigned*)(lds + (bufoff) + ldsw + _i * 8192), 16, 0, 0); } while (0)
; #define PG8_LDA(dst, b, h) do { _Pragma("unroll") for (int m = 0; m < 4; ++m) _Pragma("unroll") for (int k = 0; k < 2; ++k) dst[m][k] = *(const PG8_LAS bf16x8*)(lds + PG8_SA(b, h) + aoff + m * 2048 + k * 1024); } while (0)
; #define PG8_MMA(ai, bj, At, Bt) do { __builtin_amdgcn_s_setprio(1); _Pragma("unroll") for (int m = 0; m < 4; ++m) _Pragma("unroll") for (int n = 0; n < 2; ++n) _Pragma("unroll") for (int k = 0; k < 2; ++k) \
;         acc[ai][bj][m][n] = __builtin_amdgcn_mfma_f32_16x16x32_bf16(Bt[n][k], At[m][k], acc[ai][bj][m][n], 0, 0, 0); __builtin_amdgcn_s_setprio(0); } while (0)
; #define PG8_WAIT_V(n) asm volatile("s_waitcnt vmcnt(" #n ")" ::: "memory")
; #define PG8_WAIT_L(n) asm volatile("s_waitcnt lgkmcnt(" #n ")" ::: "memory")
; #define PG8_BAR __builtin_amdgcn_s_barrier()
; #define PG8_SCHED __builtin_amdgcn_sched_barrier(0)
;     ...
;             PG8_LDA(At, 1, 1); PG8_STAGE(PG8_SB(1, 0), b3, voffB); PG8_STAGE(PG8_SB(1, 1), b3 + hstep, voffB); PG8_STAGE(PG8_SA(1, 0), a3, voffA);
;             PG8_WAIT_V(8); PG8_WAIT_L(0); PG8_BAR; PG8_MMA(1, 0, At, B0); PG8_MMA(1, 1, At, B1); PG8_BAR; PG8_SCHED;
	s_setprio 0
	ds_read_b128 v[164:167], v234 offset:49152
	ds_read_b128 v[168:171], v234 offset:50176
	ds_read_b128 v[172:175], v234 offset:51200
	ds_read_b128 v[176:179], v234 offset:52224
	ds_read_b128 v[180:183], v234 offset:53248
	ds_read_b128 v[184:187], v234 offset:54272
	ds_read_b128 v[206:209], v234 offset:55296
	ds_read_b128 v[210:213], v234 offset:56320
	s_add_i32 s48, s48, s5
	v_lshl_add_u64 v[198:199], v[198:199], 0, s[66:67]
	s_mov_b32 m0, s48
	s_nop 0
	global_load_lds_dwordx4 v[198:199], off
	s_add_i32 m0, s48, 0x2000
	s_add_u32 s62, s70, 0x160080
	v_lshl_add_u64 v[198:199], v[214:215], 0, s[66:67]
	s_addc_u32 s63, s71, 0
	s_add_i32 s48, s49, s5
	global_load_lds_dwordx4 v[198:199], off
	v_lshl_add_u64 v[198:199], s[62:63], 0, v[200:201]
	s_mov_b32 m0, s48
	s_nop 0
	global_load_lds_dwordx4 v[198:199], off
	v_lshl_add_u64 v[198:199], s[62:63], 0, v[188:189]
	s_add_i32 m0, s48, 0x2000
	s_nop 0
	global_load_lds_dwordx4 v[198:199], off
	v_lshl_add_u64 v[198:199], v[216:217], 0, s[66:67]
	s_mov_b32 m0, s53
	s_nop 0
	global_load_lds_dwordx4 v[198:199], off
	v_lshl_add_u64 v[198:199], v[218:219], 0, s[66:67]
	s_mov_b32 m0, s54
	s_nop 0
	global_load_lds_dwordx4 v[198:199], off
	s_waitcnt vmcnt(8)
	s_waitcnt lgkmcnt(0)
	s_setprio 1
	s_barrier
	v_mfma_f32_16x16x32_bf16 v[64:67], v[108:111], v[164:167], v[64:67]
	v_mfma_f32_16x16x32_bf16 v[60:63], v[128:131], v[164:167], v[60:63]
	v_mfma_f32_16x16x32_bf16 v[48:51], v[108:111], v[172:175], v[48:51]
	v_mfma_f32_16x16x32_bf16 v[44:47], v[128:131], v[172:175], v[44:47]
	v_mfma_f32_16x16x32_bf16 v[32:35], v[108:111], v[180:183], v[32:35]
	v_mfma_f32_16x16x32_bf16 v[28:31], v[128:131], v[180:183], v[28:31]
	v_mfma_f32_16x16x32_bf16 v[16:19], v[108:111], v[206:209], v[16:19]
	v_mfma_f32_16x16x32_bf16 v[12:15], v[128:131], v[206:209], v[12:15]
	v_mfma_f32_16x16x32_bf16 v[64:67], v[112:115], v[168:171], v[64:67]
	v_mfma_f32_16x16x32_bf16 v[60:63], v[136:139], v[168:171], v[60:63]
	v_mfma_f32_16x16x32_bf16 v[48:51], v[112:115], v[176:179], v[48:51]
	v_mfma_f32_16x16x32_bf16 v[44:47], v[136:139], v[176:179], v[44:47]
	v_mfma_f32_16x16x32_bf16 v[32:35], v[112:115], v[184:187], v[32:35]
	v_mfma_f32_16x16x32_bf16 v[28:31], v[136:139], v[184:187], v[28:31]
	v_mfma_f32_16x16x32_bf16 v[16:19], v[112:115], v[210:213], v[16:19]
	v_mfma_f32_16x16x32_bf16 v[12:15], v[136:139], v[210:213], v[12:15]
	s_setprio 0
	s_setprio 1
	v_mfma_f32_16x16x32_bf16 v[56:59], v[148:151], v[164:167], v[56:59]
	v_mfma_f32_16x16x32_bf16 v[52:55], v[156:159], v[164:167], v[52:55]
	v_mfma_f32_16x16x32_bf16 v[40:43], v[148:151], v[172:175], v[40:43]
	v_mfma_f32_16x16x32_bf16 v[36:39], v[156:159], v[172:175], v[36:39]
	v_mfma_f32_16x16x32_bf16 v[24:27], v[148:151], v[180:183], v[24:27]
	v_mfma_f32_16x16x32_bf16 v[20:23], v[156:159], v[180:183], v[20:23]
	v_mfma_f32_16x16x32_bf16 v[8:11], v[148:151], v[206:209], v[8:11]
	v_mfma_f32_16x16x32_bf16 v[4:7], v[156:159], v[206:209], v[4:7]
	v_mfma_f32_16x16x32_bf16 v[56:59], v[152:155], v[168:171], v[56:59]
	v_mfma_f32_16x16x32_bf16 v[52:55], v[160:163], v[168:171], v[52:55]
	v_mfma_f32_16x16x32_bf16 v[40:43], v[152:155], v[176:179], v[40:43]
	v_mfma_f32_16x16x32_bf16 v[36:39], v[160:163], v[176:179], v[36:39]
	v_mfma_f32_16x16x32_bf16 v[24:27], v[152:155], v[184:187], v[24:27]
	v_mfma_f32_16x16x32_bf16 v[20:23], v[160:163], v[184:187], v[20:23]
	v_mfma_f32_16x16x32_bf16 v[8:11], v[152:155], v[210:213], v[8:11]
	v_mfma_f32_16x16x32_bf16 v[4:7], v[160:163], v[210:213], v[4:7]
	s_barrier
	s_setprio 0
	s_add_i32 s78, s78, 2
	s_add_u32 s73, s73, 0x100
	s_addc_u32 s75, s75, 0
	s_cmpk_gt_u32 s78, 0x55
	s_mov_b64 s[62:63], s[68:69]
	s_cbranch_scc0 .LBB0_667
	s_and_b64 vcc, exec, s[24:25]
	s_cbranch_vccz .LBB0_670
	s_barrier

; #define PG8_STAGE(bufoff, gbase, voff) do { _Pragma("unroll") for (int _i = 0; _i < 2; ++_i) \
;         __builtin_amdgcn_global_load_lds((const unsigned*)((const char*)(gbase) + (voff)[_i]), (PG8_LAS unsigned*)(lds + (bufoff) + ldsw + _i * 8192), 16, 0, 0); } while (0)
; #define PG8_LDA(dst, b, h) do { _Pragma("unroll") for (int m = 0; m < 4; ++m) _Pragma("unroll") for (int k = 0; k < 2; ++k) dst[m][k] = *(const PG8_LAS bf16x8*)(lds + PG8_SA(b, h) + aoff + m * 2048 + k * 1024); } while (0)
; #define PG8_LDB(dst, b, h) do { _Pragma("unroll") for (int n = 0; n < 2; ++n) _Pragma("unroll") for (int k = 0; k < 2; ++k) dst[n][k] = *(const PG8_LAS bf16x8*)(lds + PG8_SB(b, h) + boff + n * 2048 + k * 1024); } while (0)
; #define PG8_MMA(ai, bj, At, Bt) do { __builtin_amdgcn_s_setprio(1); _Pragma("unroll") for (int m = 0; m < 4; ++m) _Pragma("unroll") for (int n = 0; n < 2; ++n) _Pragma("unroll") for (int k = 0; k < 2; ++k) \
;         acc[ai][bj][m][n] = __builtin_amdgcn_mfma_f32_16x16x32_bf16(Bt[n][k], At[m][k], acc[ai][bj][m][n], 0, 0, 0); __builtin_amdgcn_s_setprio(0); } while (0)
; #define PG8_WAIT_V(n) asm volatile("s_waitcnt vmcnt(" #n ")" ::: "memory")
; #define PG8_WAIT_L(n) asm volatile("s_waitcnt lgkmcnt(" #n ")" ::: "memory")
; #define PG8_BAR __builtin_amdgcn_s_barrier()
; #define PG8_SCHED __builtin_amdgcn_sched_barrier(0)
;     ...
;             const bool last = (t == nt - 2);
;             const char* a1 = cA + (size_t)(t + 1) * kstep;
;             const char* a2 = last ? nA : cA + (size_t)(t + 2) * kstep; const char* b2 = last ? nB : cB + (size_t)(t + 2) * kstep;
;             const char* a3 = a2 + kstep; const char* b3 = b2 + kstep;
;             if (last && has_next) S.a_ready(nxt);
;             if (t == 0) E.pre_issue(pre, cur, tid, ui); else if (t == 2) E.pre_finish(pre, tid, ui);
;             if constexpr (SP2) {
;             PG8_LDB(B0, 0, 0); PG8_LDB(B1, 0, 1); PG8_SCHED; PG8_LDA(At, 0, 0); PG8_STAGE(PG8_SA(1, 1), a1 + hstep, voffA);
;             PG8_WAIT_V(8); PG8_WAIT_L(0); PG8_BAR; PG8_MMA(0, 0, At, B0); PG8_MMA(0, 1, At, B1); PG8_BAR; PG8_SCHED;
;             PG8_LDA(At, 0, 1); PG8_STAGE(PG8_SB(0, 0), b2, voffB); PG8_STAGE(PG8_SB(0, 1), b2 + hstep, voffB); PG8_STAGE(PG8_SA(0, 0), a2, voffA);
;             PG8_WAIT_V(8); PG8_WAIT_L(0); PG8_BAR; PG8_MMA(1, 0, At, B0); PG8_MMA(1, 1, At, B1); PG8_BAR; PG8_SCHED;
.LBB0_753:
	ds_read_b128 v[132:135], v251
	ds_read_b128 v[158:161], v251 offset:1024
	ds_read_b128 v[162:165], v251 offset:2048
	ds_read_b128 v[166:169], v251 offset:3072
	ds_read_b128 v[170:173], v251 offset:16384
	ds_read_b128 v[176:179], v251 offset:17408
	ds_read_b128 v[180:183], v251 offset:18432
	ds_read_b128 v[184:187], v251 offset:19456
	ds_read_b128 v[188:191], v175
	ds_read_b128 v[192:195], v175 offset:1024
	ds_read_b128 v[196:199], v175 offset:2048
	ds_read_b128 v[206:209], v175 offset:3072
	ds_read_b128 v[210:213], v175 offset:4096
	ds_read_b128 v[214:217], v175 offset:5120
	ds_read_b128 v[218:221], v175 offset:6144
	ds_read_b128 v[222:225], v175 offset:7168
	s_add_u32 s48, s68, 0xfff80080
	s_addc_u32 s49, s69, -1
	s_add_i32 s61, 0, 0x10000
	s_cmp_eq_u32 s59, 28
	s_cselect_b32 s79, s53, s49
	s_cselect_b32 s78, s54, s48
	s_cselect_b32 s77, s25, s58
	s_cselect_b32 s76, s55, s56
	s_add_i32 s48, 0, 0x14000
	v_lshl_add_u64 v[232:233], s[68:69], 0, v[150:151]
	s_add_i32 m0, s1, 0xc000
	s_nop 0
	global_load_lds_dwordx4 v[232:233], off
	v_lshl_add_u64 v[232:233], s[68:69], 0, v[152:153]
	s_add_i32 m0, s1, 0xe000
	s_nop 0
	global_load_lds_dwordx4 v[232:233], off
	s_waitcnt vmcnt(8)
	s_waitcnt lgkmcnt(0)
	s_setprio 1
	s_barrier
	v_mfma_f32_16x16x32_bf16 v[128:131], v[132:135], v[188:191], v[128:131]
	v_mfma_f32_16x16x32_bf16 v[124:127], v[162:165], v[188:191], v[124:127]
	v_mfma_f32_16x16x32_bf16 v[116:119], v[132:135], v[196:199], v[116:119]
	v_mfma_f32_16x16x32_bf16 v[108:111], v[162:165], v[196:199], v[108:111]
	v_mfma_f32_16x16x32_bf16 v[100:103], v[132:135], v[210:213], v[100:103]
	v_mfma_f32_16x16x32_bf16 v[92:95], v[162:165], v[210:213], v[92:95]
	v_mfma_f32_16x16x32_bf16 v[84:87], v[132:135], v[218:221], v[84:87]
	v_mfma_f32_16x16x32_bf16 v[76:79], v[162:165], v[218:221], v[76:79]
	v_mfma_f32_16x16x32_bf16 v[128:131], v[158:161], v[192:195], v[128:131]
	v_mfma_f32_16x16x32_bf16 v[124:127], v[166:169], v[192:195], v[124:127]
	v_mfma_f32_16x16x32_bf16 v[116:119], v[158:161], v[206:209], v[116:119]
	v_mfma_f32_16x16x32_bf16 v[108:111], v[166:169], v[206:209], v[108:111]
	v_mfma_f32_16x16x32_bf16 v[100:103], v[158:161], v[214:217], v[100:103]
	v_mfma_f32_16x16x32_bf16 v[92:95], v[166:169], v[214:217], v[92:95]
	v_mfma_f32_16x16x32_bf16 v[84:87], v[158:161], v[222:225], v[84:87]
	v_mfma_f32_16x16x32_bf16 v[76:79], v[166:169], v[222:225], v[76:79]
	s_setprio 0
	s_setprio 1
	v_mfma_f32_16x16x32_bf16 v[120:123], v[170:173], v[188:191], v[120:123]
	v_mfma_f32_16x16x32_bf16 v[112:115], v[180:183], v[188:191], v[112:115]
	v_mfma_f32_16x16x32_bf16 v[104:107], v[170:173], v[196:199], v[104:107]
	v_mfma_f32_16x16x32_bf16 v[96:99], v[180:183], v[196:199], v[96:99]
	v_mfma_f32_16x16x32_bf16 v[88:91], v[170:173], v[210:213], v[88:91]
	v_mfma_f32_16x16x32_bf16 v[80:83], v[180:183], v[210:213], v[80:83]
	v_mfma_f32_16x16x32_bf16 v[72:75], v[170:173], v[218:221], v[72:75]
	v_mfma_f32_16x16x32_bf16 v[68:71], v[180:183], v[218:221], v[68:71]
	v_mfma_f32_16x16x32_bf16 v[120:123], v[176:179], v[192:195], v[120:123]
	v_mfma_f32_16x16x32_bf16 v[112:115], v[184:187], v[192:195], v[112:115]
	v_mfma_f32_16x16x32_bf16 v[104:107], v[176:179], v[206:209], v[104:107]
	v_mfma_f32_16x16x32_bf16 v[96:99], v[184:187], v[206:209], v[96:99]
	v_mfma_f32_16x16x32_bf16 v[88:91], v[176:179], v[214:217], v[88:91]
	v_mfma_f32_16x16x32_bf16 v[80:83], v[184:187], v[214:217], v[80:83]
	v_mfma_f32_16x16x32_bf16 v[72:75], v[176:179], v[222:225], v[72:75]
	v_mfma_f32_16x16x32_bf16 v[68:71], v[184:187], v[222:225], v[68:71]
	s_barrier
	s_setprio 0
	ds_read_b128 v[188:191], v175 offset:16384
	ds_read_b128 v[192:195], v175 offset:17408
	ds_read_b128 v[196:199], v175 offset:18432
	ds_read_b128 v[206:209], v175 offset:19456
	ds_read_b128 v[210:213], v175 offset:20480
	ds_read_b128 v[214:217], v175 offset:21504
	ds_read_b128 v[218:221], v175 offset:22528
	ds_read_b128 v[222:225], v175 offset:23552
	s_add_i32 s49, s61, s0
	v_lshl_add_u64 v[232:233], s[76:77], 0, v[140:141]
	s_mov_b32 m0, s49
	s_nop 0
	global_load_lds_dwordx4 v[232:233], off
	s_add_i32 m0, s49, 0x2000
	s_add_u32 s82, s76, 0x80000
	v_lshl_add_u64 v[234:235], s[76:77], 0, v[136:137]
	s_addc_u32 s83, s77, 0
	s_add_i32 s48, s48, s0
	global_load_lds_dwordx4 v[234:235], off
	v_lshl_add_u64 v[236:237], s[82:83], 0, v[140:141]
	s_mov_b32 m0, s48
	v_lshl_add_u64 v[238:239], s[78:79], 0, v[138:139]
	global_load_lds_dwordx4 v[236:237], off
	v_lshl_add_u64 v[236:237], s[82:83], 0, v[136:137]
	s_add_i32 m0, s48, 0x2000
	s_nop 0
	global_load_lds_dwordx4 v[236:237], off
	v_lshl_add_u64 v[236:237], s[78:79], 0, v[142:143]
	s_mov_b32 m0, s1
	s_nop 0
	global_load_lds_dwordx4 v[236:237], off
	s_mov_b32 m0, s4
	s_nop 0
	global_load_lds_dwordx4 v[238:239], off
	s_waitcnt vmcnt(8)
	s_waitcnt lgkmcnt(0)
	s_setprio 1
	s_barrier
; #define PG8_STAGE(bufoff, gbase, voff) do { _Pragma("unroll") for (int _i = 0; _i < 2; ++_i) \
;         __builtin_amdgcn_global_load_lds((const unsigned*)((const char*)(gbase) + (voff)[_i]), (PG8_LAS unsigned*)(lds + (bufoff) + ldsw + _i * 8192), 16, 0, 0); } while (0)
; #define PG8_LDA(dst, b, h) do { _Pragma("unroll") for (int m = 0; m < 4; ++m) _Pragma("unroll") for (int k = 0; k < 2; ++k) dst[m][k] = *(const PG8_LAS bf16x8*)(lds + PG8_SA(b, h) + aoff + m * 2048 + k * 1024); } while (0)
; #define PG8_LDB(dst, b, h) do { _Pragma("unroll") for (int n = 0; n < 2; ++n) _Pragma("unroll") for (int k = 0; k < 2; ++k) dst[n][k] = *(const PG8_LAS bf16x8*)(lds + PG8_SB(b, h) + boff + n * 2048 + k * 1024); } while (0)
; #define PG8_MMA(ai, bj, At, Bt) do { __builtin_amdgcn_s_setprio(1); _Pragma("unroll") for (int m = 0; m < 4; ++m) _Pragma("unroll") for (int n = 0; n < 2; ++n) _Pragma("unroll") for (int k = 0; k < 2; ++k) \
;         acc[ai][bj][m][n] = __builtin_amdgcn_mfma_f32_16x16x32_bf16(Bt[n][k], At[m][k], acc[ai][bj][m][n], 0, 0, 0); __builtin_amdgcn_s_setprio(0); } while (0)
; #define PG8_WAIT_V(n) asm volatile("s_waitcnt vmcnt(" #n ")" ::: "memory")
; #define PG8_WAIT_L(n) asm volatile("s_waitcnt lgkmcnt(" #n ")" ::: "memory")
; #define PG8_BAR __builtin_amdgcn_s_barrier()
; #define PG8_SCHED __builtin_amdgcn_sched_barrier(0)
;     ...
;             PG8_WAIT_V(8); PG8_WAIT_L(0); PG8_BAR; PG8_MMA(1, 0, At, B0); PG8_MMA(1, 1, At, B1); PG8_BAR; PG8_SCHED;
;             PG8_LDB(B0, 1, 0); PG8_LDB(B1, 1, 1); PG8_SCHED; PG8_LDA(At, 1, 0); PG8_STAGE(PG8_SA(0, 1), a2 + hstep, voffA);
;             PG8_WAIT_V(8); PG8_WAIT_L(0); PG8_BAR; PG8_MMA(0, 0, At, B0); PG8_MMA(0, 1, At, B1); PG8_BAR; PG8_SCHED;
	v_mfma_f32_16x16x32_bf16 v[64:67], v[132:135], v[188:191], v[64:67]
	v_mfma_f32_16x16x32_bf16 v[60:63], v[162:165], v[188:191], v[60:63]
	v_mfma_f32_16x16x32_bf16 v[52:55], v[132:135], v[196:199], v[52:55]
	v_mfma_f32_16x16x32_bf16 v[44:47], v[162:165], v[196:199], v[44:47]
	v_mfma_f32_16x16x32_bf16 v[36:39], v[132:135], v[210:213], v[36:39]
	v_mfma_f32_16x16x32_bf16 v[28:31], v[162:165], v[210:213], v[28:31]
	v_mfma_f32_16x16x32_bf16 v[20:23], v[132:135], v[218:221], v[20:23]
	v_mfma_f32_16x16x32_bf16 v[12:15], v[162:165], v[218:221], v[12:15]
	v_mfma_f32_16x16x32_bf16 v[64:67], v[158:161], v[192:195], v[64:67]
	v_mfma_f32_16x16x32_bf16 v[60:63], v[166:169], v[192:195], v[60:63]
	v_mfma_f32_16x16x32_bf16 v[52:55], v[158:161], v[206:209], v[52:55]
	v_mfma_f32_16x16x32_bf16 v[44:47], v[166:169], v[206:209], v[44:47]
	v_mfma_f32_16x16x32_bf16 v[36:39], v[158:161], v[214:217], v[36:39]
	v_mfma_f32_16x16x32_bf16 v[28:31], v[166:169], v[214:217], v[28:31]
	v_mfma_f32_16x16x32_bf16 v[20:23], v[158:161], v[222:225], v[20:23]
	v_mfma_f32_16x16x32_bf16 v[12:15], v[166:169], v[222:225], v[12:15]
	s_setprio 0
	s_setprio 1
	v_mfma_f32_16x16x32_bf16 v[56:59], v[170:173], v[188:191], v[56:59]
	v_mfma_f32_16x16x32_bf16 v[48:51], v[180:183], v[188:191], v[48:51]
	v_mfma_f32_16x16x32_bf16 v[40:43], v[170:173], v[196:199], v[40:43]
	v_mfma_f32_16x16x32_bf16 v[32:35], v[180:183], v[196:199], v[32:35]
	v_mfma_f32_16x16x32_bf16 v[24:27], v[170:173], v[210:213], v[24:27]
	v_mfma_f32_16x16x32_bf16 v[16:19], v[180:183], v[210:213], v[16:19]
	v_mfma_f32_16x16x32_bf16 v[8:11], v[170:173], v[218:221], v[8:11]
	v_mfma_f32_16x16x32_bf16 v[4:7], v[180:183], v[218:221], v[4:7]
	v_mfma_f32_16x16x32_bf16 v[56:59], v[176:179], v[192:195], v[56:59]
	v_mfma_f32_16x16x32_bf16 v[48:51], v[184:187], v[192:195], v[48:51]
	v_mfma_f32_16x16x32_bf16 v[40:43], v[176:179], v[206:209], v[40:43]
	v_mfma_f32_16x16x32_bf16 v[32:35], v[184:187], v[206:209], v[32:35]
	v_mfma_f32_16x16x32_bf16 v[24:27], v[176:179], v[214:217], v[24:27]
	v_mfma_f32_16x16x32_bf16 v[16:19], v[184:187], v[214:217], v[16:19]
	v_mfma_f32_16x16x32_bf16 v[8:11], v[176:179], v[222:225], v[8:11]
	v_mfma_f32_16x16x32_bf16 v[4:7], v[184:187], v[222:225], v[4:7]
	s_barrier
	s_setprio 0
	ds_read_b128 v[132:135], v251 offset:32768
	ds_read_b128 v[158:161], v251 offset:33792
	ds_read_b128 v[162:165], v251 offset:34816
	ds_read_b128 v[166:169], v251 offset:35840
	ds_read_b128 v[170:173], v251 offset:49152
	ds_read_b128 v[176:179], v251 offset:50176
	ds_read_b128 v[180:183], v251 offset:51200
	ds_read_b128 v[184:187], v251 offset:52224
	ds_read_b128 v[188:191], v175 offset:32768
	ds_read_b128 v[192:195], v175 offset:33792
	ds_read_b128 v[196:199], v175 offset:34816
	ds_read_b128 v[206:209], v175 offset:35840
	ds_read_b128 v[210:213], v175 offset:36864
	ds_read_b128 v[214:217], v175 offset:37888
	ds_read_b128 v[218:221], v175 offset:38912
	ds_read_b128 v[222:225], v175 offset:39936
	s_add_i32 s48, 0, 0x18000
	s_add_i32 s49, 0, 0x1c000
	s_add_u32 s78, s78, 0x80000
	s_addc_u32 s79, s79, 0
	s_mov_b32 m0, s5
	v_lshl_add_u64 v[240:241], s[78:79], 0, v[142:143]
	global_load_lds_dwordx4 v[240:241], off
	v_lshl_add_u64 v[240:241], s[78:79], 0, v[138:139]
	s_mov_b32 m0, s7
	s_nop 0
	global_load_lds_dwordx4 v[240:241], off
	s_waitcnt vmcnt(8)
	s_waitcnt lgkmcnt(0)
	s_setprio 1
	s_barrier
	v_mfma_f32_16x16x32_bf16 v[128:131], v[132:135], v[188:191], v[128:131]
	v_mfma_f32_16x16x32_bf16 v[124:127], v[162:165], v[188:191], v[124:127]
	v_mfma_f32_16x16x32_bf16 v[116:119], v[132:135], v[196:199], v[116:119]
	v_mfma_f32_16x16x32_bf16 v[108:111], v[162:165], v[196:199], v[108:111]
	v_mfma_f32_16x16x32_bf16 v[100:103], v[132:135], v[210:213], v[100:103]
	v_mfma_f32_16x16x32_bf16 v[92:95], v[162:165], v[210:213], v[92:95]
	v_mfma_f32_16x16x32_bf16 v[84:87], v[132:135], v[218:221], v[84:87]
	v_mfma_f32_16x16x32_bf16 v[76:79], v[162:165], v[218:221], v[76:79]
	v_mfma_f32_16x16x32_bf16 v[128:131], v[158:161], v[192:195], v[128:131]
	v_mfma_f32_16x16x32_bf16 v[124:127], v[166:169], v[192:195], v[124:127]
	v_mfma_f32_16x16x32_bf16 v[116:119], v[158:161], v[206:209], v[116:119]
	v_mfma_f32_16x16x32_bf16 v[108:111], v[166:169], v[206:209], v[108:111]
	v_mfma_f32_16x16x32_bf16 v[100:103], v[158:161], v[214:217], v[100:103]
	v_mfma_f32_16x16x32_bf16 v[92:95], v[166:169], v[214:217], v[92:95]
	v_mfma_f32_16x16x32_bf16 v[84:87], v[158:161], v[222:225], v[84:87]
	v_mfma_f32_16x16x32_bf16 v[76:79], v[166:169], v[222:225], v[76:79]
	s_setprio 0
	s_setprio 1
	v_mfma_f32_16x16x32_bf16 v[120:123], v[170:173], v[188:191], v[120:123]
	v_mfma_f32_16x16x32_bf16 v[112:115], v[180:183], v[188:191], v[112:115]
	v_mfma_f32_16x16x32_bf16 v[104:107], v[170:173], v[196:199], v[104:107]
	v_mfma_f32_16x16x32_bf16 v[96:99], v[180:183], v[196:199], v[96:99]
	v_mfma_f32_16x16x32_bf16 v[88:91], v[170:173], v[210:213], v[88:91]
	v_mfma_f32_16x16x32_bf16 v[80:83], v[180:183], v[210:213], v[80:83]
	v_mfma_f32_16x16x32_bf16 v[72:75], v[170:173], v[218:221], v[72:75]
	v_mfma_f32_16x16x32_bf16 v[68:71], v[180:183], v[218:221], v[68:71]
	v_mfma_f32_16x16x32_bf16 v[120:123], v[176:179], v[192:195], v[120:123]
	v_mfma_f32_16x16x32_bf16 v[112:115], v[184:187], v[192:195], v[112:115]
	v_mfma_f32_16x16x32_bf16 v[104:107], v[176:179], v[206:209], v[104:107]
	v_mfma_f32_16x16x32_bf16 v[96:99], v[184:187], v[206:209], v[96:99]
	v_mfma_f32_16x16x32_bf16 v[88:91], v[176:179], v[214:217], v[88:91]
	v_mfma_f32_16x16x32_bf16 v[80:83], v[184:187], v[214:217], v[80:83]
	v_mfma_f32_16x16x32_bf16 v[72:75], v[176:179], v[222:225], v[72:75]
	v_mfma_f32_16x16x32_bf16 v[68:71], v[184:187], v[222:225], v[68:71]
	s_barrier
; #define PG8_STAGE(bufoff, gbase, voff) do { _Pragma("unroll") for (int _i = 0; _i < 2; ++_i) \
;         __builtin_amdgcn_global_load_lds((const unsigned*)((const char*)(gbase) + (voff)[_i]), (PG8_LAS unsigned*)(lds + (bufoff) + ldsw + _i * 8192), 16, 0, 0); } while (0)
; #define PG8_LDA(dst, b, h) do { _Pragma("unroll") for (int m = 0; m < 4; ++m) _Pragma("unroll") for (int k = 0; k < 2; ++k) dst[m][k] = *(const PG8_LAS bf16x8*)(lds + PG8_SA(b, h) + aoff + m * 2048 + k * 1024); } while (0)
; #define PG8_MMA(ai, bj, At, Bt) do { __builtin_amdgcn_s_setprio(1); _Pragma("unroll") for (int m = 0; m < 4; ++m) _Pragma("unroll") for (int n = 0; n < 2; ++n) _Pragma("unroll") for (int k = 0; k < 2; ++k) \
;         acc[ai][bj][m][n] = __builtin_amdgcn_mfma_f32_16x16x32_bf16(Bt[n][k], At[m][k], acc[ai][bj][m][n], 0, 0, 0); __builtin_amdgcn_s_setprio(0); } while (0)
; #define PG8_WAIT_V(n) asm volatile("s_waitcnt vmcnt(" #n ")" ::: "memory")
; #define PG8_WAIT_L(n) asm volatile("s_waitcnt lgkmcnt(" #n ")" ::: "memory")
; #define PG8_BAR __builtin_amdgcn_s_barrier()
; #define PG8_SCHED __builtin_amdgcn_sched_barrier(0)
;     ...
;             PG8_LDA(At, 1, 1); PG8_STAGE(PG8_SB(1, 0), b3, voffB); PG8_STAGE(PG8_SB(1, 1), b3 + hstep, voffB); PG8_STAGE(PG8_SA(1, 0), a3, voffA);
;             PG8_WAIT_V(8); PG8_WAIT_L(0); PG8_BAR; PG8_MMA(1, 0, At, B0); PG8_MMA(1, 1, At, B1); PG8_BAR; PG8_SCHED;
	s_setprio 0
	ds_read_b128 v[188:191], v175 offset:49152
	ds_read_b128 v[192:195], v175 offset:50176
	ds_read_b128 v[196:199], v175 offset:51200
	ds_read_b128 v[206:209], v175 offset:52224
	ds_read_b128 v[210:213], v175 offset:53248
	ds_read_b128 v[214:217], v175 offset:54272
	ds_read_b128 v[218:221], v175 offset:55296
	ds_read_b128 v[222:225], v175 offset:56320
	s_add_i32 s48, s48, s0
	v_lshl_add_u64 v[232:233], v[232:233], 0, s[66:67]
	s_mov_b32 m0, s48
	s_nop 0
	global_load_lds_dwordx4 v[232:233], off
	s_add_i32 m0, s48, 0x2000
	s_add_u32 s76, s76, 0x80080
	v_lshl_add_u64 v[232:233], v[234:235], 0, s[66:67]
	s_addc_u32 s77, s77, 0
	s_add_i32 s48, s49, s0
	global_load_lds_dwordx4 v[232:233], off
	v_lshl_add_u64 v[232:233], s[76:77], 0, v[140:141]
	s_mov_b32 m0, s48
	s_nop 0
	global_load_lds_dwordx4 v[232:233], off
	v_lshl_add_u64 v[232:233], s[76:77], 0, v[136:137]
	s_add_i32 m0, s48, 0x2000
	s_nop 0
	global_load_lds_dwordx4 v[232:233], off
	v_lshl_add_u64 v[232:233], v[236:237], 0, s[66:67]
	s_mov_b32 m0, s21
	s_nop 0
	global_load_lds_dwordx4 v[232:233], off
	v_lshl_add_u64 v[232:233], v[238:239], 0, s[66:67]
	s_mov_b32 m0, s23
	s_nop 0
	global_load_lds_dwordx4 v[232:233], off
	s_waitcnt vmcnt(8)
	s_waitcnt lgkmcnt(0)
	s_setprio 1
	s_barrier
	v_mfma_f32_16x16x32_bf16 v[64:67], v[132:135], v[188:191], v[64:67]
	v_mfma_f32_16x16x32_bf16 v[60:63], v[162:165], v[188:191], v[60:63]
	v_mfma_f32_16x16x32_bf16 v[52:55], v[132:135], v[196:199], v[52:55]
	v_mfma_f32_16x16x32_bf16 v[44:47], v[162:165], v[196:199], v[44:47]
	v_mfma_f32_16x16x32_bf16 v[36:39], v[132:135], v[210:213], v[36:39]
	v_mfma_f32_16x16x32_bf16 v[28:31], v[162:165], v[210:213], v[28:31]
	v_mfma_f32_16x16x32_bf16 v[20:23], v[132:135], v[218:221], v[20:23]
	v_mfma_f32_16x16x32_bf16 v[12:15], v[162:165], v[218:221], v[12:15]
	v_mfma_f32_16x16x32_bf16 v[64:67], v[158:161], v[192:195], v[64:67]
	v_mfma_f32_16x16x32_bf16 v[60:63], v[166:169], v[192:195], v[60:63]
	v_mfma_f32_16x16x32_bf16 v[52:55], v[158:161], v[206:209], v[52:55]
	v_mfma_f32_16x16x32_bf16 v[44:47], v[166:169], v[206:209], v[44:47]
	v_mfma_f32_16x16x32_bf16 v[36:39], v[158:161], v[214:217], v[36:39]
	v_mfma_f32_16x16x32_bf16 v[28:31], v[166:169], v[214:217], v[28:31]
	v_mfma_f32_16x16x32_bf16 v[20:23], v[158:161], v[222:225], v[20:23]
	v_mfma_f32_16x16x32_bf16 v[12:15], v[166:169], v[222:225], v[12:15]
	s_setprio 0
	s_setprio 1
	v_mfma_f32_16x16x32_bf16 v[56:59], v[170:173], v[188:191], v[56:59]
	v_mfma_f32_16x16x32_bf16 v[48:51], v[180:183], v[188:191], v[48:51]
	v_mfma_f32_16x16x32_bf16 v[40:43], v[170:173], v[196:199], v[40:43]
	v_mfma_f32_16x16x32_bf16 v[32:35], v[180:183], v[196:199], v[32:35]
	v_mfma_f32_16x16x32_bf16 v[24:27], v[170:173], v[210:213], v[24:27]
	v_mfma_f32_16x16x32_bf16 v[16:19], v[180:183], v[210:213], v[16:19]
	v_mfma_f32_16x16x32_bf16 v[8:11], v[170:173], v[218:221], v[8:11]
	v_mfma_f32_16x16x32_bf16 v[4:7], v[180:183], v[218:221], v[4:7]
	v_mfma_f32_16x16x32_bf16 v[56:59], v[176:179], v[192:195], v[56:59]
	v_mfma_f32_16x16x32_bf16 v[48:51], v[184:187], v[192:195], v[48:51]
	v_mfma_f32_16x16x32_bf16 v[40:43], v[176:179], v[206:209], v[40:43]
	v_mfma_f32_16x16x32_bf16 v[32:35], v[184:187], v[206:209], v[32:35]
	v_mfma_f32_16x16x32_bf16 v[24:27], v[176:179], v[214:217], v[24:27]
	v_mfma_f32_16x16x32_bf16 v[16:19], v[184:187], v[214:217], v[16:19]
	v_mfma_f32_16x16x32_bf16 v[8:11], v[176:179], v[222:225], v[8:11]
	v_mfma_f32_16x16x32_bf16 v[4:7], v[184:187], v[222:225], v[4:7]
	s_barrier
	s_setprio 0
	s_add_i32 s59, s59, 2
	s_add_u32 s68, s68, 0x100
	s_addc_u32 s69, s69, 0
	s_add_u32 s56, s56, 0x100
	s_addc_u32 s58, s58, 0
	s_cmp_gt_u32 s59, 29
	s_cbranch_scc0 .LBB0_753
	s_and_b64 vcc, exec, s[12:13]
	s_cbranch_vccz .LBB0_756
	s_barrier

; #define PG8_STAGE(bufoff, gbase, voff) do { _Pragma("unroll") for (int _i = 0; _i < 2; ++_i) \
;         __builtin_amdgcn_global_load_lds((const unsigned*)((const char*)(gbase) + (voff)[_i]), (PG8_LAS unsigned*)(lds + (bufoff) + ldsw + _i * 8192), 16, 0, 0); } while (0)
; #define PG8_LDA(dst, b, h) do { _Pragma("unroll") for (int m = 0; m < 4; ++m) _Pragma("unroll") for (int k = 0; k < 2; ++k) dst[m][k] = *(const PG8_LAS bf16x8*)(lds + PG8_SA(b, h) + aoff + m * 2048 + k * 1024); } while (0)
; #define PG8_LDB(dst, b, h) do { _Pragma("unroll") for (int n = 0; n < 2; ++n) _Pragma("unroll") for (int k = 0; k < 2; ++k) dst[n][k] = *(const PG8_LAS bf16x8*)(lds + PG8_SB(b, h) + boff + n * 2048 + k * 1024); } while (0)
; #define PG8_MMA(ai, bj, At, Bt) do { __builtin_amdgcn_s_setprio(1); _Pragma("unroll") for (int m = 0; m < 4; ++m) _Pragma("unroll") for (int n = 0; n < 2; ++n) _Pragma("unroll") for (int k = 0; k < 2; ++k) \
;         acc[ai][bj][m][n] = __builtin_amdgcn_mfma_f32_16x16x32_bf16(Bt[n][k], At[m][k], acc[ai][bj][m][n], 0, 0, 0); __builtin_amdgcn_s_setprio(0); } while (0)
; #define PG8_WAIT_V(n) asm volatile("s_waitcnt vmcnt(" #n ")" ::: "memory")
; #define PG8_WAIT_L(n) asm volatile("s_waitcnt lgkmcnt(" #n ")" ::: "memory")
; #define PG8_BAR __builtin_amdgcn_s_barrier()
; #define PG8_SCHED __builtin_amdgcn_sched_barrier(0)
;     ...
;             const bool last = (t == nt - 2);
;             const char* a1 = cA + (size_t)(t + 1) * kstep;
;             const char* a2 = last ? nA : cA + (size_t)(t + 2) * kstep; const char* b2 = last ? nB : cB + (size_t)(t + 2) * kstep;
;             const char* a3 = a2 + kstep; const char* b3 = b2 + kstep;
;             if (last && has_next) S.a_ready(nxt);
;             if (t == 0) E.pre_issue(pre, cur, tid, ui); else if (t == 2) E.pre_finish(pre, tid, ui);
;             if constexpr (SP2) {
;             PG8_LDB(B0, 0, 0); PG8_LDB(B1, 0, 1); PG8_SCHED; PG8_LDA(At, 0, 0); PG8_STAGE(PG8_SA(1, 1), a1 + hstep, voffA);
;             PG8_WAIT_V(8); PG8_WAIT_L(0); PG8_BAR; PG8_MMA(0, 0, At, B0); PG8_MMA(0, 1, At, B1); PG8_BAR; PG8_SCHED;
;             PG8_LDA(At, 0, 1); PG8_STAGE(PG8_SB(0, 0), b2, voffB); PG8_STAGE(PG8_SB(0, 1), b2 + hstep, voffB); PG8_STAGE(PG8_SA(0, 0), a2, voffA);
;             PG8_WAIT_V(8); PG8_WAIT_L(0); PG8_BAR; PG8_MMA(1, 0, At, B0); PG8_MMA(1, 1, At, B1); PG8_BAR; PG8_SCHED;
.LBB0_998:
	ds_read_b128 v[108:111], v251
	ds_read_b128 v[112:115], v251 offset:1024
	ds_read_b128 v[128:131], v251 offset:2048
	ds_read_b128 v[136:139], v251 offset:3072
	ds_read_b128 v[148:151], v251 offset:16384
	ds_read_b128 v[152:155], v251 offset:17408
	ds_read_b128 v[156:159], v251 offset:18432
	ds_read_b128 v[160:163], v251 offset:19456
	ds_read_b128 v[164:167], v234
	ds_read_b128 v[168:171], v234 offset:1024
	ds_read_b128 v[172:175], v234 offset:2048
	ds_read_b128 v[176:179], v234 offset:3072
	ds_read_b128 v[180:183], v234 offset:4096
	ds_read_b128 v[184:187], v234 offset:5120
	ds_read_b128 v[206:209], v234 offset:6144
	ds_read_b128 v[210:213], v234 offset:7168
	s_add_u32 s48, s68, 0xfff80080
	s_addc_u32 s49, s69, -1
	s_add_i32 s81, 0, 0x10000
	s_cmp_eq_u32 s79, 28
	s_cselect_b32 s77, s51, s49
	s_cselect_b32 s76, s59, s48
	s_cselect_b32 s71, s25, s78
	s_cselect_b32 s70, s73, s75
	s_add_i32 s48, 0, 0x14000
	v_lshl_add_u64 v[198:199], s[68:69], 0, v[196:197]
	s_add_i32 m0, s6, 0xc000
	s_nop 0
	global_load_lds_dwordx4 v[198:199], off
	v_lshl_add_u64 v[198:199], s[68:69], 0, v[194:195]
	s_add_i32 m0, s6, 0xe000
	s_nop 0
	global_load_lds_dwordx4 v[198:199], off
	s_waitcnt vmcnt(8)
	s_waitcnt lgkmcnt(0)
	s_setprio 1
	s_barrier
	v_mfma_f32_16x16x32_bf16 v[144:147], v[108:111], v[164:167], v[144:147]
	v_mfma_f32_16x16x32_bf16 v[140:143], v[128:131], v[164:167], v[140:143]
	v_mfma_f32_16x16x32_bf16 v[120:123], v[108:111], v[172:175], v[120:123]
	v_mfma_f32_16x16x32_bf16 v[116:119], v[128:131], v[172:175], v[116:119]
	v_mfma_f32_16x16x32_bf16 v[96:99], v[108:111], v[180:183], v[96:99]
	v_mfma_f32_16x16x32_bf16 v[92:95], v[128:131], v[180:183], v[92:95]
	v_mfma_f32_16x16x32_bf16 v[80:83], v[108:111], v[206:209], v[80:83]
	v_mfma_f32_16x16x32_bf16 v[76:79], v[128:131], v[206:209], v[76:79]
	v_mfma_f32_16x16x32_bf16 v[144:147], v[112:115], v[168:171], v[144:147]
	v_mfma_f32_16x16x32_bf16 v[140:143], v[136:139], v[168:171], v[140:143]
	v_mfma_f32_16x16x32_bf16 v[120:123], v[112:115], v[176:179], v[120:123]
	v_mfma_f32_16x16x32_bf16 v[116:119], v[136:139], v[176:179], v[116:119]
	v_mfma_f32_16x16x32_bf16 v[96:99], v[112:115], v[184:187], v[96:99]
	v_mfma_f32_16x16x32_bf16 v[92:95], v[136:139], v[184:187], v[92:95]
	v_mfma_f32_16x16x32_bf16 v[80:83], v[112:115], v[210:213], v[80:83]
	v_mfma_f32_16x16x32_bf16 v[76:79], v[136:139], v[210:213], v[76:79]
	s_setprio 0
	s_setprio 1
	v_mfma_f32_16x16x32_bf16 v[132:135], v[148:151], v[164:167], v[132:135]
	v_mfma_f32_16x16x32_bf16 v[124:127], v[156:159], v[164:167], v[124:127]
	v_mfma_f32_16x16x32_bf16 v[104:107], v[148:151], v[172:175], v[104:107]
	v_mfma_f32_16x16x32_bf16 v[100:103], v[156:159], v[172:175], v[100:103]
	v_mfma_f32_16x16x32_bf16 v[88:91], v[148:151], v[180:183], v[88:91]
	v_mfma_f32_16x16x32_bf16 v[84:87], v[156:159], v[180:183], v[84:87]
	v_mfma_f32_16x16x32_bf16 v[72:75], v[148:151], v[206:209], v[72:75]
	v_mfma_f32_16x16x32_bf16 v[68:71], v[156:159], v[206:209], v[68:71]
	v_mfma_f32_16x16x32_bf16 v[132:135], v[152:155], v[168:171], v[132:135]
	v_mfma_f32_16x16x32_bf16 v[124:127], v[160:163], v[168:171], v[124:127]
	v_mfma_f32_16x16x32_bf16 v[104:107], v[152:155], v[176:179], v[104:107]
	v_mfma_f32_16x16x32_bf16 v[100:103], v[160:163], v[176:179], v[100:103]
	v_mfma_f32_16x16x32_bf16 v[88:91], v[152:155], v[184:187], v[88:91]
	v_mfma_f32_16x16x32_bf16 v[84:87], v[160:163], v[184:187], v[84:87]
	v_mfma_f32_16x16x32_bf16 v[72:75], v[152:155], v[210:213], v[72:75]
	v_mfma_f32_16x16x32_bf16 v[68:71], v[160:163], v[210:213], v[68:71]
	s_barrier
	s_setprio 0
	ds_read_b128 v[164:167], v234 offset:16384
	ds_read_b128 v[168:171], v234 offset:17408
	ds_read_b128 v[172:175], v234 offset:18432
	ds_read_b128 v[176:179], v234 offset:19456
	ds_read_b128 v[180:183], v234 offset:20480
	ds_read_b128 v[184:187], v234 offset:21504
	ds_read_b128 v[206:209], v234 offset:22528
	ds_read_b128 v[210:213], v234 offset:23552
	s_add_i32 s49, s81, s5
	v_lshl_add_u64 v[198:199], s[70:71], 0, v[200:201]
	s_mov_b32 m0, s49
	s_nop 0
	global_load_lds_dwordx4 v[198:199], off
	s_add_i32 m0, s49, 0x2000
	s_add_u32 s84, s70, 0x80000
	v_lshl_add_u64 v[214:215], s[70:71], 0, v[188:189]
	s_addc_u32 s85, s71, 0
	s_add_i32 s48, s48, s5
	global_load_lds_dwordx4 v[214:215], off
	v_lshl_add_u64 v[216:217], s[84:85], 0, v[200:201]
	s_mov_b32 m0, s48
	v_lshl_add_u64 v[218:219], s[76:77], 0, v[190:191]
	global_load_lds_dwordx4 v[216:217], off
	v_lshl_add_u64 v[216:217], s[84:85], 0, v[188:189]
	s_add_i32 m0, s48, 0x2000
	s_nop 0
	global_load_lds_dwordx4 v[216:217], off
	v_lshl_add_u64 v[216:217], s[76:77], 0, v[192:193]
	s_mov_b32 m0, s6
	s_nop 0
	global_load_lds_dwordx4 v[216:217], off
	s_mov_b32 m0, s20
	s_nop 0
	global_load_lds_dwordx4 v[218:219], off
	s_waitcnt vmcnt(8)
	s_waitcnt lgkmcnt(0)
	s_setprio 1
	s_barrier
; #define PG8_STAGE(bufoff, gbase, voff) do { _Pragma("unroll") for (int _i = 0; _i < 2; ++_i) \
;         __builtin_amdgcn_global_load_lds((const unsigned*)((const char*)(gbase) + (voff)[_i]), (PG8_LAS unsigned*)(lds + (bufoff) + ldsw + _i * 8192), 16, 0, 0); } while (0)
; #define PG8_LDA(dst, b, h) do { _Pragma("unroll") for (int m = 0; m < 4; ++m) _Pragma("unroll") for (int k = 0; k < 2; ++k) dst[m][k] = *(const PG8_LAS bf16x8*)(lds + PG8_SA(b, h) + aoff + m * 2048 + k * 1024); } while (0)
; #define PG8_LDB(dst, b, h) do { _Pragma("unroll") for (int n = 0; n < 2; ++n) _Pragma("unroll") for (int k = 0; k < 2; ++k) dst[n][k] = *(const PG8_LAS bf16x8*)(lds + PG8_SB(b, h) + boff + n * 2048 + k * 1024); } while (0)
; #define PG8_MMA(ai, bj, At, Bt) do { __builtin_amdgcn_s_setprio(1); _Pragma("unroll") for (int m = 0; m < 4; ++m) _Pragma("unroll") for (int n = 0; n < 2; ++n) _Pragma("unroll") for (int k = 0; k < 2; ++k) \
;         acc[ai][bj][m][n] = __builtin_amdgcn_mfma_f32_16x16x32_bf16(Bt[n][k], At[m][k], acc[ai][bj][m][n], 0, 0, 0); __builtin_amdgcn_s_setprio(0); } while (0)
; #define PG8_WAIT_V(n) asm volatile("s_waitcnt vmcnt(" #n ")" ::: "memory")
; #define PG8_WAIT_L(n) asm volatile("s_waitcnt lgkmcnt(" #n ")" ::: "memory")
; #define PG8_BAR __builtin_amdgcn_s_barrier()
; #define PG8_SCHED __builtin_amdgcn_sched_barrier(0)
;     ...
;             PG8_WAIT_V(8); PG8_WAIT_L(0); PG8_BAR; PG8_MMA(1, 0, At, B0); PG8_MMA(1, 1, At, B1); PG8_BAR; PG8_SCHED;
;             PG8_LDB(B0, 1, 0); PG8_LDB(B1, 1, 1); PG8_SCHED; PG8_LDA(At, 1, 0); PG8_STAGE(PG8_SA(0, 1), a2 + hstep, voffA);
;             PG8_WAIT_V(8); PG8_WAIT_L(0); PG8_BAR; PG8_MMA(0, 0, At, B0); PG8_MMA(0, 1, At, B1); PG8_BAR; PG8_SCHED;
	v_mfma_f32_16x16x32_bf16 v[64:67], v[108:111], v[164:167], v[64:67]
	v_mfma_f32_16x16x32_bf16 v[60:63], v[128:131], v[164:167], v[60:63]
	v_mfma_f32_16x16x32_bf16 v[48:51], v[108:111], v[172:175], v[48:51]
	v_mfma_f32_16x16x32_bf16 v[44:47], v[128:131], v[172:175], v[44:47]
	v_mfma_f32_16x16x32_bf16 v[32:35], v[108:111], v[180:183], v[32:35]
	v_mfma_f32_16x16x32_bf16 v[28:31], v[128:131], v[180:183], v[28:31]
	v_mfma_f32_16x16x32_bf16 v[16:19], v[108:111], v[206:209], v[16:19]
	v_mfma_f32_16x16x32_bf16 v[12:15], v[128:131], v[206:209], v[12:15]
	v_mfma_f32_16x16x32_bf16 v[64:67], v[112:115], v[168:171], v[64:67]
	v_mfma_f32_16x16x32_bf16 v[60:63], v[136:139], v[168:171], v[60:63]
	v_mfma_f32_16x16x32_bf16 v[48:51], v[112:115], v[176:179], v[48:51]
	v_mfma_f32_16x16x32_bf16 v[44:47], v[136:139], v[176:179], v[44:47]
	v_mfma_f32_16x16x32_bf16 v[32:35], v[112:115], v[184:187], v[32:35]
	v_mfma_f32_16x16x32_bf16 v[28:31], v[136:139], v[184:187], v[28:31]
	v_mfma_f32_16x16x32_bf16 v[16:19], v[112:115], v[210:213], v[16:19]
	v_mfma_f32_16x16x32_bf16 v[12:15], v[136:139], v[210:213], v[12:15]
	s_setprio 0
	s_setprio 1
	v_mfma_f32_16x16x32_bf16 v[56:59], v[148:151], v[164:167], v[56:59]
	v_mfma_f32_16x16x32_bf16 v[52:55], v[156:159], v[164:167], v[52:55]
	v_mfma_f32_16x16x32_bf16 v[40:43], v[148:151], v[172:175], v[40:43]
	v_mfma_f32_16x16x32_bf16 v[36:39], v[156:159], v[172:175], v[36:39]
	v_mfma_f32_16x16x32_bf16 v[24:27], v[148:151], v[180:183], v[24:27]
	v_mfma_f32_16x16x32_bf16 v[20:23], v[156:159], v[180:183], v[20:23]
	v_mfma_f32_16x16x32_bf16 v[8:11], v[148:151], v[206:209], v[8:11]
	v_mfma_f32_16x16x32_bf16 v[4:7], v[156:159], v[206:209], v[4:7]
	v_mfma_f32_16x16x32_bf16 v[56:59], v[152:155], v[168:171], v[56:59]
	v_mfma_f32_16x16x32_bf16 v[52:55], v[160:163], v[168:171], v[52:55]
	v_mfma_f32_16x16x32_bf16 v[40:43], v[152:155], v[176:179], v[40:43]
	v_mfma_f32_16x16x32_bf16 v[36:39], v[160:163], v[176:179], v[36:39]
	v_mfma_f32_16x16x32_bf16 v[24:27], v[152:155], v[184:187], v[24:27]
	v_mfma_f32_16x16x32_bf16 v[20:23], v[160:163], v[184:187], v[20:23]
	v_mfma_f32_16x16x32_bf16 v[8:11], v[152:155], v[210:213], v[8:11]
	v_mfma_f32_16x16x32_bf16 v[4:7], v[160:163], v[210:213], v[4:7]
	s_barrier
	s_setprio 0
	ds_read_b128 v[108:111], v251 offset:32768
	ds_read_b128 v[112:115], v251 offset:33792
	ds_read_b128 v[128:131], v251 offset:34816
	ds_read_b128 v[136:139], v251 offset:35840
	ds_read_b128 v[148:151], v251 offset:49152
	ds_read_b128 v[152:155], v251 offset:50176
	ds_read_b128 v[156:159], v251 offset:51200
	ds_read_b128 v[160:163], v251 offset:52224
	ds_read_b128 v[164:167], v234 offset:32768
	ds_read_b128 v[168:171], v234 offset:33792
	ds_read_b128 v[172:175], v234 offset:34816
	ds_read_b128 v[176:179], v234 offset:35840
	ds_read_b128 v[180:183], v234 offset:36864
	ds_read_b128 v[184:187], v234 offset:37888
	ds_read_b128 v[206:209], v234 offset:38912
	ds_read_b128 v[210:213], v234 offset:39936
	s_add_i32 s48, 0, 0x18000
	s_add_i32 s49, 0, 0x1c000
	s_add_u32 s76, s76, 0x80000
	s_addc_u32 s77, s77, 0
	s_mov_b32 m0, s21
	v_lshl_add_u64 v[220:221], s[76:77], 0, v[192:193]
	global_load_lds_dwordx4 v[220:221], off
	v_lshl_add_u64 v[220:221], s[76:77], 0, v[190:191]
	s_mov_b32 m0, s23
	s_nop 0
	global_load_lds_dwordx4 v[220:221], off
	s_waitcnt vmcnt(8)
	s_waitcnt lgkmcnt(0)
	s_setprio 1
	s_barrier
	v_mfma_f32_16x16x32_bf16 v[144:147], v[108:111], v[164:167], v[144:147]
	v_mfma_f32_16x16x32_bf16 v[140:143], v[128:131], v[164:167], v[140:143]
	v_mfma_f32_16x16x32_bf16 v[120:123], v[108:111], v[172:175], v[120:123]
	v_mfma_f32_16x16x32_bf16 v[116:119], v[128:131], v[172:175], v[116:119]
	v_mfma_f32_16x16x32_bf16 v[96:99], v[108:111], v[180:183], v[96:99]
	v_mfma_f32_16x16x32_bf16 v[92:95], v[128:131], v[180:183], v[92:95]
	v_mfma_f32_16x16x32_bf16 v[80:83], v[108:111], v[206:209], v[80:83]
	v_mfma_f32_16x16x32_bf16 v[76:79], v[128:131], v[206:209], v[76:79]
	v_mfma_f32_16x16x32_bf16 v[144:147], v[112:115], v[168:171], v[144:147]
	v_mfma_f32_16x16x32_bf16 v[140:143], v[136:139], v[168:171], v[140:143]
	v_mfma_f32_16x16x32_bf16 v[120:123], v[112:115], v[176:179], v[120:123]
	v_mfma_f32_16x16x32_bf16 v[116:119], v[136:139], v[176:179], v[116:119]
	v_mfma_f32_16x16x32_bf16 v[96:99], v[112:115], v[184:187], v[96:99]
	v_mfma_f32_16x16x32_bf16 v[92:95], v[136:139], v[184:187], v[92:95]
	v_mfma_f32_16x16x32_bf16 v[80:83], v[112:115], v[210:213], v[80:83]
	v_mfma_f32_16x16x32_bf16 v[76:79], v[136:139], v[210:213], v[76:79]
	s_setprio 0
	s_setprio 1
	v_mfma_f32_16x16x32_bf16 v[132:135], v[148:151], v[164:167], v[132:135]
	v_mfma_f32_16x16x32_bf16 v[124:127], v[156:159], v[164:167], v[124:127]
	v_mfma_f32_16x16x32_bf16 v[104:107], v[148:151], v[172:175], v[104:107]
	v_mfma_f32_16x16x32_bf16 v[100:103], v[156:159], v[172:175], v[100:103]
	v_mfma_f32_16x16x32_bf16 v[88:91], v[148:151], v[180:183], v[88:91]
	v_mfma_f32_16x16x32_bf16 v[84:87], v[156:159], v[180:183], v[84:87]
	v_mfma_f32_16x16x32_bf16 v[72:75], v[148:151], v[206:209], v[72:75]
	v_mfma_f32_16x16x32_bf16 v[68:71], v[156:159], v[206:209], v[68:71]
	v_mfma_f32_16x16x32_bf16 v[132:135], v[152:155], v[168:171], v[132:135]
	v_mfma_f32_16x16x32_bf16 v[124:127], v[160:163], v[168:171], v[124:127]
	v_mfma_f32_16x16x32_bf16 v[104:107], v[152:155], v[176:179], v[104:107]
	v_mfma_f32_16x16x32_bf16 v[100:103], v[160:163], v[176:179], v[100:103]
	v_mfma_f32_16x16x32_bf16 v[88:91], v[152:155], v[184:187], v[88:91]
	v_mfma_f32_16x16x32_bf16 v[84:87], v[160:163], v[184:187], v[84:87]
	v_mfma_f32_16x16x32_bf16 v[72:75], v[152:155], v[210:213], v[72:75]
	v_mfma_f32_16x16x32_bf16 v[68:71], v[160:163], v[210:213], v[68:71]
	s_barrier
; #define PG8_STAGE(bufoff, gbase, voff) do { _Pragma("unroll") for (int _i = 0; _i < 2; ++_i) \
;         __builtin_amdgcn_global_load_lds((const unsigned*)((const char*)(gbase) + (voff)[_i]), (PG8_LAS unsigned*)(lds + (bufoff) + ldsw + _i * 8192), 16, 0, 0); } while (0)
; #define PG8_LDA(dst, b, h) do { _Pragma("unroll") for (int m = 0; m < 4; ++m) _Pragma("unroll") for (int k = 0; k < 2; ++k) dst[m][k] = *(const PG8_LAS bf16x8*)(lds + PG8_SA(b, h) + aoff + m * 2048 + k * 1024); } while (0)
; #define PG8_MMA(ai, bj, At, Bt) do { __builtin_amdgcn_s_setprio(1); _Pragma("unroll") for (int m = 0; m < 4; ++m) _Pragma("unroll") for (int n = 0; n < 2; ++n) _Pragma("unroll") for (int k = 0; k < 2; ++k) \
;         acc[ai][bj][m][n] = __builtin_amdgcn_mfma_f32_16x16x32_bf16(Bt[n][k], At[m][k], acc[ai][bj][m][n], 0, 0, 0); __builtin_amdgcn_s_setprio(0); } while (0)
; #define PG8_WAIT_V(n) asm volatile("s_waitcnt vmcnt(" #n ")" ::: "memory")
; #define PG8_WAIT_L(n) asm volatile("s_waitcnt lgkmcnt(" #n ")" ::: "memory")
; #define PG8_BAR __builtin_amdgcn_s_barrier()
; #define PG8_SCHED __builtin_amdgcn_sched_barrier(0)
;     ...
;             PG8_LDA(At, 1, 1); PG8_STAGE(PG8_SB(1, 0), b3, voffB); PG8_STAGE(PG8_SB(1, 1), b3 + hstep, voffB); PG8_STAGE(PG8_SA(1, 0), a3, voffA);
;             PG8_WAIT_V(8); PG8_WAIT_L(0); PG8_BAR; PG8_MMA(1, 0, At, B0); PG8_MMA(1, 1, At, B1); PG8_BAR; PG8_SCHED;
	s_setprio 0
	ds_read_b128 v[164:167], v234 offset:49152
	ds_read_b128 v[168:171], v234 offset:50176
	ds_read_b128 v[172:175], v234 offset:51200
	ds_read_b128 v[176:179], v234 offset:52224
	ds_read_b128 v[180:183], v234 offset:53248
	ds_read_b128 v[184:187], v234 offset:54272
	ds_read_b128 v[206:209], v234 offset:55296
	ds_read_b128 v[210:213], v234 offset:56320
	s_add_i32 s48, s48, s5
	v_lshl_add_u64 v[198:199], v[198:199], 0, s[66:67]
	s_mov_b32 m0, s48
	s_nop 0
	global_load_lds_dwordx4 v[198:199], off
	s_add_i32 m0, s48, 0x2000
	s_add_u32 s70, s70, 0x80080
	v_lshl_add_u64 v[198:199], v[214:215], 0, s[66:67]
	s_addc_u32 s71, s71, 0
	s_add_i32 s48, s49, s5
	global_load_lds_dwordx4 v[198:199], off
	v_lshl_add_u64 v[198:199], s[70:71], 0, v[200:201]
	s_mov_b32 m0, s48
	s_nop 0
	global_load_lds_dwordx4 v[198:199], off
	v_lshl_add_u64 v[198:199], s[70:71], 0, v[188:189]
	s_add_i32 m0, s48, 0x2000
	s_nop 0
	global_load_lds_dwordx4 v[198:199], off
	v_lshl_add_u64 v[198:199], v[216:217], 0, s[66:67]
	s_mov_b32 m0, s54
	s_nop 0
	global_load_lds_dwordx4 v[198:199], off
	v_lshl_add_u64 v[198:199], v[218:219], 0, s[66:67]
	s_mov_b32 m0, s55
	s_nop 0
	global_load_lds_dwordx4 v[198:199], off
	s_waitcnt vmcnt(8)
	s_waitcnt lgkmcnt(0)
	s_setprio 1
	s_barrier
	v_mfma_f32_16x16x32_bf16 v[64:67], v[108:111], v[164:167], v[64:67]
	v_mfma_f32_16x16x32_bf16 v[60:63], v[128:131], v[164:167], v[60:63]
	v_mfma_f32_16x16x32_bf16 v[48:51], v[108:111], v[172:175], v[48:51]
	v_mfma_f32_16x16x32_bf16 v[44:47], v[128:131], v[172:175], v[44:47]
	v_mfma_f32_16x16x32_bf16 v[32:35], v[108:111], v[180:183], v[32:35]
	v_mfma_f32_16x16x32_bf16 v[28:31], v[128:131], v[180:183], v[28:31]
	v_mfma_f32_16x16x32_bf16 v[16:19], v[108:111], v[206:209], v[16:19]
	v_mfma_f32_16x16x32_bf16 v[12:15], v[128:131], v[206:209], v[12:15]
	v_mfma_f32_16x16x32_bf16 v[64:67], v[112:115], v[168:171], v[64:67]
	v_mfma_f32_16x16x32_bf16 v[60:63], v[136:139], v[168:171], v[60:63]
	v_mfma_f32_16x16x32_bf16 v[48:51], v[112:115], v[176:179], v[48:51]
	v_mfma_f32_16x16x32_bf16 v[44:47], v[136:139], v[176:179], v[44:47]
	v_mfma_f32_16x16x32_bf16 v[32:35], v[112:115], v[184:187], v[32:35]
	v_mfma_f32_16x16x32_bf16 v[28:31], v[136:139], v[184:187], v[28:31]
	v_mfma_f32_16x16x32_bf16 v[16:19], v[112:115], v[210:213], v[16:19]
	v_mfma_f32_16x16x32_bf16 v[12:15], v[136:139], v[210:213], v[12:15]
	s_setprio 0
	s_setprio 1
	v_mfma_f32_16x16x32_bf16 v[56:59], v[148:151], v[164:167], v[56:59]
	v_mfma_f32_16x16x32_bf16 v[52:55], v[156:159], v[164:167], v[52:55]
	v_mfma_f32_16x16x32_bf16 v[40:43], v[148:151], v[172:175], v[40:43]
	v_mfma_f32_16x16x32_bf16 v[36:39], v[156:159], v[172:175], v[36:39]
	v_mfma_f32_16x16x32_bf16 v[24:27], v[148:151], v[180:183], v[24:27]
	v_mfma_f32_16x16x32_bf16 v[20:23], v[156:159], v[180:183], v[20:23]
	v_mfma_f32_16x16x32_bf16 v[8:11], v[148:151], v[206:209], v[8:11]
	v_mfma_f32_16x16x32_bf16 v[4:7], v[156:159], v[206:209], v[4:7]
	v_mfma_f32_16x16x32_bf16 v[56:59], v[152:155], v[168:171], v[56:59]
	v_mfma_f32_16x16x32_bf16 v[52:55], v[160:163], v[168:171], v[52:55]
	v_mfma_f32_16x16x32_bf16 v[40:43], v[152:155], v[176:179], v[40:43]
	v_mfma_f32_16x16x32_bf16 v[36:39], v[160:163], v[176:179], v[36:39]
	v_mfma_f32_16x16x32_bf16 v[24:27], v[152:155], v[184:187], v[24:27]
	v_mfma_f32_16x16x32_bf16 v[20:23], v[160:163], v[184:187], v[20:23]
	v_mfma_f32_16x16x32_bf16 v[8:11], v[152:155], v[210:213], v[8:11]
	v_mfma_f32_16x16x32_bf16 v[4:7], v[160:163], v[210:213], v[4:7]
	s_barrier
	s_setprio 0
	s_add_i32 s79, s79, 2
	s_add_u32 s75, s75, 0x100
	s_addc_u32 s78, s78, 0
	s_add_u32 s68, s68, 0x100
	s_addc_u32 s69, s69, 0
	s_cmp_gt_u32 s79, 29
	s_cbranch_scc0 .LBB0_998
	s_and_b64 vcc, exec, s[14:15]
	s_cbranch_vccz .LBB0_1001
	s_barrier

; #define PG8_STAGE(bufoff, gbase, voff) do { _Pragma("unroll") for (int _i = 0; _i < 2; ++_i) \
;         __builtin_amdgcn_global_load_lds((const unsigned*)((const char*)(gbase) + (voff)[_i]), (PG8_LAS unsigned*)(lds + (bufoff) + ldsw + _i * 8192), 16, 0, 0); } while (0)
; #define PG8_LDA(dst, b, h) do { _Pragma("unroll") for (int m = 0; m < 4; ++m) _Pragma("unroll") for (int k = 0; k < 2; ++k) dst[m][k] = *(const PG8_LAS bf16x8*)(lds + PG8_SA(b, h) + aoff + m * 2048 + k * 1024); } while (0)
; #define PG8_LDB(dst, b, h) do { _Pragma("unroll") for (int n = 0; n < 2; ++n) _Pragma("unroll") for (int k = 0; k < 2; ++k) dst[n][k] = *(const PG8_LAS bf16x8*)(lds + PG8_SB(b, h) + boff + n * 2048 + k * 1024); } while (0)
; #define PG8_MMA(ai, bj, At, Bt) do { __builtin_amdgcn_s_setprio(1); _Pragma("unroll") for (int m = 0; m < 4; ++m) _Pragma("unroll") for (int n = 0; n < 2; ++n) _Pragma("unroll") for (int k = 0; k < 2; ++k) \
;         acc[ai][bj][m][n] = __builtin_amdgcn_mfma_f32_16x16x32_bf16(Bt[n][k], At[m][k], acc[ai][bj][m][n], 0, 0, 0); __builtin_amdgcn_s_setprio(0); } while (0)
; #define PG8_WAIT_V(n) asm volatile("s_waitcnt vmcnt(" #n ")" ::: "memory")
; #define PG8_WAIT_L(n) asm volatile("s_waitcnt lgkmcnt(" #n ")" ::: "memory")
; #define PG8_BAR __builtin_amdgcn_s_barrier()
; #define PG8_SCHED __builtin_amdgcn_sched_barrier(0)
;     ...
;             const bool last = (t == nt - 2);
;             const char* a1 = cA + (size_t)(t + 1) * kstep;
;             const char* a2 = last ? nA : cA + (size_t)(t + 2) * kstep; const char* b2 = last ? nB : cB + (size_t)(t + 2) * kstep;
;             const char* a3 = a2 + kstep; const char* b3 = b2 + kstep;
;             if (last && has_next) S.a_ready(nxt);
;             if (t == 0) E.pre_issue(pre, cur, tid, ui); else if (t == 2) E.pre_finish(pre, tid, ui);
;             if constexpr (SP2) {
;             PG8_LDB(B0, 0, 0); PG8_LDB(B1, 0, 1); PG8_SCHED; PG8_LDA(At, 0, 0); PG8_STAGE(PG8_SA(1, 1), a1 + hstep, voffA);
;             PG8_WAIT_V(8); PG8_WAIT_L(0); PG8_BAR; PG8_MMA(0, 0, At, B0); PG8_MMA(0, 1, At, B1); PG8_BAR; PG8_SCHED;
;             PG8_LDA(At, 0, 1); PG8_STAGE(PG8_SB(0, 0), b2, voffB); PG8_STAGE(PG8_SB(0, 1), b2 + hstep, voffB); PG8_STAGE(PG8_SA(0, 0), a2, voffA);
;             PG8_WAIT_V(8); PG8_WAIT_L(0); PG8_BAR; PG8_MMA(1, 0, At, B0); PG8_MMA(1, 1, At, B1); PG8_BAR; PG8_SCHED;
.LBB0_1086:
	ds_read_b128 v[106:109], v251
	ds_read_b128 v[110:113], v251 offset:1024
	ds_read_b128 v[114:117], v251 offset:2048
	ds_read_b128 v[118:121], v251 offset:3072
	ds_read_b128 v[122:125], v251 offset:16384
	ds_read_b128 v[126:129], v251 offset:17408
	ds_read_b128 v[130:133], v251 offset:18432
	ds_read_b128 v[134:137], v251 offset:19456
	ds_read_b128 v[166:169], v222
	ds_read_b128 v[170:173], v222 offset:1024
	ds_read_b128 v[174:177], v222 offset:2048
	ds_read_b128 v[178:181], v222 offset:3072
	ds_read_b128 v[194:197], v222 offset:4096
	ds_read_b128 v[206:209], v222 offset:5120
	ds_read_b128 v[210:213], v222 offset:6144
	ds_read_b128 v[214:217], v222 offset:7168
	s_add_u32 s10, s8, 0xfff80080
	s_addc_u32 s11, s9, -1
	s_add_i32 s48, 0, 0x10000
	s_cmp_eq_u32 s97, 28
	s_cselect_b32 s13, s69, s11
	s_cselect_b32 s12, s76, s10
	s_cselect_b32 s11, s77, s89
	s_cselect_b32 s10, s82, s83
	s_add_i32 vcc_lo, 0, 0x14000
	v_lshl_add_u64 v[100:101], s[8:9], 0, v[190:191]
	s_add_i32 m0, s1, 0xc000
	s_nop 0
	global_load_lds_dwordx4 v[100:101], off
	v_lshl_add_u64 v[100:101], s[8:9], 0, v[192:193]
	s_add_i32 m0, s1, 0xe000
	s_nop 0
	global_load_lds_dwordx4 v[100:101], off
	s_waitcnt vmcnt(8)
	s_waitcnt lgkmcnt(0)
	s_setprio 1
	s_barrier
	v_mfma_f32_16x16x32_bf16 v[4:7], v[106:109], v[166:169], v[4:7]
	v_mfma_f32_16x16x32_bf16 v[72:75], v[114:117], v[166:169], v[72:75]
	v_mfma_f32_16x16x32_bf16 v[162:165], v[106:109], v[174:177], v[162:165]
	v_mfma_f32_16x16x32_bf16 v[60:63], v[114:117], v[174:177], v[60:63]
	v_mfma_f32_16x16x32_bf16 v[158:161], v[106:109], v[194:197], v[158:161]
	v_mfma_f32_16x16x32_bf16 v[56:59], v[114:117], v[194:197], v[56:59]
	v_mfma_f32_16x16x32_bf16 v[96:99], v[106:109], v[210:213], v[96:99]
	v_mfma_f32_16x16x32_bf16 v[76:79], v[114:117], v[210:213], v[76:79]
	v_mfma_f32_16x16x32_bf16 v[4:7], v[110:113], v[170:173], v[4:7]
	v_mfma_f32_16x16x32_bf16 v[72:75], v[118:121], v[170:173], v[72:75]
	v_mfma_f32_16x16x32_bf16 v[162:165], v[110:113], v[178:181], v[162:165]
	v_mfma_f32_16x16x32_bf16 v[60:63], v[118:121], v[178:181], v[60:63]
	v_mfma_f32_16x16x32_bf16 v[158:161], v[110:113], v[206:209], v[158:161]
	v_mfma_f32_16x16x32_bf16 v[56:59], v[118:121], v[206:209], v[56:59]
	v_mfma_f32_16x16x32_bf16 v[96:99], v[110:113], v[214:217], v[96:99]
	v_mfma_f32_16x16x32_bf16 v[76:79], v[118:121], v[214:217], v[76:79]
	s_setprio 0
	s_setprio 1
	v_mfma_f32_16x16x32_bf16 v[8:11], v[122:125], v[166:169], v[8:11]
	v_mfma_f32_16x16x32_bf16 v[64:67], v[130:133], v[166:169], v[64:67]
	v_mfma_f32_16x16x32_bf16 v[154:157], v[122:125], v[174:177], v[154:157]
	v_mfma_f32_16x16x32_bf16 v[52:55], v[130:133], v[174:177], v[52:55]
	v_mfma_f32_16x16x32_bf16 v[150:153], v[122:125], v[194:197], v[150:153]
	v_mfma_f32_16x16x32_bf16 v[48:51], v[130:133], v[194:197], v[48:51]
	v_mfma_f32_16x16x32_bf16 v[92:95], v[122:125], v[210:213], v[92:95]
	v_mfma_f32_16x16x32_bf16 v[68:71], v[130:133], v[210:213], v[68:71]
	v_mfma_f32_16x16x32_bf16 v[8:11], v[126:129], v[170:173], v[8:11]
	v_mfma_f32_16x16x32_bf16 v[64:67], v[134:137], v[170:173], v[64:67]
	v_mfma_f32_16x16x32_bf16 v[154:157], v[126:129], v[178:181], v[154:157]
	v_mfma_f32_16x16x32_bf16 v[52:55], v[134:137], v[178:181], v[52:55]
	v_mfma_f32_16x16x32_bf16 v[150:153], v[126:129], v[206:209], v[150:153]
	v_mfma_f32_16x16x32_bf16 v[48:51], v[134:137], v[206:209], v[48:51]
	v_mfma_f32_16x16x32_bf16 v[92:95], v[126:129], v[214:217], v[92:95]
	v_mfma_f32_16x16x32_bf16 v[68:71], v[134:137], v[214:217], v[68:71]
	s_barrier
	s_setprio 0
	ds_read_b128 v[166:169], v222 offset:16384
	ds_read_b128 v[170:173], v222 offset:17408
	ds_read_b128 v[174:177], v222 offset:18432
	ds_read_b128 v[178:181], v222 offset:19456
	ds_read_b128 v[194:197], v222 offset:20480
	ds_read_b128 v[206:209], v222 offset:21504
	ds_read_b128 v[210:213], v222 offset:22528
	ds_read_b128 v[214:217], v222 offset:23552
	s_add_i32 s48, s48, s0
	v_lshl_add_u64 v[198:199], s[10:11], 0, v[186:187]
	s_mov_b32 m0, s48
	s_nop 0
	global_load_lds_dwordx4 v[198:199], off
	s_add_i32 m0, s48, 0x2000
	s_add_u32 s48, s10, 0x80000
	v_lshl_add_u64 v[218:219], s[10:11], 0, v[182:183]
	s_addc_u32 s49, s11, 0
	s_add_i32 vcc_lo, vcc_lo, s0
	global_load_lds_dwordx4 v[218:219], off
	v_lshl_add_u64 v[100:101], s[48:49], 0, v[186:187]
	s_mov_b32 m0, vcc_lo
	v_lshl_add_u64 v[224:225], s[12:13], 0, v[188:189]
	global_load_lds_dwordx4 v[100:101], off
	v_lshl_add_u64 v[100:101], s[48:49], 0, v[182:183]
	s_add_i32 m0, vcc_lo, 0x2000
	v_lshl_add_u64 v[232:233], s[12:13], 0, v[184:185]
	global_load_lds_dwordx4 v[100:101], off
	s_mov_b32 m0, s1
	s_nop 0
	global_load_lds_dwordx4 v[224:225], off
	s_mov_b32 m0, s4
	s_nop 0
	global_load_lds_dwordx4 v[232:233], off
	s_waitcnt vmcnt(8)
	s_waitcnt lgkmcnt(0)
	s_setprio 1
	s_barrier
; #define PG8_STAGE(bufoff, gbase, voff) do { _Pragma("unroll") for (int _i = 0; _i < 2; ++_i) \
;         __builtin_amdgcn_global_load_lds((const unsigned*)((const char*)(gbase) + (voff)[_i]), (PG8_LAS unsigned*)(lds + (bufoff) + ldsw + _i * 8192), 16, 0, 0); } while (0)
; #define PG8_LDA(dst, b, h) do { _Pragma("unroll") for (int m = 0; m < 4; ++m) _Pragma("unroll") for (int k = 0; k < 2; ++k) dst[m][k] = *(const PG8_LAS bf16x8*)(lds + PG8_SA(b, h) + aoff + m * 2048 + k * 1024); } while (0)
; #define PG8_LDB(dst, b, h) do { _Pragma("unroll") for (int n = 0; n < 2; ++n) _Pragma("unroll") for (int k = 0; k < 2; ++k) dst[n][k] = *(const PG8_LAS bf16x8*)(lds + PG8_SB(b, h) + boff + n * 2048 + k * 1024); } while (0)
; #define PG8_MMA(ai, bj, At, Bt) do { __builtin_amdgcn_s_setprio(1); _Pragma("unroll") for (int m = 0; m < 4; ++m) _Pragma("unroll") for (int n = 0; n < 2; ++n) _Pragma("unroll") for (int k = 0; k < 2; ++k) \
;         acc[ai][bj][m][n] = __builtin_amdgcn_mfma_f32_16x16x32_bf16(Bt[n][k], At[m][k], acc[ai][bj][m][n], 0, 0, 0); __builtin_amdgcn_s_setprio(0); } while (0)
; #define PG8_WAIT_V(n) asm volatile("s_waitcnt vmcnt(" #n ")" ::: "memory")
; #define PG8_WAIT_L(n) asm volatile("s_waitcnt lgkmcnt(" #n ")" ::: "memory")
; #define PG8_BAR __builtin_amdgcn_s_barrier()
; #define PG8_SCHED __builtin_amdgcn_sched_barrier(0)
;     ...
;             PG8_WAIT_V(8); PG8_WAIT_L(0); PG8_BAR; PG8_MMA(1, 0, At, B0); PG8_MMA(1, 1, At, B1); PG8_BAR; PG8_SCHED;
;             PG8_LDB(B0, 1, 0); PG8_LDB(B1, 1, 1); PG8_SCHED; PG8_LDA(At, 1, 0); PG8_STAGE(PG8_SA(0, 1), a2 + hstep, voffA);
;             PG8_WAIT_V(8); PG8_WAIT_L(0); PG8_BAR; PG8_MMA(0, 0, At, B0); PG8_MMA(0, 1, At, B1); PG8_BAR; PG8_SCHED;
	v_mfma_f32_16x16x32_bf16 v[146:149], v[106:109], v[166:169], v[146:149]
	v_mfma_f32_16x16x32_bf16 v[44:47], v[114:117], v[166:169], v[44:47]
	v_mfma_f32_16x16x32_bf16 v[142:145], v[106:109], v[174:177], v[142:145]
	v_mfma_f32_16x16x32_bf16 v[40:43], v[114:117], v[174:177], v[40:43]
	v_mfma_f32_16x16x32_bf16 v[138:141], v[106:109], v[194:197], v[138:141]
	v_mfma_f32_16x16x32_bf16 v[36:39], v[114:117], v[194:197], v[36:39]
	v_mfma_f32_16x16x32_bf16 v[80:83], v[106:109], v[210:213], v[80:83]
	v_mfma_f32_16x16x32_bf16 v[20:23], v[114:117], v[210:213], v[20:23]
	v_mfma_f32_16x16x32_bf16 v[146:149], v[110:113], v[170:173], v[146:149]
	v_mfma_f32_16x16x32_bf16 v[44:47], v[118:121], v[170:173], v[44:47]
	v_mfma_f32_16x16x32_bf16 v[142:145], v[110:113], v[178:181], v[142:145]
	v_mfma_f32_16x16x32_bf16 v[40:43], v[118:121], v[178:181], v[40:43]
	v_mfma_f32_16x16x32_bf16 v[138:141], v[110:113], v[206:209], v[138:141]
	v_mfma_f32_16x16x32_bf16 v[36:39], v[118:121], v[206:209], v[36:39]
	v_mfma_f32_16x16x32_bf16 v[80:83], v[110:113], v[214:217], v[80:83]
	v_mfma_f32_16x16x32_bf16 v[20:23], v[118:121], v[214:217], v[20:23]
	s_setprio 0
	s_setprio 1
	v_mfma_f32_16x16x32_bf16 v[100:103], v[122:125], v[166:169], v[102:105]
	v_mfma_f32_16x16x32_bf16 v[32:35], v[130:133], v[166:169], v[32:35]
	v_mfma_f32_16x16x32_bf16 v[88:91], v[122:125], v[174:177], v[88:91]
	v_mfma_f32_16x16x32_bf16 v[28:31], v[130:133], v[174:177], v[28:31]
	v_mfma_f32_16x16x32_bf16 v[84:87], v[122:125], v[194:197], v[84:87]
	v_mfma_f32_16x16x32_bf16 v[24:27], v[130:133], v[194:197], v[24:27]
	v_mfma_f32_16x16x32_bf16 v[16:19], v[122:125], v[210:213], v[16:19]
	v_mfma_f32_16x16x32_bf16 v[12:15], v[130:133], v[210:213], v[12:15]
	v_mfma_f32_16x16x32_bf16 v[100:103], v[126:129], v[170:173], v[100:103]
	v_mfma_f32_16x16x32_bf16 v[32:35], v[134:137], v[170:173], v[32:35]
	v_mfma_f32_16x16x32_bf16 v[88:91], v[126:129], v[178:181], v[88:91]
	v_mfma_f32_16x16x32_bf16 v[28:31], v[134:137], v[178:181], v[28:31]
	v_mfma_f32_16x16x32_bf16 v[84:87], v[126:129], v[206:209], v[84:87]
	v_mfma_f32_16x16x32_bf16 v[24:27], v[134:137], v[206:209], v[24:27]
	v_mfma_f32_16x16x32_bf16 v[16:19], v[126:129], v[214:217], v[16:19]
	v_mfma_f32_16x16x32_bf16 v[12:15], v[134:137], v[214:217], v[12:15]
	s_barrier
	s_setprio 0
	ds_read_b128 v[104:107], v251 offset:32768
	ds_read_b128 v[108:111], v251 offset:33792
	ds_read_b128 v[112:115], v251 offset:34816
	ds_read_b128 v[116:119], v251 offset:35840
	ds_read_b128 v[120:123], v251 offset:49152
	ds_read_b128 v[124:127], v251 offset:50176
	ds_read_b128 v[128:131], v251 offset:51200
	ds_read_b128 v[132:135], v251 offset:52224
	ds_read_b128 v[166:169], v222 offset:32768
	ds_read_b128 v[170:173], v222 offset:33792
	ds_read_b128 v[174:177], v222 offset:34816
	ds_read_b128 v[178:181], v222 offset:35840
	ds_read_b128 v[194:197], v222 offset:36864
	ds_read_b128 v[206:209], v222 offset:37888
	ds_read_b128 v[210:213], v222 offset:38912
	ds_read_b128 v[214:217], v222 offset:39936
	s_add_i32 s48, 0, 0x18000
	s_add_i32 s49, 0, 0x1c000
	s_add_u32 s12, s12, 0x80000
	s_addc_u32 s13, s13, 0
	s_mov_b32 m0, s5
	v_lshl_add_u64 v[136:137], s[12:13], 0, v[188:189]
	global_load_lds_dwordx4 v[136:137], off
	v_lshl_add_u64 v[136:137], s[12:13], 0, v[184:185]
	s_mov_b32 m0, s44
	s_nop 0
	global_load_lds_dwordx4 v[136:137], off
	s_waitcnt vmcnt(8)
	s_waitcnt lgkmcnt(0)
	s_setprio 1
	s_barrier
	v_mfma_f32_16x16x32_bf16 v[4:7], v[104:107], v[166:169], v[4:7]
	v_mfma_f32_16x16x32_bf16 v[72:75], v[112:115], v[166:169], v[72:75]
	v_mfma_f32_16x16x32_bf16 v[162:165], v[104:107], v[174:177], v[162:165]
	v_mfma_f32_16x16x32_bf16 v[60:63], v[112:115], v[174:177], v[60:63]
	v_mfma_f32_16x16x32_bf16 v[158:161], v[104:107], v[194:197], v[158:161]
	v_mfma_f32_16x16x32_bf16 v[56:59], v[112:115], v[194:197], v[56:59]
	v_mfma_f32_16x16x32_bf16 v[96:99], v[104:107], v[210:213], v[96:99]
	v_mfma_f32_16x16x32_bf16 v[76:79], v[112:115], v[210:213], v[76:79]
	v_mfma_f32_16x16x32_bf16 v[4:7], v[108:111], v[170:173], v[4:7]
	v_mfma_f32_16x16x32_bf16 v[72:75], v[116:119], v[170:173], v[72:75]
	v_mfma_f32_16x16x32_bf16 v[162:165], v[108:111], v[178:181], v[162:165]
	v_mfma_f32_16x16x32_bf16 v[60:63], v[116:119], v[178:181], v[60:63]
	v_mfma_f32_16x16x32_bf16 v[158:161], v[108:111], v[206:209], v[158:161]
	v_mfma_f32_16x16x32_bf16 v[56:59], v[116:119], v[206:209], v[56:59]
	v_mfma_f32_16x16x32_bf16 v[96:99], v[108:111], v[214:217], v[96:99]
	v_mfma_f32_16x16x32_bf16 v[76:79], v[116:119], v[214:217], v[76:79]
	s_setprio 0
	s_setprio 1
	v_mfma_f32_16x16x32_bf16 v[8:11], v[120:123], v[166:169], v[8:11]
	v_mfma_f32_16x16x32_bf16 v[64:67], v[128:131], v[166:169], v[64:67]
	v_mfma_f32_16x16x32_bf16 v[154:157], v[120:123], v[174:177], v[154:157]
	v_mfma_f32_16x16x32_bf16 v[52:55], v[128:131], v[174:177], v[52:55]
	v_mfma_f32_16x16x32_bf16 v[150:153], v[120:123], v[194:197], v[150:153]
	v_mfma_f32_16x16x32_bf16 v[48:51], v[128:131], v[194:197], v[48:51]
	v_mfma_f32_16x16x32_bf16 v[92:95], v[120:123], v[210:213], v[92:95]
	v_mfma_f32_16x16x32_bf16 v[68:71], v[128:131], v[210:213], v[68:71]
	v_mfma_f32_16x16x32_bf16 v[8:11], v[124:127], v[170:173], v[8:11]
	v_mfma_f32_16x16x32_bf16 v[64:67], v[132:135], v[170:173], v[64:67]
	v_mfma_f32_16x16x32_bf16 v[154:157], v[124:127], v[178:181], v[154:157]
	v_mfma_f32_16x16x32_bf16 v[52:55], v[132:135], v[178:181], v[52:55]
	v_mfma_f32_16x16x32_bf16 v[150:153], v[124:127], v[206:209], v[150:153]
	v_mfma_f32_16x16x32_bf16 v[48:51], v[132:135], v[206:209], v[48:51]
	v_mfma_f32_16x16x32_bf16 v[92:95], v[124:127], v[214:217], v[92:95]
	v_mfma_f32_16x16x32_bf16 v[68:71], v[132:135], v[214:217], v[68:71]
	s_barrier
; #define PG8_STAGE(bufoff, gbase, voff) do { _Pragma("unroll") for (int _i = 0; _i < 2; ++_i) \
;         __builtin_amdgcn_global_load_lds((const unsigned*)((const char*)(gbase) + (voff)[_i]), (PG8_LAS unsigned*)(lds + (bufoff) + ldsw + _i * 8192), 16, 0, 0); } while (0)
; #define PG8_LDA(dst, b, h) do { _Pragma("unroll") for (int m = 0; m < 4; ++m) _Pragma("unroll") for (int k = 0; k < 2; ++k) dst[m][k] = *(const PG8_LAS bf16x8*)(lds + PG8_SA(b, h) + aoff + m * 2048 + k * 1024); } while (0)
; #define PG8_MMA(ai, bj, At, Bt) do { __builtin_amdgcn_s_setprio(1); _Pragma("unroll") for (int m = 0; m < 4; ++m) _Pragma("unroll") for (int n = 0; n < 2; ++n) _Pragma("unroll") for (int k = 0; k < 2; ++k) \
;         acc[ai][bj][m][n] = __builtin_amdgcn_mfma_f32_16x16x32_bf16(Bt[n][k], At[m][k], acc[ai][bj][m][n], 0, 0, 0); __builtin_amdgcn_s_setprio(0); } while (0)
; #define PG8_WAIT_V(n) asm volatile("s_waitcnt vmcnt(" #n ")" ::: "memory")
; #define PG8_WAIT_L(n) asm volatile("s_waitcnt lgkmcnt(" #n ")" ::: "memory")
; #define PG8_BAR __builtin_amdgcn_s_barrier()
; #define PG8_SCHED __builtin_amdgcn_sched_barrier(0)
;     ...
;             PG8_LDA(At, 1, 1); PG8_STAGE(PG8_SB(1, 0), b3, voffB); PG8_STAGE(PG8_SB(1, 1), b3 + hstep, voffB); PG8_STAGE(PG8_SA(1, 0), a3, voffA);
;             PG8_WAIT_V(8); PG8_WAIT_L(0); PG8_BAR; PG8_MMA(1, 0, At, B0); PG8_MMA(1, 1, At, B1); PG8_BAR; PG8_SCHED;
	s_setprio 0
	ds_read_b128 v[166:169], v222 offset:49152
	ds_read_b128 v[170:173], v222 offset:50176
	ds_read_b128 v[174:177], v222 offset:51200
	ds_read_b128 v[178:181], v222 offset:52224
	ds_read_b128 v[194:197], v222 offset:53248
	ds_read_b128 v[206:209], v222 offset:54272
	ds_read_b128 v[210:213], v222 offset:55296
	ds_read_b128 v[214:217], v222 offset:56320
	s_add_i32 s12, s48, s0
	v_lshl_add_u64 v[136:137], v[198:199], 0, s[66:67]
	s_mov_b32 m0, s12
	s_nop 0
	global_load_lds_dwordx4 v[136:137], off
	s_add_i32 m0, s12, 0x2000
	s_add_u32 s10, s10, 0x80080
	v_lshl_add_u64 v[136:137], v[218:219], 0, s[66:67]
	s_addc_u32 s11, s11, 0
	s_add_i32 s12, s49, s0
	global_load_lds_dwordx4 v[136:137], off
	v_lshl_add_u64 v[136:137], s[10:11], 0, v[186:187]
	s_mov_b32 m0, s12
	s_nop 0
	global_load_lds_dwordx4 v[136:137], off
	v_lshl_add_u64 v[136:137], s[10:11], 0, v[182:183]
	s_add_i32 m0, s12, 0x2000
	s_nop 0
	global_load_lds_dwordx4 v[136:137], off
	v_lshl_add_u64 v[136:137], v[224:225], 0, s[66:67]
	s_mov_b32 m0, s42
	s_nop 0
	global_load_lds_dwordx4 v[136:137], off
	v_lshl_add_u64 v[136:137], v[232:233], 0, s[66:67]
	s_mov_b32 m0, s55
	s_nop 0
	global_load_lds_dwordx4 v[136:137], off
	s_waitcnt vmcnt(8)
	s_waitcnt lgkmcnt(0)
	s_setprio 1
	s_barrier
	v_mfma_f32_16x16x32_bf16 v[146:149], v[104:107], v[166:169], v[146:149]
	v_mfma_f32_16x16x32_bf16 v[44:47], v[112:115], v[166:169], v[44:47]
	v_mfma_f32_16x16x32_bf16 v[142:145], v[104:107], v[174:177], v[142:145]
	v_mfma_f32_16x16x32_bf16 v[40:43], v[112:115], v[174:177], v[40:43]
	v_mfma_f32_16x16x32_bf16 v[136:139], v[104:107], v[194:197], v[138:141]
	v_mfma_f32_16x16x32_bf16 v[36:39], v[112:115], v[194:197], v[36:39]
	v_mfma_f32_16x16x32_bf16 v[80:83], v[104:107], v[210:213], v[80:83]
	v_mfma_f32_16x16x32_bf16 v[20:23], v[112:115], v[210:213], v[20:23]
	v_mfma_f32_16x16x32_bf16 v[146:149], v[108:111], v[170:173], v[146:149]
	v_mfma_f32_16x16x32_bf16 v[44:47], v[116:119], v[170:173], v[44:47]
	v_mfma_f32_16x16x32_bf16 v[142:145], v[108:111], v[178:181], v[142:145]
	v_mfma_f32_16x16x32_bf16 v[40:43], v[116:119], v[178:181], v[40:43]
	v_mfma_f32_16x16x32_bf16 v[138:141], v[108:111], v[206:209], v[136:139]
	v_mfma_f32_16x16x32_bf16 v[36:39], v[116:119], v[206:209], v[36:39]
	v_mfma_f32_16x16x32_bf16 v[80:83], v[108:111], v[214:217], v[80:83]
	v_mfma_f32_16x16x32_bf16 v[20:23], v[116:119], v[214:217], v[20:23]
	s_setprio 0
	s_setprio 1
	v_mfma_f32_16x16x32_bf16 v[100:103], v[120:123], v[166:169], v[100:103]
	v_mfma_f32_16x16x32_bf16 v[32:35], v[128:131], v[166:169], v[32:35]
	v_mfma_f32_16x16x32_bf16 v[88:91], v[120:123], v[174:177], v[88:91]
	v_mfma_f32_16x16x32_bf16 v[28:31], v[128:131], v[174:177], v[28:31]
	v_mfma_f32_16x16x32_bf16 v[84:87], v[120:123], v[194:197], v[84:87]
	v_mfma_f32_16x16x32_bf16 v[24:27], v[128:131], v[194:197], v[24:27]
	v_mfma_f32_16x16x32_bf16 v[16:19], v[120:123], v[210:213], v[16:19]
	v_mfma_f32_16x16x32_bf16 v[12:15], v[128:131], v[210:213], v[12:15]
	v_mfma_f32_16x16x32_bf16 v[102:105], v[124:127], v[170:173], v[100:103]
	v_mfma_f32_16x16x32_bf16 v[32:35], v[132:135], v[170:173], v[32:35]
	v_mfma_f32_16x16x32_bf16 v[88:91], v[124:127], v[178:181], v[88:91]
	v_mfma_f32_16x16x32_bf16 v[28:31], v[132:135], v[178:181], v[28:31]
	v_mfma_f32_16x16x32_bf16 v[84:87], v[124:127], v[206:209], v[84:87]
	v_mfma_f32_16x16x32_bf16 v[24:27], v[132:135], v[206:209], v[24:27]
	v_mfma_f32_16x16x32_bf16 v[16:19], v[124:127], v[214:217], v[16:19]
	v_mfma_f32_16x16x32_bf16 v[12:15], v[132:135], v[214:217], v[12:15]
	s_barrier
	s_setprio 0
	s_add_i32 s97, s97, 2
	s_add_u32 s8, s8, 0x100
	s_addc_u32 s9, s9, 0
	s_add_u32 s83, s83, 0x100
	s_addc_u32 s89, s89, 0
	s_cmp_gt_u32 s97, 29
	s_cbranch_scc0 .LBB0_1086
	s_and_b64 vcc, exec, s[70:71]
	s_cbranch_vccz .LBB0_1089
	s_barrier

; #define PG8_STAGE(bufoff, gbase, voff) do { _Pragma("unroll") for (int _i = 0; _i < 2; ++_i) \
;         __builtin_amdgcn_global_load_lds((const unsigned*)((const char*)(gbase) + (voff)[_i]), (PG8_LAS unsigned*)(lds + (bufoff) + ldsw + _i * 8192), 16, 0, 0); } while (0)
; #define PG8_LDA(dst, b, h) do { _Pragma("unroll") for (int m = 0; m < 4; ++m) _Pragma("unroll") for (int k = 0; k < 2; ++k) dst[m][k] = *(const PG8_LAS bf16x8*)(lds + PG8_SA(b, h) + aoff + m * 2048 + k * 1024); } while (0)
; #define PG8_LDB(dst, b, h) do { _Pragma("unroll") for (int n = 0; n < 2; ++n) _Pragma("unroll") for (int k = 0; k < 2; ++k) dst[n][k] = *(const PG8_LAS bf16x8*)(lds + PG8_SB(b, h) + boff + n * 2048 + k * 1024); } while (0)
; #define PG8_MMA(ai, bj, At, Bt) do { __builtin_amdgcn_s_setprio(1); _Pragma("unroll") for (int m = 0; m < 4; ++m) _Pragma("unroll") for (int n = 0; n < 2; ++n) _Pragma("unroll") for (int k = 0; k < 2; ++k) \
;         acc[ai][bj][m][n] = __builtin_amdgcn_mfma_f32_16x16x32_bf16(Bt[n][k], At[m][k], acc[ai][bj][m][n], 0, 0, 0); __builtin_amdgcn_s_setprio(0); } while (0)
; #define PG8_WAIT_V(n) asm volatile("s_waitcnt vmcnt(" #n ")" ::: "memory")
; #define PG8_WAIT_L(n) asm volatile("s_waitcnt lgkmcnt(" #n ")" ::: "memory")
; #define PG8_BAR __builtin_amdgcn_s_barrier()
; #define PG8_SCHED __builtin_amdgcn_sched_barrier(0)
;     ...
;             const bool last = (t == nt - 2);
;             const char* a1 = cA + (size_t)(t + 1) * kstep;
;             const char* a2 = last ? nA : cA + (size_t)(t + 2) * kstep; const char* b2 = last ? nB : cB + (size_t)(t + 2) * kstep;
;             const char* a3 = a2 + kstep; const char* b3 = b2 + kstep;
;             if (last && has_next) S.a_ready(nxt);
;             if (t == 0) E.pre_issue(pre, cur, tid, ui); else if (t == 2) E.pre_finish(pre, tid, ui);
;             if constexpr (SP2) {
;             PG8_LDB(B0, 0, 0); PG8_LDB(B1, 0, 1); PG8_SCHED; PG8_LDA(At, 0, 0); PG8_STAGE(PG8_SA(1, 1), a1 + hstep, voffA);
;             PG8_WAIT_V(8); PG8_WAIT_L(0); PG8_BAR; PG8_MMA(0, 0, At, B0); PG8_MMA(0, 1, At, B1); PG8_BAR; PG8_SCHED;
;             PG8_LDA(At, 0, 1); PG8_STAGE(PG8_SB(0, 0), b2, voffB); PG8_STAGE(PG8_SB(0, 1), b2 + hstep, voffB); PG8_STAGE(PG8_SA(0, 0), a2, voffA);
;             PG8_WAIT_V(8); PG8_WAIT_L(0); PG8_BAR; PG8_MMA(1, 0, At, B0); PG8_MMA(1, 1, At, B1); PG8_BAR; PG8_SCHED;
.LBB0_1212:
	ds_read_b128 v[108:111], v251
	ds_read_b128 v[112:115], v251 offset:1024
	ds_read_b128 v[128:131], v251 offset:2048
	ds_read_b128 v[136:139], v251 offset:3072
	ds_read_b128 v[148:151], v251 offset:16384
	ds_read_b128 v[152:155], v251 offset:17408
	ds_read_b128 v[156:159], v251 offset:18432
	ds_read_b128 v[160:163], v251 offset:19456
	ds_read_b128 v[164:167], v234
	ds_read_b128 v[168:171], v234 offset:1024
	ds_read_b128 v[172:175], v234 offset:2048
	ds_read_b128 v[176:179], v234 offset:3072
	ds_read_b128 v[180:183], v234 offset:4096
	ds_read_b128 v[184:187], v234 offset:5120
	ds_read_b128 v[206:209], v234 offset:6144
	ds_read_b128 v[210:213], v234 offset:7168
	s_add_u32 s62, s60, 0x100
	s_addc_u32 s63, s61, 0
	s_add_i32 s48, 0, 0x10000
	s_cmpk_eq_i32 s79, 0x54
	s_cselect_b32 s71, s9, s63
	s_cselect_b32 s70, s8, s62
	s_cselect_b32 s69, s25, s78
	s_cselect_b32 s68, s24, s77
	s_add_i32 s81, 0, 0x14000
	v_lshl_add_u64 v[198:199], s[60:61], 0, v[196:197]
	s_add_i32 m0, s5, 0xc000
	s_nop 0
	global_load_lds_dwordx4 v[198:199], off
	v_lshl_add_u64 v[198:199], s[60:61], 0, v[194:195]
	s_add_i32 m0, s5, 0xe000
	s_nop 0
	global_load_lds_dwordx4 v[198:199], off
	s_waitcnt vmcnt(8)
	s_waitcnt lgkmcnt(0)
	s_setprio 1
	s_barrier
	v_mfma_f32_16x16x32_bf16 v[144:147], v[108:111], v[164:167], v[144:147]
	v_mfma_f32_16x16x32_bf16 v[140:143], v[128:131], v[164:167], v[140:143]
	v_mfma_f32_16x16x32_bf16 v[120:123], v[108:111], v[172:175], v[120:123]
	v_mfma_f32_16x16x32_bf16 v[116:119], v[128:131], v[172:175], v[116:119]
	v_mfma_f32_16x16x32_bf16 v[96:99], v[108:111], v[180:183], v[96:99]
	v_mfma_f32_16x16x32_bf16 v[92:95], v[128:131], v[180:183], v[92:95]
	v_mfma_f32_16x16x32_bf16 v[80:83], v[108:111], v[206:209], v[80:83]
	v_mfma_f32_16x16x32_bf16 v[76:79], v[128:131], v[206:209], v[76:79]
	v_mfma_f32_16x16x32_bf16 v[144:147], v[112:115], v[168:171], v[144:147]
	v_mfma_f32_16x16x32_bf16 v[140:143], v[136:139], v[168:171], v[140:143]
	v_mfma_f32_16x16x32_bf16 v[120:123], v[112:115], v[176:179], v[120:123]
	v_mfma_f32_16x16x32_bf16 v[116:119], v[136:139], v[176:179], v[116:119]
	v_mfma_f32_16x16x32_bf16 v[96:99], v[112:115], v[184:187], v[96:99]
	v_mfma_f32_16x16x32_bf16 v[92:95], v[136:139], v[184:187], v[92:95]
	v_mfma_f32_16x16x32_bf16 v[80:83], v[112:115], v[210:213], v[80:83]
	v_mfma_f32_16x16x32_bf16 v[76:79], v[136:139], v[210:213], v[76:79]
	s_setprio 0
	s_setprio 1
	v_mfma_f32_16x16x32_bf16 v[132:135], v[148:151], v[164:167], v[132:135]
	v_mfma_f32_16x16x32_bf16 v[124:127], v[156:159], v[164:167], v[124:127]
	v_mfma_f32_16x16x32_bf16 v[104:107], v[148:151], v[172:175], v[104:107]
	v_mfma_f32_16x16x32_bf16 v[100:103], v[156:159], v[172:175], v[100:103]
	v_mfma_f32_16x16x32_bf16 v[88:91], v[148:151], v[180:183], v[88:91]
	v_mfma_f32_16x16x32_bf16 v[84:87], v[156:159], v[180:183], v[84:87]
	v_mfma_f32_16x16x32_bf16 v[72:75], v[148:151], v[206:209], v[72:75]
	v_mfma_f32_16x16x32_bf16 v[68:71], v[156:159], v[206:209], v[68:71]
	v_mfma_f32_16x16x32_bf16 v[132:135], v[152:155], v[168:171], v[132:135]
	v_mfma_f32_16x16x32_bf16 v[124:127], v[160:163], v[168:171], v[124:127]
	v_mfma_f32_16x16x32_bf16 v[104:107], v[152:155], v[176:179], v[104:107]
	v_mfma_f32_16x16x32_bf16 v[100:103], v[160:163], v[176:179], v[100:103]
	v_mfma_f32_16x16x32_bf16 v[88:91], v[152:155], v[184:187], v[88:91]
	v_mfma_f32_16x16x32_bf16 v[84:87], v[160:163], v[184:187], v[84:87]
	v_mfma_f32_16x16x32_bf16 v[72:75], v[152:155], v[210:213], v[72:75]
	v_mfma_f32_16x16x32_bf16 v[68:71], v[160:163], v[210:213], v[68:71]
	s_barrier
	s_setprio 0
	ds_read_b128 v[164:167], v234 offset:16384
	ds_read_b128 v[168:171], v234 offset:17408
	ds_read_b128 v[172:175], v234 offset:18432
	ds_read_b128 v[176:179], v234 offset:19456
	ds_read_b128 v[180:183], v234 offset:20480
	ds_read_b128 v[184:187], v234 offset:21504
	ds_read_b128 v[206:209], v234 offset:22528
	ds_read_b128 v[210:213], v234 offset:23552
	s_add_i32 s48, s48, s4
	v_lshl_add_u64 v[198:199], s[68:69], 0, v[200:201]
	s_mov_b32 m0, s48
	s_nop 0
	global_load_lds_dwordx4 v[198:199], off
	s_add_i32 m0, s48, 0x2000
	s_add_u32 s48, s68, 0x160000
	v_lshl_add_u64 v[214:215], s[68:69], 0, v[188:189]
	s_addc_u32 s49, s69, 0
	s_add_i32 s60, s81, s4
	global_load_lds_dwordx4 v[214:215], off
	v_lshl_add_u64 v[216:217], s[48:49], 0, v[200:201]
	s_mov_b32 m0, s60
	v_lshl_add_u64 v[218:219], s[70:71], 0, v[190:191]
	global_load_lds_dwordx4 v[216:217], off
	v_lshl_add_u64 v[216:217], s[48:49], 0, v[188:189]
	s_add_i32 m0, s60, 0x2000
	s_nop 0
	global_load_lds_dwordx4 v[216:217], off
	v_lshl_add_u64 v[216:217], s[70:71], 0, v[192:193]
	s_mov_b32 m0, s5
	s_nop 0
	global_load_lds_dwordx4 v[216:217], off
	s_mov_b32 m0, s20
	s_nop 0
	global_load_lds_dwordx4 v[218:219], off
	s_waitcnt vmcnt(8)
	s_waitcnt lgkmcnt(0)
	s_setprio 1
	s_barrier
; #define PG8_STAGE(bufoff, gbase, voff) do { _Pragma("unroll") for (int _i = 0; _i < 2; ++_i) \
;         __builtin_amdgcn_global_load_lds((const unsigned*)((const char*)(gbase) + (voff)[_i]), (PG8_LAS unsigned*)(lds + (bufoff) + ldsw + _i * 8192), 16, 0, 0); } while (0)
; #define PG8_LDA(dst, b, h) do { _Pragma("unroll") for (int m = 0; m < 4; ++m) _Pragma("unroll") for (int k = 0; k < 2; ++k) dst[m][k] = *(const PG8_LAS bf16x8*)(lds + PG8_SA(b, h) + aoff + m * 2048 + k * 1024); } while (0)
; #define PG8_LDB(dst, b, h) do { _Pragma("unroll") for (int n = 0; n < 2; ++n) _Pragma("unroll") for (int k = 0; k < 2; ++k) dst[n][k] = *(const PG8_LAS bf16x8*)(lds + PG8_SB(b, h) + boff + n * 2048 + k * 1024); } while (0)
; #define PG8_MMA(ai, bj, At, Bt) do { __builtin_amdgcn_s_setprio(1); _Pragma("unroll") for (int m = 0; m < 4; ++m) _Pragma("unroll") for (int n = 0; n < 2; ++n) _Pragma("unroll") for (int k = 0; k < 2; ++k) \
;         acc[ai][bj][m][n] = __builtin_amdgcn_mfma_f32_16x16x32_bf16(Bt[n][k], At[m][k], acc[ai][bj][m][n], 0, 0, 0); __builtin_amdgcn_s_setprio(0); } while (0)
; #define PG8_WAIT_V(n) asm volatile("s_waitcnt vmcnt(" #n ")" ::: "memory")
; #define PG8_WAIT_L(n) asm volatile("s_waitcnt lgkmcnt(" #n ")" ::: "memory")
; #define PG8_BAR __builtin_amdgcn_s_barrier()
; #define PG8_SCHED __builtin_amdgcn_sched_barrier(0)
;     ...
;             PG8_WAIT_V(8); PG8_WAIT_L(0); PG8_BAR; PG8_MMA(1, 0, At, B0); PG8_MMA(1, 1, At, B1); PG8_BAR; PG8_SCHED;
;             PG8_LDB(B0, 1, 0); PG8_LDB(B1, 1, 1); PG8_SCHED; PG8_LDA(At, 1, 0); PG8_STAGE(PG8_SA(0, 1), a2 + hstep, voffA);
;             PG8_WAIT_V(8); PG8_WAIT_L(0); PG8_BAR; PG8_MMA(0, 0, At, B0); PG8_MMA(0, 1, At, B1); PG8_BAR; PG8_SCHED;
	v_mfma_f32_16x16x32_bf16 v[64:67], v[108:111], v[164:167], v[64:67]
	v_mfma_f32_16x16x32_bf16 v[60:63], v[128:131], v[164:167], v[60:63]
	v_mfma_f32_16x16x32_bf16 v[48:51], v[108:111], v[172:175], v[48:51]
	v_mfma_f32_16x16x32_bf16 v[44:47], v[128:131], v[172:175], v[44:47]
	v_mfma_f32_16x16x32_bf16 v[32:35], v[108:111], v[180:183], v[32:35]
	v_mfma_f32_16x16x32_bf16 v[28:31], v[128:131], v[180:183], v[28:31]
	v_mfma_f32_16x16x32_bf16 v[16:19], v[108:111], v[206:209], v[16:19]
	v_mfma_f32_16x16x32_bf16 v[12:15], v[128:131], v[206:209], v[12:15]
	v_mfma_f32_16x16x32_bf16 v[64:67], v[112:115], v[168:171], v[64:67]
	v_mfma_f32_16x16x32_bf16 v[60:63], v[136:139], v[168:171], v[60:63]
	v_mfma_f32_16x16x32_bf16 v[48:51], v[112:115], v[176:179], v[48:51]
	v_mfma_f32_16x16x32_bf16 v[44:47], v[136:139], v[176:179], v[44:47]
	v_mfma_f32_16x16x32_bf16 v[32:35], v[112:115], v[184:187], v[32:35]
	v_mfma_f32_16x16x32_bf16 v[28:31], v[136:139], v[184:187], v[28:31]
	v_mfma_f32_16x16x32_bf16 v[16:19], v[112:115], v[210:213], v[16:19]
	v_mfma_f32_16x16x32_bf16 v[12:15], v[136:139], v[210:213], v[12:15]
	s_setprio 0
	s_setprio 1
	v_mfma_f32_16x16x32_bf16 v[56:59], v[148:151], v[164:167], v[56:59]
	v_mfma_f32_16x16x32_bf16 v[52:55], v[156:159], v[164:167], v[52:55]
	v_mfma_f32_16x16x32_bf16 v[40:43], v[148:151], v[172:175], v[40:43]
	v_mfma_f32_16x16x32_bf16 v[36:39], v[156:159], v[172:175], v[36:39]
	v_mfma_f32_16x16x32_bf16 v[24:27], v[148:151], v[180:183], v[24:27]
	v_mfma_f32_16x16x32_bf16 v[20:23], v[156:159], v[180:183], v[20:23]
	v_mfma_f32_16x16x32_bf16 v[8:11], v[148:151], v[206:209], v[8:11]
	v_mfma_f32_16x16x32_bf16 v[4:7], v[156:159], v[206:209], v[4:7]
	v_mfma_f32_16x16x32_bf16 v[56:59], v[152:155], v[168:171], v[56:59]
	v_mfma_f32_16x16x32_bf16 v[52:55], v[160:163], v[168:171], v[52:55]
	v_mfma_f32_16x16x32_bf16 v[40:43], v[152:155], v[176:179], v[40:43]
	v_mfma_f32_16x16x32_bf16 v[36:39], v[160:163], v[176:179], v[36:39]
	v_mfma_f32_16x16x32_bf16 v[24:27], v[152:155], v[184:187], v[24:27]
	v_mfma_f32_16x16x32_bf16 v[20:23], v[160:163], v[184:187], v[20:23]
	v_mfma_f32_16x16x32_bf16 v[8:11], v[152:155], v[210:213], v[8:11]
	v_mfma_f32_16x16x32_bf16 v[4:7], v[160:163], v[210:213], v[4:7]
	s_barrier
	s_setprio 0
	ds_read_b128 v[108:111], v251 offset:32768
	ds_read_b128 v[112:115], v251 offset:33792
	ds_read_b128 v[128:131], v251 offset:34816
	ds_read_b128 v[136:139], v251 offset:35840
	ds_read_b128 v[148:151], v251 offset:49152
	ds_read_b128 v[152:155], v251 offset:50176
	ds_read_b128 v[156:159], v251 offset:51200
	ds_read_b128 v[160:163], v251 offset:52224
	ds_read_b128 v[164:167], v234 offset:32768
	ds_read_b128 v[168:171], v234 offset:33792
	ds_read_b128 v[172:175], v234 offset:34816
	ds_read_b128 v[176:179], v234 offset:35840
	ds_read_b128 v[180:183], v234 offset:36864
	ds_read_b128 v[184:187], v234 offset:37888
	ds_read_b128 v[206:209], v234 offset:38912
	ds_read_b128 v[210:213], v234 offset:39936
	s_add_i32 s60, 0, 0x18000
	s_add_i32 s61, 0, 0x1c000
	s_add_u32 s48, s70, 0x160000
	s_addc_u32 s49, s71, 0
	s_mov_b32 m0, s21
	v_lshl_add_u64 v[220:221], s[48:49], 0, v[192:193]
	global_load_lds_dwordx4 v[220:221], off
	v_lshl_add_u64 v[220:221], s[48:49], 0, v[190:191]
	s_mov_b32 m0, s23
	s_nop 0
	global_load_lds_dwordx4 v[220:221], off
	s_waitcnt vmcnt(8)
	s_waitcnt lgkmcnt(0)
	s_setprio 1
	s_barrier
	v_mfma_f32_16x16x32_bf16 v[144:147], v[108:111], v[164:167], v[144:147]
	v_mfma_f32_16x16x32_bf16 v[140:143], v[128:131], v[164:167], v[140:143]
	v_mfma_f32_16x16x32_bf16 v[120:123], v[108:111], v[172:175], v[120:123]
	v_mfma_f32_16x16x32_bf16 v[116:119], v[128:131], v[172:175], v[116:119]
	v_mfma_f32_16x16x32_bf16 v[96:99], v[108:111], v[180:183], v[96:99]
	v_mfma_f32_16x16x32_bf16 v[92:95], v[128:131], v[180:183], v[92:95]
	v_mfma_f32_16x16x32_bf16 v[80:83], v[108:111], v[206:209], v[80:83]
	v_mfma_f32_16x16x32_bf16 v[76:79], v[128:131], v[206:209], v[76:79]
	v_mfma_f32_16x16x32_bf16 v[144:147], v[112:115], v[168:171], v[144:147]
	v_mfma_f32_16x16x32_bf16 v[140:143], v[136:139], v[168:171], v[140:143]
	v_mfma_f32_16x16x32_bf16 v[120:123], v[112:115], v[176:179], v[120:123]
	v_mfma_f32_16x16x32_bf16 v[116:119], v[136:139], v[176:179], v[116:119]
	v_mfma_f32_16x16x32_bf16 v[96:99], v[112:115], v[184:187], v[96:99]
	v_mfma_f32_16x16x32_bf16 v[92:95], v[136:139], v[184:187], v[92:95]
	v_mfma_f32_16x16x32_bf16 v[80:83], v[112:115], v[210:213], v[80:83]
	v_mfma_f32_16x16x32_bf16 v[76:79], v[136:139], v[210:213], v[76:79]
	s_setprio 0
	s_setprio 1
	v_mfma_f32_16x16x32_bf16 v[132:135], v[148:151], v[164:167], v[132:135]
	v_mfma_f32_16x16x32_bf16 v[124:127], v[156:159], v[164:167], v[124:127]
	v_mfma_f32_16x16x32_bf16 v[104:107], v[148:151], v[172:175], v[104:107]
	v_mfma_f32_16x16x32_bf16 v[100:103], v[156:159], v[172:175], v[100:103]
	v_mfma_f32_16x16x32_bf16 v[88:91], v[148:151], v[180:183], v[88:91]
	v_mfma_f32_16x16x32_bf16 v[84:87], v[156:159], v[180:183], v[84:87]
	v_mfma_f32_16x16x32_bf16 v[72:75], v[148:151], v[206:209], v[72:75]
	v_mfma_f32_16x16x32_bf16 v[68:71], v[156:159], v[206:209], v[68:71]
	v_mfma_f32_16x16x32_bf16 v[132:135], v[152:155], v[168:171], v[132:135]
	v_mfma_f32_16x16x32_bf16 v[124:127], v[160:163], v[168:171], v[124:127]
	v_mfma_f32_16x16x32_bf16 v[104:107], v[152:155], v[176:179], v[104:107]
	v_mfma_f32_16x16x32_bf16 v[100:103], v[160:163], v[176:179], v[100:103]
	v_mfma_f32_16x16x32_bf16 v[88:91], v[152:155], v[184:187], v[88:91]
	v_mfma_f32_16x16x32_bf16 v[84:87], v[160:163], v[184:187], v[84:87]
	v_mfma_f32_16x16x32_bf16 v[72:75], v[152:155], v[210:213], v[72:75]
	v_mfma_f32_16x16x32_bf16 v[68:71], v[160:163], v[210:213], v[68:71]
	s_barrier
; #define PG8_STAGE(bufoff, gbase, voff) do { _Pragma("unroll") for (int _i = 0; _i < 2; ++_i) \
;         __builtin_amdgcn_global_load_lds((const unsigned*)((const char*)(gbase) + (voff)[_i]), (PG8_LAS unsigned*)(lds + (bufoff) + ldsw + _i * 8192), 16, 0, 0); } while (0)
; #define PG8_LDA(dst, b, h) do { _Pragma("unroll") for (int m = 0; m < 4; ++m) _Pragma("unroll") for (int k = 0; k < 2; ++k) dst[m][k] = *(const PG8_LAS bf16x8*)(lds + PG8_SA(b, h) + aoff + m * 2048 + k * 1024); } while (0)
; #define PG8_MMA(ai, bj, At, Bt) do { __builtin_amdgcn_s_setprio(1); _Pragma("unroll") for (int m = 0; m < 4; ++m) _Pragma("unroll") for (int n = 0; n < 2; ++n) _Pragma("unroll") for (int k = 0; k < 2; ++k) \
;         acc[ai][bj][m][n] = __builtin_amdgcn_mfma_f32_16x16x32_bf16(Bt[n][k], At[m][k], acc[ai][bj][m][n], 0, 0, 0); __builtin_amdgcn_s_setprio(0); } while (0)
; #define PG8_WAIT_V(n) asm volatile("s_waitcnt vmcnt(" #n ")" ::: "memory")
; #define PG8_WAIT_L(n) asm volatile("s_waitcnt lgkmcnt(" #n ")" ::: "memory")
; #define PG8_BAR __builtin_amdgcn_s_barrier()
; #define PG8_SCHED __builtin_amdgcn_sched_barrier(0)
;     ...
;             PG8_LDA(At, 1, 1); PG8_STAGE(PG8_SB(1, 0), b3, voffB); PG8_STAGE(PG8_SB(1, 1), b3 + hstep, voffB); PG8_STAGE(PG8_SA(1, 0), a3, voffA);
;             PG8_WAIT_V(8); PG8_WAIT_L(0); PG8_BAR; PG8_MMA(1, 0, At, B0); PG8_MMA(1, 1, At, B1); PG8_BAR; PG8_SCHED;
	s_setprio 0
	ds_read_b128 v[164:167], v234 offset:49152
	ds_read_b128 v[168:171], v234 offset:50176
	ds_read_b128 v[172:175], v234 offset:51200
	ds_read_b128 v[176:179], v234 offset:52224
	ds_read_b128 v[180:183], v234 offset:53248
	ds_read_b128 v[184:187], v234 offset:54272
	ds_read_b128 v[206:209], v234 offset:55296
	ds_read_b128 v[210:213], v234 offset:56320
	s_add_i32 s48, s60, s4
	v_lshl_add_u64 v[198:199], v[198:199], 0, s[66:67]
	s_mov_b32 m0, s48
	s_nop 0
	global_load_lds_dwordx4 v[198:199], off
	s_add_i32 m0, s48, 0x2000
	s_add_u32 s48, s68, 0x160080
	v_lshl_add_u64 v[198:199], v[214:215], 0, s[66:67]
	s_addc_u32 s49, s69, 0
	s_add_i32 s60, s61, s4
	global_load_lds_dwordx4 v[198:199], off
	v_lshl_add_u64 v[198:199], s[48:49], 0, v[200:201]
	s_mov_b32 m0, s60
	s_nop 0
	global_load_lds_dwordx4 v[198:199], off
	v_lshl_add_u64 v[198:199], s[48:49], 0, v[188:189]
	s_add_i32 m0, s60, 0x2000
	s_nop 0
	global_load_lds_dwordx4 v[198:199], off
	v_lshl_add_u64 v[198:199], v[216:217], 0, s[66:67]
	s_mov_b32 m0, s54
	s_nop 0
	global_load_lds_dwordx4 v[198:199], off
	v_lshl_add_u64 v[198:199], v[218:219], 0, s[66:67]
	s_mov_b32 m0, s55
	s_nop 0
	global_load_lds_dwordx4 v[198:199], off
	s_waitcnt vmcnt(8)
	s_waitcnt lgkmcnt(0)
	s_setprio 1
	s_barrier
	v_mfma_f32_16x16x32_bf16 v[64:67], v[108:111], v[164:167], v[64:67]
	v_mfma_f32_16x16x32_bf16 v[60:63], v[128:131], v[164:167], v[60:63]
	v_mfma_f32_16x16x32_bf16 v[48:51], v[108:111], v[172:175], v[48:51]
	v_mfma_f32_16x16x32_bf16 v[44:47], v[128:131], v[172:175], v[44:47]
	v_mfma_f32_16x16x32_bf16 v[32:35], v[108:111], v[180:183], v[32:35]
	v_mfma_f32_16x16x32_bf16 v[28:31], v[128:131], v[180:183], v[28:31]
	v_mfma_f32_16x16x32_bf16 v[16:19], v[108:111], v[206:209], v[16:19]
	v_mfma_f32_16x16x32_bf16 v[12:15], v[128:131], v[206:209], v[12:15]
	v_mfma_f32_16x16x32_bf16 v[64:67], v[112:115], v[168:171], v[64:67]
	v_mfma_f32_16x16x32_bf16 v[60:63], v[136:139], v[168:171], v[60:63]
	v_mfma_f32_16x16x32_bf16 v[48:51], v[112:115], v[176:179], v[48:51]
	v_mfma_f32_16x16x32_bf16 v[44:47], v[136:139], v[176:179], v[44:47]
	v_mfma_f32_16x16x32_bf16 v[32:35], v[112:115], v[184:187], v[32:35]
	v_mfma_f32_16x16x32_bf16 v[28:31], v[136:139], v[184:187], v[28:31]
	v_mfma_f32_16x16x32_bf16 v[16:19], v[112:115], v[210:213], v[16:19]
	v_mfma_f32_16x16x32_bf16 v[12:15], v[136:139], v[210:213], v[12:15]
	s_setprio 0
	s_setprio 1
	v_mfma_f32_16x16x32_bf16 v[56:59], v[148:151], v[164:167], v[56:59]
	v_mfma_f32_16x16x32_bf16 v[52:55], v[156:159], v[164:167], v[52:55]
	v_mfma_f32_16x16x32_bf16 v[40:43], v[148:151], v[172:175], v[40:43]
	v_mfma_f32_16x16x32_bf16 v[36:39], v[156:159], v[172:175], v[36:39]
	v_mfma_f32_16x16x32_bf16 v[24:27], v[148:151], v[180:183], v[24:27]
	v_mfma_f32_16x16x32_bf16 v[20:23], v[156:159], v[180:183], v[20:23]
	v_mfma_f32_16x16x32_bf16 v[8:11], v[148:151], v[206:209], v[8:11]
	v_mfma_f32_16x16x32_bf16 v[4:7], v[156:159], v[206:209], v[4:7]
	v_mfma_f32_16x16x32_bf16 v[56:59], v[152:155], v[168:171], v[56:59]
	v_mfma_f32_16x16x32_bf16 v[52:55], v[160:163], v[168:171], v[52:55]
	v_mfma_f32_16x16x32_bf16 v[40:43], v[152:155], v[176:179], v[40:43]
	v_mfma_f32_16x16x32_bf16 v[36:39], v[160:163], v[176:179], v[36:39]
	v_mfma_f32_16x16x32_bf16 v[24:27], v[152:155], v[184:187], v[24:27]
	v_mfma_f32_16x16x32_bf16 v[20:23], v[160:163], v[184:187], v[20:23]
	v_mfma_f32_16x16x32_bf16 v[8:11], v[152:155], v[210:213], v[8:11]
	v_mfma_f32_16x16x32_bf16 v[4:7], v[160:163], v[210:213], v[4:7]
	s_barrier
	s_setprio 0
	s_add_i32 s79, s79, 2
	s_add_u32 s77, s77, 0x100
	s_addc_u32 s78, s78, 0
	s_cmpk_gt_u32 s79, 0x55
	s_mov_b64 s[60:61], s[62:63]
	s_cbranch_scc0 .LBB0_1212
	s_and_b64 vcc, exec, s[12:13]
	s_cbranch_vccz .LBB0_1215
	s_barrier

; #define PG8_STAGE(bufoff, gbase, voff) do { _Pragma("unroll") for (int _i = 0; _i < 2; ++_i) \
;         __builtin_amdgcn_global_load_lds((const unsigned*)((const char*)(gbase) + (voff)[_i]), (PG8_LAS unsigned*)(lds + (bufoff) + ldsw + _i * 8192), 16, 0, 0); } while (0)
; #define PG8_LDA(dst, b, h) do { _Pragma("unroll") for (int m = 0; m < 4; ++m) _Pragma("unroll") for (int k = 0; k < 2; ++k) dst[m][k] = *(const PG8_LAS bf16x8*)(lds + PG8_SA(b, h) + aoff + m * 2048 + k * 1024); } while (0)
; #define PG8_LDB(dst, b, h) do { _Pragma("unroll") for (int n = 0; n < 2; ++n) _Pragma("unroll") for (int k = 0; k < 2; ++k) dst[n][k] = *(const PG8_LAS bf16x8*)(lds + PG8_SB(b, h) + boff + n * 2048 + k * 1024); } while (0)
; #define PG8_MMA(ai, bj, At, Bt) do { __builtin_amdgcn_s_setprio(1); _Pragma("unroll") for (int m = 0; m < 4; ++m) _Pragma("unroll") for (int n = 0; n < 2; ++n) _Pragma("unroll") for (int k = 0; k < 2; ++k) \
;         acc[ai][bj][m][n] = __builtin_amdgcn_mfma_f32_16x16x32_bf16(Bt[n][k], At[m][k], acc[ai][bj][m][n], 0, 0, 0); __builtin_amdgcn_s_setprio(0); } while (0)
; #define PG8_WAIT_V(n) asm volatile("s_waitcnt vmcnt(" #n ")" ::: "memory")
; #define PG8_WAIT_L(n) asm volatile("s_waitcnt lgkmcnt(" #n ")" ::: "memory")
; #define PG8_BAR __builtin_amdgcn_s_barrier()
; #define PG8_SCHED __builtin_amdgcn_sched_barrier(0)
;     ...
;             const bool last = (t == nt - 2);
;             const char* a1 = cA + (size_t)(t + 1) * kstep;
;             const char* a2 = last ? nA : cA + (size_t)(t + 2) * kstep; const char* b2 = last ? nB : cB + (size_t)(t + 2) * kstep;
;             const char* a3 = a2 + kstep; const char* b3 = b2 + kstep;
;             if (last && has_next) S.a_ready(nxt);
;             if (t == 0) E.pre_issue(pre, cur, tid, ui); else if (t == 2) E.pre_finish(pre, tid, ui);
;             if constexpr (SP2) {
;             PG8_LDB(B0, 0, 0); PG8_LDB(B1, 0, 1); PG8_SCHED; PG8_LDA(At, 0, 0); PG8_STAGE(PG8_SA(1, 1), a1 + hstep, voffA);
;             PG8_WAIT_V(8); PG8_WAIT_L(0); PG8_BAR; PG8_MMA(0, 0, At, B0); PG8_MMA(0, 1, At, B1); PG8_BAR; PG8_SCHED;
;             PG8_LDA(At, 0, 1); PG8_STAGE(PG8_SB(0, 0), b2, voffB); PG8_STAGE(PG8_SB(0, 1), b2 + hstep, voffB); PG8_STAGE(PG8_SA(0, 0), a2, voffA);
;             PG8_WAIT_V(8); PG8_WAIT_L(0); PG8_BAR; PG8_MMA(1, 0, At, B0); PG8_MMA(1, 1, At, B1); PG8_BAR; PG8_SCHED;
.LBB0_1254:
	ds_read_b128 v[108:111], v251
	ds_read_b128 v[112:115], v251 offset:1024
	ds_read_b128 v[128:131], v251 offset:2048
	ds_read_b128 v[136:139], v251 offset:3072
	ds_read_b128 v[148:151], v251 offset:16384
	ds_read_b128 v[152:155], v251 offset:17408
	ds_read_b128 v[156:159], v251 offset:18432
	ds_read_b128 v[160:163], v251 offset:19456
	ds_read_b128 v[164:167], v234
	ds_read_b128 v[168:171], v234 offset:1024
	ds_read_b128 v[172:175], v234 offset:2048
	ds_read_b128 v[176:179], v234 offset:3072
	ds_read_b128 v[180:183], v234 offset:4096
	ds_read_b128 v[184:187], v234 offset:5120
	ds_read_b128 v[206:209], v234 offset:6144
	ds_read_b128 v[210:213], v234 offset:7168
	s_add_u32 s60, s50, 0x100
	s_addc_u32 s61, s51, 0
	s_add_i32 s48, 0, 0x10000
	s_cmpk_eq_i32 s77, 0x54
	s_cselect_b32 s69, s7, s61
	s_cselect_b32 s68, s6, s60
	s_cselect_b32 s63, s25, s76
	s_cselect_b32 s62, s24, s75
	s_add_i32 s78, 0, 0x14000
	v_lshl_add_u64 v[198:199], s[50:51], 0, v[196:197]
	s_add_i32 m0, s21, 0xc000
	s_nop 0
	global_load_lds_dwordx4 v[198:199], off
	v_lshl_add_u64 v[198:199], s[50:51], 0, v[194:195]
	s_add_i32 m0, s21, 0xe000
	s_nop 0
	global_load_lds_dwordx4 v[198:199], off
	s_waitcnt vmcnt(8)
	s_waitcnt lgkmcnt(0)
	s_setprio 1
	s_barrier
	v_mfma_f32_16x16x32_bf16 v[144:147], v[108:111], v[164:167], v[144:147]
	v_mfma_f32_16x16x32_bf16 v[140:143], v[128:131], v[164:167], v[140:143]
	v_mfma_f32_16x16x32_bf16 v[120:123], v[108:111], v[172:175], v[120:123]
	v_mfma_f32_16x16x32_bf16 v[116:119], v[128:131], v[172:175], v[116:119]
	v_mfma_f32_16x16x32_bf16 v[96:99], v[108:111], v[180:183], v[96:99]
	v_mfma_f32_16x16x32_bf16 v[92:95], v[128:131], v[180:183], v[92:95]
	v_mfma_f32_16x16x32_bf16 v[80:83], v[108:111], v[206:209], v[80:83]
	v_mfma_f32_16x16x32_bf16 v[76:79], v[128:131], v[206:209], v[76:79]
	v_mfma_f32_16x16x32_bf16 v[144:147], v[112:115], v[168:171], v[144:147]
	v_mfma_f32_16x16x32_bf16 v[140:143], v[136:139], v[168:171], v[140:143]
	v_mfma_f32_16x16x32_bf16 v[120:123], v[112:115], v[176:179], v[120:123]
	v_mfma_f32_16x16x32_bf16 v[116:119], v[136:139], v[176:179], v[116:119]
	v_mfma_f32_16x16x32_bf16 v[96:99], v[112:115], v[184:187], v[96:99]
	v_mfma_f32_16x16x32_bf16 v[92:95], v[136:139], v[184:187], v[92:95]
	v_mfma_f32_16x16x32_bf16 v[80:83], v[112:115], v[210:213], v[80:83]
	v_mfma_f32_16x16x32_bf16 v[76:79], v[136:139], v[210:213], v[76:79]
	s_setprio 0
	s_setprio 1
	v_mfma_f32_16x16x32_bf16 v[132:135], v[148:151], v[164:167], v[132:135]
	v_mfma_f32_16x16x32_bf16 v[124:127], v[156:159], v[164:167], v[124:127]
	v_mfma_f32_16x16x32_bf16 v[104:107], v[148:151], v[172:175], v[104:107]
	v_mfma_f32_16x16x32_bf16 v[100:103], v[156:159], v[172:175], v[100:103]
	v_mfma_f32_16x16x32_bf16 v[88:91], v[148:151], v[180:183], v[88:91]
	v_mfma_f32_16x16x32_bf16 v[84:87], v[156:159], v[180:183], v[84:87]
	v_mfma_f32_16x16x32_bf16 v[72:75], v[148:151], v[206:209], v[72:75]
	v_mfma_f32_16x16x32_bf16 v[68:71], v[156:159], v[206:209], v[68:71]
	v_mfma_f32_16x16x32_bf16 v[132:135], v[152:155], v[168:171], v[132:135]
	v_mfma_f32_16x16x32_bf16 v[124:127], v[160:163], v[168:171], v[124:127]
	v_mfma_f32_16x16x32_bf16 v[104:107], v[152:155], v[176:179], v[104:107]
	v_mfma_f32_16x16x32_bf16 v[100:103], v[160:163], v[176:179], v[100:103]
	v_mfma_f32_16x16x32_bf16 v[88:91], v[152:155], v[184:187], v[88:91]
	v_mfma_f32_16x16x32_bf16 v[84:87], v[160:163], v[184:187], v[84:87]
	v_mfma_f32_16x16x32_bf16 v[72:75], v[152:155], v[210:213], v[72:75]
	v_mfma_f32_16x16x32_bf16 v[68:71], v[160:163], v[210:213], v[68:71]
	s_barrier
	s_setprio 0
	ds_read_b128 v[164:167], v234 offset:16384
	ds_read_b128 v[168:171], v234 offset:17408
	ds_read_b128 v[172:175], v234 offset:18432
	ds_read_b128 v[176:179], v234 offset:19456
	ds_read_b128 v[180:183], v234 offset:20480
	ds_read_b128 v[184:187], v234 offset:21504
	ds_read_b128 v[206:209], v234 offset:22528
	ds_read_b128 v[210:213], v234 offset:23552
	s_add_i32 s48, s48, s20
	v_lshl_add_u64 v[198:199], s[62:63], 0, v[200:201]
	s_mov_b32 m0, s48
	s_nop 0
	global_load_lds_dwordx4 v[198:199], off
	s_add_i32 m0, s48, 0x2000
	s_add_u32 s48, s62, 0x160000
	v_lshl_add_u64 v[214:215], s[62:63], 0, v[188:189]
	s_addc_u32 s49, s63, 0
	s_add_i32 s50, s78, s20
	global_load_lds_dwordx4 v[214:215], off
	v_lshl_add_u64 v[216:217], s[48:49], 0, v[200:201]
	s_mov_b32 m0, s50
	v_lshl_add_u64 v[218:219], s[68:69], 0, v[190:191]
	global_load_lds_dwordx4 v[216:217], off
	v_lshl_add_u64 v[216:217], s[48:49], 0, v[188:189]
	s_add_i32 m0, s50, 0x2000
	s_nop 0
	global_load_lds_dwordx4 v[216:217], off
	v_lshl_add_u64 v[216:217], s[68:69], 0, v[192:193]
	s_mov_b32 m0, s21
	s_nop 0
	global_load_lds_dwordx4 v[216:217], off
	s_mov_b32 m0, s23
	s_nop 0
	global_load_lds_dwordx4 v[218:219], off
	s_waitcnt vmcnt(8)
	s_waitcnt lgkmcnt(0)
	s_setprio 1
	s_barrier
; #define PG8_STAGE(bufoff, gbase, voff) do { _Pragma("unroll") for (int _i = 0; _i < 2; ++_i) \
;         __builtin_amdgcn_global_load_lds((const unsigned*)((const char*)(gbase) + (voff)[_i]), (PG8_LAS unsigned*)(lds + (bufoff) + ldsw + _i * 8192), 16, 0, 0); } while (0)
; #define PG8_LDA(dst, b, h) do { _Pragma("unroll") for (int m = 0; m < 4; ++m) _Pragma("unroll") for (int k = 0; k < 2; ++k) dst[m][k] = *(const PG8_LAS bf16x8*)(lds + PG8_SA(b, h) + aoff + m * 2048 + k * 1024); } while (0)
; #define PG8_LDB(dst, b, h) do { _Pragma("unroll") for (int n = 0; n < 2; ++n) _Pragma("unroll") for (int k = 0; k < 2; ++k) dst[n][k] = *(const PG8_LAS bf16x8*)(lds + PG8_SB(b, h) + boff + n * 2048 + k * 1024); } while (0)
; #define PG8_MMA(ai, bj, At, Bt) do { __builtin_amdgcn_s_setprio(1); _Pragma("unroll") for (int m = 0; m < 4; ++m) _Pragma("unroll") for (int n = 0; n < 2; ++n) _Pragma("unroll") for (int k = 0; k < 2; ++k) \
;         acc[ai][bj][m][n] = __builtin_amdgcn_mfma_f32_16x16x32_bf16(Bt[n][k], At[m][k], acc[ai][bj][m][n], 0, 0, 0); __builtin_amdgcn_s_setprio(0); } while (0)
; #define PG8_WAIT_V(n) asm volatile("s_waitcnt vmcnt(" #n ")" ::: "memory")
; #define PG8_WAIT_L(n) asm volatile("s_waitcnt lgkmcnt(" #n ")" ::: "memory")
; #define PG8_BAR __builtin_amdgcn_s_barrier()
; #define PG8_SCHED __builtin_amdgcn_sched_barrier(0)
;     ...
;             PG8_WAIT_V(8); PG8_WAIT_L(0); PG8_BAR; PG8_MMA(1, 0, At, B0); PG8_MMA(1, 1, At, B1); PG8_BAR; PG8_SCHED;
;             PG8_LDB(B0, 1, 0); PG8_LDB(B1, 1, 1); PG8_SCHED; PG8_LDA(At, 1, 0); PG8_STAGE(PG8_SA(0, 1), a2 + hstep, voffA);
;             PG8_WAIT_V(8); PG8_WAIT_L(0); PG8_BAR; PG8_MMA(0, 0, At, B0); PG8_MMA(0, 1, At, B1); PG8_BAR; PG8_SCHED;
	v_mfma_f32_16x16x32_bf16 v[64:67], v[108:111], v[164:167], v[64:67]
	v_mfma_f32_16x16x32_bf16 v[60:63], v[128:131], v[164:167], v[60:63]
	v_mfma_f32_16x16x32_bf16 v[48:51], v[108:111], v[172:175], v[48:51]
	v_mfma_f32_16x16x32_bf16 v[44:47], v[128:131], v[172:175], v[44:47]
	v_mfma_f32_16x16x32_bf16 v[32:35], v[108:111], v[180:183], v[32:35]
	v_mfma_f32_16x16x32_bf16 v[28:31], v[128:131], v[180:183], v[28:31]
	v_mfma_f32_16x16x32_bf16 v[16:19], v[108:111], v[206:209], v[16:19]
	v_mfma_f32_16x16x32_bf16 v[12:15], v[128:131], v[206:209], v[12:15]
	v_mfma_f32_16x16x32_bf16 v[64:67], v[112:115], v[168:171], v[64:67]
	v_mfma_f32_16x16x32_bf16 v[60:63], v[136:139], v[168:171], v[60:63]
	v_mfma_f32_16x16x32_bf16 v[48:51], v[112:115], v[176:179], v[48:51]
	v_mfma_f32_16x16x32_bf16 v[44:47], v[136:139], v[176:179], v[44:47]
	v_mfma_f32_16x16x32_bf16 v[32:35], v[112:115], v[184:187], v[32:35]
	v_mfma_f32_16x16x32_bf16 v[28:31], v[136:139], v[184:187], v[28:31]
	v_mfma_f32_16x16x32_bf16 v[16:19], v[112:115], v[210:213], v[16:19]
	v_mfma_f32_16x16x32_bf16 v[12:15], v[136:139], v[210:213], v[12:15]
	s_setprio 0
	s_setprio 1
	v_mfma_f32_16x16x32_bf16 v[56:59], v[148:151], v[164:167], v[56:59]
	v_mfma_f32_16x16x32_bf16 v[52:55], v[156:159], v[164:167], v[52:55]
	v_mfma_f32_16x16x32_bf16 v[40:43], v[148:151], v[172:175], v[40:43]
	v_mfma_f32_16x16x32_bf16 v[36:39], v[156:159], v[172:175], v[36:39]
	v_mfma_f32_16x16x32_bf16 v[24:27], v[148:151], v[180:183], v[24:27]
	v_mfma_f32_16x16x32_bf16 v[20:23], v[156:159], v[180:183], v[20:23]
	v_mfma_f32_16x16x32_bf16 v[8:11], v[148:151], v[206:209], v[8:11]
	v_mfma_f32_16x16x32_bf16 v[4:7], v[156:159], v[206:209], v[4:7]
	v_mfma_f32_16x16x32_bf16 v[56:59], v[152:155], v[168:171], v[56:59]
	v_mfma_f32_16x16x32_bf16 v[52:55], v[160:163], v[168:171], v[52:55]
	v_mfma_f32_16x16x32_bf16 v[40:43], v[152:155], v[176:179], v[40:43]
	v_mfma_f32_16x16x32_bf16 v[36:39], v[160:163], v[176:179], v[36:39]
	v_mfma_f32_16x16x32_bf16 v[24:27], v[152:155], v[184:187], v[24:27]
	v_mfma_f32_16x16x32_bf16 v[20:23], v[160:163], v[184:187], v[20:23]
	v_mfma_f32_16x16x32_bf16 v[8:11], v[152:155], v[210:213], v[8:11]
	v_mfma_f32_16x16x32_bf16 v[4:7], v[160:163], v[210:213], v[4:7]
	s_barrier
	s_setprio 0
	ds_read_b128 v[108:111], v251 offset:32768
	ds_read_b128 v[112:115], v251 offset:33792
	ds_read_b128 v[128:131], v251 offset:34816
	ds_read_b128 v[136:139], v251 offset:35840
	ds_read_b128 v[148:151], v251 offset:49152
	ds_read_b128 v[152:155], v251 offset:50176
	ds_read_b128 v[156:159], v251 offset:51200
	ds_read_b128 v[160:163], v251 offset:52224
	ds_read_b128 v[164:167], v234 offset:32768
	ds_read_b128 v[168:171], v234 offset:33792
	ds_read_b128 v[172:175], v234 offset:34816
	ds_read_b128 v[176:179], v234 offset:35840
	ds_read_b128 v[180:183], v234 offset:36864
	ds_read_b128 v[184:187], v234 offset:37888
	ds_read_b128 v[206:209], v234 offset:38912
	ds_read_b128 v[210:213], v234 offset:39936
	s_add_i32 s50, 0, 0x18000
	s_add_i32 s51, 0, 0x1c000
	s_add_u32 s48, s68, 0x160000
	s_addc_u32 s49, s69, 0
	s_mov_b32 m0, s42
	v_lshl_add_u64 v[220:221], s[48:49], 0, v[192:193]
	global_load_lds_dwordx4 v[220:221], off
	v_lshl_add_u64 v[220:221], s[48:49], 0, v[190:191]
	s_mov_b32 m0, s52
	s_nop 0
	global_load_lds_dwordx4 v[220:221], off
	s_waitcnt vmcnt(8)
	s_waitcnt lgkmcnt(0)
	s_setprio 1
	s_barrier
	v_mfma_f32_16x16x32_bf16 v[144:147], v[108:111], v[164:167], v[144:147]
	v_mfma_f32_16x16x32_bf16 v[140:143], v[128:131], v[164:167], v[140:143]
	v_mfma_f32_16x16x32_bf16 v[120:123], v[108:111], v[172:175], v[120:123]
	v_mfma_f32_16x16x32_bf16 v[116:119], v[128:131], v[172:175], v[116:119]
	v_mfma_f32_16x16x32_bf16 v[96:99], v[108:111], v[180:183], v[96:99]
	v_mfma_f32_16x16x32_bf16 v[92:95], v[128:131], v[180:183], v[92:95]
	v_mfma_f32_16x16x32_bf16 v[80:83], v[108:111], v[206:209], v[80:83]
	v_mfma_f32_16x16x32_bf16 v[76:79], v[128:131], v[206:209], v[76:79]
	v_mfma_f32_16x16x32_bf16 v[144:147], v[112:115], v[168:171], v[144:147]
	v_mfma_f32_16x16x32_bf16 v[140:143], v[136:139], v[168:171], v[140:143]
	v_mfma_f32_16x16x32_bf16 v[120:123], v[112:115], v[176:179], v[120:123]
	v_mfma_f32_16x16x32_bf16 v[116:119], v[136:139], v[176:179], v[116:119]
	v_mfma_f32_16x16x32_bf16 v[96:99], v[112:115], v[184:187], v[96:99]
	v_mfma_f32_16x16x32_bf16 v[92:95], v[136:139], v[184:187], v[92:95]
	v_mfma_f32_16x16x32_bf16 v[80:83], v[112:115], v[210:213], v[80:83]
	v_mfma_f32_16x16x32_bf16 v[76:79], v[136:139], v[210:213], v[76:79]
	s_setprio 0
	s_setprio 1
	v_mfma_f32_16x16x32_bf16 v[132:135], v[148:151], v[164:167], v[132:135]
	v_mfma_f32_16x16x32_bf16 v[124:127], v[156:159], v[164:167], v[124:127]
	v_mfma_f32_16x16x32_bf16 v[104:107], v[148:151], v[172:175], v[104:107]
	v_mfma_f32_16x16x32_bf16 v[100:103], v[156:159], v[172:175], v[100:103]
	v_mfma_f32_16x16x32_bf16 v[88:91], v[148:151], v[180:183], v[88:91]
	v_mfma_f32_16x16x32_bf16 v[84:87], v[156:159], v[180:183], v[84:87]
	v_mfma_f32_16x16x32_bf16 v[72:75], v[148:151], v[206:209], v[72:75]
	v_mfma_f32_16x16x32_bf16 v[68:71], v[156:159], v[206:209], v[68:71]
	v_mfma_f32_16x16x32_bf16 v[132:135], v[152:155], v[168:171], v[132:135]
	v_mfma_f32_16x16x32_bf16 v[124:127], v[160:163], v[168:171], v[124:127]
	v_mfma_f32_16x16x32_bf16 v[104:107], v[152:155], v[176:179], v[104:107]
	v_mfma_f32_16x16x32_bf16 v[100:103], v[160:163], v[176:179], v[100:103]
	v_mfma_f32_16x16x32_bf16 v[88:91], v[152:155], v[184:187], v[88:91]
	v_mfma_f32_16x16x32_bf16 v[84:87], v[160:163], v[184:187], v[84:87]
	v_mfma_f32_16x16x32_bf16 v[72:75], v[152:155], v[210:213], v[72:75]
	v_mfma_f32_16x16x32_bf16 v[68:71], v[160:163], v[210:213], v[68:71]
	s_barrier
; #define PG8_STAGE(bufoff, gbase, voff) do { _Pragma("unroll") for (int _i = 0; _i < 2; ++_i) \
;         __builtin_amdgcn_global_load_lds((const unsigned*)((const char*)(gbase) + (voff)[_i]), (PG8_LAS unsigned*)(lds + (bufoff) + ldsw + _i * 8192), 16, 0, 0); } while (0)
; #define PG8_LDA(dst, b, h) do { _Pragma("unroll") for (int m = 0; m < 4; ++m) _Pragma("unroll") for (int k = 0; k < 2; ++k) dst[m][k] = *(const PG8_LAS bf16x8*)(lds + PG8_SA(b, h) + aoff + m * 2048 + k * 1024); } while (0)
; #define PG8_MMA(ai, bj, At, Bt) do { __builtin_amdgcn_s_setprio(1); _Pragma("unroll") for (int m = 0; m < 4; ++m) _Pragma("unroll") for (int n = 0; n < 2; ++n) _Pragma("unroll") for (int k = 0; k < 2; ++k) \
;         acc[ai][bj][m][n] = __builtin_amdgcn_mfma_f32_16x16x32_bf16(Bt[n][k], At[m][k], acc[ai][bj][m][n], 0, 0, 0); __builtin_amdgcn_s_setprio(0); } while (0)
; #define PG8_WAIT_V(n) asm volatile("s_waitcnt vmcnt(" #n ")" ::: "memory")
; #define PG8_WAIT_L(n) asm volatile("s_waitcnt lgkmcnt(" #n ")" ::: "memory")
; #define PG8_BAR __builtin_amdgcn_s_barrier()
; #define PG8_SCHED __builtin_amdgcn_sched_barrier(0)
;     ...
;             PG8_LDA(At, 1, 1); PG8_STAGE(PG8_SB(1, 0), b3, voffB); PG8_STAGE(PG8_SB(1, 1), b3 + hstep, voffB); PG8_STAGE(PG8_SA(1, 0), a3, voffA);
;             PG8_WAIT_V(8); PG8_WAIT_L(0); PG8_BAR; PG8_MMA(1, 0, At, B0); PG8_MMA(1, 1, At, B1); PG8_BAR; PG8_SCHED;
	s_setprio 0
	ds_read_b128 v[164:167], v234 offset:49152
	ds_read_b128 v[168:171], v234 offset:50176
	ds_read_b128 v[172:175], v234 offset:51200
	ds_read_b128 v[176:179], v234 offset:52224
	ds_read_b128 v[180:183], v234 offset:53248
	ds_read_b128 v[184:187], v234 offset:54272
	ds_read_b128 v[206:209], v234 offset:55296
	ds_read_b128 v[210:213], v234 offset:56320
	s_add_i32 s48, s50, s20
	v_lshl_add_u64 v[198:199], v[198:199], 0, s[66:67]
	s_mov_b32 m0, s48
	s_nop 0
	global_load_lds_dwordx4 v[198:199], off
	s_add_i32 m0, s48, 0x2000
	s_add_u32 s48, s62, 0x160080
	v_lshl_add_u64 v[198:199], v[214:215], 0, s[66:67]
	s_addc_u32 s49, s63, 0
	s_add_i32 s50, s51, s20
	global_load_lds_dwordx4 v[198:199], off
	v_lshl_add_u64 v[198:199], s[48:49], 0, v[200:201]
	s_mov_b32 m0, s50
	s_nop 0
	global_load_lds_dwordx4 v[198:199], off
	v_lshl_add_u64 v[198:199], s[48:49], 0, v[188:189]
	s_add_i32 m0, s50, 0x2000
	s_nop 0
	global_load_lds_dwordx4 v[198:199], off
	v_lshl_add_u64 v[198:199], v[216:217], 0, s[66:67]
	s_mov_b32 m0, s56
	s_nop 0
	global_load_lds_dwordx4 v[198:199], off
	v_lshl_add_u64 v[198:199], v[218:219], 0, s[66:67]
	s_mov_b32 m0, s58
	s_nop 0
	global_load_lds_dwordx4 v[198:199], off
	s_waitcnt vmcnt(8)
	s_waitcnt lgkmcnt(0)
	s_setprio 1
	s_barrier
	v_mfma_f32_16x16x32_bf16 v[64:67], v[108:111], v[164:167], v[64:67]
	v_mfma_f32_16x16x32_bf16 v[60:63], v[128:131], v[164:167], v[60:63]
	v_mfma_f32_16x16x32_bf16 v[48:51], v[108:111], v[172:175], v[48:51]
	v_mfma_f32_16x16x32_bf16 v[44:47], v[128:131], v[172:175], v[44:47]
	v_mfma_f32_16x16x32_bf16 v[32:35], v[108:111], v[180:183], v[32:35]
	v_mfma_f32_16x16x32_bf16 v[28:31], v[128:131], v[180:183], v[28:31]
	v_mfma_f32_16x16x32_bf16 v[16:19], v[108:111], v[206:209], v[16:19]
	v_mfma_f32_16x16x32_bf16 v[12:15], v[128:131], v[206:209], v[12:15]
	v_mfma_f32_16x16x32_bf16 v[64:67], v[112:115], v[168:171], v[64:67]
	v_mfma_f32_16x16x32_bf16 v[60:63], v[136:139], v[168:171], v[60:63]
	v_mfma_f32_16x16x32_bf16 v[48:51], v[112:115], v[176:179], v[48:51]
	v_mfma_f32_16x16x32_bf16 v[44:47], v[136:139], v[176:179], v[44:47]
	v_mfma_f32_16x16x32_bf16 v[32:35], v[112:115], v[184:187], v[32:35]
	v_mfma_f32_16x16x32_bf16 v[28:31], v[136:139], v[184:187], v[28:31]
	v_mfma_f32_16x16x32_bf16 v[16:19], v[112:115], v[210:213], v[16:19]
	v_mfma_f32_16x16x32_bf16 v[12:15], v[136:139], v[210:213], v[12:15]
	s_setprio 0
	s_setprio 1
	v_mfma_f32_16x16x32_bf16 v[56:59], v[148:151], v[164:167], v[56:59]
	v_mfma_f32_16x16x32_bf16 v[52:55], v[156:159], v[164:167], v[52:55]
	v_mfma_f32_16x16x32_bf16 v[40:43], v[148:151], v[172:175], v[40:43]
	v_mfma_f32_16x16x32_bf16 v[36:39], v[156:159], v[172:175], v[36:39]
	v_mfma_f32_16x16x32_bf16 v[24:27], v[148:151], v[180:183], v[24:27]
	v_mfma_f32_16x16x32_bf16 v[20:23], v[156:159], v[180:183], v[20:23]
	v_mfma_f32_16x16x32_bf16 v[8:11], v[148:151], v[206:209], v[8:11]
	v_mfma_f32_16x16x32_bf16 v[4:7], v[156:159], v[206:209], v[4:7]
	v_mfma_f32_16x16x32_bf16 v[56:59], v[152:155], v[168:171], v[56:59]
	v_mfma_f32_16x16x32_bf16 v[52:55], v[160:163], v[168:171], v[52:55]
	v_mfma_f32_16x16x32_bf16 v[40:43], v[152:155], v[176:179], v[40:43]
	v_mfma_f32_16x16x32_bf16 v[36:39], v[160:163], v[176:179], v[36:39]
	v_mfma_f32_16x16x32_bf16 v[24:27], v[152:155], v[184:187], v[24:27]
	v_mfma_f32_16x16x32_bf16 v[20:23], v[160:163], v[184:187], v[20:23]
	v_mfma_f32_16x16x32_bf16 v[8:11], v[152:155], v[210:213], v[8:11]
	v_mfma_f32_16x16x32_bf16 v[4:7], v[160:163], v[210:213], v[4:7]
	s_barrier
	s_setprio 0
	s_add_i32 s77, s77, 2
	s_add_u32 s75, s75, 0x100
	s_addc_u32 s76, s76, 0
	s_cmpk_gt_u32 s77, 0x55
	s_mov_b64 s[50:51], s[60:61]
	s_cbranch_scc0 .LBB0_1254
	s_and_b64 vcc, exec, s[12:13]
	s_cbranch_vccz .LBB0_1257
	s_barrier
